# c17: c16 + k order flipped inside every second pair so consecutive MFMAs share the accumulator or one input fragment (k-step add order within a K-tile changes)
# baseline (speedup 1.0000x reference)
.LBB0_343:
	s_ashr_i32 s11, s10, 31
	s_lshl_b64 s[12:13], s[10:11], 20
	s_add_u32 s12, s26, s12
	s_addc_u32 s13, s27, s13
	s_and_b64 s[14:15], s[2:3], exec
	s_cselect_b32 s11, s13, s21
	s_cselect_b32 s75, s12, s20
	s_ashr_i32 s9, s8, 31
	s_lshl_b64 s[14:15], s[8:9], 20
	s_add_u32 s14, s28, s14
	s_addc_u32 s15, s29, s15
	s_and_b64 s[22:23], s[2:3], exec
	s_cselect_b32 s9, s15, s19
	s_cselect_b32 s76, s14, s18
	s_add_u32 s77, s18, 0x100
	s_addc_u32 s78, s19, 0
	s_add_u32 s18, s20, 0x80080
	s_addc_u32 s19, s21, 0
	s_add_u32 s79, s20, 0x100
	s_addc_u32 s80, s21, 0
	s_mov_b32 s81, -2
	ds_read_b128 v[148:151], v143
	ds_read_b128 v[152:155], v143 offset:1024
	ds_read_b128 v[156:159], v143 offset:2048
	ds_read_b128 v[160:163], v143 offset:3072
	ds_read_b128 v[164:167], v144
	ds_read_b128 v[168:171], v144 offset:1024
	ds_read_b128 v[172:175], v144 offset:2048
	ds_read_b128 v[176:179], v144 offset:3072
	s_cmp_eq_u32 s81, 28
	s_cselect_b32 s21, s9, s78
	s_cselect_b32 s20, s76, s77
	s_cselect_b32 s23, s11, s80
	s_cselect_b32 s22, s75, s79
	ds_read_b128 v[180:183], v145
	ds_read_b128 v[184:187], v145 offset:1024
	ds_read_b128 v[188:191], v145 offset:2048
	ds_read_b128 v[192:195], v145 offset:3072
	ds_read_b128 v[196:199], v145 offset:4096
	ds_read_b128 v[200:203], v145 offset:5120
	ds_read_b128 v[204:207], v145 offset:6144
	ds_read_b128 v[208:211], v145 offset:7168
	s_add_u32 s82, s18, 0xfff80000
	s_addc_u32 s83, s19, -1
	s_mov_b32 s86, m0
	s_mov_b32 m0, s64
	s_nop 0
	global_load_lds_dwordx4 v138, s[82:83]
	s_mov_b32 m0, s86
	s_nop 0
	s_mov_b32 s86, m0
	s_mov_b32 m0, s67
	s_nop 0
	global_load_lds_dwordx4 v140, s[82:83]
	s_mov_b32 m0, s86
	s_mov_b32 s82, m0
	s_mov_b32 m0, s65
	s_nop 0
	global_load_lds_dwordx4 v138, s[18:19]
	s_mov_b32 m0, s82
	s_nop 0
	s_mov_b32 s82, m0
	s_mov_b32 m0, s73
	s_nop 0
	global_load_lds_dwordx4 v140, s[18:19]
	s_mov_b32 m0, s82
	s_waitcnt vmcnt(8)
	s_waitcnt lgkmcnt(0)
	s_barrier
	s_setprio 1
	s_waitcnt lgkmcnt(7)
	v_mfma_f32_16x16x32_bf16 v[126:129], v[148:151], v[180:183], 0
	v_mfma_f32_16x16x32_bf16 v[126:129], v[152:155], v[184:187], v[126:129]
	s_waitcnt lgkmcnt(5)
	v_mfma_f32_16x16x32_bf16 v[122:125], v[160:163], v[184:187], 0
	v_mfma_f32_16x16x32_bf16 v[122:125], v[156:159], v[180:183], v[122:125]
	s_waitcnt lgkmcnt(3)
	v_mfma_f32_16x16x32_bf16 v[106:109], v[156:159], v[188:191], 0
	v_mfma_f32_16x16x32_bf16 v[106:109], v[160:163], v[192:195], v[106:109]
	s_waitcnt lgkmcnt(1)
	v_mfma_f32_16x16x32_bf16 v[110:113], v[152:155], v[192:195], 0
	v_mfma_f32_16x16x32_bf16 v[110:113], v[148:151], v[188:191], v[110:113]
	v_mfma_f32_16x16x32_bf16 v[94:97], v[148:151], v[196:199], 0
	v_mfma_f32_16x16x32_bf16 v[94:97], v[152:155], v[200:203], v[94:97]
	v_mfma_f32_16x16x32_bf16 v[90:93], v[160:163], v[200:203], 0
	v_mfma_f32_16x16x32_bf16 v[90:93], v[156:159], v[196:199], v[90:93]
	v_mfma_f32_16x16x32_bf16 v[74:77], v[156:159], v[204:207], 0
	v_mfma_f32_16x16x32_bf16 v[74:77], v[160:163], v[208:211], v[74:77]
	s_waitcnt lgkmcnt(0)
	v_mfma_f32_16x16x32_bf16 v[78:81], v[152:155], v[208:211], 0
	v_mfma_f32_16x16x32_bf16 v[78:81], v[148:151], v[204:207], v[78:81]
	s_setprio 0
	s_setprio 1
	v_mfma_f32_16x16x32_bf16 v[118:121], v[164:167], v[180:183], 0
	v_mfma_f32_16x16x32_bf16 v[118:121], v[168:171], v[184:187], v[118:121]
	v_mfma_f32_16x16x32_bf16 v[114:117], v[176:179], v[184:187], 0
	v_mfma_f32_16x16x32_bf16 v[114:117], v[172:175], v[180:183], v[114:117]
	v_mfma_f32_16x16x32_bf16 v[98:101], v[172:175], v[188:191], 0
	v_mfma_f32_16x16x32_bf16 v[98:101], v[176:179], v[192:195], v[98:101]
	v_mfma_f32_16x16x32_bf16 v[102:105], v[168:171], v[192:195], 0
	v_mfma_f32_16x16x32_bf16 v[102:105], v[164:167], v[188:191], v[102:105]
	v_mfma_f32_16x16x32_bf16 v[86:89], v[164:167], v[196:199], 0
	v_mfma_f32_16x16x32_bf16 v[86:89], v[168:171], v[200:203], v[86:89]
	v_mfma_f32_16x16x32_bf16 v[82:85], v[176:179], v[200:203], 0
	v_mfma_f32_16x16x32_bf16 v[82:85], v[172:175], v[196:199], v[82:85]
	v_mfma_f32_16x16x32_bf16 v[66:69], v[172:175], v[204:207], 0
	v_mfma_f32_16x16x32_bf16 v[66:69], v[176:179], v[208:211], v[66:69]
	s_setprio 2
	s_barrier
	v_mfma_f32_16x16x32_bf16 v[70:73], v[168:171], v[208:211], 0
	v_mfma_f32_16x16x32_bf16 v[70:73], v[164:167], v[204:207], v[70:73]
	s_setprio 0
	ds_read_b128 v[180:183], v145 offset:16384
	ds_read_b128 v[184:187], v145 offset:17408
	ds_read_b128 v[188:191], v145 offset:18432
	ds_read_b128 v[192:195], v145 offset:19456
	ds_read_b128 v[196:199], v145 offset:20480
	ds_read_b128 v[200:203], v145 offset:21504
	ds_read_b128 v[204:207], v145 offset:22528
	ds_read_b128 v[208:211], v145 offset:23552
	s_mov_b32 s82, m0
	s_mov_b32 m0, s35
	s_nop 0
	global_load_lds_dwordx4 v139, s[20:21]
	s_mov_b32 m0, s82
	s_nop 0
	s_mov_b32 s82, m0
	s_mov_b32 m0, s36
	s_nop 0
	global_load_lds_dwordx4 v141, s[20:21]
	s_mov_b32 m0, s82
	s_add_u32 s82, s20, 0x80000
	s_addc_u32 s83, s21, 0
	s_mov_b32 s86, m0
	s_mov_b32 m0, s37
	s_nop 0
	global_load_lds_dwordx4 v139, s[82:83]
	s_mov_b32 m0, s86
	s_nop 0
	s_mov_b32 s86, m0
	s_mov_b32 m0, s42
	s_nop 0
	global_load_lds_dwordx4 v141, s[82:83]
	s_mov_b32 m0, s86
	s_waitcnt vmcnt(4)
	s_waitcnt lgkmcnt(0)
	s_barrier
	s_setprio 1
	s_waitcnt lgkmcnt(7)
	v_mfma_f32_16x16x32_bf16 v[62:65], v[148:151], v[180:183], 0
	v_mfma_f32_16x16x32_bf16 v[62:65], v[152:155], v[184:187], v[62:65]
	s_waitcnt lgkmcnt(5)
	v_mfma_f32_16x16x32_bf16 v[58:61], v[160:163], v[184:187], 0
	v_mfma_f32_16x16x32_bf16 v[58:61], v[156:159], v[180:183], v[58:61]
	s_waitcnt lgkmcnt(3)
	v_mfma_f32_16x16x32_bf16 v[42:45], v[156:159], v[188:191], 0
	v_mfma_f32_16x16x32_bf16 v[42:45], v[160:163], v[192:195], v[42:45]
	s_waitcnt lgkmcnt(1)
	v_mfma_f32_16x16x32_bf16 v[46:49], v[152:155], v[192:195], 0
	v_mfma_f32_16x16x32_bf16 v[46:49], v[148:151], v[188:191], v[46:49]
	v_mfma_f32_16x16x32_bf16 v[30:33], v[148:151], v[196:199], 0
	v_mfma_f32_16x16x32_bf16 v[30:33], v[152:155], v[200:203], v[30:33]
	v_mfma_f32_16x16x32_bf16 v[26:29], v[160:163], v[200:203], 0
	v_mfma_f32_16x16x32_bf16 v[26:29], v[156:159], v[196:199], v[26:29]
	v_mfma_f32_16x16x32_bf16 v[10:13], v[156:159], v[204:207], 0
	v_mfma_f32_16x16x32_bf16 v[10:13], v[160:163], v[208:211], v[10:13]
	s_waitcnt lgkmcnt(0)
	v_mfma_f32_16x16x32_bf16 v[14:17], v[152:155], v[208:211], 0
	v_mfma_f32_16x16x32_bf16 v[14:17], v[148:151], v[204:207], v[14:17]
	s_setprio 0
	s_setprio 1
	v_mfma_f32_16x16x32_bf16 v[54:57], v[164:167], v[180:183], 0
	v_mfma_f32_16x16x32_bf16 v[54:57], v[168:171], v[184:187], v[54:57]
	v_mfma_f32_16x16x32_bf16 v[50:53], v[176:179], v[184:187], 0
	v_mfma_f32_16x16x32_bf16 v[50:53], v[172:175], v[180:183], v[50:53]
	v_mfma_f32_16x16x32_bf16 v[34:37], v[172:175], v[188:191], 0
	v_mfma_f32_16x16x32_bf16 v[34:37], v[176:179], v[192:195], v[34:37]
	v_mfma_f32_16x16x32_bf16 v[38:41], v[168:171], v[192:195], 0
	v_mfma_f32_16x16x32_bf16 v[38:41], v[164:167], v[188:191], v[38:41]
	v_mfma_f32_16x16x32_bf16 v[22:25], v[164:167], v[196:199], 0
	v_mfma_f32_16x16x32_bf16 v[22:25], v[168:171], v[200:203], v[22:25]
	v_mfma_f32_16x16x32_bf16 v[18:21], v[176:179], v[200:203], 0
	v_mfma_f32_16x16x32_bf16 v[18:21], v[172:175], v[196:199], v[18:21]
	v_mfma_f32_16x16x32_bf16 v[2:5], v[172:175], v[204:207], 0
	v_mfma_f32_16x16x32_bf16 v[2:5], v[176:179], v[208:211], v[2:5]
	s_setprio 2
	s_barrier
	v_mfma_f32_16x16x32_bf16 v[6:9], v[168:171], v[208:211], 0
	v_mfma_f32_16x16x32_bf16 v[6:9], v[164:167], v[204:207], v[6:9]
	s_setprio 0
	ds_read_b128 v[148:151], v146
	ds_read_b128 v[152:155], v146 offset:1024
	ds_read_b128 v[156:159], v146 offset:2048
	ds_read_b128 v[160:163], v146 offset:3072
	ds_read_b128 v[164:167], v147
	ds_read_b128 v[168:171], v147 offset:1024
	ds_read_b128 v[172:175], v147 offset:2048
	ds_read_b128 v[176:179], v147 offset:3072
	ds_read_b128 v[180:183], v145 offset:32768
	ds_read_b128 v[184:187], v145 offset:33792
	ds_read_b128 v[188:191], v145 offset:34816
	ds_read_b128 v[192:195], v145 offset:35840
	ds_read_b128 v[196:199], v145 offset:36864
	ds_read_b128 v[200:203], v145 offset:37888
	ds_read_b128 v[204:207], v145 offset:38912
	ds_read_b128 v[208:211], v145 offset:39936
	s_mov_b32 s82, m0
	s_mov_b32 m0, s31
	s_nop 0
	global_load_lds_dwordx4 v138, s[22:23]
	s_mov_b32 m0, s82
	s_nop 0
	s_mov_b32 s82, m0
	s_mov_b32 m0, s43
	s_nop 0
	global_load_lds_dwordx4 v140, s[22:23]
	s_mov_b32 m0, s82
	s_add_u32 s22, s22, 0x80000
	s_addc_u32 s23, s23, 0
	s_mov_b32 s82, m0
	s_mov_b32 m0, s46
	s_nop 0
	global_load_lds_dwordx4 v138, s[22:23]
	s_mov_b32 m0, s82
	s_nop 0
	s_mov_b32 s82, m0
	s_mov_b32 m0, s47
	s_nop 0
	global_load_lds_dwordx4 v140, s[22:23]
	s_mov_b32 m0, s82
	s_waitcnt vmcnt(8)
	s_waitcnt lgkmcnt(0)
	s_barrier
	s_setprio 1
	s_waitcnt lgkmcnt(7)
	v_mfma_f32_16x16x32_bf16 v[126:129], v[148:151], v[180:183], v[126:129]
	v_mfma_f32_16x16x32_bf16 v[126:129], v[152:155], v[184:187], v[126:129]
	s_waitcnt lgkmcnt(5)
	v_mfma_f32_16x16x32_bf16 v[122:125], v[160:163], v[184:187], v[122:125]
	v_mfma_f32_16x16x32_bf16 v[122:125], v[156:159], v[180:183], v[122:125]
	s_waitcnt lgkmcnt(3)
	v_mfma_f32_16x16x32_bf16 v[106:109], v[156:159], v[188:191], v[106:109]
	v_mfma_f32_16x16x32_bf16 v[106:109], v[160:163], v[192:195], v[106:109]
	s_waitcnt lgkmcnt(1)
	v_mfma_f32_16x16x32_bf16 v[110:113], v[152:155], v[192:195], v[110:113]
	v_mfma_f32_16x16x32_bf16 v[110:113], v[148:151], v[188:191], v[110:113]
	v_mfma_f32_16x16x32_bf16 v[94:97], v[148:151], v[196:199], v[94:97]
	v_mfma_f32_16x16x32_bf16 v[94:97], v[152:155], v[200:203], v[94:97]
	v_mfma_f32_16x16x32_bf16 v[90:93], v[160:163], v[200:203], v[90:93]
	v_mfma_f32_16x16x32_bf16 v[90:93], v[156:159], v[196:199], v[90:93]
	v_mfma_f32_16x16x32_bf16 v[74:77], v[156:159], v[204:207], v[74:77]
	v_mfma_f32_16x16x32_bf16 v[74:77], v[160:163], v[208:211], v[74:77]
	s_waitcnt lgkmcnt(0)
	v_mfma_f32_16x16x32_bf16 v[78:81], v[152:155], v[208:211], v[78:81]
	v_mfma_f32_16x16x32_bf16 v[78:81], v[148:151], v[204:207], v[78:81]
	s_setprio 0
	s_setprio 1
	v_mfma_f32_16x16x32_bf16 v[118:121], v[164:167], v[180:183], v[118:121]
	v_mfma_f32_16x16x32_bf16 v[118:121], v[168:171], v[184:187], v[118:121]
	v_mfma_f32_16x16x32_bf16 v[114:117], v[176:179], v[184:187], v[114:117]
	v_mfma_f32_16x16x32_bf16 v[114:117], v[172:175], v[180:183], v[114:117]
	v_mfma_f32_16x16x32_bf16 v[98:101], v[172:175], v[188:191], v[98:101]
	v_mfma_f32_16x16x32_bf16 v[98:101], v[176:179], v[192:195], v[98:101]
	v_mfma_f32_16x16x32_bf16 v[102:105], v[168:171], v[192:195], v[102:105]
	v_mfma_f32_16x16x32_bf16 v[102:105], v[164:167], v[188:191], v[102:105]
	v_mfma_f32_16x16x32_bf16 v[86:89], v[164:167], v[196:199], v[86:89]
	v_mfma_f32_16x16x32_bf16 v[86:89], v[168:171], v[200:203], v[86:89]
	v_mfma_f32_16x16x32_bf16 v[82:85], v[176:179], v[200:203], v[82:85]
	v_mfma_f32_16x16x32_bf16 v[82:85], v[172:175], v[196:199], v[82:85]
	v_mfma_f32_16x16x32_bf16 v[66:69], v[172:175], v[204:207], v[66:69]
	v_mfma_f32_16x16x32_bf16 v[66:69], v[176:179], v[208:211], v[66:69]
	s_setprio 2
	s_barrier
	v_mfma_f32_16x16x32_bf16 v[70:73], v[168:171], v[208:211], v[70:73]
	v_mfma_f32_16x16x32_bf16 v[70:73], v[164:167], v[204:207], v[70:73]
	s_setprio 0
	ds_read_b128 v[180:183], v145 offset:49152
	ds_read_b128 v[184:187], v145 offset:50176
	ds_read_b128 v[188:191], v145 offset:51200
	ds_read_b128 v[192:195], v145 offset:52224
	ds_read_b128 v[196:199], v145 offset:53248
	ds_read_b128 v[200:203], v145 offset:54272
	ds_read_b128 v[204:207], v145 offset:55296
	ds_read_b128 v[208:211], v145 offset:56320
	s_add_u32 s22, s20, 0x80
	s_addc_u32 s23, s21, 0
	s_mov_b32 s82, m0
	s_mov_b32 m0, s48
	s_nop 0
	global_load_lds_dwordx4 v139, s[22:23]
	s_mov_b32 m0, s82
	s_add_u32 s20, s20, 0x80080
	s_mov_b32 s82, m0
	s_mov_b32 m0, s49
	s_nop 0
	global_load_lds_dwordx4 v141, s[22:23]
	s_mov_b32 m0, s82
	s_addc_u32 s21, s21, 0
	s_mov_b32 s22, m0
	s_mov_b32 m0, s56
	s_nop 0
	global_load_lds_dwordx4 v139, s[20:21]
	s_mov_b32 m0, s22
	s_nop 0
	s_mov_b32 s22, m0
	s_mov_b32 m0, s57
	s_nop 0
	global_load_lds_dwordx4 v141, s[20:21]
	s_mov_b32 m0, s22
	s_waitcnt vmcnt(4)
	s_waitcnt lgkmcnt(0)
	s_barrier
	s_setprio 1
	s_waitcnt lgkmcnt(7)
	v_mfma_f32_16x16x32_bf16 v[62:65], v[148:151], v[180:183], v[62:65]
	v_mfma_f32_16x16x32_bf16 v[62:65], v[152:155], v[184:187], v[62:65]
	s_waitcnt lgkmcnt(5)
	v_mfma_f32_16x16x32_bf16 v[58:61], v[160:163], v[184:187], v[58:61]
	v_mfma_f32_16x16x32_bf16 v[58:61], v[156:159], v[180:183], v[58:61]
	s_waitcnt lgkmcnt(3)
	v_mfma_f32_16x16x32_bf16 v[42:45], v[156:159], v[188:191], v[42:45]
	v_mfma_f32_16x16x32_bf16 v[42:45], v[160:163], v[192:195], v[42:45]
	s_waitcnt lgkmcnt(1)
	v_mfma_f32_16x16x32_bf16 v[46:49], v[152:155], v[192:195], v[46:49]
	v_mfma_f32_16x16x32_bf16 v[46:49], v[148:151], v[188:191], v[46:49]
	v_mfma_f32_16x16x32_bf16 v[30:33], v[148:151], v[196:199], v[30:33]
	v_mfma_f32_16x16x32_bf16 v[30:33], v[152:155], v[200:203], v[30:33]
	v_mfma_f32_16x16x32_bf16 v[26:29], v[160:163], v[200:203], v[26:29]
	v_mfma_f32_16x16x32_bf16 v[26:29], v[156:159], v[196:199], v[26:29]
	v_mfma_f32_16x16x32_bf16 v[10:13], v[156:159], v[204:207], v[10:13]
	v_mfma_f32_16x16x32_bf16 v[10:13], v[160:163], v[208:211], v[10:13]
	s_waitcnt lgkmcnt(0)
	v_mfma_f32_16x16x32_bf16 v[14:17], v[152:155], v[208:211], v[14:17]
	v_mfma_f32_16x16x32_bf16 v[14:17], v[148:151], v[204:207], v[14:17]
	s_setprio 0
	s_setprio 1
	v_mfma_f32_16x16x32_bf16 v[54:57], v[164:167], v[180:183], v[54:57]
	v_mfma_f32_16x16x32_bf16 v[54:57], v[168:171], v[184:187], v[54:57]
	v_mfma_f32_16x16x32_bf16 v[50:53], v[176:179], v[184:187], v[50:53]
	v_mfma_f32_16x16x32_bf16 v[50:53], v[172:175], v[180:183], v[50:53]
	v_mfma_f32_16x16x32_bf16 v[34:37], v[172:175], v[188:191], v[34:37]
	v_mfma_f32_16x16x32_bf16 v[34:37], v[176:179], v[192:195], v[34:37]
	v_mfma_f32_16x16x32_bf16 v[38:41], v[168:171], v[192:195], v[38:41]
	v_mfma_f32_16x16x32_bf16 v[38:41], v[164:167], v[188:191], v[38:41]
	v_mfma_f32_16x16x32_bf16 v[22:25], v[164:167], v[196:199], v[22:25]
	v_mfma_f32_16x16x32_bf16 v[22:25], v[168:171], v[200:203], v[22:25]
	v_mfma_f32_16x16x32_bf16 v[18:21], v[176:179], v[200:203], v[18:21]
	v_mfma_f32_16x16x32_bf16 v[18:21], v[172:175], v[196:199], v[18:21]
	v_mfma_f32_16x16x32_bf16 v[2:5], v[172:175], v[204:207], v[2:5]
	v_mfma_f32_16x16x32_bf16 v[2:5], v[176:179], v[208:211], v[2:5]
	s_setprio 2
	s_barrier
	v_mfma_f32_16x16x32_bf16 v[6:9], v[168:171], v[208:211], v[6:9]
	v_mfma_f32_16x16x32_bf16 v[6:9], v[164:167], v[204:207], v[6:9]
	s_setprio 0
	s_add_i32 s81, s81, 2
	s_add_u32 s77, s77, 0x100
	s_addc_u32 s78, s78, 0
	s_add_u32 s18, s18, 0x100
	s_addc_u32 s19, s19, 0
	s_add_u32 s79, s79, 0x100
	s_addc_u32 s80, s80, 0
	s_cmp_gt_u32 s81, 29
	.p2align 6
.LBB0_344:
	ds_read_b128 v[148:151], v143
	ds_read_b128 v[152:155], v143 offset:1024
	ds_read_b128 v[156:159], v143 offset:2048
	ds_read_b128 v[160:163], v143 offset:3072
	ds_read_b128 v[164:167], v144
	ds_read_b128 v[168:171], v144 offset:1024
	ds_read_b128 v[172:175], v144 offset:2048
	ds_read_b128 v[176:179], v144 offset:3072
	s_cmp_eq_u32 s81, 28
	s_cselect_b32 s21, s9, s78
	s_cselect_b32 s20, s76, s77
	s_cselect_b32 s23, s11, s80
	s_cselect_b32 s22, s75, s79
	ds_read_b128 v[180:183], v145
	ds_read_b128 v[184:187], v145 offset:1024
	ds_read_b128 v[188:191], v145 offset:2048
	ds_read_b128 v[192:195], v145 offset:3072
	ds_read_b128 v[196:199], v145 offset:4096
	ds_read_b128 v[200:203], v145 offset:5120
	ds_read_b128 v[204:207], v145 offset:6144
	ds_read_b128 v[208:211], v145 offset:7168
	s_add_u32 s82, s18, 0xfff80000
	s_addc_u32 s83, s19, -1
	s_mov_b32 s86, m0
	s_mov_b32 m0, s64
	s_nop 0
	global_load_lds_dwordx4 v138, s[82:83]
	s_mov_b32 m0, s86
	s_nop 0
	s_mov_b32 s86, m0
	s_mov_b32 m0, s67
	s_nop 0
	global_load_lds_dwordx4 v140, s[82:83]
	s_mov_b32 m0, s86
	s_mov_b32 s82, m0
	s_mov_b32 m0, s65
	s_nop 0
	global_load_lds_dwordx4 v138, s[18:19]
	s_mov_b32 m0, s82
	s_nop 0
	s_mov_b32 s82, m0
	s_mov_b32 m0, s73
	s_nop 0
	global_load_lds_dwordx4 v140, s[18:19]
	s_mov_b32 m0, s82
	s_waitcnt vmcnt(8)
	s_waitcnt lgkmcnt(0)
	s_barrier
	s_setprio 1
	s_waitcnt lgkmcnt(7)
	v_mfma_f32_16x16x32_bf16 v[126:129], v[148:151], v[180:183], v[126:129]
	v_mfma_f32_16x16x32_bf16 v[126:129], v[152:155], v[184:187], v[126:129]
	s_waitcnt lgkmcnt(5)
	v_mfma_f32_16x16x32_bf16 v[122:125], v[160:163], v[184:187], v[122:125]
	v_mfma_f32_16x16x32_bf16 v[122:125], v[156:159], v[180:183], v[122:125]
	s_waitcnt lgkmcnt(3)
	v_mfma_f32_16x16x32_bf16 v[106:109], v[156:159], v[188:191], v[106:109]
	v_mfma_f32_16x16x32_bf16 v[106:109], v[160:163], v[192:195], v[106:109]
	s_waitcnt lgkmcnt(1)
	v_mfma_f32_16x16x32_bf16 v[110:113], v[152:155], v[192:195], v[110:113]
	v_mfma_f32_16x16x32_bf16 v[110:113], v[148:151], v[188:191], v[110:113]
	v_mfma_f32_16x16x32_bf16 v[94:97], v[148:151], v[196:199], v[94:97]
	v_mfma_f32_16x16x32_bf16 v[94:97], v[152:155], v[200:203], v[94:97]
	v_mfma_f32_16x16x32_bf16 v[90:93], v[160:163], v[200:203], v[90:93]
	v_mfma_f32_16x16x32_bf16 v[90:93], v[156:159], v[196:199], v[90:93]
	v_mfma_f32_16x16x32_bf16 v[74:77], v[156:159], v[204:207], v[74:77]
	v_mfma_f32_16x16x32_bf16 v[74:77], v[160:163], v[208:211], v[74:77]
	s_waitcnt lgkmcnt(0)
	v_mfma_f32_16x16x32_bf16 v[78:81], v[152:155], v[208:211], v[78:81]
	v_mfma_f32_16x16x32_bf16 v[78:81], v[148:151], v[204:207], v[78:81]
	s_setprio 0
	s_setprio 1
	v_mfma_f32_16x16x32_bf16 v[118:121], v[164:167], v[180:183], v[118:121]
	v_mfma_f32_16x16x32_bf16 v[118:121], v[168:171], v[184:187], v[118:121]
	v_mfma_f32_16x16x32_bf16 v[114:117], v[176:179], v[184:187], v[114:117]
	v_mfma_f32_16x16x32_bf16 v[114:117], v[172:175], v[180:183], v[114:117]
	v_mfma_f32_16x16x32_bf16 v[98:101], v[172:175], v[188:191], v[98:101]
	v_mfma_f32_16x16x32_bf16 v[98:101], v[176:179], v[192:195], v[98:101]
	v_mfma_f32_16x16x32_bf16 v[102:105], v[168:171], v[192:195], v[102:105]
	v_mfma_f32_16x16x32_bf16 v[102:105], v[164:167], v[188:191], v[102:105]
	v_mfma_f32_16x16x32_bf16 v[86:89], v[164:167], v[196:199], v[86:89]
	v_mfma_f32_16x16x32_bf16 v[86:89], v[168:171], v[200:203], v[86:89]
	v_mfma_f32_16x16x32_bf16 v[82:85], v[176:179], v[200:203], v[82:85]
	v_mfma_f32_16x16x32_bf16 v[82:85], v[172:175], v[196:199], v[82:85]
	v_mfma_f32_16x16x32_bf16 v[66:69], v[172:175], v[204:207], v[66:69]
	v_mfma_f32_16x16x32_bf16 v[66:69], v[176:179], v[208:211], v[66:69]
	s_setprio 2
	s_barrier
	v_mfma_f32_16x16x32_bf16 v[70:73], v[168:171], v[208:211], v[70:73]
	v_mfma_f32_16x16x32_bf16 v[70:73], v[164:167], v[204:207], v[70:73]
	s_setprio 0
	ds_read_b128 v[180:183], v145 offset:16384
	ds_read_b128 v[184:187], v145 offset:17408
	ds_read_b128 v[188:191], v145 offset:18432
	ds_read_b128 v[192:195], v145 offset:19456
	ds_read_b128 v[196:199], v145 offset:20480
	ds_read_b128 v[200:203], v145 offset:21504
	ds_read_b128 v[204:207], v145 offset:22528
	ds_read_b128 v[208:211], v145 offset:23552
	s_mov_b32 s82, m0
	s_mov_b32 m0, s35
	s_nop 0
	global_load_lds_dwordx4 v139, s[20:21]
	s_mov_b32 m0, s82
	s_nop 0
	s_mov_b32 s82, m0
	s_mov_b32 m0, s36
	s_nop 0
	global_load_lds_dwordx4 v141, s[20:21]
	s_mov_b32 m0, s82
	s_add_u32 s82, s20, 0x80000
	s_addc_u32 s83, s21, 0
	s_mov_b32 s86, m0
	s_mov_b32 m0, s37
	s_nop 0
	global_load_lds_dwordx4 v139, s[82:83]
	s_mov_b32 m0, s86
	s_nop 0
	s_mov_b32 s86, m0
	s_mov_b32 m0, s42
	s_nop 0
	global_load_lds_dwordx4 v141, s[82:83]
	s_mov_b32 m0, s86
	s_waitcnt vmcnt(4)
	s_waitcnt lgkmcnt(0)
	s_barrier
	s_setprio 1
	s_waitcnt lgkmcnt(7)
	v_mfma_f32_16x16x32_bf16 v[62:65], v[148:151], v[180:183], v[62:65]
	v_mfma_f32_16x16x32_bf16 v[62:65], v[152:155], v[184:187], v[62:65]
	s_waitcnt lgkmcnt(5)
	v_mfma_f32_16x16x32_bf16 v[58:61], v[160:163], v[184:187], v[58:61]
	v_mfma_f32_16x16x32_bf16 v[58:61], v[156:159], v[180:183], v[58:61]
	s_waitcnt lgkmcnt(3)
	v_mfma_f32_16x16x32_bf16 v[42:45], v[156:159], v[188:191], v[42:45]
	v_mfma_f32_16x16x32_bf16 v[42:45], v[160:163], v[192:195], v[42:45]
	s_waitcnt lgkmcnt(1)
	v_mfma_f32_16x16x32_bf16 v[46:49], v[152:155], v[192:195], v[46:49]
	v_mfma_f32_16x16x32_bf16 v[46:49], v[148:151], v[188:191], v[46:49]
	v_mfma_f32_16x16x32_bf16 v[30:33], v[148:151], v[196:199], v[30:33]
	v_mfma_f32_16x16x32_bf16 v[30:33], v[152:155], v[200:203], v[30:33]
	v_mfma_f32_16x16x32_bf16 v[26:29], v[160:163], v[200:203], v[26:29]
	v_mfma_f32_16x16x32_bf16 v[26:29], v[156:159], v[196:199], v[26:29]
	v_mfma_f32_16x16x32_bf16 v[10:13], v[156:159], v[204:207], v[10:13]
	v_mfma_f32_16x16x32_bf16 v[10:13], v[160:163], v[208:211], v[10:13]
	s_waitcnt lgkmcnt(0)
	v_mfma_f32_16x16x32_bf16 v[14:17], v[152:155], v[208:211], v[14:17]
	v_mfma_f32_16x16x32_bf16 v[14:17], v[148:151], v[204:207], v[14:17]
	s_setprio 0
	s_setprio 1
	v_mfma_f32_16x16x32_bf16 v[54:57], v[164:167], v[180:183], v[54:57]
	v_mfma_f32_16x16x32_bf16 v[54:57], v[168:171], v[184:187], v[54:57]
	v_mfma_f32_16x16x32_bf16 v[50:53], v[176:179], v[184:187], v[50:53]
	v_mfma_f32_16x16x32_bf16 v[50:53], v[172:175], v[180:183], v[50:53]
	v_mfma_f32_16x16x32_bf16 v[34:37], v[172:175], v[188:191], v[34:37]
	v_mfma_f32_16x16x32_bf16 v[34:37], v[176:179], v[192:195], v[34:37]
	v_mfma_f32_16x16x32_bf16 v[38:41], v[168:171], v[192:195], v[38:41]
	v_mfma_f32_16x16x32_bf16 v[38:41], v[164:167], v[188:191], v[38:41]
	v_mfma_f32_16x16x32_bf16 v[22:25], v[164:167], v[196:199], v[22:25]
	v_mfma_f32_16x16x32_bf16 v[22:25], v[168:171], v[200:203], v[22:25]
	v_mfma_f32_16x16x32_bf16 v[18:21], v[176:179], v[200:203], v[18:21]
	v_mfma_f32_16x16x32_bf16 v[18:21], v[172:175], v[196:199], v[18:21]
	v_mfma_f32_16x16x32_bf16 v[2:5], v[172:175], v[204:207], v[2:5]
	v_mfma_f32_16x16x32_bf16 v[2:5], v[176:179], v[208:211], v[2:5]
	s_setprio 2
	s_barrier
	v_mfma_f32_16x16x32_bf16 v[6:9], v[168:171], v[208:211], v[6:9]
	v_mfma_f32_16x16x32_bf16 v[6:9], v[164:167], v[204:207], v[6:9]
	s_setprio 0
	ds_read_b128 v[148:151], v146
	ds_read_b128 v[152:155], v146 offset:1024
	ds_read_b128 v[156:159], v146 offset:2048
	ds_read_b128 v[160:163], v146 offset:3072
	ds_read_b128 v[164:167], v147
	ds_read_b128 v[168:171], v147 offset:1024
	ds_read_b128 v[172:175], v147 offset:2048
	ds_read_b128 v[176:179], v147 offset:3072
	ds_read_b128 v[180:183], v145 offset:32768
	ds_read_b128 v[184:187], v145 offset:33792
	ds_read_b128 v[188:191], v145 offset:34816
	ds_read_b128 v[192:195], v145 offset:35840
	ds_read_b128 v[196:199], v145 offset:36864
	ds_read_b128 v[200:203], v145 offset:37888
	ds_read_b128 v[204:207], v145 offset:38912
	ds_read_b128 v[208:211], v145 offset:39936
	s_mov_b32 s82, m0
	s_mov_b32 m0, s31
	s_nop 0
	global_load_lds_dwordx4 v138, s[22:23]
	s_mov_b32 m0, s82
	s_nop 0
	s_mov_b32 s82, m0
	s_mov_b32 m0, s43
	s_nop 0
	global_load_lds_dwordx4 v140, s[22:23]
	s_mov_b32 m0, s82
	s_add_u32 s22, s22, 0x80000
	s_addc_u32 s23, s23, 0
	s_mov_b32 s82, m0
	s_mov_b32 m0, s46
	s_nop 0
	global_load_lds_dwordx4 v138, s[22:23]
	s_mov_b32 m0, s82
	s_nop 0
	s_mov_b32 s82, m0
	s_mov_b32 m0, s47
	s_nop 0
	global_load_lds_dwordx4 v140, s[22:23]
	s_mov_b32 m0, s82
	s_waitcnt vmcnt(8)
	s_waitcnt lgkmcnt(0)
	s_barrier
	s_setprio 1
	s_waitcnt lgkmcnt(7)
	v_mfma_f32_16x16x32_bf16 v[126:129], v[148:151], v[180:183], v[126:129]
	v_mfma_f32_16x16x32_bf16 v[126:129], v[152:155], v[184:187], v[126:129]
	s_waitcnt lgkmcnt(5)
	v_mfma_f32_16x16x32_bf16 v[122:125], v[160:163], v[184:187], v[122:125]
	v_mfma_f32_16x16x32_bf16 v[122:125], v[156:159], v[180:183], v[122:125]
	s_waitcnt lgkmcnt(3)
	v_mfma_f32_16x16x32_bf16 v[106:109], v[156:159], v[188:191], v[106:109]
	v_mfma_f32_16x16x32_bf16 v[106:109], v[160:163], v[192:195], v[106:109]
	s_waitcnt lgkmcnt(1)
	v_mfma_f32_16x16x32_bf16 v[110:113], v[152:155], v[192:195], v[110:113]
	v_mfma_f32_16x16x32_bf16 v[110:113], v[148:151], v[188:191], v[110:113]
	v_mfma_f32_16x16x32_bf16 v[94:97], v[148:151], v[196:199], v[94:97]
	v_mfma_f32_16x16x32_bf16 v[94:97], v[152:155], v[200:203], v[94:97]
	v_mfma_f32_16x16x32_bf16 v[90:93], v[160:163], v[200:203], v[90:93]
	v_mfma_f32_16x16x32_bf16 v[90:93], v[156:159], v[196:199], v[90:93]
	v_mfma_f32_16x16x32_bf16 v[74:77], v[156:159], v[204:207], v[74:77]
	v_mfma_f32_16x16x32_bf16 v[74:77], v[160:163], v[208:211], v[74:77]
	s_waitcnt lgkmcnt(0)
	v_mfma_f32_16x16x32_bf16 v[78:81], v[152:155], v[208:211], v[78:81]
	v_mfma_f32_16x16x32_bf16 v[78:81], v[148:151], v[204:207], v[78:81]
	s_setprio 0
	s_setprio 1
	v_mfma_f32_16x16x32_bf16 v[118:121], v[164:167], v[180:183], v[118:121]
	v_mfma_f32_16x16x32_bf16 v[118:121], v[168:171], v[184:187], v[118:121]
	v_mfma_f32_16x16x32_bf16 v[114:117], v[176:179], v[184:187], v[114:117]
	v_mfma_f32_16x16x32_bf16 v[114:117], v[172:175], v[180:183], v[114:117]
	v_mfma_f32_16x16x32_bf16 v[98:101], v[172:175], v[188:191], v[98:101]
	v_mfma_f32_16x16x32_bf16 v[98:101], v[176:179], v[192:195], v[98:101]
	v_mfma_f32_16x16x32_bf16 v[102:105], v[168:171], v[192:195], v[102:105]
	v_mfma_f32_16x16x32_bf16 v[102:105], v[164:167], v[188:191], v[102:105]
	v_mfma_f32_16x16x32_bf16 v[86:89], v[164:167], v[196:199], v[86:89]
	v_mfma_f32_16x16x32_bf16 v[86:89], v[168:171], v[200:203], v[86:89]
	v_mfma_f32_16x16x32_bf16 v[82:85], v[176:179], v[200:203], v[82:85]
	v_mfma_f32_16x16x32_bf16 v[82:85], v[172:175], v[196:199], v[82:85]
	v_mfma_f32_16x16x32_bf16 v[66:69], v[172:175], v[204:207], v[66:69]
	v_mfma_f32_16x16x32_bf16 v[66:69], v[176:179], v[208:211], v[66:69]
	s_setprio 2
	s_barrier
	v_mfma_f32_16x16x32_bf16 v[70:73], v[168:171], v[208:211], v[70:73]
	v_mfma_f32_16x16x32_bf16 v[70:73], v[164:167], v[204:207], v[70:73]
	s_setprio 0
	ds_read_b128 v[180:183], v145 offset:49152
	ds_read_b128 v[184:187], v145 offset:50176
	ds_read_b128 v[188:191], v145 offset:51200
	ds_read_b128 v[192:195], v145 offset:52224
	ds_read_b128 v[196:199], v145 offset:53248
	ds_read_b128 v[200:203], v145 offset:54272
	ds_read_b128 v[204:207], v145 offset:55296
	ds_read_b128 v[208:211], v145 offset:56320
	s_add_u32 s22, s20, 0x80
	s_addc_u32 s23, s21, 0
	s_mov_b32 s82, m0
	s_mov_b32 m0, s48
	s_nop 0
	global_load_lds_dwordx4 v139, s[22:23]
	s_mov_b32 m0, s82
	s_add_u32 s20, s20, 0x80080
	s_mov_b32 s82, m0
	s_mov_b32 m0, s49
	s_nop 0
	global_load_lds_dwordx4 v141, s[22:23]
	s_mov_b32 m0, s82
	s_addc_u32 s21, s21, 0
	s_mov_b32 s22, m0
	s_mov_b32 m0, s56
	s_nop 0
	global_load_lds_dwordx4 v139, s[20:21]
	s_mov_b32 m0, s22
	s_nop 0
	s_mov_b32 s22, m0
	s_mov_b32 m0, s57
	s_nop 0
	global_load_lds_dwordx4 v141, s[20:21]
	s_mov_b32 m0, s22
	s_waitcnt vmcnt(4)
	s_waitcnt lgkmcnt(0)
	s_barrier
	s_setprio 1
	s_waitcnt lgkmcnt(7)
	v_mfma_f32_16x16x32_bf16 v[62:65], v[148:151], v[180:183], v[62:65]
	v_mfma_f32_16x16x32_bf16 v[62:65], v[152:155], v[184:187], v[62:65]
	s_waitcnt lgkmcnt(5)
	v_mfma_f32_16x16x32_bf16 v[58:61], v[160:163], v[184:187], v[58:61]
	v_mfma_f32_16x16x32_bf16 v[58:61], v[156:159], v[180:183], v[58:61]
	s_waitcnt lgkmcnt(3)
	v_mfma_f32_16x16x32_bf16 v[42:45], v[156:159], v[188:191], v[42:45]
	v_mfma_f32_16x16x32_bf16 v[42:45], v[160:163], v[192:195], v[42:45]
	s_waitcnt lgkmcnt(1)
	v_mfma_f32_16x16x32_bf16 v[46:49], v[152:155], v[192:195], v[46:49]
	v_mfma_f32_16x16x32_bf16 v[46:49], v[148:151], v[188:191], v[46:49]
	v_mfma_f32_16x16x32_bf16 v[30:33], v[148:151], v[196:199], v[30:33]
	v_mfma_f32_16x16x32_bf16 v[30:33], v[152:155], v[200:203], v[30:33]
	v_mfma_f32_16x16x32_bf16 v[26:29], v[160:163], v[200:203], v[26:29]
	v_mfma_f32_16x16x32_bf16 v[26:29], v[156:159], v[196:199], v[26:29]
	v_mfma_f32_16x16x32_bf16 v[10:13], v[156:159], v[204:207], v[10:13]
	v_mfma_f32_16x16x32_bf16 v[10:13], v[160:163], v[208:211], v[10:13]
	s_waitcnt lgkmcnt(0)
	v_mfma_f32_16x16x32_bf16 v[14:17], v[152:155], v[208:211], v[14:17]
	v_mfma_f32_16x16x32_bf16 v[14:17], v[148:151], v[204:207], v[14:17]
	s_setprio 0
	s_setprio 1
	v_mfma_f32_16x16x32_bf16 v[54:57], v[164:167], v[180:183], v[54:57]
	v_mfma_f32_16x16x32_bf16 v[54:57], v[168:171], v[184:187], v[54:57]
	v_mfma_f32_16x16x32_bf16 v[50:53], v[176:179], v[184:187], v[50:53]
	v_mfma_f32_16x16x32_bf16 v[50:53], v[172:175], v[180:183], v[50:53]
	v_mfma_f32_16x16x32_bf16 v[34:37], v[172:175], v[188:191], v[34:37]
	v_mfma_f32_16x16x32_bf16 v[34:37], v[176:179], v[192:195], v[34:37]
	v_mfma_f32_16x16x32_bf16 v[38:41], v[168:171], v[192:195], v[38:41]
	v_mfma_f32_16x16x32_bf16 v[38:41], v[164:167], v[188:191], v[38:41]
	v_mfma_f32_16x16x32_bf16 v[22:25], v[164:167], v[196:199], v[22:25]
	v_mfma_f32_16x16x32_bf16 v[22:25], v[168:171], v[200:203], v[22:25]
	v_mfma_f32_16x16x32_bf16 v[18:21], v[176:179], v[200:203], v[18:21]
	v_mfma_f32_16x16x32_bf16 v[18:21], v[172:175], v[196:199], v[18:21]
	v_mfma_f32_16x16x32_bf16 v[2:5], v[172:175], v[204:207], v[2:5]
	v_mfma_f32_16x16x32_bf16 v[2:5], v[176:179], v[208:211], v[2:5]
	s_setprio 2
	s_barrier
	v_mfma_f32_16x16x32_bf16 v[6:9], v[168:171], v[208:211], v[6:9]
	v_mfma_f32_16x16x32_bf16 v[6:9], v[164:167], v[204:207], v[6:9]
	s_setprio 0
	s_add_i32 s81, s81, 2
	s_add_u32 s77, s77, 0x100
	s_addc_u32 s78, s78, 0
	s_add_u32 s18, s18, 0x100
	s_addc_u32 s19, s19, 0
	s_add_u32 s79, s79, 0x100
	s_addc_u32 s80, s80, 0
	s_cmp_gt_u32 s81, 29
	s_cbranch_scc0 .LBB0_344
	s_and_b64 vcc, exec, s[6:7]
	s_cbranch_vccz .LBB0_347
	s_barrier

.LBB0_472:
	s_ashr_i32 s13, s12, 31
	s_lshl_b64 s[14:15], s[12:13], 15
	s_add_u32 s14, s28, s14
	s_addc_u32 s15, s29, s15
	s_and_b64 s[16:17], s[2:3], exec
	s_cselect_b32 s13, s15, s23
	s_cselect_b32 s76, s14, s22
	s_ashr_i32 s11, s10, 31
	s_lshl_b64 s[16:17], s[10:11], 15
	s_add_u32 s16, s30, s16
	s_addc_u32 s17, s31, s17
	s_and_b64 s[24:25], s[2:3], exec
	s_cselect_b32 s11, s17, s21
	s_cselect_b32 s77, s16, s20
	s_add_u32 s78, s20, 0x80000
	s_addc_u32 s79, s21, 0
	s_add_u32 s20, s22, 0x204000
	s_addc_u32 s21, s23, 0
	s_add_u32 s80, s22, 0x400000
	s_addc_u32 s81, s23, 0
	s_mov_b32 s82, -2
	s_waitcnt vmcnt(25)
	s_waitcnt vmcnt(24)
	s_waitcnt vmcnt(23)
	s_waitcnt vmcnt(22)
	s_waitcnt vmcnt(21)
	s_waitcnt vmcnt(20)
	s_waitcnt vmcnt(15)
	s_waitcnt vmcnt(14)
	s_waitcnt vmcnt(13)
	s_waitcnt vmcnt(12)
	s_waitcnt vmcnt(7)
	s_waitcnt vmcnt(6)
	s_waitcnt vmcnt(5)
	s_waitcnt vmcnt(4)
	s_waitcnt vmcnt(3)
	s_waitcnt vmcnt(2)
	s_waitcnt vmcnt(1)
	s_waitcnt vmcnt(0)
	ds_read_b128 v[134:137], v161
	ds_read_b128 v[138:141], v161 offset:1024
	ds_read_b128 v[142:145], v161 offset:2048
	ds_read_b128 v[146:149], v161 offset:3072
	ds_read_b128 v[150:153], v162
	ds_read_b128 v[166:169], v162 offset:1024
	ds_read_b128 v[170:173], v162 offset:2048
	ds_read_b128 v[174:177], v162 offset:3072
	s_cmpk_eq_i32 s82, 0x52
	s_cselect_b32 s23, s11, s79
	s_cselect_b32 s22, s77, s78
	s_cselect_b32 s25, s13, s81
	s_cselect_b32 s24, s76, s80
	ds_read_b128 v[178:181], v163
	ds_read_b128 v[182:185], v163 offset:1024
	ds_read_b128 v[186:189], v163 offset:2048
	ds_read_b128 v[190:193], v163 offset:3072
	ds_read_b128 v[194:197], v163 offset:4096
	ds_read_b128 v[198:201], v163 offset:5120
	ds_read_b128 v[202:205], v163 offset:6144
	ds_read_b128 v[206:209], v163 offset:7168
	s_add_u32 s86, s20, 0xffffc000
	s_addc_u32 s87, s21, -1
	s_mov_b32 s83, m0
	s_mov_b32 m0, s65
	s_nop 0
	global_load_lds_dwordx4 v1, s[86:87]
	s_mov_b32 m0, s83
	s_nop 0
	s_mov_b32 s83, m0
	s_mov_b32 m0, s67
	s_nop 0
	global_load_lds_dwordx4 v157, s[86:87]
	s_mov_b32 m0, s83
	s_nop 0
	s_mov_b32 s83, m0
	s_mov_b32 m0, s66
	s_nop 0
	global_load_lds_dwordx4 v1, s[20:21]
	s_mov_b32 m0, s83
	s_nop 0
	s_mov_b32 s83, m0
	s_mov_b32 m0, s73
	s_nop 0
	global_load_lds_dwordx4 v157, s[20:21]
	s_mov_b32 m0, s83
	s_waitcnt vmcnt(8)
	s_waitcnt lgkmcnt(0)
	s_barrier
	s_setprio 1
	s_waitcnt lgkmcnt(7)
	v_mfma_f32_16x16x32_bf16 v[126:129], v[134:137], v[178:181], 0
	v_mfma_f32_16x16x32_bf16 v[126:129], v[138:141], v[182:185], v[126:129]
	s_waitcnt lgkmcnt(5)
	v_mfma_f32_16x16x32_bf16 v[122:125], v[146:149], v[182:185], 0
	v_mfma_f32_16x16x32_bf16 v[122:125], v[142:145], v[178:181], v[122:125]
	s_waitcnt lgkmcnt(3)
	v_mfma_f32_16x16x32_bf16 v[114:117], v[142:145], v[186:189], 0
	v_mfma_f32_16x16x32_bf16 v[114:117], v[146:149], v[190:193], v[114:117]
	s_waitcnt lgkmcnt(1)
	v_mfma_f32_16x16x32_bf16 v[118:121], v[138:141], v[190:193], 0
	v_mfma_f32_16x16x32_bf16 v[118:121], v[134:137], v[186:189], v[118:121]
	v_mfma_f32_16x16x32_bf16 v[102:105], v[134:137], v[194:197], 0
	v_mfma_f32_16x16x32_bf16 v[102:105], v[138:141], v[198:201], v[102:105]
	v_mfma_f32_16x16x32_bf16 v[94:97], v[146:149], v[198:201], 0
	v_mfma_f32_16x16x32_bf16 v[94:97], v[142:145], v[194:197], v[94:97]
	v_mfma_f32_16x16x32_bf16 v[78:81], v[142:145], v[202:205], 0
	v_mfma_f32_16x16x32_bf16 v[78:81], v[146:149], v[206:209], v[78:81]
	s_waitcnt lgkmcnt(0)
	v_mfma_f32_16x16x32_bf16 v[86:89], v[138:141], v[206:209], 0
	v_mfma_f32_16x16x32_bf16 v[86:89], v[134:137], v[202:205], v[86:89]
	s_setprio 0
	s_setprio 1
	v_mfma_f32_16x16x32_bf16 v[110:113], v[150:153], v[178:181], 0
	v_mfma_f32_16x16x32_bf16 v[110:113], v[166:169], v[182:185], v[110:113]
	v_mfma_f32_16x16x32_bf16 v[106:109], v[174:177], v[182:185], 0
	v_mfma_f32_16x16x32_bf16 v[106:109], v[170:173], v[178:181], v[106:109]
	v_mfma_f32_16x16x32_bf16 v[90:93], v[170:173], v[186:189], 0
	v_mfma_f32_16x16x32_bf16 v[90:93], v[174:177], v[190:193], v[90:93]
	v_mfma_f32_16x16x32_bf16 v[98:101], v[166:169], v[190:193], 0
	v_mfma_f32_16x16x32_bf16 v[98:101], v[150:153], v[186:189], v[98:101]
	v_mfma_f32_16x16x32_bf16 v[82:85], v[150:153], v[194:197], 0
	v_mfma_f32_16x16x32_bf16 v[82:85], v[166:169], v[198:201], v[82:85]
	v_mfma_f32_16x16x32_bf16 v[74:77], v[174:177], v[198:201], 0
	v_mfma_f32_16x16x32_bf16 v[74:77], v[170:173], v[194:197], v[74:77]
	v_mfma_f32_16x16x32_bf16 v[66:69], v[170:173], v[202:205], 0
	v_mfma_f32_16x16x32_bf16 v[66:69], v[174:177], v[206:209], v[66:69]
	s_setprio 2
	s_barrier
	v_mfma_f32_16x16x32_bf16 v[70:73], v[166:169], v[206:209], 0
	v_mfma_f32_16x16x32_bf16 v[70:73], v[150:153], v[202:205], v[70:73]
	s_setprio 0
	ds_read_b128 v[178:181], v163 offset:16384
	ds_read_b128 v[182:185], v163 offset:17408
	ds_read_b128 v[186:189], v163 offset:18432
	ds_read_b128 v[190:193], v163 offset:19456
	ds_read_b128 v[194:197], v163 offset:20480
	ds_read_b128 v[198:201], v163 offset:21504
	ds_read_b128 v[202:205], v163 offset:22528
	ds_read_b128 v[206:209], v163 offset:23552
	s_mov_b32 s83, m0
	s_mov_b32 m0, s19
	s_nop 0
	global_load_lds_dwordx4 v156, s[22:23]
	s_mov_b32 m0, s83
	s_add_u32 s86, s22, 0x4000
	s_mov_b32 s83, m0
	s_mov_b32 m0, s35
	s_nop 0
	global_load_lds_dwordx4 v158, s[22:23]
	s_mov_b32 m0, s83
	s_addc_u32 s87, s23, 0
	s_mov_b32 s83, m0
	s_mov_b32 m0, s36
	s_nop 0
	global_load_lds_dwordx4 v156, s[86:87]
	s_mov_b32 m0, s83
	s_nop 0
	s_mov_b32 s83, m0
	s_mov_b32 m0, s37
	s_nop 0
	global_load_lds_dwordx4 v158, s[86:87]
	s_mov_b32 m0, s83
	s_waitcnt vmcnt(4)
	s_waitcnt lgkmcnt(0)
	s_barrier
	s_setprio 1
	s_waitcnt lgkmcnt(7)
	v_mfma_f32_16x16x32_bf16 v[62:65], v[134:137], v[178:181], 0
	v_mfma_f32_16x16x32_bf16 v[62:65], v[138:141], v[182:185], v[62:65]
	s_waitcnt lgkmcnt(5)
	v_mfma_f32_16x16x32_bf16 v[58:61], v[146:149], v[182:185], 0
	v_mfma_f32_16x16x32_bf16 v[58:61], v[142:145], v[178:181], v[58:61]
	s_waitcnt lgkmcnt(3)
	v_mfma_f32_16x16x32_bf16 v[46:49], v[142:145], v[186:189], 0
	v_mfma_f32_16x16x32_bf16 v[46:49], v[146:149], v[190:193], v[46:49]
	s_waitcnt lgkmcnt(1)
	v_mfma_f32_16x16x32_bf16 v[54:57], v[138:141], v[190:193], 0
	v_mfma_f32_16x16x32_bf16 v[54:57], v[134:137], v[186:189], v[54:57]
	v_mfma_f32_16x16x32_bf16 v[38:41], v[134:137], v[194:197], 0
	v_mfma_f32_16x16x32_bf16 v[38:41], v[138:141], v[198:201], v[38:41]
	v_mfma_f32_16x16x32_bf16 v[30:33], v[146:149], v[198:201], 0
	v_mfma_f32_16x16x32_bf16 v[30:33], v[142:145], v[194:197], v[30:33]
	v_mfma_f32_16x16x32_bf16 v[14:17], v[142:145], v[202:205], 0
	v_mfma_f32_16x16x32_bf16 v[14:17], v[146:149], v[206:209], v[14:17]
	s_waitcnt lgkmcnt(0)
	v_mfma_f32_16x16x32_bf16 v[22:25], v[138:141], v[206:209], 0
	v_mfma_f32_16x16x32_bf16 v[22:25], v[134:137], v[202:205], v[22:25]
	s_setprio 0
	s_setprio 1
	v_mfma_f32_16x16x32_bf16 v[50:53], v[150:153], v[178:181], 0
	v_mfma_f32_16x16x32_bf16 v[50:53], v[166:169], v[182:185], v[50:53]
	v_mfma_f32_16x16x32_bf16 v[42:45], v[174:177], v[182:185], 0
	v_mfma_f32_16x16x32_bf16 v[42:45], v[170:173], v[178:181], v[42:45]
	v_mfma_f32_16x16x32_bf16 v[26:29], v[170:173], v[186:189], 0
	v_mfma_f32_16x16x32_bf16 v[26:29], v[174:177], v[190:193], v[26:29]
	v_mfma_f32_16x16x32_bf16 v[34:37], v[166:169], v[190:193], 0
	v_mfma_f32_16x16x32_bf16 v[34:37], v[150:153], v[186:189], v[34:37]
	v_mfma_f32_16x16x32_bf16 v[18:21], v[150:153], v[194:197], 0
	v_mfma_f32_16x16x32_bf16 v[18:21], v[166:169], v[198:201], v[18:21]
	v_mfma_f32_16x16x32_bf16 v[10:13], v[174:177], v[198:201], 0
	v_mfma_f32_16x16x32_bf16 v[10:13], v[170:173], v[194:197], v[10:13]
	v_mfma_f32_16x16x32_bf16 v[2:5], v[170:173], v[202:205], 0
	v_mfma_f32_16x16x32_bf16 v[2:5], v[174:177], v[206:209], v[2:5]
	s_setprio 2
	s_barrier
	v_mfma_f32_16x16x32_bf16 v[6:9], v[166:169], v[206:209], 0
	v_mfma_f32_16x16x32_bf16 v[6:9], v[150:153], v[202:205], v[6:9]
	s_setprio 0
	ds_read_b128 v[134:137], v164
	ds_read_b128 v[138:141], v164 offset:1024
	ds_read_b128 v[142:145], v164 offset:2048
	ds_read_b128 v[146:149], v164 offset:3072
	ds_read_b128 v[150:153], v165
	ds_read_b128 v[166:169], v165 offset:1024
	ds_read_b128 v[170:173], v165 offset:2048
	ds_read_b128 v[174:177], v165 offset:3072
	ds_read_b128 v[178:181], v163 offset:32768
	ds_read_b128 v[182:185], v163 offset:33792
	ds_read_b128 v[186:189], v163 offset:34816
	ds_read_b128 v[190:193], v163 offset:35840
	ds_read_b128 v[194:197], v163 offset:36864
	ds_read_b128 v[198:201], v163 offset:37888
	ds_read_b128 v[202:205], v163 offset:38912
	ds_read_b128 v[206:209], v163 offset:39936
	s_mov_b32 s83, m0
	s_mov_b32 m0, s34
	s_nop 0
	global_load_lds_dwordx4 v1, s[24:25]
	s_mov_b32 m0, s83
	s_nop 0
	s_mov_b32 s83, m0
	s_mov_b32 m0, s42
	s_nop 0
	global_load_lds_dwordx4 v157, s[24:25]
	s_mov_b32 m0, s83
	s_add_u32 s24, s24, 0x4000
	s_addc_u32 s25, s25, 0
	s_mov_b32 s83, m0
	s_mov_b32 m0, s43
	s_nop 0
	global_load_lds_dwordx4 v1, s[24:25]
	s_mov_b32 m0, s83
	s_nop 0
	s_mov_b32 s83, m0
	s_mov_b32 m0, s46
	s_nop 0
	global_load_lds_dwordx4 v157, s[24:25]
	s_mov_b32 m0, s83
	s_waitcnt vmcnt(8)
	s_waitcnt lgkmcnt(0)
	s_barrier
	s_setprio 1
	s_waitcnt lgkmcnt(7)
	v_mfma_f32_16x16x32_bf16 v[126:129], v[134:137], v[178:181], v[126:129]
	v_mfma_f32_16x16x32_bf16 v[126:129], v[138:141], v[182:185], v[126:129]
	s_waitcnt lgkmcnt(5)
	v_mfma_f32_16x16x32_bf16 v[122:125], v[146:149], v[182:185], v[122:125]
	v_mfma_f32_16x16x32_bf16 v[122:125], v[142:145], v[178:181], v[122:125]
	s_waitcnt lgkmcnt(3)
	v_mfma_f32_16x16x32_bf16 v[114:117], v[142:145], v[186:189], v[114:117]
	v_mfma_f32_16x16x32_bf16 v[114:117], v[146:149], v[190:193], v[114:117]
	s_waitcnt lgkmcnt(1)
	v_mfma_f32_16x16x32_bf16 v[118:121], v[138:141], v[190:193], v[118:121]
	v_mfma_f32_16x16x32_bf16 v[118:121], v[134:137], v[186:189], v[118:121]
	v_mfma_f32_16x16x32_bf16 v[102:105], v[134:137], v[194:197], v[102:105]
	v_mfma_f32_16x16x32_bf16 v[102:105], v[138:141], v[198:201], v[102:105]
	v_mfma_f32_16x16x32_bf16 v[94:97], v[146:149], v[198:201], v[94:97]
	v_mfma_f32_16x16x32_bf16 v[94:97], v[142:145], v[194:197], v[94:97]
	v_mfma_f32_16x16x32_bf16 v[78:81], v[142:145], v[202:205], v[78:81]
	v_mfma_f32_16x16x32_bf16 v[78:81], v[146:149], v[206:209], v[78:81]
	s_waitcnt lgkmcnt(0)
	v_mfma_f32_16x16x32_bf16 v[86:89], v[138:141], v[206:209], v[86:89]
	v_mfma_f32_16x16x32_bf16 v[86:89], v[134:137], v[202:205], v[86:89]
	s_setprio 0
	s_setprio 1
	v_mfma_f32_16x16x32_bf16 v[110:113], v[150:153], v[178:181], v[110:113]
	v_mfma_f32_16x16x32_bf16 v[110:113], v[166:169], v[182:185], v[110:113]
	v_mfma_f32_16x16x32_bf16 v[106:109], v[174:177], v[182:185], v[106:109]
	v_mfma_f32_16x16x32_bf16 v[106:109], v[170:173], v[178:181], v[106:109]
	v_mfma_f32_16x16x32_bf16 v[90:93], v[170:173], v[186:189], v[90:93]
	v_mfma_f32_16x16x32_bf16 v[90:93], v[174:177], v[190:193], v[90:93]
	v_mfma_f32_16x16x32_bf16 v[98:101], v[166:169], v[190:193], v[98:101]
	v_mfma_f32_16x16x32_bf16 v[98:101], v[150:153], v[186:189], v[98:101]
	v_mfma_f32_16x16x32_bf16 v[82:85], v[150:153], v[194:197], v[82:85]
	v_mfma_f32_16x16x32_bf16 v[82:85], v[166:169], v[198:201], v[82:85]
	v_mfma_f32_16x16x32_bf16 v[74:77], v[174:177], v[198:201], v[74:77]
	v_mfma_f32_16x16x32_bf16 v[74:77], v[170:173], v[194:197], v[74:77]
	v_mfma_f32_16x16x32_bf16 v[66:69], v[170:173], v[202:205], v[66:69]
	v_mfma_f32_16x16x32_bf16 v[66:69], v[174:177], v[206:209], v[66:69]
	s_setprio 2
	s_barrier
	v_mfma_f32_16x16x32_bf16 v[70:73], v[166:169], v[206:209], v[70:73]
	v_mfma_f32_16x16x32_bf16 v[70:73], v[150:153], v[202:205], v[70:73]
	s_setprio 0
	ds_read_b128 v[178:181], v163 offset:49152
	ds_read_b128 v[182:185], v163 offset:50176
	ds_read_b128 v[186:189], v163 offset:51200
	ds_read_b128 v[190:193], v163 offset:52224
	ds_read_b128 v[194:197], v163 offset:53248
	ds_read_b128 v[198:201], v163 offset:54272
	ds_read_b128 v[202:205], v163 offset:55296
	ds_read_b128 v[206:209], v163 offset:56320
	s_add_u32 s24, s22, 0x40000
	s_addc_u32 s25, s23, 0
	s_mov_b32 s83, m0
	s_mov_b32 m0, s47
	s_nop 0
	global_load_lds_dwordx4 v156, s[24:25]
	s_mov_b32 m0, s83
	s_add_u32 s22, s22, 0x44000
	s_mov_b32 s83, m0
	s_mov_b32 m0, s48
	s_nop 0
	global_load_lds_dwordx4 v158, s[24:25]
	s_mov_b32 m0, s83
	s_addc_u32 s23, s23, 0
	s_mov_b32 s24, m0
	s_mov_b32 m0, s49
	s_nop 0
	global_load_lds_dwordx4 v156, s[22:23]
	s_mov_b32 m0, s24
	s_nop 0
	s_mov_b32 s24, m0
	s_mov_b32 m0, s56
	s_nop 0
	global_load_lds_dwordx4 v158, s[22:23]
	s_mov_b32 m0, s24
	s_waitcnt vmcnt(4)
	s_waitcnt lgkmcnt(0)
	s_barrier
	s_setprio 1
	s_waitcnt lgkmcnt(7)
	v_mfma_f32_16x16x32_bf16 v[62:65], v[134:137], v[178:181], v[62:65]
	v_mfma_f32_16x16x32_bf16 v[62:65], v[138:141], v[182:185], v[62:65]
	s_waitcnt lgkmcnt(5)
	v_mfma_f32_16x16x32_bf16 v[58:61], v[146:149], v[182:185], v[58:61]
	v_mfma_f32_16x16x32_bf16 v[58:61], v[142:145], v[178:181], v[58:61]
	s_waitcnt lgkmcnt(3)
	v_mfma_f32_16x16x32_bf16 v[46:49], v[142:145], v[186:189], v[46:49]
	v_mfma_f32_16x16x32_bf16 v[46:49], v[146:149], v[190:193], v[46:49]
	s_waitcnt lgkmcnt(1)
	v_mfma_f32_16x16x32_bf16 v[54:57], v[138:141], v[190:193], v[54:57]
	v_mfma_f32_16x16x32_bf16 v[54:57], v[134:137], v[186:189], v[54:57]
	v_mfma_f32_16x16x32_bf16 v[38:41], v[134:137], v[194:197], v[38:41]
	v_mfma_f32_16x16x32_bf16 v[38:41], v[138:141], v[198:201], v[38:41]
	v_mfma_f32_16x16x32_bf16 v[30:33], v[146:149], v[198:201], v[30:33]
	v_mfma_f32_16x16x32_bf16 v[30:33], v[142:145], v[194:197], v[30:33]
	v_mfma_f32_16x16x32_bf16 v[14:17], v[142:145], v[202:205], v[14:17]
	v_mfma_f32_16x16x32_bf16 v[14:17], v[146:149], v[206:209], v[14:17]
	s_waitcnt lgkmcnt(0)
	v_mfma_f32_16x16x32_bf16 v[22:25], v[138:141], v[206:209], v[22:25]
	v_mfma_f32_16x16x32_bf16 v[22:25], v[134:137], v[202:205], v[22:25]
	s_setprio 0
	s_setprio 1
	v_mfma_f32_16x16x32_bf16 v[50:53], v[150:153], v[178:181], v[50:53]
	v_mfma_f32_16x16x32_bf16 v[50:53], v[166:169], v[182:185], v[50:53]
	v_mfma_f32_16x16x32_bf16 v[42:45], v[174:177], v[182:185], v[42:45]
	v_mfma_f32_16x16x32_bf16 v[42:45], v[170:173], v[178:181], v[42:45]
	v_mfma_f32_16x16x32_bf16 v[26:29], v[170:173], v[186:189], v[26:29]
	v_mfma_f32_16x16x32_bf16 v[26:29], v[174:177], v[190:193], v[26:29]
	v_mfma_f32_16x16x32_bf16 v[34:37], v[166:169], v[190:193], v[34:37]
	v_mfma_f32_16x16x32_bf16 v[34:37], v[150:153], v[186:189], v[34:37]
	v_mfma_f32_16x16x32_bf16 v[18:21], v[150:153], v[194:197], v[18:21]
	v_mfma_f32_16x16x32_bf16 v[18:21], v[166:169], v[198:201], v[18:21]
	v_mfma_f32_16x16x32_bf16 v[10:13], v[174:177], v[198:201], v[10:13]
	v_mfma_f32_16x16x32_bf16 v[10:13], v[170:173], v[194:197], v[10:13]
	v_mfma_f32_16x16x32_bf16 v[2:5], v[170:173], v[202:205], v[2:5]
	v_mfma_f32_16x16x32_bf16 v[2:5], v[174:177], v[206:209], v[2:5]
	s_setprio 2
	s_barrier
	v_mfma_f32_16x16x32_bf16 v[6:9], v[166:169], v[206:209], v[6:9]
	v_mfma_f32_16x16x32_bf16 v[6:9], v[150:153], v[202:205], v[6:9]
	s_setprio 0
	s_add_i32 s82, s82, 2
	s_add_u32 s78, s78, 0x80000
	s_addc_u32 s79, s79, 0
	s_add_u32 s20, s20, 0x400000
	s_addc_u32 s21, s21, 0
	s_add_u32 s80, s80, 0x400000
	s_addc_u32 s81, s81, 0
	s_cmpk_gt_u32 s82, 0x53
	.p2align 6
.LBB0_473:
	ds_read_b128 v[134:137], v161
	ds_read_b128 v[138:141], v161 offset:1024
	ds_read_b128 v[142:145], v161 offset:2048
	ds_read_b128 v[146:149], v161 offset:3072
	ds_read_b128 v[150:153], v162
	ds_read_b128 v[166:169], v162 offset:1024
	ds_read_b128 v[170:173], v162 offset:2048
	ds_read_b128 v[174:177], v162 offset:3072
	s_cmpk_eq_i32 s82, 0x52
	s_cselect_b32 s23, s11, s79
	s_cselect_b32 s22, s77, s78
	s_cselect_b32 s25, s13, s81
	s_cselect_b32 s24, s76, s80
	ds_read_b128 v[178:181], v163
	ds_read_b128 v[182:185], v163 offset:1024
	ds_read_b128 v[186:189], v163 offset:2048
	ds_read_b128 v[190:193], v163 offset:3072
	ds_read_b128 v[194:197], v163 offset:4096
	ds_read_b128 v[198:201], v163 offset:5120
	ds_read_b128 v[202:205], v163 offset:6144
	ds_read_b128 v[206:209], v163 offset:7168
	s_add_u32 s86, s20, 0xffffc000
	s_addc_u32 s87, s21, -1
	s_mov_b32 s83, m0
	s_mov_b32 m0, s65
	s_nop 0
	global_load_lds_dwordx4 v1, s[86:87]
	s_mov_b32 m0, s83
	s_nop 0
	s_mov_b32 s83, m0
	s_mov_b32 m0, s67
	s_nop 0
	global_load_lds_dwordx4 v157, s[86:87]
	s_mov_b32 m0, s83
	s_nop 0
	s_mov_b32 s83, m0
	s_mov_b32 m0, s66
	s_nop 0
	global_load_lds_dwordx4 v1, s[20:21]
	s_mov_b32 m0, s83
	s_nop 0
	s_mov_b32 s83, m0
	s_mov_b32 m0, s73
	s_nop 0
	global_load_lds_dwordx4 v157, s[20:21]
	s_mov_b32 m0, s83
	s_waitcnt vmcnt(8)
	s_waitcnt lgkmcnt(0)
	s_barrier
	s_setprio 1
	s_waitcnt lgkmcnt(7)
	v_mfma_f32_16x16x32_bf16 v[126:129], v[134:137], v[178:181], v[126:129]
	v_mfma_f32_16x16x32_bf16 v[126:129], v[138:141], v[182:185], v[126:129]
	s_waitcnt lgkmcnt(5)
	v_mfma_f32_16x16x32_bf16 v[122:125], v[146:149], v[182:185], v[122:125]
	v_mfma_f32_16x16x32_bf16 v[122:125], v[142:145], v[178:181], v[122:125]
	s_waitcnt lgkmcnt(3)
	v_mfma_f32_16x16x32_bf16 v[114:117], v[142:145], v[186:189], v[114:117]
	v_mfma_f32_16x16x32_bf16 v[114:117], v[146:149], v[190:193], v[114:117]
	s_waitcnt lgkmcnt(1)
	v_mfma_f32_16x16x32_bf16 v[118:121], v[138:141], v[190:193], v[118:121]
	v_mfma_f32_16x16x32_bf16 v[118:121], v[134:137], v[186:189], v[118:121]
	v_mfma_f32_16x16x32_bf16 v[102:105], v[134:137], v[194:197], v[102:105]
	v_mfma_f32_16x16x32_bf16 v[102:105], v[138:141], v[198:201], v[102:105]
	v_mfma_f32_16x16x32_bf16 v[94:97], v[146:149], v[198:201], v[94:97]
	v_mfma_f32_16x16x32_bf16 v[94:97], v[142:145], v[194:197], v[94:97]
	v_mfma_f32_16x16x32_bf16 v[78:81], v[142:145], v[202:205], v[78:81]
	v_mfma_f32_16x16x32_bf16 v[78:81], v[146:149], v[206:209], v[78:81]
	s_waitcnt lgkmcnt(0)
	v_mfma_f32_16x16x32_bf16 v[86:89], v[138:141], v[206:209], v[86:89]
	v_mfma_f32_16x16x32_bf16 v[86:89], v[134:137], v[202:205], v[86:89]
	s_setprio 0
	s_setprio 1
	v_mfma_f32_16x16x32_bf16 v[110:113], v[150:153], v[178:181], v[110:113]
	v_mfma_f32_16x16x32_bf16 v[110:113], v[166:169], v[182:185], v[110:113]
	v_mfma_f32_16x16x32_bf16 v[106:109], v[174:177], v[182:185], v[106:109]
	v_mfma_f32_16x16x32_bf16 v[106:109], v[170:173], v[178:181], v[106:109]
	v_mfma_f32_16x16x32_bf16 v[90:93], v[170:173], v[186:189], v[90:93]
	v_mfma_f32_16x16x32_bf16 v[90:93], v[174:177], v[190:193], v[90:93]
	v_mfma_f32_16x16x32_bf16 v[98:101], v[166:169], v[190:193], v[98:101]
	v_mfma_f32_16x16x32_bf16 v[98:101], v[150:153], v[186:189], v[98:101]
	v_mfma_f32_16x16x32_bf16 v[82:85], v[150:153], v[194:197], v[82:85]
	v_mfma_f32_16x16x32_bf16 v[82:85], v[166:169], v[198:201], v[82:85]
	v_mfma_f32_16x16x32_bf16 v[74:77], v[174:177], v[198:201], v[74:77]
	v_mfma_f32_16x16x32_bf16 v[74:77], v[170:173], v[194:197], v[74:77]
	v_mfma_f32_16x16x32_bf16 v[66:69], v[170:173], v[202:205], v[66:69]
	v_mfma_f32_16x16x32_bf16 v[66:69], v[174:177], v[206:209], v[66:69]
	s_setprio 2
	s_barrier
	v_mfma_f32_16x16x32_bf16 v[70:73], v[166:169], v[206:209], v[70:73]
	v_mfma_f32_16x16x32_bf16 v[70:73], v[150:153], v[202:205], v[70:73]
	s_setprio 0
	ds_read_b128 v[178:181], v163 offset:16384
	ds_read_b128 v[182:185], v163 offset:17408
	ds_read_b128 v[186:189], v163 offset:18432
	ds_read_b128 v[190:193], v163 offset:19456
	ds_read_b128 v[194:197], v163 offset:20480
	ds_read_b128 v[198:201], v163 offset:21504
	ds_read_b128 v[202:205], v163 offset:22528
	ds_read_b128 v[206:209], v163 offset:23552
	s_mov_b32 s83, m0
	s_mov_b32 m0, s19
	s_nop 0
	global_load_lds_dwordx4 v156, s[22:23]
	s_mov_b32 m0, s83
	s_add_u32 s86, s22, 0x4000
	s_mov_b32 s83, m0
	s_mov_b32 m0, s35
	s_nop 0
	global_load_lds_dwordx4 v158, s[22:23]
	s_mov_b32 m0, s83
	s_addc_u32 s87, s23, 0
	s_mov_b32 s83, m0
	s_mov_b32 m0, s36
	s_nop 0
	global_load_lds_dwordx4 v156, s[86:87]
	s_mov_b32 m0, s83
	s_nop 0
	s_mov_b32 s83, m0
	s_mov_b32 m0, s37
	s_nop 0
	global_load_lds_dwordx4 v158, s[86:87]
	s_mov_b32 m0, s83
	s_waitcnt vmcnt(4)
	s_waitcnt lgkmcnt(0)
	s_barrier
	s_setprio 1
	s_waitcnt lgkmcnt(7)
	v_mfma_f32_16x16x32_bf16 v[62:65], v[134:137], v[178:181], v[62:65]
	v_mfma_f32_16x16x32_bf16 v[62:65], v[138:141], v[182:185], v[62:65]
	s_waitcnt lgkmcnt(5)
	v_mfma_f32_16x16x32_bf16 v[58:61], v[146:149], v[182:185], v[58:61]
	v_mfma_f32_16x16x32_bf16 v[58:61], v[142:145], v[178:181], v[58:61]
	s_waitcnt lgkmcnt(3)
	v_mfma_f32_16x16x32_bf16 v[46:49], v[142:145], v[186:189], v[46:49]
	v_mfma_f32_16x16x32_bf16 v[46:49], v[146:149], v[190:193], v[46:49]
	s_waitcnt lgkmcnt(1)
	v_mfma_f32_16x16x32_bf16 v[54:57], v[138:141], v[190:193], v[54:57]
	v_mfma_f32_16x16x32_bf16 v[54:57], v[134:137], v[186:189], v[54:57]
	v_mfma_f32_16x16x32_bf16 v[38:41], v[134:137], v[194:197], v[38:41]
	v_mfma_f32_16x16x32_bf16 v[38:41], v[138:141], v[198:201], v[38:41]
	v_mfma_f32_16x16x32_bf16 v[30:33], v[146:149], v[198:201], v[30:33]
	v_mfma_f32_16x16x32_bf16 v[30:33], v[142:145], v[194:197], v[30:33]
	v_mfma_f32_16x16x32_bf16 v[14:17], v[142:145], v[202:205], v[14:17]
	v_mfma_f32_16x16x32_bf16 v[14:17], v[146:149], v[206:209], v[14:17]
	s_waitcnt lgkmcnt(0)
	v_mfma_f32_16x16x32_bf16 v[22:25], v[138:141], v[206:209], v[22:25]
	v_mfma_f32_16x16x32_bf16 v[22:25], v[134:137], v[202:205], v[22:25]
	s_setprio 0
	s_setprio 1
	v_mfma_f32_16x16x32_bf16 v[50:53], v[150:153], v[178:181], v[50:53]
	v_mfma_f32_16x16x32_bf16 v[50:53], v[166:169], v[182:185], v[50:53]
	v_mfma_f32_16x16x32_bf16 v[42:45], v[174:177], v[182:185], v[42:45]
	v_mfma_f32_16x16x32_bf16 v[42:45], v[170:173], v[178:181], v[42:45]
	v_mfma_f32_16x16x32_bf16 v[26:29], v[170:173], v[186:189], v[26:29]
	v_mfma_f32_16x16x32_bf16 v[26:29], v[174:177], v[190:193], v[26:29]
	v_mfma_f32_16x16x32_bf16 v[34:37], v[166:169], v[190:193], v[34:37]
	v_mfma_f32_16x16x32_bf16 v[34:37], v[150:153], v[186:189], v[34:37]
	v_mfma_f32_16x16x32_bf16 v[18:21], v[150:153], v[194:197], v[18:21]
	v_mfma_f32_16x16x32_bf16 v[18:21], v[166:169], v[198:201], v[18:21]
	v_mfma_f32_16x16x32_bf16 v[10:13], v[174:177], v[198:201], v[10:13]
	v_mfma_f32_16x16x32_bf16 v[10:13], v[170:173], v[194:197], v[10:13]
	v_mfma_f32_16x16x32_bf16 v[2:5], v[170:173], v[202:205], v[2:5]
	v_mfma_f32_16x16x32_bf16 v[2:5], v[174:177], v[206:209], v[2:5]
	s_setprio 2
	s_barrier
	v_mfma_f32_16x16x32_bf16 v[6:9], v[166:169], v[206:209], v[6:9]
	v_mfma_f32_16x16x32_bf16 v[6:9], v[150:153], v[202:205], v[6:9]
	s_setprio 0
	ds_read_b128 v[134:137], v164
	ds_read_b128 v[138:141], v164 offset:1024
	ds_read_b128 v[142:145], v164 offset:2048
	ds_read_b128 v[146:149], v164 offset:3072
	ds_read_b128 v[150:153], v165
	ds_read_b128 v[166:169], v165 offset:1024
	ds_read_b128 v[170:173], v165 offset:2048
	ds_read_b128 v[174:177], v165 offset:3072
	ds_read_b128 v[178:181], v163 offset:32768
	ds_read_b128 v[182:185], v163 offset:33792
	ds_read_b128 v[186:189], v163 offset:34816
	ds_read_b128 v[190:193], v163 offset:35840
	ds_read_b128 v[194:197], v163 offset:36864
	ds_read_b128 v[198:201], v163 offset:37888
	ds_read_b128 v[202:205], v163 offset:38912
	ds_read_b128 v[206:209], v163 offset:39936
	s_mov_b32 s83, m0
	s_mov_b32 m0, s34
	s_nop 0
	global_load_lds_dwordx4 v1, s[24:25]
	s_mov_b32 m0, s83
	s_nop 0
	s_mov_b32 s83, m0
	s_mov_b32 m0, s42
	s_nop 0
	global_load_lds_dwordx4 v157, s[24:25]
	s_mov_b32 m0, s83
	s_add_u32 s24, s24, 0x4000
	s_addc_u32 s25, s25, 0
	s_mov_b32 s83, m0
	s_mov_b32 m0, s43
	s_nop 0
	global_load_lds_dwordx4 v1, s[24:25]
	s_mov_b32 m0, s83
	s_nop 0
	s_mov_b32 s83, m0
	s_mov_b32 m0, s46
	s_nop 0
	global_load_lds_dwordx4 v157, s[24:25]
	s_mov_b32 m0, s83
	s_waitcnt vmcnt(8)
	s_waitcnt lgkmcnt(0)
	s_barrier
	s_setprio 1
	s_waitcnt lgkmcnt(7)
	v_mfma_f32_16x16x32_bf16 v[126:129], v[134:137], v[178:181], v[126:129]
	v_mfma_f32_16x16x32_bf16 v[126:129], v[138:141], v[182:185], v[126:129]
	s_waitcnt lgkmcnt(5)
	v_mfma_f32_16x16x32_bf16 v[122:125], v[146:149], v[182:185], v[122:125]
	v_mfma_f32_16x16x32_bf16 v[122:125], v[142:145], v[178:181], v[122:125]
	s_waitcnt lgkmcnt(3)
	v_mfma_f32_16x16x32_bf16 v[114:117], v[142:145], v[186:189], v[114:117]
	v_mfma_f32_16x16x32_bf16 v[114:117], v[146:149], v[190:193], v[114:117]
	s_waitcnt lgkmcnt(1)
	v_mfma_f32_16x16x32_bf16 v[118:121], v[138:141], v[190:193], v[118:121]
	v_mfma_f32_16x16x32_bf16 v[118:121], v[134:137], v[186:189], v[118:121]
	v_mfma_f32_16x16x32_bf16 v[102:105], v[134:137], v[194:197], v[102:105]
	v_mfma_f32_16x16x32_bf16 v[102:105], v[138:141], v[198:201], v[102:105]
	v_mfma_f32_16x16x32_bf16 v[94:97], v[146:149], v[198:201], v[94:97]
	v_mfma_f32_16x16x32_bf16 v[94:97], v[142:145], v[194:197], v[94:97]
	v_mfma_f32_16x16x32_bf16 v[78:81], v[142:145], v[202:205], v[78:81]
	v_mfma_f32_16x16x32_bf16 v[78:81], v[146:149], v[206:209], v[78:81]
	s_waitcnt lgkmcnt(0)
	v_mfma_f32_16x16x32_bf16 v[86:89], v[138:141], v[206:209], v[86:89]
	v_mfma_f32_16x16x32_bf16 v[86:89], v[134:137], v[202:205], v[86:89]
	s_setprio 0
	s_setprio 1
	v_mfma_f32_16x16x32_bf16 v[110:113], v[150:153], v[178:181], v[110:113]
	v_mfma_f32_16x16x32_bf16 v[110:113], v[166:169], v[182:185], v[110:113]
	v_mfma_f32_16x16x32_bf16 v[106:109], v[174:177], v[182:185], v[106:109]
	v_mfma_f32_16x16x32_bf16 v[106:109], v[170:173], v[178:181], v[106:109]
	v_mfma_f32_16x16x32_bf16 v[90:93], v[170:173], v[186:189], v[90:93]
	v_mfma_f32_16x16x32_bf16 v[90:93], v[174:177], v[190:193], v[90:93]
	v_mfma_f32_16x16x32_bf16 v[98:101], v[166:169], v[190:193], v[98:101]
	v_mfma_f32_16x16x32_bf16 v[98:101], v[150:153], v[186:189], v[98:101]
	v_mfma_f32_16x16x32_bf16 v[82:85], v[150:153], v[194:197], v[82:85]
	v_mfma_f32_16x16x32_bf16 v[82:85], v[166:169], v[198:201], v[82:85]
	v_mfma_f32_16x16x32_bf16 v[74:77], v[174:177], v[198:201], v[74:77]
	v_mfma_f32_16x16x32_bf16 v[74:77], v[170:173], v[194:197], v[74:77]
	v_mfma_f32_16x16x32_bf16 v[66:69], v[170:173], v[202:205], v[66:69]
	v_mfma_f32_16x16x32_bf16 v[66:69], v[174:177], v[206:209], v[66:69]
	s_setprio 2
	s_barrier
	v_mfma_f32_16x16x32_bf16 v[70:73], v[166:169], v[206:209], v[70:73]
	v_mfma_f32_16x16x32_bf16 v[70:73], v[150:153], v[202:205], v[70:73]
	s_setprio 0
	ds_read_b128 v[178:181], v163 offset:49152
	ds_read_b128 v[182:185], v163 offset:50176
	ds_read_b128 v[186:189], v163 offset:51200
	ds_read_b128 v[190:193], v163 offset:52224
	ds_read_b128 v[194:197], v163 offset:53248
	ds_read_b128 v[198:201], v163 offset:54272
	ds_read_b128 v[202:205], v163 offset:55296
	ds_read_b128 v[206:209], v163 offset:56320
	s_add_u32 s24, s22, 0x40000
	s_addc_u32 s25, s23, 0
	s_mov_b32 s83, m0
	s_mov_b32 m0, s47
	s_nop 0
	global_load_lds_dwordx4 v156, s[24:25]
	s_mov_b32 m0, s83
	s_add_u32 s22, s22, 0x44000
	s_mov_b32 s83, m0
	s_mov_b32 m0, s48
	s_nop 0
	global_load_lds_dwordx4 v158, s[24:25]
	s_mov_b32 m0, s83
	s_addc_u32 s23, s23, 0
	s_mov_b32 s24, m0
	s_mov_b32 m0, s49
	s_nop 0
	global_load_lds_dwordx4 v156, s[22:23]
	s_mov_b32 m0, s24
	s_nop 0
	s_mov_b32 s24, m0
	s_mov_b32 m0, s56
	s_nop 0
	global_load_lds_dwordx4 v158, s[22:23]
	s_mov_b32 m0, s24
	s_waitcnt vmcnt(4)
	s_waitcnt lgkmcnt(0)
	s_barrier
	s_setprio 1
	s_waitcnt lgkmcnt(7)
	v_mfma_f32_16x16x32_bf16 v[62:65], v[134:137], v[178:181], v[62:65]
	v_mfma_f32_16x16x32_bf16 v[62:65], v[138:141], v[182:185], v[62:65]
	s_waitcnt lgkmcnt(5)
	v_mfma_f32_16x16x32_bf16 v[58:61], v[146:149], v[182:185], v[58:61]
	v_mfma_f32_16x16x32_bf16 v[58:61], v[142:145], v[178:181], v[58:61]
	s_waitcnt lgkmcnt(3)
	v_mfma_f32_16x16x32_bf16 v[46:49], v[142:145], v[186:189], v[46:49]
	v_mfma_f32_16x16x32_bf16 v[46:49], v[146:149], v[190:193], v[46:49]
	s_waitcnt lgkmcnt(1)
	v_mfma_f32_16x16x32_bf16 v[54:57], v[138:141], v[190:193], v[54:57]
	v_mfma_f32_16x16x32_bf16 v[54:57], v[134:137], v[186:189], v[54:57]
	v_mfma_f32_16x16x32_bf16 v[38:41], v[134:137], v[194:197], v[38:41]
	v_mfma_f32_16x16x32_bf16 v[38:41], v[138:141], v[198:201], v[38:41]
	v_mfma_f32_16x16x32_bf16 v[30:33], v[146:149], v[198:201], v[30:33]
	v_mfma_f32_16x16x32_bf16 v[30:33], v[142:145], v[194:197], v[30:33]
	v_mfma_f32_16x16x32_bf16 v[14:17], v[142:145], v[202:205], v[14:17]
	v_mfma_f32_16x16x32_bf16 v[14:17], v[146:149], v[206:209], v[14:17]
	s_waitcnt lgkmcnt(0)
	v_mfma_f32_16x16x32_bf16 v[22:25], v[138:141], v[206:209], v[22:25]
	v_mfma_f32_16x16x32_bf16 v[22:25], v[134:137], v[202:205], v[22:25]
	s_setprio 0
	s_setprio 1
	v_mfma_f32_16x16x32_bf16 v[50:53], v[150:153], v[178:181], v[50:53]
	v_mfma_f32_16x16x32_bf16 v[50:53], v[166:169], v[182:185], v[50:53]
	v_mfma_f32_16x16x32_bf16 v[42:45], v[174:177], v[182:185], v[42:45]
	v_mfma_f32_16x16x32_bf16 v[42:45], v[170:173], v[178:181], v[42:45]
	v_mfma_f32_16x16x32_bf16 v[26:29], v[170:173], v[186:189], v[26:29]
	v_mfma_f32_16x16x32_bf16 v[26:29], v[174:177], v[190:193], v[26:29]
	v_mfma_f32_16x16x32_bf16 v[34:37], v[166:169], v[190:193], v[34:37]
	v_mfma_f32_16x16x32_bf16 v[34:37], v[150:153], v[186:189], v[34:37]
	v_mfma_f32_16x16x32_bf16 v[18:21], v[150:153], v[194:197], v[18:21]
	v_mfma_f32_16x16x32_bf16 v[18:21], v[166:169], v[198:201], v[18:21]
	v_mfma_f32_16x16x32_bf16 v[10:13], v[174:177], v[198:201], v[10:13]
	v_mfma_f32_16x16x32_bf16 v[10:13], v[170:173], v[194:197], v[10:13]
	v_mfma_f32_16x16x32_bf16 v[2:5], v[170:173], v[202:205], v[2:5]
	v_mfma_f32_16x16x32_bf16 v[2:5], v[174:177], v[206:209], v[2:5]
	s_setprio 2
	s_barrier
	v_mfma_f32_16x16x32_bf16 v[6:9], v[166:169], v[206:209], v[6:9]
	v_mfma_f32_16x16x32_bf16 v[6:9], v[150:153], v[202:205], v[6:9]
	s_setprio 0
	s_add_i32 s82, s82, 2
	s_add_u32 s78, s78, 0x80000
	s_addc_u32 s79, s79, 0
	s_add_u32 s20, s20, 0x400000
	s_addc_u32 s21, s21, 0
	s_add_u32 s80, s80, 0x400000
	s_addc_u32 s81, s81, 0
	s_cmpk_gt_u32 s82, 0x53
	s_cbranch_scc0 .LBB0_473
	s_and_b64 vcc, exec, s[8:9]
	s_cbranch_vccz .LBB0_476
	s_barrier

.LBB0_653:
	s_ashr_i32 s23, s22, 31
	s_lshl_b64 s[24:25], s[22:23], 20
	s_add_u32 s24, s35, s24
	s_addc_u32 s25, s36, s25
	s_and_b64 s[26:27], s[2:3], exec
	s_cselect_b32 s7, s25, s11
	s_cselect_b32 s9, s24, s10
	s_ashr_i32 s21, s20, 31
	s_lshl_b64 s[26:27], s[20:21], 20
	s_add_u32 s26, s37, s26
	s_addc_u32 s27, s40, s27
	s_and_b64 s[28:29], s[2:3], exec
	s_cselect_b32 s21, s27, s5
	s_cselect_b32 s23, s26, s4
	s_add_u32 s30, s4, 0x100
	s_addc_u32 s31, s5, 0
	s_add_u32 s4, s10, 0x80080
	s_addc_u32 s5, s11, 0
	s_add_u32 s33, s10, 0x100
	s_addc_u32 s73, s11, 0
	s_mov_b32 s74, -2
	s_waitcnt vmcnt(25)
	s_waitcnt vmcnt(24)
	s_waitcnt vmcnt(15)
	s_waitcnt vmcnt(14)
	s_waitcnt vmcnt(13)
	s_waitcnt vmcnt(12)
	s_waitcnt vmcnt(11)
	s_waitcnt vmcnt(10)
	s_waitcnt vmcnt(9)
	s_waitcnt vmcnt(8)
	s_waitcnt vmcnt(7)
	s_waitcnt vmcnt(6)
	s_waitcnt vmcnt(5)
	s_waitcnt vmcnt(4)
	s_waitcnt vmcnt(3)
	s_waitcnt vmcnt(2)
	s_waitcnt vmcnt(1)
	s_waitcnt vmcnt(0)
	ds_read_b128 v[130:133], v161
	ds_read_b128 v[138:141], v161 offset:1024
	ds_read_b128 v[142:145], v161 offset:2048
	ds_read_b128 v[146:149], v161 offset:3072
	ds_read_b128 v[150:153], v162
	ds_read_b128 v[168:171], v162 offset:1024
	ds_read_b128 v[172:175], v162 offset:2048
	ds_read_b128 v[176:179], v162 offset:3072
	s_cmp_eq_u32 s74, 28
	s_cselect_b32 s11, s21, s31
	s_cselect_b32 s10, s23, s30
	s_cselect_b32 s29, s7, s73
	s_cselect_b32 s28, s9, s33
	ds_read_b128 v[180:183], v163
	ds_read_b128 v[184:187], v163 offset:1024
	ds_read_b128 v[188:191], v163 offset:2048
	ds_read_b128 v[192:195], v163 offset:3072
	ds_read_b128 v[196:199], v163 offset:4096
	ds_read_b128 v[200:203], v163 offset:5120
	ds_read_b128 v[204:207], v163 offset:6144
	ds_read_b128 v[208:211], v163 offset:7168
	s_add_u32 s76, s4, 0xfff80000
	s_addc_u32 s77, s5, -1
	s_mov_b32 s75, m0
	s_mov_b32 m0, s80
	s_nop 0
	global_load_lds_dwordx4 v1, s[76:77]
	s_mov_b32 m0, s75
	s_nop 0
	s_mov_b32 s75, m0
	s_mov_b32 m0, s82
	s_nop 0
	global_load_lds_dwordx4 v157, s[76:77]
	s_mov_b32 m0, s75
	s_nop 0
	s_mov_b32 s75, m0
	s_mov_b32 m0, s81
	s_nop 0
	global_load_lds_dwordx4 v1, s[4:5]
	s_mov_b32 m0, s75
	s_nop 0
	s_mov_b32 s75, m0
	s_mov_b32 m0, s83
	s_nop 0
	global_load_lds_dwordx4 v157, s[4:5]
	s_mov_b32 m0, s75
	s_waitcnt vmcnt(8)
	s_waitcnt lgkmcnt(0)
	s_barrier
	s_setprio 1
	s_waitcnt lgkmcnt(7)
	v_mfma_f32_16x16x32_bf16 v[126:129], v[130:133], v[180:183], 0
	v_mfma_f32_16x16x32_bf16 v[126:129], v[138:141], v[184:187], v[126:129]
	s_waitcnt lgkmcnt(5)
	v_mfma_f32_16x16x32_bf16 v[122:125], v[146:149], v[184:187], 0
	v_mfma_f32_16x16x32_bf16 v[122:125], v[142:145], v[180:183], v[122:125]
	s_waitcnt lgkmcnt(3)
	v_mfma_f32_16x16x32_bf16 v[106:109], v[142:145], v[188:191], 0
	v_mfma_f32_16x16x32_bf16 v[106:109], v[146:149], v[192:195], v[106:109]
	s_waitcnt lgkmcnt(1)
	v_mfma_f32_16x16x32_bf16 v[110:113], v[138:141], v[192:195], 0
	v_mfma_f32_16x16x32_bf16 v[110:113], v[130:133], v[188:191], v[110:113]
	v_mfma_f32_16x16x32_bf16 v[94:97], v[130:133], v[196:199], 0
	v_mfma_f32_16x16x32_bf16 v[94:97], v[138:141], v[200:203], v[94:97]
	v_mfma_f32_16x16x32_bf16 v[90:93], v[146:149], v[200:203], 0
	v_mfma_f32_16x16x32_bf16 v[90:93], v[142:145], v[196:199], v[90:93]
	v_mfma_f32_16x16x32_bf16 v[74:77], v[142:145], v[204:207], 0
	v_mfma_f32_16x16x32_bf16 v[74:77], v[146:149], v[208:211], v[74:77]
	s_waitcnt lgkmcnt(0)
	v_mfma_f32_16x16x32_bf16 v[78:81], v[138:141], v[208:211], 0
	v_mfma_f32_16x16x32_bf16 v[78:81], v[130:133], v[204:207], v[78:81]
	s_setprio 0
	s_setprio 1
	v_mfma_f32_16x16x32_bf16 v[118:121], v[150:153], v[180:183], 0
	v_mfma_f32_16x16x32_bf16 v[118:121], v[168:171], v[184:187], v[118:121]
	v_mfma_f32_16x16x32_bf16 v[114:117], v[176:179], v[184:187], 0
	v_mfma_f32_16x16x32_bf16 v[114:117], v[172:175], v[180:183], v[114:117]
	v_mfma_f32_16x16x32_bf16 v[98:101], v[172:175], v[188:191], 0
	v_mfma_f32_16x16x32_bf16 v[98:101], v[176:179], v[192:195], v[98:101]
	v_mfma_f32_16x16x32_bf16 v[102:105], v[168:171], v[192:195], 0
	v_mfma_f32_16x16x32_bf16 v[102:105], v[150:153], v[188:191], v[102:105]
	v_mfma_f32_16x16x32_bf16 v[86:89], v[150:153], v[196:199], 0
	v_mfma_f32_16x16x32_bf16 v[86:89], v[168:171], v[200:203], v[86:89]
	v_mfma_f32_16x16x32_bf16 v[82:85], v[176:179], v[200:203], 0
	v_mfma_f32_16x16x32_bf16 v[82:85], v[172:175], v[196:199], v[82:85]
	v_mfma_f32_16x16x32_bf16 v[66:69], v[172:175], v[204:207], 0
	v_mfma_f32_16x16x32_bf16 v[66:69], v[176:179], v[208:211], v[66:69]
	s_setprio 2
	s_barrier
	v_mfma_f32_16x16x32_bf16 v[70:73], v[168:171], v[208:211], 0
	v_mfma_f32_16x16x32_bf16 v[70:73], v[150:153], v[204:207], v[70:73]
	s_setprio 0
	ds_read_b128 v[180:183], v163 offset:16384
	ds_read_b128 v[184:187], v163 offset:17408
	ds_read_b128 v[188:191], v163 offset:18432
	ds_read_b128 v[192:195], v163 offset:19456
	ds_read_b128 v[196:199], v163 offset:20480
	ds_read_b128 v[200:203], v163 offset:21504
	ds_read_b128 v[204:207], v163 offset:22528
	ds_read_b128 v[208:211], v163 offset:23552
	s_mov_b32 s75, m0
	s_mov_b32 m0, s43
	s_nop 0
	global_load_lds_dwordx4 v156, s[10:11]
	s_mov_b32 m0, s75
	s_add_u32 s76, s10, 0x80000
	s_mov_b32 s75, m0
	s_mov_b32 m0, s46
	s_nop 0
	global_load_lds_dwordx4 v158, s[10:11]
	s_mov_b32 m0, s75
	s_addc_u32 s77, s11, 0
	s_mov_b32 s75, m0
	s_mov_b32 m0, s47
	s_nop 0
	global_load_lds_dwordx4 v156, s[76:77]
	s_mov_b32 m0, s75
	s_nop 0
	s_mov_b32 s75, m0
	s_mov_b32 m0, s48
	s_nop 0
	global_load_lds_dwordx4 v158, s[76:77]
	s_mov_b32 m0, s75
	s_waitcnt vmcnt(4)
	s_waitcnt lgkmcnt(0)
	s_barrier
	s_setprio 1
	s_waitcnt lgkmcnt(7)
	v_mfma_f32_16x16x32_bf16 v[62:65], v[130:133], v[180:183], 0
	v_mfma_f32_16x16x32_bf16 v[62:65], v[138:141], v[184:187], v[62:65]
	s_waitcnt lgkmcnt(5)
	v_mfma_f32_16x16x32_bf16 v[58:61], v[146:149], v[184:187], 0
	v_mfma_f32_16x16x32_bf16 v[58:61], v[142:145], v[180:183], v[58:61]
	s_waitcnt lgkmcnt(3)
	v_mfma_f32_16x16x32_bf16 v[42:45], v[142:145], v[188:191], 0
	v_mfma_f32_16x16x32_bf16 v[42:45], v[146:149], v[192:195], v[42:45]
	s_waitcnt lgkmcnt(1)
	v_mfma_f32_16x16x32_bf16 v[46:49], v[138:141], v[192:195], 0
	v_mfma_f32_16x16x32_bf16 v[46:49], v[130:133], v[188:191], v[46:49]
	v_mfma_f32_16x16x32_bf16 v[30:33], v[130:133], v[196:199], 0
	v_mfma_f32_16x16x32_bf16 v[30:33], v[138:141], v[200:203], v[30:33]
	v_mfma_f32_16x16x32_bf16 v[26:29], v[146:149], v[200:203], 0
	v_mfma_f32_16x16x32_bf16 v[26:29], v[142:145], v[196:199], v[26:29]
	v_mfma_f32_16x16x32_bf16 v[10:13], v[142:145], v[204:207], 0
	v_mfma_f32_16x16x32_bf16 v[10:13], v[146:149], v[208:211], v[10:13]
	s_waitcnt lgkmcnt(0)
	v_mfma_f32_16x16x32_bf16 v[14:17], v[138:141], v[208:211], 0
	v_mfma_f32_16x16x32_bf16 v[14:17], v[130:133], v[204:207], v[14:17]
	s_setprio 0
	s_setprio 1
	v_mfma_f32_16x16x32_bf16 v[54:57], v[150:153], v[180:183], 0
	v_mfma_f32_16x16x32_bf16 v[54:57], v[168:171], v[184:187], v[54:57]
	v_mfma_f32_16x16x32_bf16 v[50:53], v[176:179], v[184:187], 0
	v_mfma_f32_16x16x32_bf16 v[50:53], v[172:175], v[180:183], v[50:53]
	v_mfma_f32_16x16x32_bf16 v[34:37], v[172:175], v[188:191], 0
	v_mfma_f32_16x16x32_bf16 v[34:37], v[176:179], v[192:195], v[34:37]
	v_mfma_f32_16x16x32_bf16 v[38:41], v[168:171], v[192:195], 0
	v_mfma_f32_16x16x32_bf16 v[38:41], v[150:153], v[188:191], v[38:41]
	v_mfma_f32_16x16x32_bf16 v[22:25], v[150:153], v[196:199], 0
	v_mfma_f32_16x16x32_bf16 v[22:25], v[168:171], v[200:203], v[22:25]
	v_mfma_f32_16x16x32_bf16 v[18:21], v[176:179], v[200:203], 0
	v_mfma_f32_16x16x32_bf16 v[18:21], v[172:175], v[196:199], v[18:21]
	v_mfma_f32_16x16x32_bf16 v[2:5], v[172:175], v[204:207], 0
	v_mfma_f32_16x16x32_bf16 v[2:5], v[176:179], v[208:211], v[2:5]
	s_setprio 2
	s_barrier
	v_mfma_f32_16x16x32_bf16 v[6:9], v[168:171], v[208:211], 0
	v_mfma_f32_16x16x32_bf16 v[6:9], v[150:153], v[204:207], v[6:9]
	s_setprio 0
	ds_read_b128 v[130:133], v164
	ds_read_b128 v[138:141], v164 offset:1024
	ds_read_b128 v[142:145], v164 offset:2048
	ds_read_b128 v[146:149], v164 offset:3072
	ds_read_b128 v[150:153], v165
	ds_read_b128 v[168:171], v165 offset:1024
	ds_read_b128 v[172:175], v165 offset:2048
	ds_read_b128 v[176:179], v165 offset:3072
	ds_read_b128 v[180:183], v163 offset:32768
	ds_read_b128 v[184:187], v163 offset:33792
	ds_read_b128 v[188:191], v163 offset:34816
	ds_read_b128 v[192:195], v163 offset:35840
	ds_read_b128 v[196:199], v163 offset:36864
	ds_read_b128 v[200:203], v163 offset:37888
	ds_read_b128 v[204:207], v163 offset:38912
	ds_read_b128 v[208:211], v163 offset:39936
	s_mov_b32 s75, m0
	s_mov_b32 m0, s42
	s_nop 0
	global_load_lds_dwordx4 v1, s[28:29]
	s_mov_b32 m0, s75
	s_nop 0
	s_mov_b32 s75, m0
	s_mov_b32 m0, s49
	s_nop 0
	global_load_lds_dwordx4 v157, s[28:29]
	s_mov_b32 m0, s75
	s_add_u32 s28, s28, 0x80000
	s_addc_u32 s29, s29, 0
	s_mov_b32 s75, m0
	s_mov_b32 m0, s56
	s_nop 0
	global_load_lds_dwordx4 v1, s[28:29]
	s_mov_b32 m0, s75
	s_nop 0
	s_mov_b32 s75, m0
	s_mov_b32 m0, s57
	s_nop 0
	global_load_lds_dwordx4 v157, s[28:29]
	s_mov_b32 m0, s75
	s_waitcnt vmcnt(8)
	s_waitcnt lgkmcnt(0)
	s_barrier
	s_setprio 1
	s_waitcnt lgkmcnt(7)
	v_mfma_f32_16x16x32_bf16 v[126:129], v[130:133], v[180:183], v[126:129]
	v_mfma_f32_16x16x32_bf16 v[126:129], v[138:141], v[184:187], v[126:129]
	s_waitcnt lgkmcnt(5)
	v_mfma_f32_16x16x32_bf16 v[122:125], v[146:149], v[184:187], v[122:125]
	v_mfma_f32_16x16x32_bf16 v[122:125], v[142:145], v[180:183], v[122:125]
	s_waitcnt lgkmcnt(3)
	v_mfma_f32_16x16x32_bf16 v[106:109], v[142:145], v[188:191], v[106:109]
	v_mfma_f32_16x16x32_bf16 v[106:109], v[146:149], v[192:195], v[106:109]
	s_waitcnt lgkmcnt(1)
	v_mfma_f32_16x16x32_bf16 v[110:113], v[138:141], v[192:195], v[110:113]
	v_mfma_f32_16x16x32_bf16 v[110:113], v[130:133], v[188:191], v[110:113]
	v_mfma_f32_16x16x32_bf16 v[94:97], v[130:133], v[196:199], v[94:97]
	v_mfma_f32_16x16x32_bf16 v[94:97], v[138:141], v[200:203], v[94:97]
	v_mfma_f32_16x16x32_bf16 v[90:93], v[146:149], v[200:203], v[90:93]
	v_mfma_f32_16x16x32_bf16 v[90:93], v[142:145], v[196:199], v[90:93]
	v_mfma_f32_16x16x32_bf16 v[74:77], v[142:145], v[204:207], v[74:77]
	v_mfma_f32_16x16x32_bf16 v[74:77], v[146:149], v[208:211], v[74:77]
	s_waitcnt lgkmcnt(0)
	v_mfma_f32_16x16x32_bf16 v[78:81], v[138:141], v[208:211], v[78:81]
	v_mfma_f32_16x16x32_bf16 v[78:81], v[130:133], v[204:207], v[78:81]
	s_setprio 0
	s_setprio 1
	v_mfma_f32_16x16x32_bf16 v[118:121], v[150:153], v[180:183], v[118:121]
	v_mfma_f32_16x16x32_bf16 v[118:121], v[168:171], v[184:187], v[118:121]
	v_mfma_f32_16x16x32_bf16 v[114:117], v[176:179], v[184:187], v[114:117]
	v_mfma_f32_16x16x32_bf16 v[114:117], v[172:175], v[180:183], v[114:117]
	v_mfma_f32_16x16x32_bf16 v[98:101], v[172:175], v[188:191], v[98:101]
	v_mfma_f32_16x16x32_bf16 v[98:101], v[176:179], v[192:195], v[98:101]
	v_mfma_f32_16x16x32_bf16 v[102:105], v[168:171], v[192:195], v[102:105]
	v_mfma_f32_16x16x32_bf16 v[102:105], v[150:153], v[188:191], v[102:105]
	v_mfma_f32_16x16x32_bf16 v[86:89], v[150:153], v[196:199], v[86:89]
	v_mfma_f32_16x16x32_bf16 v[86:89], v[168:171], v[200:203], v[86:89]
	v_mfma_f32_16x16x32_bf16 v[82:85], v[176:179], v[200:203], v[82:85]
	v_mfma_f32_16x16x32_bf16 v[82:85], v[172:175], v[196:199], v[82:85]
	v_mfma_f32_16x16x32_bf16 v[66:69], v[172:175], v[204:207], v[66:69]
	v_mfma_f32_16x16x32_bf16 v[66:69], v[176:179], v[208:211], v[66:69]
	s_setprio 2
	s_barrier
	v_mfma_f32_16x16x32_bf16 v[70:73], v[168:171], v[208:211], v[70:73]
	v_mfma_f32_16x16x32_bf16 v[70:73], v[150:153], v[204:207], v[70:73]
	s_setprio 0
	ds_read_b128 v[180:183], v163 offset:49152
	ds_read_b128 v[184:187], v163 offset:50176
	ds_read_b128 v[188:191], v163 offset:51200
	ds_read_b128 v[192:195], v163 offset:52224
	ds_read_b128 v[196:199], v163 offset:53248
	ds_read_b128 v[200:203], v163 offset:54272
	ds_read_b128 v[204:207], v163 offset:55296
	ds_read_b128 v[208:211], v163 offset:56320
	s_add_u32 s28, s10, 0x80
	s_addc_u32 s29, s11, 0
	s_mov_b32 s75, m0
	s_mov_b32 m0, s64
	s_nop 0
	global_load_lds_dwordx4 v156, s[28:29]
	s_mov_b32 m0, s75
	s_add_u32 s10, s10, 0x80080
	s_mov_b32 s75, m0
	s_mov_b32 m0, s65
	s_nop 0
	global_load_lds_dwordx4 v158, s[28:29]
	s_mov_b32 m0, s75
	s_addc_u32 s11, s11, 0
	s_mov_b32 s28, m0
	s_mov_b32 m0, s66
	s_nop 0
	global_load_lds_dwordx4 v156, s[10:11]
	s_mov_b32 m0, s28
	s_nop 0
	s_mov_b32 s28, m0
	s_mov_b32 m0, s67
	s_nop 0
	global_load_lds_dwordx4 v158, s[10:11]
	s_mov_b32 m0, s28
	s_waitcnt vmcnt(4)
	s_waitcnt lgkmcnt(0)
	s_barrier
	s_setprio 1
	s_waitcnt lgkmcnt(7)
	v_mfma_f32_16x16x32_bf16 v[62:65], v[130:133], v[180:183], v[62:65]
	v_mfma_f32_16x16x32_bf16 v[62:65], v[138:141], v[184:187], v[62:65]
	s_waitcnt lgkmcnt(5)
	v_mfma_f32_16x16x32_bf16 v[58:61], v[146:149], v[184:187], v[58:61]
	v_mfma_f32_16x16x32_bf16 v[58:61], v[142:145], v[180:183], v[58:61]
	s_waitcnt lgkmcnt(3)
	v_mfma_f32_16x16x32_bf16 v[42:45], v[142:145], v[188:191], v[42:45]
	v_mfma_f32_16x16x32_bf16 v[42:45], v[146:149], v[192:195], v[42:45]
	s_waitcnt lgkmcnt(1)
	v_mfma_f32_16x16x32_bf16 v[46:49], v[138:141], v[192:195], v[46:49]
	v_mfma_f32_16x16x32_bf16 v[46:49], v[130:133], v[188:191], v[46:49]
	v_mfma_f32_16x16x32_bf16 v[30:33], v[130:133], v[196:199], v[30:33]
	v_mfma_f32_16x16x32_bf16 v[30:33], v[138:141], v[200:203], v[30:33]
	v_mfma_f32_16x16x32_bf16 v[26:29], v[146:149], v[200:203], v[26:29]
	v_mfma_f32_16x16x32_bf16 v[26:29], v[142:145], v[196:199], v[26:29]
	v_mfma_f32_16x16x32_bf16 v[10:13], v[142:145], v[204:207], v[10:13]
	v_mfma_f32_16x16x32_bf16 v[10:13], v[146:149], v[208:211], v[10:13]
	s_waitcnt lgkmcnt(0)
	v_mfma_f32_16x16x32_bf16 v[14:17], v[138:141], v[208:211], v[14:17]
	v_mfma_f32_16x16x32_bf16 v[14:17], v[130:133], v[204:207], v[14:17]
	s_setprio 0
	s_setprio 1
	v_mfma_f32_16x16x32_bf16 v[54:57], v[150:153], v[180:183], v[54:57]
	v_mfma_f32_16x16x32_bf16 v[54:57], v[168:171], v[184:187], v[54:57]
	v_mfma_f32_16x16x32_bf16 v[50:53], v[176:179], v[184:187], v[50:53]
	v_mfma_f32_16x16x32_bf16 v[50:53], v[172:175], v[180:183], v[50:53]
	v_mfma_f32_16x16x32_bf16 v[34:37], v[172:175], v[188:191], v[34:37]
	v_mfma_f32_16x16x32_bf16 v[34:37], v[176:179], v[192:195], v[34:37]
	v_mfma_f32_16x16x32_bf16 v[38:41], v[168:171], v[192:195], v[38:41]
	v_mfma_f32_16x16x32_bf16 v[38:41], v[150:153], v[188:191], v[38:41]
	v_mfma_f32_16x16x32_bf16 v[22:25], v[150:153], v[196:199], v[22:25]
	v_mfma_f32_16x16x32_bf16 v[22:25], v[168:171], v[200:203], v[22:25]
	v_mfma_f32_16x16x32_bf16 v[18:21], v[176:179], v[200:203], v[18:21]
	v_mfma_f32_16x16x32_bf16 v[18:21], v[172:175], v[196:199], v[18:21]
	v_mfma_f32_16x16x32_bf16 v[2:5], v[172:175], v[204:207], v[2:5]
	v_mfma_f32_16x16x32_bf16 v[2:5], v[176:179], v[208:211], v[2:5]
	s_setprio 2
	s_barrier
	v_mfma_f32_16x16x32_bf16 v[6:9], v[168:171], v[208:211], v[6:9]
	v_mfma_f32_16x16x32_bf16 v[6:9], v[150:153], v[204:207], v[6:9]
	s_setprio 0
	s_add_i32 s74, s74, 2
	s_add_u32 s30, s30, 0x100
	s_addc_u32 s31, s31, 0
	s_add_u32 s4, s4, 0x100
	s_addc_u32 s5, s5, 0
	s_add_u32 s33, s33, 0x100
	s_addc_u32 s73, s73, 0
	s_cmp_gt_u32 s74, 29
	.p2align 6
.LBB0_654:
	ds_read_b128 v[130:133], v161
	ds_read_b128 v[138:141], v161 offset:1024
	ds_read_b128 v[142:145], v161 offset:2048
	ds_read_b128 v[146:149], v161 offset:3072
	ds_read_b128 v[150:153], v162
	ds_read_b128 v[168:171], v162 offset:1024
	ds_read_b128 v[172:175], v162 offset:2048
	ds_read_b128 v[176:179], v162 offset:3072
	s_cmp_eq_u32 s74, 28
	s_cselect_b32 s11, s21, s31
	s_cselect_b32 s10, s23, s30
	s_cselect_b32 s29, s7, s73
	s_cselect_b32 s28, s9, s33
	ds_read_b128 v[180:183], v163
	ds_read_b128 v[184:187], v163 offset:1024
	ds_read_b128 v[188:191], v163 offset:2048
	ds_read_b128 v[192:195], v163 offset:3072
	ds_read_b128 v[196:199], v163 offset:4096
	ds_read_b128 v[200:203], v163 offset:5120
	ds_read_b128 v[204:207], v163 offset:6144
	ds_read_b128 v[208:211], v163 offset:7168
	s_add_u32 s76, s4, 0xfff80000
	s_addc_u32 s77, s5, -1
	s_mov_b32 s75, m0
	s_mov_b32 m0, s80
	s_nop 0
	global_load_lds_dwordx4 v1, s[76:77]
	s_mov_b32 m0, s75
	s_nop 0
	s_mov_b32 s75, m0
	s_mov_b32 m0, s82
	s_nop 0
	global_load_lds_dwordx4 v157, s[76:77]
	s_mov_b32 m0, s75
	s_nop 0
	s_mov_b32 s75, m0
	s_mov_b32 m0, s81
	s_nop 0
	global_load_lds_dwordx4 v1, s[4:5]
	s_mov_b32 m0, s75
	s_nop 0
	s_mov_b32 s75, m0
	s_mov_b32 m0, s83
	s_nop 0
	global_load_lds_dwordx4 v157, s[4:5]
	s_mov_b32 m0, s75
	s_waitcnt vmcnt(8)
	s_waitcnt lgkmcnt(0)
	s_barrier
	s_setprio 1
	s_waitcnt lgkmcnt(7)
	v_mfma_f32_16x16x32_bf16 v[126:129], v[130:133], v[180:183], v[126:129]
	v_mfma_f32_16x16x32_bf16 v[126:129], v[138:141], v[184:187], v[126:129]
	s_waitcnt lgkmcnt(5)
	v_mfma_f32_16x16x32_bf16 v[122:125], v[146:149], v[184:187], v[122:125]
	v_mfma_f32_16x16x32_bf16 v[122:125], v[142:145], v[180:183], v[122:125]
	s_waitcnt lgkmcnt(3)
	v_mfma_f32_16x16x32_bf16 v[106:109], v[142:145], v[188:191], v[106:109]
	v_mfma_f32_16x16x32_bf16 v[106:109], v[146:149], v[192:195], v[106:109]
	s_waitcnt lgkmcnt(1)
	v_mfma_f32_16x16x32_bf16 v[110:113], v[138:141], v[192:195], v[110:113]
	v_mfma_f32_16x16x32_bf16 v[110:113], v[130:133], v[188:191], v[110:113]
	v_mfma_f32_16x16x32_bf16 v[94:97], v[130:133], v[196:199], v[94:97]
	v_mfma_f32_16x16x32_bf16 v[94:97], v[138:141], v[200:203], v[94:97]
	v_mfma_f32_16x16x32_bf16 v[90:93], v[146:149], v[200:203], v[90:93]
	v_mfma_f32_16x16x32_bf16 v[90:93], v[142:145], v[196:199], v[90:93]
	v_mfma_f32_16x16x32_bf16 v[74:77], v[142:145], v[204:207], v[74:77]
	v_mfma_f32_16x16x32_bf16 v[74:77], v[146:149], v[208:211], v[74:77]
	s_waitcnt lgkmcnt(0)
	v_mfma_f32_16x16x32_bf16 v[78:81], v[138:141], v[208:211], v[78:81]
	v_mfma_f32_16x16x32_bf16 v[78:81], v[130:133], v[204:207], v[78:81]
	s_setprio 0
	s_setprio 1
	v_mfma_f32_16x16x32_bf16 v[118:121], v[150:153], v[180:183], v[118:121]
	v_mfma_f32_16x16x32_bf16 v[118:121], v[168:171], v[184:187], v[118:121]
	v_mfma_f32_16x16x32_bf16 v[114:117], v[176:179], v[184:187], v[114:117]
	v_mfma_f32_16x16x32_bf16 v[114:117], v[172:175], v[180:183], v[114:117]
	v_mfma_f32_16x16x32_bf16 v[98:101], v[172:175], v[188:191], v[98:101]
	v_mfma_f32_16x16x32_bf16 v[98:101], v[176:179], v[192:195], v[98:101]
	v_mfma_f32_16x16x32_bf16 v[102:105], v[168:171], v[192:195], v[102:105]
	v_mfma_f32_16x16x32_bf16 v[102:105], v[150:153], v[188:191], v[102:105]
	v_mfma_f32_16x16x32_bf16 v[86:89], v[150:153], v[196:199], v[86:89]
	v_mfma_f32_16x16x32_bf16 v[86:89], v[168:171], v[200:203], v[86:89]
	v_mfma_f32_16x16x32_bf16 v[82:85], v[176:179], v[200:203], v[82:85]
	v_mfma_f32_16x16x32_bf16 v[82:85], v[172:175], v[196:199], v[82:85]
	v_mfma_f32_16x16x32_bf16 v[66:69], v[172:175], v[204:207], v[66:69]
	v_mfma_f32_16x16x32_bf16 v[66:69], v[176:179], v[208:211], v[66:69]
	s_setprio 2
	s_barrier
	v_mfma_f32_16x16x32_bf16 v[70:73], v[168:171], v[208:211], v[70:73]
	v_mfma_f32_16x16x32_bf16 v[70:73], v[150:153], v[204:207], v[70:73]
	s_setprio 0
	ds_read_b128 v[180:183], v163 offset:16384
	ds_read_b128 v[184:187], v163 offset:17408
	ds_read_b128 v[188:191], v163 offset:18432
	ds_read_b128 v[192:195], v163 offset:19456
	ds_read_b128 v[196:199], v163 offset:20480
	ds_read_b128 v[200:203], v163 offset:21504
	ds_read_b128 v[204:207], v163 offset:22528
	ds_read_b128 v[208:211], v163 offset:23552
	s_mov_b32 s75, m0
	s_mov_b32 m0, s43
	s_nop 0
	global_load_lds_dwordx4 v156, s[10:11]
	s_mov_b32 m0, s75
	s_add_u32 s76, s10, 0x80000
	s_mov_b32 s75, m0
	s_mov_b32 m0, s46
	s_nop 0
	global_load_lds_dwordx4 v158, s[10:11]
	s_mov_b32 m0, s75
	s_addc_u32 s77, s11, 0
	s_mov_b32 s75, m0
	s_mov_b32 m0, s47
	s_nop 0
	global_load_lds_dwordx4 v156, s[76:77]
	s_mov_b32 m0, s75
	s_nop 0
	s_mov_b32 s75, m0
	s_mov_b32 m0, s48
	s_nop 0
	global_load_lds_dwordx4 v158, s[76:77]
	s_mov_b32 m0, s75
	s_waitcnt vmcnt(4)
	s_waitcnt lgkmcnt(0)
	s_barrier
	s_setprio 1
	s_waitcnt lgkmcnt(7)
	v_mfma_f32_16x16x32_bf16 v[62:65], v[130:133], v[180:183], v[62:65]
	v_mfma_f32_16x16x32_bf16 v[62:65], v[138:141], v[184:187], v[62:65]
	s_waitcnt lgkmcnt(5)
	v_mfma_f32_16x16x32_bf16 v[58:61], v[146:149], v[184:187], v[58:61]
	v_mfma_f32_16x16x32_bf16 v[58:61], v[142:145], v[180:183], v[58:61]
	s_waitcnt lgkmcnt(3)
	v_mfma_f32_16x16x32_bf16 v[42:45], v[142:145], v[188:191], v[42:45]
	v_mfma_f32_16x16x32_bf16 v[42:45], v[146:149], v[192:195], v[42:45]
	s_waitcnt lgkmcnt(1)
	v_mfma_f32_16x16x32_bf16 v[46:49], v[138:141], v[192:195], v[46:49]
	v_mfma_f32_16x16x32_bf16 v[46:49], v[130:133], v[188:191], v[46:49]
	v_mfma_f32_16x16x32_bf16 v[30:33], v[130:133], v[196:199], v[30:33]
	v_mfma_f32_16x16x32_bf16 v[30:33], v[138:141], v[200:203], v[30:33]
	v_mfma_f32_16x16x32_bf16 v[26:29], v[146:149], v[200:203], v[26:29]
	v_mfma_f32_16x16x32_bf16 v[26:29], v[142:145], v[196:199], v[26:29]
	v_mfma_f32_16x16x32_bf16 v[10:13], v[142:145], v[204:207], v[10:13]
	v_mfma_f32_16x16x32_bf16 v[10:13], v[146:149], v[208:211], v[10:13]
	s_waitcnt lgkmcnt(0)
	v_mfma_f32_16x16x32_bf16 v[14:17], v[138:141], v[208:211], v[14:17]
	v_mfma_f32_16x16x32_bf16 v[14:17], v[130:133], v[204:207], v[14:17]
	s_setprio 0
	s_setprio 1
	v_mfma_f32_16x16x32_bf16 v[54:57], v[150:153], v[180:183], v[54:57]
	v_mfma_f32_16x16x32_bf16 v[54:57], v[168:171], v[184:187], v[54:57]
	v_mfma_f32_16x16x32_bf16 v[50:53], v[176:179], v[184:187], v[50:53]
	v_mfma_f32_16x16x32_bf16 v[50:53], v[172:175], v[180:183], v[50:53]
	v_mfma_f32_16x16x32_bf16 v[34:37], v[172:175], v[188:191], v[34:37]
	v_mfma_f32_16x16x32_bf16 v[34:37], v[176:179], v[192:195], v[34:37]
	v_mfma_f32_16x16x32_bf16 v[38:41], v[168:171], v[192:195], v[38:41]
	v_mfma_f32_16x16x32_bf16 v[38:41], v[150:153], v[188:191], v[38:41]
	v_mfma_f32_16x16x32_bf16 v[22:25], v[150:153], v[196:199], v[22:25]
	v_mfma_f32_16x16x32_bf16 v[22:25], v[168:171], v[200:203], v[22:25]
	v_mfma_f32_16x16x32_bf16 v[18:21], v[176:179], v[200:203], v[18:21]
	v_mfma_f32_16x16x32_bf16 v[18:21], v[172:175], v[196:199], v[18:21]
	v_mfma_f32_16x16x32_bf16 v[2:5], v[172:175], v[204:207], v[2:5]
	v_mfma_f32_16x16x32_bf16 v[2:5], v[176:179], v[208:211], v[2:5]
	s_setprio 2
	s_barrier
	v_mfma_f32_16x16x32_bf16 v[6:9], v[168:171], v[208:211], v[6:9]
	v_mfma_f32_16x16x32_bf16 v[6:9], v[150:153], v[204:207], v[6:9]
	s_setprio 0
	ds_read_b128 v[130:133], v164
	ds_read_b128 v[138:141], v164 offset:1024
	ds_read_b128 v[142:145], v164 offset:2048
	ds_read_b128 v[146:149], v164 offset:3072
	ds_read_b128 v[150:153], v165
	ds_read_b128 v[168:171], v165 offset:1024
	ds_read_b128 v[172:175], v165 offset:2048
	ds_read_b128 v[176:179], v165 offset:3072
	ds_read_b128 v[180:183], v163 offset:32768
	ds_read_b128 v[184:187], v163 offset:33792
	ds_read_b128 v[188:191], v163 offset:34816
	ds_read_b128 v[192:195], v163 offset:35840
	ds_read_b128 v[196:199], v163 offset:36864
	ds_read_b128 v[200:203], v163 offset:37888
	ds_read_b128 v[204:207], v163 offset:38912
	ds_read_b128 v[208:211], v163 offset:39936
	s_mov_b32 s75, m0
	s_mov_b32 m0, s42
	s_nop 0
	global_load_lds_dwordx4 v1, s[28:29]
	s_mov_b32 m0, s75
	s_nop 0
	s_mov_b32 s75, m0
	s_mov_b32 m0, s49
	s_nop 0
	global_load_lds_dwordx4 v157, s[28:29]
	s_mov_b32 m0, s75
	s_add_u32 s28, s28, 0x80000
	s_addc_u32 s29, s29, 0
	s_mov_b32 s75, m0
	s_mov_b32 m0, s56
	s_nop 0
	global_load_lds_dwordx4 v1, s[28:29]
	s_mov_b32 m0, s75
	s_nop 0
	s_mov_b32 s75, m0
	s_mov_b32 m0, s57
	s_nop 0
	global_load_lds_dwordx4 v157, s[28:29]
	s_mov_b32 m0, s75
	s_waitcnt vmcnt(8)
	s_waitcnt lgkmcnt(0)
	s_barrier
	s_setprio 1
	s_waitcnt lgkmcnt(7)
	v_mfma_f32_16x16x32_bf16 v[126:129], v[130:133], v[180:183], v[126:129]
	v_mfma_f32_16x16x32_bf16 v[126:129], v[138:141], v[184:187], v[126:129]
	s_waitcnt lgkmcnt(5)
	v_mfma_f32_16x16x32_bf16 v[122:125], v[146:149], v[184:187], v[122:125]
	v_mfma_f32_16x16x32_bf16 v[122:125], v[142:145], v[180:183], v[122:125]
	s_waitcnt lgkmcnt(3)
	v_mfma_f32_16x16x32_bf16 v[106:109], v[142:145], v[188:191], v[106:109]
	v_mfma_f32_16x16x32_bf16 v[106:109], v[146:149], v[192:195], v[106:109]
	s_waitcnt lgkmcnt(1)
	v_mfma_f32_16x16x32_bf16 v[110:113], v[138:141], v[192:195], v[110:113]
	v_mfma_f32_16x16x32_bf16 v[110:113], v[130:133], v[188:191], v[110:113]
	v_mfma_f32_16x16x32_bf16 v[94:97], v[130:133], v[196:199], v[94:97]
	v_mfma_f32_16x16x32_bf16 v[94:97], v[138:141], v[200:203], v[94:97]
	v_mfma_f32_16x16x32_bf16 v[90:93], v[146:149], v[200:203], v[90:93]
	v_mfma_f32_16x16x32_bf16 v[90:93], v[142:145], v[196:199], v[90:93]
	v_mfma_f32_16x16x32_bf16 v[74:77], v[142:145], v[204:207], v[74:77]
	v_mfma_f32_16x16x32_bf16 v[74:77], v[146:149], v[208:211], v[74:77]
	s_waitcnt lgkmcnt(0)
	v_mfma_f32_16x16x32_bf16 v[78:81], v[138:141], v[208:211], v[78:81]
	v_mfma_f32_16x16x32_bf16 v[78:81], v[130:133], v[204:207], v[78:81]
	s_setprio 0
	s_setprio 1
	v_mfma_f32_16x16x32_bf16 v[118:121], v[150:153], v[180:183], v[118:121]
	v_mfma_f32_16x16x32_bf16 v[118:121], v[168:171], v[184:187], v[118:121]
	v_mfma_f32_16x16x32_bf16 v[114:117], v[176:179], v[184:187], v[114:117]
	v_mfma_f32_16x16x32_bf16 v[114:117], v[172:175], v[180:183], v[114:117]
	v_mfma_f32_16x16x32_bf16 v[98:101], v[172:175], v[188:191], v[98:101]
	v_mfma_f32_16x16x32_bf16 v[98:101], v[176:179], v[192:195], v[98:101]
	v_mfma_f32_16x16x32_bf16 v[102:105], v[168:171], v[192:195], v[102:105]
	v_mfma_f32_16x16x32_bf16 v[102:105], v[150:153], v[188:191], v[102:105]
	v_mfma_f32_16x16x32_bf16 v[86:89], v[150:153], v[196:199], v[86:89]
	v_mfma_f32_16x16x32_bf16 v[86:89], v[168:171], v[200:203], v[86:89]
	v_mfma_f32_16x16x32_bf16 v[82:85], v[176:179], v[200:203], v[82:85]
	v_mfma_f32_16x16x32_bf16 v[82:85], v[172:175], v[196:199], v[82:85]
	v_mfma_f32_16x16x32_bf16 v[66:69], v[172:175], v[204:207], v[66:69]
	v_mfma_f32_16x16x32_bf16 v[66:69], v[176:179], v[208:211], v[66:69]
	s_setprio 2
	s_barrier
	v_mfma_f32_16x16x32_bf16 v[70:73], v[168:171], v[208:211], v[70:73]
	v_mfma_f32_16x16x32_bf16 v[70:73], v[150:153], v[204:207], v[70:73]
	s_setprio 0
	ds_read_b128 v[180:183], v163 offset:49152
	ds_read_b128 v[184:187], v163 offset:50176
	ds_read_b128 v[188:191], v163 offset:51200
	ds_read_b128 v[192:195], v163 offset:52224
	ds_read_b128 v[196:199], v163 offset:53248
	ds_read_b128 v[200:203], v163 offset:54272
	ds_read_b128 v[204:207], v163 offset:55296
	ds_read_b128 v[208:211], v163 offset:56320
	s_add_u32 s28, s10, 0x80
	s_addc_u32 s29, s11, 0
	s_mov_b32 s75, m0
	s_mov_b32 m0, s64
	s_nop 0
	global_load_lds_dwordx4 v156, s[28:29]
	s_mov_b32 m0, s75
	s_add_u32 s10, s10, 0x80080
	s_mov_b32 s75, m0
	s_mov_b32 m0, s65
	s_nop 0
	global_load_lds_dwordx4 v158, s[28:29]
	s_mov_b32 m0, s75
	s_addc_u32 s11, s11, 0
	s_mov_b32 s28, m0
	s_mov_b32 m0, s66
	s_nop 0
	global_load_lds_dwordx4 v156, s[10:11]
	s_mov_b32 m0, s28
	s_nop 0
	s_mov_b32 s28, m0
	s_mov_b32 m0, s67
	s_nop 0
	global_load_lds_dwordx4 v158, s[10:11]
	s_mov_b32 m0, s28
	s_waitcnt vmcnt(4)
	s_waitcnt lgkmcnt(0)
	s_barrier
	s_setprio 1
	s_waitcnt lgkmcnt(7)
	v_mfma_f32_16x16x32_bf16 v[62:65], v[130:133], v[180:183], v[62:65]
	v_mfma_f32_16x16x32_bf16 v[62:65], v[138:141], v[184:187], v[62:65]
	s_waitcnt lgkmcnt(5)
	v_mfma_f32_16x16x32_bf16 v[58:61], v[146:149], v[184:187], v[58:61]
	v_mfma_f32_16x16x32_bf16 v[58:61], v[142:145], v[180:183], v[58:61]
	s_waitcnt lgkmcnt(3)
	v_mfma_f32_16x16x32_bf16 v[42:45], v[142:145], v[188:191], v[42:45]
	v_mfma_f32_16x16x32_bf16 v[42:45], v[146:149], v[192:195], v[42:45]
	s_waitcnt lgkmcnt(1)
	v_mfma_f32_16x16x32_bf16 v[46:49], v[138:141], v[192:195], v[46:49]
	v_mfma_f32_16x16x32_bf16 v[46:49], v[130:133], v[188:191], v[46:49]
	v_mfma_f32_16x16x32_bf16 v[30:33], v[130:133], v[196:199], v[30:33]
	v_mfma_f32_16x16x32_bf16 v[30:33], v[138:141], v[200:203], v[30:33]
	v_mfma_f32_16x16x32_bf16 v[26:29], v[146:149], v[200:203], v[26:29]
	v_mfma_f32_16x16x32_bf16 v[26:29], v[142:145], v[196:199], v[26:29]
	v_mfma_f32_16x16x32_bf16 v[10:13], v[142:145], v[204:207], v[10:13]
	v_mfma_f32_16x16x32_bf16 v[10:13], v[146:149], v[208:211], v[10:13]
	s_waitcnt lgkmcnt(0)
	v_mfma_f32_16x16x32_bf16 v[14:17], v[138:141], v[208:211], v[14:17]
	v_mfma_f32_16x16x32_bf16 v[14:17], v[130:133], v[204:207], v[14:17]
	s_setprio 0
	s_setprio 1
	v_mfma_f32_16x16x32_bf16 v[54:57], v[150:153], v[180:183], v[54:57]
	v_mfma_f32_16x16x32_bf16 v[54:57], v[168:171], v[184:187], v[54:57]
	v_mfma_f32_16x16x32_bf16 v[50:53], v[176:179], v[184:187], v[50:53]
	v_mfma_f32_16x16x32_bf16 v[50:53], v[172:175], v[180:183], v[50:53]
	v_mfma_f32_16x16x32_bf16 v[34:37], v[172:175], v[188:191], v[34:37]
	v_mfma_f32_16x16x32_bf16 v[34:37], v[176:179], v[192:195], v[34:37]
	v_mfma_f32_16x16x32_bf16 v[38:41], v[168:171], v[192:195], v[38:41]
	v_mfma_f32_16x16x32_bf16 v[38:41], v[150:153], v[188:191], v[38:41]
	v_mfma_f32_16x16x32_bf16 v[22:25], v[150:153], v[196:199], v[22:25]
	v_mfma_f32_16x16x32_bf16 v[22:25], v[168:171], v[200:203], v[22:25]
	v_mfma_f32_16x16x32_bf16 v[18:21], v[176:179], v[200:203], v[18:21]
	v_mfma_f32_16x16x32_bf16 v[18:21], v[172:175], v[196:199], v[18:21]
	v_mfma_f32_16x16x32_bf16 v[2:5], v[172:175], v[204:207], v[2:5]
	v_mfma_f32_16x16x32_bf16 v[2:5], v[176:179], v[208:211], v[2:5]
	s_setprio 2
	s_barrier
	v_mfma_f32_16x16x32_bf16 v[6:9], v[168:171], v[208:211], v[6:9]
	v_mfma_f32_16x16x32_bf16 v[6:9], v[150:153], v[204:207], v[6:9]
	s_setprio 0
	s_add_i32 s74, s74, 2
	s_add_u32 s30, s30, 0x100
	s_addc_u32 s31, s31, 0
	s_add_u32 s4, s4, 0x100
	s_addc_u32 s5, s5, 0
	s_add_u32 s33, s33, 0x100
	s_addc_u32 s73, s73, 0
	s_cmp_gt_u32 s74, 29
	s_cbranch_scc0 .LBB0_654
	s_and_b64 vcc, exec, s[18:19]
	s_cbranch_vccz .LBB0_657
	s_barrier

.LBB0_1052:
	s_ashr_i32 s13, s12, 31
	s_lshl_b64 s[14:15], s[12:13], 20
	s_add_u32 s14, s28, s14
	s_addc_u32 s15, s29, s15
	s_and_b64 s[16:17], s[2:3], exec
	s_cselect_b32 s13, s15, s23
	s_cselect_b32 s67, s14, s22
	s_ashr_i32 s11, s10, 31
	s_lshl_b64 s[16:17], s[10:11], 20
	s_add_u32 s16, s30, s16
	s_addc_u32 s17, s31, s17
	s_and_b64 s[24:25], s[2:3], exec
	s_cselect_b32 s11, s17, s21
	s_cselect_b32 s73, s16, s20
	s_add_u32 s74, s20, 0x100
	s_addc_u32 s75, s21, 0
	s_add_u32 s20, s22, 0x80080
	s_addc_u32 s21, s23, 0
	s_add_u32 s76, s22, 0x100
	s_addc_u32 s77, s23, 0
	s_mov_b32 s78, -2
	s_waitcnt vmcnt(25)
	s_waitcnt vmcnt(24)
	s_waitcnt vmcnt(15)
	s_waitcnt vmcnt(14)
	s_waitcnt vmcnt(13)
	s_waitcnt vmcnt(12)
	s_waitcnt vmcnt(11)
	s_waitcnt vmcnt(10)
	s_waitcnt vmcnt(9)
	s_waitcnt vmcnt(8)
	s_waitcnt vmcnt(7)
	s_waitcnt vmcnt(6)
	s_waitcnt vmcnt(5)
	s_waitcnt vmcnt(4)
	s_waitcnt vmcnt(3)
	s_waitcnt vmcnt(2)
	s_waitcnt vmcnt(1)
	s_waitcnt vmcnt(0)
	ds_read_b128 v[130:133], v181
	ds_read_b128 v[134:137], v181 offset:1024
	ds_read_b128 v[138:141], v181 offset:2048
	ds_read_b128 v[142:145], v181 offset:3072
	ds_read_b128 v[146:149], v182
	ds_read_b128 v[150:153], v182 offset:1024
	ds_read_b128 v[154:157], v182 offset:2048
	ds_read_b128 v[158:161], v182 offset:3072
	s_cmp_eq_u32 s78, 28
	s_cselect_b32 s23, s11, s75
	s_cselect_b32 s22, s73, s74
	s_cselect_b32 s25, s13, s77
	s_cselect_b32 s24, s67, s76
	ds_read_b128 v[166:169], v183
	ds_read_b128 v[170:173], v183 offset:1024
	ds_read_b128 v[186:189], v183 offset:2048
	ds_read_b128 v[190:193], v183 offset:3072
	ds_read_b128 v[194:197], v183 offset:4096
	ds_read_b128 v[198:201], v183 offset:5120
	ds_read_b128 v[202:205], v183 offset:6144
	ds_read_b128 v[206:209], v183 offset:7168
	s_add_u32 s80, s20, 0xfff80000
	s_addc_u32 s81, s21, -1
	s_mov_b32 s79, m0
	s_mov_b32 m0, s58
	s_nop 0
	global_load_lds_dwordx4 v1, s[80:81]
	s_mov_b32 m0, s79
	s_nop 0
	s_mov_b32 s79, m0
	s_mov_b32 m0, s64
	s_nop 0
	global_load_lds_dwordx4 v177, s[80:81]
	s_mov_b32 m0, s79
	s_nop 0
	s_mov_b32 s79, m0
	s_mov_b32 m0, s59
	s_nop 0
	global_load_lds_dwordx4 v1, s[20:21]
	s_mov_b32 m0, s79
	s_nop 0
	s_mov_b32 s79, m0
	s_mov_b32 m0, s65
	s_nop 0
	global_load_lds_dwordx4 v177, s[20:21]
	s_mov_b32 m0, s79
	s_waitcnt vmcnt(8)
	s_waitcnt lgkmcnt(0)
	s_barrier
	s_setprio 1
	s_waitcnt lgkmcnt(7)
	v_mfma_f32_16x16x32_bf16 v[126:129], v[130:133], v[166:169], 0
	v_mfma_f32_16x16x32_bf16 v[126:129], v[134:137], v[170:173], v[126:129]
	s_waitcnt lgkmcnt(5)
	v_mfma_f32_16x16x32_bf16 v[122:125], v[142:145], v[170:173], 0
	v_mfma_f32_16x16x32_bf16 v[122:125], v[138:141], v[166:169], v[122:125]
	s_waitcnt lgkmcnt(3)
	v_mfma_f32_16x16x32_bf16 v[114:117], v[138:141], v[186:189], 0
	v_mfma_f32_16x16x32_bf16 v[114:117], v[142:145], v[190:193], v[114:117]
	s_waitcnt lgkmcnt(1)
	v_mfma_f32_16x16x32_bf16 v[118:121], v[134:137], v[190:193], 0
	v_mfma_f32_16x16x32_bf16 v[118:121], v[130:133], v[186:189], v[118:121]
	v_mfma_f32_16x16x32_bf16 v[94:97], v[130:133], v[194:197], 0
	v_mfma_f32_16x16x32_bf16 v[94:97], v[134:137], v[198:201], v[94:97]
	v_mfma_f32_16x16x32_bf16 v[90:93], v[142:145], v[198:201], 0
	v_mfma_f32_16x16x32_bf16 v[90:93], v[138:141], v[194:197], v[90:93]
	v_mfma_f32_16x16x32_bf16 v[78:81], v[138:141], v[202:205], 0
	v_mfma_f32_16x16x32_bf16 v[78:81], v[142:145], v[206:209], v[78:81]
	s_waitcnt lgkmcnt(0)
	v_mfma_f32_16x16x32_bf16 v[86:89], v[134:137], v[206:209], 0
	v_mfma_f32_16x16x32_bf16 v[86:89], v[130:133], v[202:205], v[86:89]
	s_setprio 0
	s_setprio 1
	v_mfma_f32_16x16x32_bf16 v[110:113], v[146:149], v[166:169], 0
	v_mfma_f32_16x16x32_bf16 v[110:113], v[150:153], v[170:173], v[110:113]
	v_mfma_f32_16x16x32_bf16 v[106:109], v[158:161], v[170:173], 0
	v_mfma_f32_16x16x32_bf16 v[106:109], v[154:157], v[166:169], v[106:109]
	v_mfma_f32_16x16x32_bf16 v[98:101], v[154:157], v[186:189], 0
	v_mfma_f32_16x16x32_bf16 v[98:101], v[158:161], v[190:193], v[98:101]
	v_mfma_f32_16x16x32_bf16 v[102:105], v[150:153], v[190:193], 0
	v_mfma_f32_16x16x32_bf16 v[102:105], v[146:149], v[186:189], v[102:105]
	v_mfma_f32_16x16x32_bf16 v[82:85], v[146:149], v[194:197], 0
	v_mfma_f32_16x16x32_bf16 v[82:85], v[150:153], v[198:201], v[82:85]
	v_mfma_f32_16x16x32_bf16 v[74:77], v[158:161], v[198:201], 0
	v_mfma_f32_16x16x32_bf16 v[74:77], v[154:157], v[194:197], v[74:77]
	v_mfma_f32_16x16x32_bf16 v[66:69], v[154:157], v[202:205], 0
	v_mfma_f32_16x16x32_bf16 v[66:69], v[158:161], v[206:209], v[66:69]
	s_setprio 2
	s_barrier
	v_mfma_f32_16x16x32_bf16 v[70:73], v[150:153], v[206:209], 0
	v_mfma_f32_16x16x32_bf16 v[70:73], v[146:149], v[202:205], v[70:73]
	s_setprio 0
	ds_read_b128 v[166:169], v183 offset:16384
	ds_read_b128 v[170:173], v183 offset:17408
	ds_read_b128 v[186:189], v183 offset:18432
	ds_read_b128 v[190:193], v183 offset:19456
	ds_read_b128 v[194:197], v183 offset:20480
	ds_read_b128 v[198:201], v183 offset:21504
	ds_read_b128 v[202:205], v183 offset:22528
	ds_read_b128 v[206:209], v183 offset:23552
	s_mov_b32 s79, m0
	s_mov_b32 m0, s35
	s_nop 0
	global_load_lds_dwordx4 v176, s[22:23]
	s_mov_b32 m0, s79
	s_add_u32 s80, s22, 0x80000
	s_mov_b32 s79, m0
	s_mov_b32 m0, s36
	s_nop 0
	global_load_lds_dwordx4 v178, s[22:23]
	s_mov_b32 m0, s79
	s_addc_u32 s81, s23, 0
	s_mov_b32 s79, m0
	s_mov_b32 m0, s37
	s_nop 0
	global_load_lds_dwordx4 v176, s[80:81]
	s_mov_b32 m0, s79
	s_nop 0
	s_mov_b32 s79, m0
	s_mov_b32 m0, s40
	s_nop 0
	global_load_lds_dwordx4 v178, s[80:81]
	s_mov_b32 m0, s79
	s_waitcnt vmcnt(4)
	s_waitcnt lgkmcnt(0)
	s_barrier
	s_setprio 1
	s_waitcnt lgkmcnt(7)
	v_mfma_f32_16x16x32_bf16 v[62:65], v[130:133], v[166:169], 0
	v_mfma_f32_16x16x32_bf16 v[62:65], v[134:137], v[170:173], v[62:65]
	s_waitcnt lgkmcnt(5)
	v_mfma_f32_16x16x32_bf16 v[58:61], v[142:145], v[170:173], 0
	v_mfma_f32_16x16x32_bf16 v[58:61], v[138:141], v[166:169], v[58:61]
	s_waitcnt lgkmcnt(3)
	v_mfma_f32_16x16x32_bf16 v[42:45], v[138:141], v[186:189], 0
	v_mfma_f32_16x16x32_bf16 v[42:45], v[142:145], v[190:193], v[42:45]
	s_waitcnt lgkmcnt(1)
	v_mfma_f32_16x16x32_bf16 v[46:49], v[134:137], v[190:193], 0
	v_mfma_f32_16x16x32_bf16 v[46:49], v[130:133], v[186:189], v[46:49]
	v_mfma_f32_16x16x32_bf16 v[30:33], v[130:133], v[194:197], 0
	v_mfma_f32_16x16x32_bf16 v[30:33], v[134:137], v[198:201], v[30:33]
	v_mfma_f32_16x16x32_bf16 v[26:29], v[142:145], v[198:201], 0
	v_mfma_f32_16x16x32_bf16 v[26:29], v[138:141], v[194:197], v[26:29]
	v_mfma_f32_16x16x32_bf16 v[10:13], v[138:141], v[202:205], 0
	v_mfma_f32_16x16x32_bf16 v[10:13], v[142:145], v[206:209], v[10:13]
	s_waitcnt lgkmcnt(0)
	v_mfma_f32_16x16x32_bf16 v[14:17], v[134:137], v[206:209], 0
	v_mfma_f32_16x16x32_bf16 v[14:17], v[130:133], v[202:205], v[14:17]
	s_setprio 0
	s_setprio 1
	v_mfma_f32_16x16x32_bf16 v[54:57], v[146:149], v[166:169], 0
	v_mfma_f32_16x16x32_bf16 v[54:57], v[150:153], v[170:173], v[54:57]
	v_mfma_f32_16x16x32_bf16 v[50:53], v[158:161], v[170:173], 0
	v_mfma_f32_16x16x32_bf16 v[50:53], v[154:157], v[166:169], v[50:53]
	v_mfma_f32_16x16x32_bf16 v[34:37], v[154:157], v[186:189], 0
	v_mfma_f32_16x16x32_bf16 v[34:37], v[158:161], v[190:193], v[34:37]
	v_mfma_f32_16x16x32_bf16 v[38:41], v[150:153], v[190:193], 0
	v_mfma_f32_16x16x32_bf16 v[38:41], v[146:149], v[186:189], v[38:41]
	v_mfma_f32_16x16x32_bf16 v[22:25], v[146:149], v[194:197], 0
	v_mfma_f32_16x16x32_bf16 v[22:25], v[150:153], v[198:201], v[22:25]
	v_mfma_f32_16x16x32_bf16 v[18:21], v[158:161], v[198:201], 0
	v_mfma_f32_16x16x32_bf16 v[18:21], v[154:157], v[194:197], v[18:21]
	v_mfma_f32_16x16x32_bf16 v[2:5], v[154:157], v[202:205], 0
	v_mfma_f32_16x16x32_bf16 v[2:5], v[158:161], v[206:209], v[2:5]
	s_setprio 2
	s_barrier
	v_mfma_f32_16x16x32_bf16 v[6:9], v[150:153], v[206:209], 0
	v_mfma_f32_16x16x32_bf16 v[6:9], v[146:149], v[202:205], v[6:9]
	s_setprio 0
	ds_read_b128 v[130:133], v184
	ds_read_b128 v[134:137], v184 offset:1024
	ds_read_b128 v[138:141], v184 offset:2048
	ds_read_b128 v[142:145], v184 offset:3072
	ds_read_b128 v[146:149], v185
	ds_read_b128 v[150:153], v185 offset:1024
	ds_read_b128 v[154:157], v185 offset:2048
	ds_read_b128 v[158:161], v185 offset:3072
	ds_read_b128 v[166:169], v183 offset:32768
	ds_read_b128 v[170:173], v183 offset:33792
	ds_read_b128 v[186:189], v183 offset:34816
	ds_read_b128 v[190:193], v183 offset:35840
	ds_read_b128 v[194:197], v183 offset:36864
	ds_read_b128 v[198:201], v183 offset:37888
	ds_read_b128 v[202:205], v183 offset:38912
	ds_read_b128 v[206:209], v183 offset:39936
	s_mov_b32 s79, m0
	s_mov_b32 m0, s34
	s_nop 0
	global_load_lds_dwordx4 v1, s[24:25]
	s_mov_b32 m0, s79
	s_nop 0
	s_mov_b32 s79, m0
	s_mov_b32 m0, s41
	s_nop 0
	global_load_lds_dwordx4 v177, s[24:25]
	s_mov_b32 m0, s79
	s_add_u32 s24, s24, 0x80000
	s_addc_u32 s25, s25, 0
	s_mov_b32 s79, m0
	s_mov_b32 m0, s42
	s_nop 0
	global_load_lds_dwordx4 v1, s[24:25]
	s_mov_b32 m0, s79
	s_nop 0
	s_mov_b32 s79, m0
	s_mov_b32 m0, s43
	s_nop 0
	global_load_lds_dwordx4 v177, s[24:25]
	s_mov_b32 m0, s79
	s_waitcnt vmcnt(8)
	s_waitcnt lgkmcnt(0)
	s_barrier
	s_setprio 1
	s_waitcnt lgkmcnt(7)
	v_mfma_f32_16x16x32_bf16 v[126:129], v[130:133], v[166:169], v[126:129]
	v_mfma_f32_16x16x32_bf16 v[126:129], v[134:137], v[170:173], v[126:129]
	s_waitcnt lgkmcnt(5)
	v_mfma_f32_16x16x32_bf16 v[122:125], v[142:145], v[170:173], v[122:125]
	v_mfma_f32_16x16x32_bf16 v[122:125], v[138:141], v[166:169], v[122:125]
	s_waitcnt lgkmcnt(3)
	v_mfma_f32_16x16x32_bf16 v[114:117], v[138:141], v[186:189], v[114:117]
	v_mfma_f32_16x16x32_bf16 v[114:117], v[142:145], v[190:193], v[114:117]
	s_waitcnt lgkmcnt(1)
	v_mfma_f32_16x16x32_bf16 v[118:121], v[134:137], v[190:193], v[118:121]
	v_mfma_f32_16x16x32_bf16 v[118:121], v[130:133], v[186:189], v[118:121]
	v_mfma_f32_16x16x32_bf16 v[94:97], v[130:133], v[194:197], v[94:97]
	v_mfma_f32_16x16x32_bf16 v[94:97], v[134:137], v[198:201], v[94:97]
	v_mfma_f32_16x16x32_bf16 v[90:93], v[142:145], v[198:201], v[90:93]
	v_mfma_f32_16x16x32_bf16 v[90:93], v[138:141], v[194:197], v[90:93]
	v_mfma_f32_16x16x32_bf16 v[78:81], v[138:141], v[202:205], v[78:81]
	v_mfma_f32_16x16x32_bf16 v[78:81], v[142:145], v[206:209], v[78:81]
	s_waitcnt lgkmcnt(0)
	v_mfma_f32_16x16x32_bf16 v[86:89], v[134:137], v[206:209], v[86:89]
	v_mfma_f32_16x16x32_bf16 v[86:89], v[130:133], v[202:205], v[86:89]
	s_setprio 0
	s_setprio 1
	v_mfma_f32_16x16x32_bf16 v[110:113], v[146:149], v[166:169], v[110:113]
	v_mfma_f32_16x16x32_bf16 v[110:113], v[150:153], v[170:173], v[110:113]
	v_mfma_f32_16x16x32_bf16 v[106:109], v[158:161], v[170:173], v[106:109]
	v_mfma_f32_16x16x32_bf16 v[106:109], v[154:157], v[166:169], v[106:109]
	v_mfma_f32_16x16x32_bf16 v[98:101], v[154:157], v[186:189], v[98:101]
	v_mfma_f32_16x16x32_bf16 v[98:101], v[158:161], v[190:193], v[98:101]
	v_mfma_f32_16x16x32_bf16 v[102:105], v[150:153], v[190:193], v[102:105]
	v_mfma_f32_16x16x32_bf16 v[102:105], v[146:149], v[186:189], v[102:105]
	v_mfma_f32_16x16x32_bf16 v[82:85], v[146:149], v[194:197], v[82:85]
	v_mfma_f32_16x16x32_bf16 v[82:85], v[150:153], v[198:201], v[82:85]
	v_mfma_f32_16x16x32_bf16 v[74:77], v[158:161], v[198:201], v[74:77]
	v_mfma_f32_16x16x32_bf16 v[74:77], v[154:157], v[194:197], v[74:77]
	v_mfma_f32_16x16x32_bf16 v[66:69], v[154:157], v[202:205], v[66:69]
	v_mfma_f32_16x16x32_bf16 v[66:69], v[158:161], v[206:209], v[66:69]
	s_setprio 2
	s_barrier
	v_mfma_f32_16x16x32_bf16 v[70:73], v[150:153], v[206:209], v[70:73]
	v_mfma_f32_16x16x32_bf16 v[70:73], v[146:149], v[202:205], v[70:73]
	s_setprio 0
	ds_read_b128 v[166:169], v183 offset:49152
	ds_read_b128 v[170:173], v183 offset:50176
	ds_read_b128 v[186:189], v183 offset:51200
	ds_read_b128 v[190:193], v183 offset:52224
	ds_read_b128 v[194:197], v183 offset:53248
	ds_read_b128 v[198:201], v183 offset:54272
	ds_read_b128 v[202:205], v183 offset:55296
	ds_read_b128 v[206:209], v183 offset:56320
	s_add_u32 s24, s22, 0x80
	s_addc_u32 s25, s23, 0
	s_mov_b32 s79, m0
	s_mov_b32 m0, s46
	s_nop 0
	global_load_lds_dwordx4 v176, s[24:25]
	s_mov_b32 m0, s79
	s_add_u32 s22, s22, 0x80080
	s_mov_b32 s79, m0
	s_mov_b32 m0, s47
	s_nop 0
	global_load_lds_dwordx4 v178, s[24:25]
	s_mov_b32 m0, s79
	s_addc_u32 s23, s23, 0
	s_mov_b32 s24, m0
	s_mov_b32 m0, s48
	s_nop 0
	global_load_lds_dwordx4 v176, s[22:23]
	s_mov_b32 m0, s24
	s_nop 0
	s_mov_b32 s24, m0
	s_mov_b32 m0, s49
	s_nop 0
	global_load_lds_dwordx4 v178, s[22:23]
	s_mov_b32 m0, s24
	s_waitcnt vmcnt(4)
	s_waitcnt lgkmcnt(0)
	s_barrier
	s_setprio 1
	s_waitcnt lgkmcnt(7)
	v_mfma_f32_16x16x32_bf16 v[62:65], v[130:133], v[166:169], v[62:65]
	v_mfma_f32_16x16x32_bf16 v[62:65], v[134:137], v[170:173], v[62:65]
	s_waitcnt lgkmcnt(5)
	v_mfma_f32_16x16x32_bf16 v[58:61], v[142:145], v[170:173], v[58:61]
	v_mfma_f32_16x16x32_bf16 v[58:61], v[138:141], v[166:169], v[58:61]
	s_waitcnt lgkmcnt(3)
	v_mfma_f32_16x16x32_bf16 v[42:45], v[138:141], v[186:189], v[42:45]
	v_mfma_f32_16x16x32_bf16 v[42:45], v[142:145], v[190:193], v[42:45]
	s_waitcnt lgkmcnt(1)
	v_mfma_f32_16x16x32_bf16 v[46:49], v[134:137], v[190:193], v[46:49]
	v_mfma_f32_16x16x32_bf16 v[46:49], v[130:133], v[186:189], v[46:49]
	v_mfma_f32_16x16x32_bf16 v[30:33], v[130:133], v[194:197], v[30:33]
	v_mfma_f32_16x16x32_bf16 v[30:33], v[134:137], v[198:201], v[30:33]
	v_mfma_f32_16x16x32_bf16 v[26:29], v[142:145], v[198:201], v[26:29]
	v_mfma_f32_16x16x32_bf16 v[26:29], v[138:141], v[194:197], v[26:29]
	v_mfma_f32_16x16x32_bf16 v[10:13], v[138:141], v[202:205], v[10:13]
	v_mfma_f32_16x16x32_bf16 v[10:13], v[142:145], v[206:209], v[10:13]
	s_waitcnt lgkmcnt(0)
	v_mfma_f32_16x16x32_bf16 v[14:17], v[134:137], v[206:209], v[14:17]
	v_mfma_f32_16x16x32_bf16 v[14:17], v[130:133], v[202:205], v[14:17]
	s_setprio 0
	s_setprio 1
	v_mfma_f32_16x16x32_bf16 v[54:57], v[146:149], v[166:169], v[54:57]
	v_mfma_f32_16x16x32_bf16 v[54:57], v[150:153], v[170:173], v[54:57]
	v_mfma_f32_16x16x32_bf16 v[50:53], v[158:161], v[170:173], v[50:53]
	v_mfma_f32_16x16x32_bf16 v[50:53], v[154:157], v[166:169], v[50:53]
	v_mfma_f32_16x16x32_bf16 v[34:37], v[154:157], v[186:189], v[34:37]
	v_mfma_f32_16x16x32_bf16 v[34:37], v[158:161], v[190:193], v[34:37]
	v_mfma_f32_16x16x32_bf16 v[38:41], v[150:153], v[190:193], v[38:41]
	v_mfma_f32_16x16x32_bf16 v[38:41], v[146:149], v[186:189], v[38:41]
	v_mfma_f32_16x16x32_bf16 v[22:25], v[146:149], v[194:197], v[22:25]
	v_mfma_f32_16x16x32_bf16 v[22:25], v[150:153], v[198:201], v[22:25]
	v_mfma_f32_16x16x32_bf16 v[18:21], v[158:161], v[198:201], v[18:21]
	v_mfma_f32_16x16x32_bf16 v[18:21], v[154:157], v[194:197], v[18:21]
	v_mfma_f32_16x16x32_bf16 v[2:5], v[154:157], v[202:205], v[2:5]
	v_mfma_f32_16x16x32_bf16 v[2:5], v[158:161], v[206:209], v[2:5]
	s_setprio 2
	s_barrier
	v_mfma_f32_16x16x32_bf16 v[6:9], v[150:153], v[206:209], v[6:9]
	v_mfma_f32_16x16x32_bf16 v[6:9], v[146:149], v[202:205], v[6:9]
	s_setprio 0
	s_add_i32 s78, s78, 2
	s_add_u32 s74, s74, 0x100
	s_addc_u32 s75, s75, 0
	s_add_u32 s20, s20, 0x100
	s_addc_u32 s21, s21, 0
	s_add_u32 s76, s76, 0x100
	s_addc_u32 s77, s77, 0
	s_cmp_gt_u32 s78, 29
	.p2align 6
.LBB0_1053:
	ds_read_b128 v[130:133], v181
	ds_read_b128 v[134:137], v181 offset:1024
	ds_read_b128 v[138:141], v181 offset:2048
	ds_read_b128 v[142:145], v181 offset:3072
	ds_read_b128 v[146:149], v182
	ds_read_b128 v[150:153], v182 offset:1024
	ds_read_b128 v[154:157], v182 offset:2048
	ds_read_b128 v[158:161], v182 offset:3072
	s_cmp_eq_u32 s78, 28
	s_cselect_b32 s23, s11, s75
	s_cselect_b32 s22, s73, s74
	s_cselect_b32 s25, s13, s77
	s_cselect_b32 s24, s67, s76
	ds_read_b128 v[166:169], v183
	ds_read_b128 v[170:173], v183 offset:1024
	ds_read_b128 v[186:189], v183 offset:2048
	ds_read_b128 v[190:193], v183 offset:3072
	ds_read_b128 v[194:197], v183 offset:4096
	ds_read_b128 v[198:201], v183 offset:5120
	ds_read_b128 v[202:205], v183 offset:6144
	ds_read_b128 v[206:209], v183 offset:7168
	s_add_u32 s80, s20, 0xfff80000
	s_addc_u32 s81, s21, -1
	s_mov_b32 s79, m0
	s_mov_b32 m0, s58
	s_nop 0
	global_load_lds_dwordx4 v1, s[80:81]
	s_mov_b32 m0, s79
	s_nop 0
	s_mov_b32 s79, m0
	s_mov_b32 m0, s64
	s_nop 0
	global_load_lds_dwordx4 v177, s[80:81]
	s_mov_b32 m0, s79
	s_nop 0
	s_mov_b32 s79, m0
	s_mov_b32 m0, s59
	s_nop 0
	global_load_lds_dwordx4 v1, s[20:21]
	s_mov_b32 m0, s79
	s_nop 0
	s_mov_b32 s79, m0
	s_mov_b32 m0, s65
	s_nop 0
	global_load_lds_dwordx4 v177, s[20:21]
	s_mov_b32 m0, s79
	s_waitcnt vmcnt(8)
	s_waitcnt lgkmcnt(0)
	s_barrier
	s_setprio 1
	s_waitcnt lgkmcnt(7)
	v_mfma_f32_16x16x32_bf16 v[126:129], v[130:133], v[166:169], v[126:129]
	v_mfma_f32_16x16x32_bf16 v[126:129], v[134:137], v[170:173], v[126:129]
	s_waitcnt lgkmcnt(5)
	v_mfma_f32_16x16x32_bf16 v[122:125], v[142:145], v[170:173], v[122:125]
	v_mfma_f32_16x16x32_bf16 v[122:125], v[138:141], v[166:169], v[122:125]
	s_waitcnt lgkmcnt(3)
	v_mfma_f32_16x16x32_bf16 v[114:117], v[138:141], v[186:189], v[114:117]
	v_mfma_f32_16x16x32_bf16 v[114:117], v[142:145], v[190:193], v[114:117]
	s_waitcnt lgkmcnt(1)
	v_mfma_f32_16x16x32_bf16 v[118:121], v[134:137], v[190:193], v[118:121]
	v_mfma_f32_16x16x32_bf16 v[118:121], v[130:133], v[186:189], v[118:121]
	v_mfma_f32_16x16x32_bf16 v[94:97], v[130:133], v[194:197], v[94:97]
	v_mfma_f32_16x16x32_bf16 v[94:97], v[134:137], v[198:201], v[94:97]
	v_mfma_f32_16x16x32_bf16 v[90:93], v[142:145], v[198:201], v[90:93]
	v_mfma_f32_16x16x32_bf16 v[90:93], v[138:141], v[194:197], v[90:93]
	v_mfma_f32_16x16x32_bf16 v[78:81], v[138:141], v[202:205], v[78:81]
	v_mfma_f32_16x16x32_bf16 v[78:81], v[142:145], v[206:209], v[78:81]
	s_waitcnt lgkmcnt(0)
	v_mfma_f32_16x16x32_bf16 v[86:89], v[134:137], v[206:209], v[86:89]
	v_mfma_f32_16x16x32_bf16 v[86:89], v[130:133], v[202:205], v[86:89]
	s_setprio 0
	s_setprio 1
	v_mfma_f32_16x16x32_bf16 v[110:113], v[146:149], v[166:169], v[110:113]
	v_mfma_f32_16x16x32_bf16 v[110:113], v[150:153], v[170:173], v[110:113]
	v_mfma_f32_16x16x32_bf16 v[106:109], v[158:161], v[170:173], v[106:109]
	v_mfma_f32_16x16x32_bf16 v[106:109], v[154:157], v[166:169], v[106:109]
	v_mfma_f32_16x16x32_bf16 v[98:101], v[154:157], v[186:189], v[98:101]
	v_mfma_f32_16x16x32_bf16 v[98:101], v[158:161], v[190:193], v[98:101]
	v_mfma_f32_16x16x32_bf16 v[102:105], v[150:153], v[190:193], v[102:105]
	v_mfma_f32_16x16x32_bf16 v[102:105], v[146:149], v[186:189], v[102:105]
	v_mfma_f32_16x16x32_bf16 v[82:85], v[146:149], v[194:197], v[82:85]
	v_mfma_f32_16x16x32_bf16 v[82:85], v[150:153], v[198:201], v[82:85]
	v_mfma_f32_16x16x32_bf16 v[74:77], v[158:161], v[198:201], v[74:77]
	v_mfma_f32_16x16x32_bf16 v[74:77], v[154:157], v[194:197], v[74:77]
	v_mfma_f32_16x16x32_bf16 v[66:69], v[154:157], v[202:205], v[66:69]
	v_mfma_f32_16x16x32_bf16 v[66:69], v[158:161], v[206:209], v[66:69]
	s_setprio 2
	s_barrier
	v_mfma_f32_16x16x32_bf16 v[70:73], v[150:153], v[206:209], v[70:73]
	v_mfma_f32_16x16x32_bf16 v[70:73], v[146:149], v[202:205], v[70:73]
	s_setprio 0
	ds_read_b128 v[166:169], v183 offset:16384
	ds_read_b128 v[170:173], v183 offset:17408
	ds_read_b128 v[186:189], v183 offset:18432
	ds_read_b128 v[190:193], v183 offset:19456
	ds_read_b128 v[194:197], v183 offset:20480
	ds_read_b128 v[198:201], v183 offset:21504
	ds_read_b128 v[202:205], v183 offset:22528
	ds_read_b128 v[206:209], v183 offset:23552
	s_mov_b32 s79, m0
	s_mov_b32 m0, s35
	s_nop 0
	global_load_lds_dwordx4 v176, s[22:23]
	s_mov_b32 m0, s79
	s_add_u32 s80, s22, 0x80000
	s_mov_b32 s79, m0
	s_mov_b32 m0, s36
	s_nop 0
	global_load_lds_dwordx4 v178, s[22:23]
	s_mov_b32 m0, s79
	s_addc_u32 s81, s23, 0
	s_mov_b32 s79, m0
	s_mov_b32 m0, s37
	s_nop 0
	global_load_lds_dwordx4 v176, s[80:81]
	s_mov_b32 m0, s79
	s_nop 0
	s_mov_b32 s79, m0
	s_mov_b32 m0, s40
	s_nop 0
	global_load_lds_dwordx4 v178, s[80:81]
	s_mov_b32 m0, s79
	s_waitcnt vmcnt(4)
	s_waitcnt lgkmcnt(0)
	s_barrier
	s_setprio 1
	s_waitcnt lgkmcnt(7)
	v_mfma_f32_16x16x32_bf16 v[62:65], v[130:133], v[166:169], v[62:65]
	v_mfma_f32_16x16x32_bf16 v[62:65], v[134:137], v[170:173], v[62:65]
	s_waitcnt lgkmcnt(5)
	v_mfma_f32_16x16x32_bf16 v[58:61], v[142:145], v[170:173], v[58:61]
	v_mfma_f32_16x16x32_bf16 v[58:61], v[138:141], v[166:169], v[58:61]
	s_waitcnt lgkmcnt(3)
	v_mfma_f32_16x16x32_bf16 v[42:45], v[138:141], v[186:189], v[42:45]
	v_mfma_f32_16x16x32_bf16 v[42:45], v[142:145], v[190:193], v[42:45]
	s_waitcnt lgkmcnt(1)
	v_mfma_f32_16x16x32_bf16 v[46:49], v[134:137], v[190:193], v[46:49]
	v_mfma_f32_16x16x32_bf16 v[46:49], v[130:133], v[186:189], v[46:49]
	v_mfma_f32_16x16x32_bf16 v[30:33], v[130:133], v[194:197], v[30:33]
	v_mfma_f32_16x16x32_bf16 v[30:33], v[134:137], v[198:201], v[30:33]
	v_mfma_f32_16x16x32_bf16 v[26:29], v[142:145], v[198:201], v[26:29]
	v_mfma_f32_16x16x32_bf16 v[26:29], v[138:141], v[194:197], v[26:29]
	v_mfma_f32_16x16x32_bf16 v[10:13], v[138:141], v[202:205], v[10:13]
	v_mfma_f32_16x16x32_bf16 v[10:13], v[142:145], v[206:209], v[10:13]
	s_waitcnt lgkmcnt(0)
	v_mfma_f32_16x16x32_bf16 v[14:17], v[134:137], v[206:209], v[14:17]
	v_mfma_f32_16x16x32_bf16 v[14:17], v[130:133], v[202:205], v[14:17]
	s_setprio 0
	s_setprio 1
	v_mfma_f32_16x16x32_bf16 v[54:57], v[146:149], v[166:169], v[54:57]
	v_mfma_f32_16x16x32_bf16 v[54:57], v[150:153], v[170:173], v[54:57]
	v_mfma_f32_16x16x32_bf16 v[50:53], v[158:161], v[170:173], v[50:53]
	v_mfma_f32_16x16x32_bf16 v[50:53], v[154:157], v[166:169], v[50:53]
	v_mfma_f32_16x16x32_bf16 v[34:37], v[154:157], v[186:189], v[34:37]
	v_mfma_f32_16x16x32_bf16 v[34:37], v[158:161], v[190:193], v[34:37]
	v_mfma_f32_16x16x32_bf16 v[38:41], v[150:153], v[190:193], v[38:41]
	v_mfma_f32_16x16x32_bf16 v[38:41], v[146:149], v[186:189], v[38:41]
	v_mfma_f32_16x16x32_bf16 v[22:25], v[146:149], v[194:197], v[22:25]
	v_mfma_f32_16x16x32_bf16 v[22:25], v[150:153], v[198:201], v[22:25]
	v_mfma_f32_16x16x32_bf16 v[18:21], v[158:161], v[198:201], v[18:21]
	v_mfma_f32_16x16x32_bf16 v[18:21], v[154:157], v[194:197], v[18:21]
	v_mfma_f32_16x16x32_bf16 v[2:5], v[154:157], v[202:205], v[2:5]
	v_mfma_f32_16x16x32_bf16 v[2:5], v[158:161], v[206:209], v[2:5]
	s_setprio 2
	s_barrier
	v_mfma_f32_16x16x32_bf16 v[6:9], v[150:153], v[206:209], v[6:9]
	v_mfma_f32_16x16x32_bf16 v[6:9], v[146:149], v[202:205], v[6:9]
	s_setprio 0
	ds_read_b128 v[130:133], v184
	ds_read_b128 v[134:137], v184 offset:1024
	ds_read_b128 v[138:141], v184 offset:2048
	ds_read_b128 v[142:145], v184 offset:3072
	ds_read_b128 v[146:149], v185
	ds_read_b128 v[150:153], v185 offset:1024
	ds_read_b128 v[154:157], v185 offset:2048
	ds_read_b128 v[158:161], v185 offset:3072
	ds_read_b128 v[166:169], v183 offset:32768
	ds_read_b128 v[170:173], v183 offset:33792
	ds_read_b128 v[186:189], v183 offset:34816
	ds_read_b128 v[190:193], v183 offset:35840
	ds_read_b128 v[194:197], v183 offset:36864
	ds_read_b128 v[198:201], v183 offset:37888
	ds_read_b128 v[202:205], v183 offset:38912
	ds_read_b128 v[206:209], v183 offset:39936
	s_mov_b32 s79, m0
	s_mov_b32 m0, s34
	s_nop 0
	global_load_lds_dwordx4 v1, s[24:25]
	s_mov_b32 m0, s79
	s_nop 0
	s_mov_b32 s79, m0
	s_mov_b32 m0, s41
	s_nop 0
	global_load_lds_dwordx4 v177, s[24:25]
	s_mov_b32 m0, s79
	s_add_u32 s24, s24, 0x80000
	s_addc_u32 s25, s25, 0
	s_mov_b32 s79, m0
	s_mov_b32 m0, s42
	s_nop 0
	global_load_lds_dwordx4 v1, s[24:25]
	s_mov_b32 m0, s79
	s_nop 0
	s_mov_b32 s79, m0
	s_mov_b32 m0, s43
	s_nop 0
	global_load_lds_dwordx4 v177, s[24:25]
	s_mov_b32 m0, s79
	s_waitcnt vmcnt(8)
	s_waitcnt lgkmcnt(0)
	s_barrier
	s_setprio 1
	s_waitcnt lgkmcnt(7)
	v_mfma_f32_16x16x32_bf16 v[126:129], v[130:133], v[166:169], v[126:129]
	v_mfma_f32_16x16x32_bf16 v[126:129], v[134:137], v[170:173], v[126:129]
	s_waitcnt lgkmcnt(5)
	v_mfma_f32_16x16x32_bf16 v[122:125], v[142:145], v[170:173], v[122:125]
	v_mfma_f32_16x16x32_bf16 v[122:125], v[138:141], v[166:169], v[122:125]
	s_waitcnt lgkmcnt(3)
	v_mfma_f32_16x16x32_bf16 v[114:117], v[138:141], v[186:189], v[114:117]
	v_mfma_f32_16x16x32_bf16 v[114:117], v[142:145], v[190:193], v[114:117]
	s_waitcnt lgkmcnt(1)
	v_mfma_f32_16x16x32_bf16 v[118:121], v[134:137], v[190:193], v[118:121]
	v_mfma_f32_16x16x32_bf16 v[118:121], v[130:133], v[186:189], v[118:121]
	v_mfma_f32_16x16x32_bf16 v[94:97], v[130:133], v[194:197], v[94:97]
	v_mfma_f32_16x16x32_bf16 v[94:97], v[134:137], v[198:201], v[94:97]
	v_mfma_f32_16x16x32_bf16 v[90:93], v[142:145], v[198:201], v[90:93]
	v_mfma_f32_16x16x32_bf16 v[90:93], v[138:141], v[194:197], v[90:93]
	v_mfma_f32_16x16x32_bf16 v[78:81], v[138:141], v[202:205], v[78:81]
	v_mfma_f32_16x16x32_bf16 v[78:81], v[142:145], v[206:209], v[78:81]
	s_waitcnt lgkmcnt(0)
	v_mfma_f32_16x16x32_bf16 v[86:89], v[134:137], v[206:209], v[86:89]
	v_mfma_f32_16x16x32_bf16 v[86:89], v[130:133], v[202:205], v[86:89]
	s_setprio 0
	s_setprio 1
	v_mfma_f32_16x16x32_bf16 v[110:113], v[146:149], v[166:169], v[110:113]
	v_mfma_f32_16x16x32_bf16 v[110:113], v[150:153], v[170:173], v[110:113]
	v_mfma_f32_16x16x32_bf16 v[106:109], v[158:161], v[170:173], v[106:109]
	v_mfma_f32_16x16x32_bf16 v[106:109], v[154:157], v[166:169], v[106:109]
	v_mfma_f32_16x16x32_bf16 v[98:101], v[154:157], v[186:189], v[98:101]
	v_mfma_f32_16x16x32_bf16 v[98:101], v[158:161], v[190:193], v[98:101]
	v_mfma_f32_16x16x32_bf16 v[102:105], v[150:153], v[190:193], v[102:105]
	v_mfma_f32_16x16x32_bf16 v[102:105], v[146:149], v[186:189], v[102:105]
	v_mfma_f32_16x16x32_bf16 v[82:85], v[146:149], v[194:197], v[82:85]
	v_mfma_f32_16x16x32_bf16 v[82:85], v[150:153], v[198:201], v[82:85]
	v_mfma_f32_16x16x32_bf16 v[74:77], v[158:161], v[198:201], v[74:77]
	v_mfma_f32_16x16x32_bf16 v[74:77], v[154:157], v[194:197], v[74:77]
	v_mfma_f32_16x16x32_bf16 v[66:69], v[154:157], v[202:205], v[66:69]
	v_mfma_f32_16x16x32_bf16 v[66:69], v[158:161], v[206:209], v[66:69]
	s_setprio 2
	s_barrier
	v_mfma_f32_16x16x32_bf16 v[70:73], v[150:153], v[206:209], v[70:73]
	v_mfma_f32_16x16x32_bf16 v[70:73], v[146:149], v[202:205], v[70:73]
	s_setprio 0
	ds_read_b128 v[166:169], v183 offset:49152
	ds_read_b128 v[170:173], v183 offset:50176
	ds_read_b128 v[186:189], v183 offset:51200
	ds_read_b128 v[190:193], v183 offset:52224
	ds_read_b128 v[194:197], v183 offset:53248
	ds_read_b128 v[198:201], v183 offset:54272
	ds_read_b128 v[202:205], v183 offset:55296
	ds_read_b128 v[206:209], v183 offset:56320
	s_add_u32 s24, s22, 0x80
	s_addc_u32 s25, s23, 0
	s_mov_b32 s79, m0
	s_mov_b32 m0, s46
	s_nop 0
	global_load_lds_dwordx4 v176, s[24:25]
	s_mov_b32 m0, s79
	s_add_u32 s22, s22, 0x80080
	s_mov_b32 s79, m0
	s_mov_b32 m0, s47
	s_nop 0
	global_load_lds_dwordx4 v178, s[24:25]
	s_mov_b32 m0, s79
	s_addc_u32 s23, s23, 0
	s_mov_b32 s24, m0
	s_mov_b32 m0, s48
	s_nop 0
	global_load_lds_dwordx4 v176, s[22:23]
	s_mov_b32 m0, s24
	s_nop 0
	s_mov_b32 s24, m0
	s_mov_b32 m0, s49
	s_nop 0
	global_load_lds_dwordx4 v178, s[22:23]
	s_mov_b32 m0, s24
	s_waitcnt vmcnt(4)
	s_waitcnt lgkmcnt(0)
	s_barrier
	s_setprio 1
	s_waitcnt lgkmcnt(7)
	v_mfma_f32_16x16x32_bf16 v[62:65], v[130:133], v[166:169], v[62:65]
	v_mfma_f32_16x16x32_bf16 v[62:65], v[134:137], v[170:173], v[62:65]
	s_waitcnt lgkmcnt(5)
	v_mfma_f32_16x16x32_bf16 v[58:61], v[142:145], v[170:173], v[58:61]
	v_mfma_f32_16x16x32_bf16 v[58:61], v[138:141], v[166:169], v[58:61]
	s_waitcnt lgkmcnt(3)
	v_mfma_f32_16x16x32_bf16 v[42:45], v[138:141], v[186:189], v[42:45]
	v_mfma_f32_16x16x32_bf16 v[42:45], v[142:145], v[190:193], v[42:45]
	s_waitcnt lgkmcnt(1)
	v_mfma_f32_16x16x32_bf16 v[46:49], v[134:137], v[190:193], v[46:49]
	v_mfma_f32_16x16x32_bf16 v[46:49], v[130:133], v[186:189], v[46:49]
	v_mfma_f32_16x16x32_bf16 v[30:33], v[130:133], v[194:197], v[30:33]
	v_mfma_f32_16x16x32_bf16 v[30:33], v[134:137], v[198:201], v[30:33]
	v_mfma_f32_16x16x32_bf16 v[26:29], v[142:145], v[198:201], v[26:29]
	v_mfma_f32_16x16x32_bf16 v[26:29], v[138:141], v[194:197], v[26:29]
	v_mfma_f32_16x16x32_bf16 v[10:13], v[138:141], v[202:205], v[10:13]
	v_mfma_f32_16x16x32_bf16 v[10:13], v[142:145], v[206:209], v[10:13]
	s_waitcnt lgkmcnt(0)
	v_mfma_f32_16x16x32_bf16 v[14:17], v[134:137], v[206:209], v[14:17]
	v_mfma_f32_16x16x32_bf16 v[14:17], v[130:133], v[202:205], v[14:17]
	s_setprio 0
	s_setprio 1
	v_mfma_f32_16x16x32_bf16 v[54:57], v[146:149], v[166:169], v[54:57]
	v_mfma_f32_16x16x32_bf16 v[54:57], v[150:153], v[170:173], v[54:57]
	v_mfma_f32_16x16x32_bf16 v[50:53], v[158:161], v[170:173], v[50:53]
	v_mfma_f32_16x16x32_bf16 v[50:53], v[154:157], v[166:169], v[50:53]
	v_mfma_f32_16x16x32_bf16 v[34:37], v[154:157], v[186:189], v[34:37]
	v_mfma_f32_16x16x32_bf16 v[34:37], v[158:161], v[190:193], v[34:37]
	v_mfma_f32_16x16x32_bf16 v[38:41], v[150:153], v[190:193], v[38:41]
	v_mfma_f32_16x16x32_bf16 v[38:41], v[146:149], v[186:189], v[38:41]
	v_mfma_f32_16x16x32_bf16 v[22:25], v[146:149], v[194:197], v[22:25]
	v_mfma_f32_16x16x32_bf16 v[22:25], v[150:153], v[198:201], v[22:25]
	v_mfma_f32_16x16x32_bf16 v[18:21], v[158:161], v[198:201], v[18:21]
	v_mfma_f32_16x16x32_bf16 v[18:21], v[154:157], v[194:197], v[18:21]
	v_mfma_f32_16x16x32_bf16 v[2:5], v[154:157], v[202:205], v[2:5]
	v_mfma_f32_16x16x32_bf16 v[2:5], v[158:161], v[206:209], v[2:5]
	s_setprio 2
	s_barrier
	v_mfma_f32_16x16x32_bf16 v[6:9], v[150:153], v[206:209], v[6:9]
	v_mfma_f32_16x16x32_bf16 v[6:9], v[146:149], v[202:205], v[6:9]
	s_setprio 0
	s_add_i32 s78, s78, 2
	s_add_u32 s74, s74, 0x100
	s_addc_u32 s75, s75, 0
	s_add_u32 s20, s20, 0x100
	s_addc_u32 s21, s21, 0
	s_add_u32 s76, s76, 0x100
	s_addc_u32 s77, s77, 0
	s_cmp_gt_u32 s78, 29
	s_cbranch_scc0 .LBB0_1053
	s_and_b64 vcc, exec, s[8:9]
	s_cbranch_vccz .LBB0_1056
	s_barrier

.LBB0_1223:
	s_ashr_i32 s11, s10, 31
	s_lshl_b64 s[12:13], s[10:11], 20
	s_add_u32 s12, s26, s12
	s_addc_u32 s13, s27, s13
	s_and_b64 s[14:15], s[2:3], exec
	s_cselect_b32 s11, s13, s21
	s_cselect_b32 s66, s12, s20
	s_ashr_i32 s9, s8, 31
	s_lshl_b64 s[14:15], s[8:9], 20
	s_add_u32 s14, s28, s14
	s_addc_u32 s15, s29, s15
	s_and_b64 s[22:23], s[2:3], exec
	s_cselect_b32 s9, s15, s19
	s_cselect_b32 s67, s14, s18
	s_add_u32 s73, s18, 0x100
	s_addc_u32 s74, s19, 0
	s_add_u32 s18, s20, 0x80080
	s_addc_u32 s19, s21, 0
	s_add_u32 s75, s20, 0x100
	s_addc_u32 s76, s21, 0
	s_mov_b32 s77, -2
	ds_read_b128 v[148:151], v143
	ds_read_b128 v[152:155], v143 offset:1024
	ds_read_b128 v[156:159], v143 offset:2048
	ds_read_b128 v[160:163], v143 offset:3072
	ds_read_b128 v[164:167], v144
	ds_read_b128 v[168:171], v144 offset:1024
	ds_read_b128 v[172:175], v144 offset:2048
	ds_read_b128 v[176:179], v144 offset:3072
	s_cmp_eq_u32 s77, 28
	s_cselect_b32 s21, s9, s74
	s_cselect_b32 s20, s67, s73
	s_cselect_b32 s23, s11, s76
	s_cselect_b32 s22, s66, s75
	ds_read_b128 v[180:183], v145
	ds_read_b128 v[184:187], v145 offset:1024
	ds_read_b128 v[188:191], v145 offset:2048
	ds_read_b128 v[192:195], v145 offset:3072
	ds_read_b128 v[196:199], v145 offset:4096
	ds_read_b128 v[200:203], v145 offset:5120
	ds_read_b128 v[204:207], v145 offset:6144
	ds_read_b128 v[208:211], v145 offset:7168
	s_add_u32 s78, s18, 0xfff80000
	s_addc_u32 s79, s19, -1
	s_mov_b32 s80, m0
	s_mov_b32 m0, s56
	s_nop 0
	global_load_lds_dwordx4 v138, s[78:79]
	s_mov_b32 m0, s80
	s_nop 0
	s_mov_b32 s80, m0
	s_mov_b32 m0, s59
	s_nop 0
	global_load_lds_dwordx4 v140, s[78:79]
	s_mov_b32 m0, s80
	s_mov_b32 s78, m0
	s_mov_b32 m0, s57
	s_nop 0
	global_load_lds_dwordx4 v138, s[18:19]
	s_mov_b32 m0, s78
	s_nop 0
	s_mov_b32 s78, m0
	s_mov_b32 m0, s64
	s_nop 0
	global_load_lds_dwordx4 v140, s[18:19]
	s_mov_b32 m0, s78
	s_waitcnt vmcnt(8)
	s_waitcnt lgkmcnt(0)
	s_barrier
	s_setprio 1
	s_waitcnt lgkmcnt(7)
	v_mfma_f32_16x16x32_bf16 v[126:129], v[148:151], v[180:183], 0
	v_mfma_f32_16x16x32_bf16 v[126:129], v[152:155], v[184:187], v[126:129]
	s_waitcnt lgkmcnt(5)
	v_mfma_f32_16x16x32_bf16 v[122:125], v[160:163], v[184:187], 0
	v_mfma_f32_16x16x32_bf16 v[122:125], v[156:159], v[180:183], v[122:125]
	s_waitcnt lgkmcnt(3)
	v_mfma_f32_16x16x32_bf16 v[106:109], v[156:159], v[188:191], 0
	v_mfma_f32_16x16x32_bf16 v[106:109], v[160:163], v[192:195], v[106:109]
	s_waitcnt lgkmcnt(1)
	v_mfma_f32_16x16x32_bf16 v[110:113], v[152:155], v[192:195], 0
	v_mfma_f32_16x16x32_bf16 v[110:113], v[148:151], v[188:191], v[110:113]
	v_mfma_f32_16x16x32_bf16 v[94:97], v[148:151], v[196:199], 0
	v_mfma_f32_16x16x32_bf16 v[94:97], v[152:155], v[200:203], v[94:97]
	v_mfma_f32_16x16x32_bf16 v[90:93], v[160:163], v[200:203], 0
	v_mfma_f32_16x16x32_bf16 v[90:93], v[156:159], v[196:199], v[90:93]
	v_mfma_f32_16x16x32_bf16 v[74:77], v[156:159], v[204:207], 0
	v_mfma_f32_16x16x32_bf16 v[74:77], v[160:163], v[208:211], v[74:77]
	s_waitcnt lgkmcnt(0)
	v_mfma_f32_16x16x32_bf16 v[78:81], v[152:155], v[208:211], 0
	v_mfma_f32_16x16x32_bf16 v[78:81], v[148:151], v[204:207], v[78:81]
	s_setprio 0
	s_setprio 1
	v_mfma_f32_16x16x32_bf16 v[118:121], v[164:167], v[180:183], 0
	v_mfma_f32_16x16x32_bf16 v[118:121], v[168:171], v[184:187], v[118:121]
	v_mfma_f32_16x16x32_bf16 v[114:117], v[176:179], v[184:187], 0
	v_mfma_f32_16x16x32_bf16 v[114:117], v[172:175], v[180:183], v[114:117]
	v_mfma_f32_16x16x32_bf16 v[98:101], v[172:175], v[188:191], 0
	v_mfma_f32_16x16x32_bf16 v[98:101], v[176:179], v[192:195], v[98:101]
	v_mfma_f32_16x16x32_bf16 v[102:105], v[168:171], v[192:195], 0
	v_mfma_f32_16x16x32_bf16 v[102:105], v[164:167], v[188:191], v[102:105]
	v_mfma_f32_16x16x32_bf16 v[86:89], v[164:167], v[196:199], 0
	v_mfma_f32_16x16x32_bf16 v[86:89], v[168:171], v[200:203], v[86:89]
	v_mfma_f32_16x16x32_bf16 v[82:85], v[176:179], v[200:203], 0
	v_mfma_f32_16x16x32_bf16 v[82:85], v[172:175], v[196:199], v[82:85]
	v_mfma_f32_16x16x32_bf16 v[66:69], v[172:175], v[204:207], 0
	v_mfma_f32_16x16x32_bf16 v[66:69], v[176:179], v[208:211], v[66:69]
	s_setprio 2
	s_barrier
	v_mfma_f32_16x16x32_bf16 v[70:73], v[168:171], v[208:211], 0
	v_mfma_f32_16x16x32_bf16 v[70:73], v[164:167], v[204:207], v[70:73]
	s_setprio 0
	ds_read_b128 v[180:183], v145 offset:16384
	ds_read_b128 v[184:187], v145 offset:17408
	ds_read_b128 v[188:191], v145 offset:18432
	ds_read_b128 v[192:195], v145 offset:19456
	ds_read_b128 v[196:199], v145 offset:20480
	ds_read_b128 v[200:203], v145 offset:21504
	ds_read_b128 v[204:207], v145 offset:22528
	ds_read_b128 v[208:211], v145 offset:23552
	s_mov_b32 s78, m0
	s_mov_b32 m0, s35
	s_nop 0
	global_load_lds_dwordx4 v139, s[20:21]
	s_mov_b32 m0, s78
	s_nop 0
	s_mov_b32 s78, m0
	s_mov_b32 m0, s36
	s_nop 0
	global_load_lds_dwordx4 v141, s[20:21]
	s_mov_b32 m0, s78
	s_add_u32 s78, s20, 0x80000
	s_addc_u32 s79, s21, 0
	s_mov_b32 s80, m0
	s_mov_b32 m0, s37
	s_nop 0
	global_load_lds_dwordx4 v139, s[78:79]
	s_mov_b32 m0, s80
	s_nop 0
	s_mov_b32 s80, m0
	s_mov_b32 m0, s40
	s_nop 0
	global_load_lds_dwordx4 v141, s[78:79]
	s_mov_b32 m0, s80
	s_waitcnt vmcnt(4)
	s_waitcnt lgkmcnt(0)
	s_barrier
	s_setprio 1
	s_waitcnt lgkmcnt(7)
	v_mfma_f32_16x16x32_bf16 v[62:65], v[148:151], v[180:183], 0
	v_mfma_f32_16x16x32_bf16 v[62:65], v[152:155], v[184:187], v[62:65]
	s_waitcnt lgkmcnt(5)
	v_mfma_f32_16x16x32_bf16 v[58:61], v[160:163], v[184:187], 0
	v_mfma_f32_16x16x32_bf16 v[58:61], v[156:159], v[180:183], v[58:61]
	s_waitcnt lgkmcnt(3)
	v_mfma_f32_16x16x32_bf16 v[42:45], v[156:159], v[188:191], 0
	v_mfma_f32_16x16x32_bf16 v[42:45], v[160:163], v[192:195], v[42:45]
	s_waitcnt lgkmcnt(1)
	v_mfma_f32_16x16x32_bf16 v[46:49], v[152:155], v[192:195], 0
	v_mfma_f32_16x16x32_bf16 v[46:49], v[148:151], v[188:191], v[46:49]
	v_mfma_f32_16x16x32_bf16 v[30:33], v[148:151], v[196:199], 0
	v_mfma_f32_16x16x32_bf16 v[30:33], v[152:155], v[200:203], v[30:33]
	v_mfma_f32_16x16x32_bf16 v[26:29], v[160:163], v[200:203], 0
	v_mfma_f32_16x16x32_bf16 v[26:29], v[156:159], v[196:199], v[26:29]
	v_mfma_f32_16x16x32_bf16 v[10:13], v[156:159], v[204:207], 0
	v_mfma_f32_16x16x32_bf16 v[10:13], v[160:163], v[208:211], v[10:13]
	s_waitcnt lgkmcnt(0)
	v_mfma_f32_16x16x32_bf16 v[14:17], v[152:155], v[208:211], 0
	v_mfma_f32_16x16x32_bf16 v[14:17], v[148:151], v[204:207], v[14:17]
	s_setprio 0
	s_setprio 1
	v_mfma_f32_16x16x32_bf16 v[54:57], v[164:167], v[180:183], 0
	v_mfma_f32_16x16x32_bf16 v[54:57], v[168:171], v[184:187], v[54:57]
	v_mfma_f32_16x16x32_bf16 v[50:53], v[176:179], v[184:187], 0
	v_mfma_f32_16x16x32_bf16 v[50:53], v[172:175], v[180:183], v[50:53]
	v_mfma_f32_16x16x32_bf16 v[34:37], v[172:175], v[188:191], 0
	v_mfma_f32_16x16x32_bf16 v[34:37], v[176:179], v[192:195], v[34:37]
	v_mfma_f32_16x16x32_bf16 v[38:41], v[168:171], v[192:195], 0
	v_mfma_f32_16x16x32_bf16 v[38:41], v[164:167], v[188:191], v[38:41]
	v_mfma_f32_16x16x32_bf16 v[22:25], v[164:167], v[196:199], 0
	v_mfma_f32_16x16x32_bf16 v[22:25], v[168:171], v[200:203], v[22:25]
	v_mfma_f32_16x16x32_bf16 v[18:21], v[176:179], v[200:203], 0
	v_mfma_f32_16x16x32_bf16 v[18:21], v[172:175], v[196:199], v[18:21]
	v_mfma_f32_16x16x32_bf16 v[2:5], v[172:175], v[204:207], 0
	v_mfma_f32_16x16x32_bf16 v[2:5], v[176:179], v[208:211], v[2:5]
	s_setprio 2
	s_barrier
	v_mfma_f32_16x16x32_bf16 v[6:9], v[168:171], v[208:211], 0
	v_mfma_f32_16x16x32_bf16 v[6:9], v[164:167], v[204:207], v[6:9]
	s_setprio 0
	ds_read_b128 v[148:151], v146
	ds_read_b128 v[152:155], v146 offset:1024
	ds_read_b128 v[156:159], v146 offset:2048
	ds_read_b128 v[160:163], v146 offset:3072
	ds_read_b128 v[164:167], v147
	ds_read_b128 v[168:171], v147 offset:1024
	ds_read_b128 v[172:175], v147 offset:2048
	ds_read_b128 v[176:179], v147 offset:3072
	ds_read_b128 v[180:183], v145 offset:32768
	ds_read_b128 v[184:187], v145 offset:33792
	ds_read_b128 v[188:191], v145 offset:34816
	ds_read_b128 v[192:195], v145 offset:35840
	ds_read_b128 v[196:199], v145 offset:36864
	ds_read_b128 v[200:203], v145 offset:37888
	ds_read_b128 v[204:207], v145 offset:38912
	ds_read_b128 v[208:211], v145 offset:39936
	s_mov_b32 s78, m0
	s_mov_b32 m0, s31
	s_nop 0
	global_load_lds_dwordx4 v138, s[22:23]
	s_mov_b32 m0, s78
	s_nop 0
	s_mov_b32 s78, m0
	s_mov_b32 m0, s41
	s_nop 0
	global_load_lds_dwordx4 v140, s[22:23]
	s_mov_b32 m0, s78
	s_add_u32 s22, s22, 0x80000
	s_addc_u32 s23, s23, 0
	s_mov_b32 s78, m0
	s_mov_b32 m0, s42
	s_nop 0
	global_load_lds_dwordx4 v138, s[22:23]
	s_mov_b32 m0, s78
	s_nop 0
	s_mov_b32 s78, m0
	s_mov_b32 m0, s43
	s_nop 0
	global_load_lds_dwordx4 v140, s[22:23]
	s_mov_b32 m0, s78
	s_waitcnt vmcnt(8)
	s_waitcnt lgkmcnt(0)
	s_barrier
	s_setprio 1
	s_waitcnt lgkmcnt(7)
	v_mfma_f32_16x16x32_bf16 v[126:129], v[148:151], v[180:183], v[126:129]
	v_mfma_f32_16x16x32_bf16 v[126:129], v[152:155], v[184:187], v[126:129]
	s_waitcnt lgkmcnt(5)
	v_mfma_f32_16x16x32_bf16 v[122:125], v[160:163], v[184:187], v[122:125]
	v_mfma_f32_16x16x32_bf16 v[122:125], v[156:159], v[180:183], v[122:125]
	s_waitcnt lgkmcnt(3)
	v_mfma_f32_16x16x32_bf16 v[106:109], v[156:159], v[188:191], v[106:109]
	v_mfma_f32_16x16x32_bf16 v[106:109], v[160:163], v[192:195], v[106:109]
	s_waitcnt lgkmcnt(1)
	v_mfma_f32_16x16x32_bf16 v[110:113], v[152:155], v[192:195], v[110:113]
	v_mfma_f32_16x16x32_bf16 v[110:113], v[148:151], v[188:191], v[110:113]
	v_mfma_f32_16x16x32_bf16 v[94:97], v[148:151], v[196:199], v[94:97]
	v_mfma_f32_16x16x32_bf16 v[94:97], v[152:155], v[200:203], v[94:97]
	v_mfma_f32_16x16x32_bf16 v[90:93], v[160:163], v[200:203], v[90:93]
	v_mfma_f32_16x16x32_bf16 v[90:93], v[156:159], v[196:199], v[90:93]
	v_mfma_f32_16x16x32_bf16 v[74:77], v[156:159], v[204:207], v[74:77]
	v_mfma_f32_16x16x32_bf16 v[74:77], v[160:163], v[208:211], v[74:77]
	s_waitcnt lgkmcnt(0)
	v_mfma_f32_16x16x32_bf16 v[78:81], v[152:155], v[208:211], v[78:81]
	v_mfma_f32_16x16x32_bf16 v[78:81], v[148:151], v[204:207], v[78:81]
	s_setprio 0
	s_setprio 1
	v_mfma_f32_16x16x32_bf16 v[118:121], v[164:167], v[180:183], v[118:121]
	v_mfma_f32_16x16x32_bf16 v[118:121], v[168:171], v[184:187], v[118:121]
	v_mfma_f32_16x16x32_bf16 v[114:117], v[176:179], v[184:187], v[114:117]
	v_mfma_f32_16x16x32_bf16 v[114:117], v[172:175], v[180:183], v[114:117]
	v_mfma_f32_16x16x32_bf16 v[98:101], v[172:175], v[188:191], v[98:101]
	v_mfma_f32_16x16x32_bf16 v[98:101], v[176:179], v[192:195], v[98:101]
	v_mfma_f32_16x16x32_bf16 v[102:105], v[168:171], v[192:195], v[102:105]
	v_mfma_f32_16x16x32_bf16 v[102:105], v[164:167], v[188:191], v[102:105]
	v_mfma_f32_16x16x32_bf16 v[86:89], v[164:167], v[196:199], v[86:89]
	v_mfma_f32_16x16x32_bf16 v[86:89], v[168:171], v[200:203], v[86:89]
	v_mfma_f32_16x16x32_bf16 v[82:85], v[176:179], v[200:203], v[82:85]
	v_mfma_f32_16x16x32_bf16 v[82:85], v[172:175], v[196:199], v[82:85]
	v_mfma_f32_16x16x32_bf16 v[66:69], v[172:175], v[204:207], v[66:69]
	v_mfma_f32_16x16x32_bf16 v[66:69], v[176:179], v[208:211], v[66:69]
	s_setprio 2
	s_barrier
	v_mfma_f32_16x16x32_bf16 v[70:73], v[168:171], v[208:211], v[70:73]
	v_mfma_f32_16x16x32_bf16 v[70:73], v[164:167], v[204:207], v[70:73]
	s_setprio 0
	ds_read_b128 v[180:183], v145 offset:49152
	ds_read_b128 v[184:187], v145 offset:50176
	ds_read_b128 v[188:191], v145 offset:51200
	ds_read_b128 v[192:195], v145 offset:52224
	ds_read_b128 v[196:199], v145 offset:53248
	ds_read_b128 v[200:203], v145 offset:54272
	ds_read_b128 v[204:207], v145 offset:55296
	ds_read_b128 v[208:211], v145 offset:56320
	s_add_u32 s22, s20, 0x80
	s_addc_u32 s23, s21, 0
	s_mov_b32 s78, m0
	s_mov_b32 m0, s46
	s_nop 0
	global_load_lds_dwordx4 v139, s[22:23]
	s_mov_b32 m0, s78
	s_add_u32 s20, s20, 0x80080
	s_mov_b32 s78, m0
	s_mov_b32 m0, s47
	s_nop 0
	global_load_lds_dwordx4 v141, s[22:23]
	s_mov_b32 m0, s78
	s_addc_u32 s21, s21, 0
	s_mov_b32 s22, m0
	s_mov_b32 m0, s48
	s_nop 0
	global_load_lds_dwordx4 v139, s[20:21]
	s_mov_b32 m0, s22
	s_nop 0
	s_mov_b32 s22, m0
	s_mov_b32 m0, s49
	s_nop 0
	global_load_lds_dwordx4 v141, s[20:21]
	s_mov_b32 m0, s22
	s_waitcnt vmcnt(4)
	s_waitcnt lgkmcnt(0)
	s_barrier
	s_setprio 1
	s_waitcnt lgkmcnt(7)
	v_mfma_f32_16x16x32_bf16 v[62:65], v[148:151], v[180:183], v[62:65]
	v_mfma_f32_16x16x32_bf16 v[62:65], v[152:155], v[184:187], v[62:65]
	s_waitcnt lgkmcnt(5)
	v_mfma_f32_16x16x32_bf16 v[58:61], v[160:163], v[184:187], v[58:61]
	v_mfma_f32_16x16x32_bf16 v[58:61], v[156:159], v[180:183], v[58:61]
	s_waitcnt lgkmcnt(3)
	v_mfma_f32_16x16x32_bf16 v[42:45], v[156:159], v[188:191], v[42:45]
	v_mfma_f32_16x16x32_bf16 v[42:45], v[160:163], v[192:195], v[42:45]
	s_waitcnt lgkmcnt(1)
	v_mfma_f32_16x16x32_bf16 v[46:49], v[152:155], v[192:195], v[46:49]
	v_mfma_f32_16x16x32_bf16 v[46:49], v[148:151], v[188:191], v[46:49]
	v_mfma_f32_16x16x32_bf16 v[30:33], v[148:151], v[196:199], v[30:33]
	v_mfma_f32_16x16x32_bf16 v[30:33], v[152:155], v[200:203], v[30:33]
	v_mfma_f32_16x16x32_bf16 v[26:29], v[160:163], v[200:203], v[26:29]
	v_mfma_f32_16x16x32_bf16 v[26:29], v[156:159], v[196:199], v[26:29]
	v_mfma_f32_16x16x32_bf16 v[10:13], v[156:159], v[204:207], v[10:13]
	v_mfma_f32_16x16x32_bf16 v[10:13], v[160:163], v[208:211], v[10:13]
	s_waitcnt lgkmcnt(0)
	v_mfma_f32_16x16x32_bf16 v[14:17], v[152:155], v[208:211], v[14:17]
	v_mfma_f32_16x16x32_bf16 v[14:17], v[148:151], v[204:207], v[14:17]
	s_setprio 0
	s_setprio 1
	v_mfma_f32_16x16x32_bf16 v[54:57], v[164:167], v[180:183], v[54:57]
	v_mfma_f32_16x16x32_bf16 v[54:57], v[168:171], v[184:187], v[54:57]
	v_mfma_f32_16x16x32_bf16 v[50:53], v[176:179], v[184:187], v[50:53]
	v_mfma_f32_16x16x32_bf16 v[50:53], v[172:175], v[180:183], v[50:53]
	v_mfma_f32_16x16x32_bf16 v[34:37], v[172:175], v[188:191], v[34:37]
	v_mfma_f32_16x16x32_bf16 v[34:37], v[176:179], v[192:195], v[34:37]
	v_mfma_f32_16x16x32_bf16 v[38:41], v[168:171], v[192:195], v[38:41]
	v_mfma_f32_16x16x32_bf16 v[38:41], v[164:167], v[188:191], v[38:41]
	v_mfma_f32_16x16x32_bf16 v[22:25], v[164:167], v[196:199], v[22:25]
	v_mfma_f32_16x16x32_bf16 v[22:25], v[168:171], v[200:203], v[22:25]
	v_mfma_f32_16x16x32_bf16 v[18:21], v[176:179], v[200:203], v[18:21]
	v_mfma_f32_16x16x32_bf16 v[18:21], v[172:175], v[196:199], v[18:21]
	v_mfma_f32_16x16x32_bf16 v[2:5], v[172:175], v[204:207], v[2:5]
	v_mfma_f32_16x16x32_bf16 v[2:5], v[176:179], v[208:211], v[2:5]
	s_setprio 2
	s_barrier
	v_mfma_f32_16x16x32_bf16 v[6:9], v[168:171], v[208:211], v[6:9]
	v_mfma_f32_16x16x32_bf16 v[6:9], v[164:167], v[204:207], v[6:9]
	s_setprio 0
	s_add_i32 s77, s77, 2
	s_add_u32 s73, s73, 0x100
	s_addc_u32 s74, s74, 0
	s_add_u32 s18, s18, 0x100
	s_addc_u32 s19, s19, 0
	s_add_u32 s75, s75, 0x100
	s_addc_u32 s76, s76, 0
	s_cmp_gt_u32 s77, 29
	.p2align 6
.LBB0_1224:
	ds_read_b128 v[148:151], v143
	ds_read_b128 v[152:155], v143 offset:1024
	ds_read_b128 v[156:159], v143 offset:2048
	ds_read_b128 v[160:163], v143 offset:3072
	ds_read_b128 v[164:167], v144
	ds_read_b128 v[168:171], v144 offset:1024
	ds_read_b128 v[172:175], v144 offset:2048
	ds_read_b128 v[176:179], v144 offset:3072
	s_cmp_eq_u32 s77, 28
	s_cselect_b32 s21, s9, s74
	s_cselect_b32 s20, s67, s73
	s_cselect_b32 s23, s11, s76
	s_cselect_b32 s22, s66, s75
	ds_read_b128 v[180:183], v145
	ds_read_b128 v[184:187], v145 offset:1024
	ds_read_b128 v[188:191], v145 offset:2048
	ds_read_b128 v[192:195], v145 offset:3072
	ds_read_b128 v[196:199], v145 offset:4096
	ds_read_b128 v[200:203], v145 offset:5120
	ds_read_b128 v[204:207], v145 offset:6144
	ds_read_b128 v[208:211], v145 offset:7168
	s_add_u32 s78, s18, 0xfff80000
	s_addc_u32 s79, s19, -1
	s_mov_b32 s80, m0
	s_mov_b32 m0, s56
	s_nop 0
	global_load_lds_dwordx4 v138, s[78:79]
	s_mov_b32 m0, s80
	s_nop 0
	s_mov_b32 s80, m0
	s_mov_b32 m0, s59
	s_nop 0
	global_load_lds_dwordx4 v140, s[78:79]
	s_mov_b32 m0, s80
	s_mov_b32 s78, m0
	s_mov_b32 m0, s57
	s_nop 0
	global_load_lds_dwordx4 v138, s[18:19]
	s_mov_b32 m0, s78
	s_nop 0
	s_mov_b32 s78, m0
	s_mov_b32 m0, s64
	s_nop 0
	global_load_lds_dwordx4 v140, s[18:19]
	s_mov_b32 m0, s78
	s_waitcnt vmcnt(8)
	s_waitcnt lgkmcnt(0)
	s_barrier
	s_setprio 1
	s_waitcnt lgkmcnt(7)
	v_mfma_f32_16x16x32_bf16 v[126:129], v[148:151], v[180:183], v[126:129]
	v_mfma_f32_16x16x32_bf16 v[126:129], v[152:155], v[184:187], v[126:129]
	s_waitcnt lgkmcnt(5)
	v_mfma_f32_16x16x32_bf16 v[122:125], v[160:163], v[184:187], v[122:125]
	v_mfma_f32_16x16x32_bf16 v[122:125], v[156:159], v[180:183], v[122:125]
	s_waitcnt lgkmcnt(3)
	v_mfma_f32_16x16x32_bf16 v[106:109], v[156:159], v[188:191], v[106:109]
	v_mfma_f32_16x16x32_bf16 v[106:109], v[160:163], v[192:195], v[106:109]
	s_waitcnt lgkmcnt(1)
	v_mfma_f32_16x16x32_bf16 v[110:113], v[152:155], v[192:195], v[110:113]
	v_mfma_f32_16x16x32_bf16 v[110:113], v[148:151], v[188:191], v[110:113]
	v_mfma_f32_16x16x32_bf16 v[94:97], v[148:151], v[196:199], v[94:97]
	v_mfma_f32_16x16x32_bf16 v[94:97], v[152:155], v[200:203], v[94:97]
	v_mfma_f32_16x16x32_bf16 v[90:93], v[160:163], v[200:203], v[90:93]
	v_mfma_f32_16x16x32_bf16 v[90:93], v[156:159], v[196:199], v[90:93]
	v_mfma_f32_16x16x32_bf16 v[74:77], v[156:159], v[204:207], v[74:77]
	v_mfma_f32_16x16x32_bf16 v[74:77], v[160:163], v[208:211], v[74:77]
	s_waitcnt lgkmcnt(0)
	v_mfma_f32_16x16x32_bf16 v[78:81], v[152:155], v[208:211], v[78:81]
	v_mfma_f32_16x16x32_bf16 v[78:81], v[148:151], v[204:207], v[78:81]
	s_setprio 0
	s_setprio 1
	v_mfma_f32_16x16x32_bf16 v[118:121], v[164:167], v[180:183], v[118:121]
	v_mfma_f32_16x16x32_bf16 v[118:121], v[168:171], v[184:187], v[118:121]
	v_mfma_f32_16x16x32_bf16 v[114:117], v[176:179], v[184:187], v[114:117]
	v_mfma_f32_16x16x32_bf16 v[114:117], v[172:175], v[180:183], v[114:117]
	v_mfma_f32_16x16x32_bf16 v[98:101], v[172:175], v[188:191], v[98:101]
	v_mfma_f32_16x16x32_bf16 v[98:101], v[176:179], v[192:195], v[98:101]
	v_mfma_f32_16x16x32_bf16 v[102:105], v[168:171], v[192:195], v[102:105]
	v_mfma_f32_16x16x32_bf16 v[102:105], v[164:167], v[188:191], v[102:105]
	v_mfma_f32_16x16x32_bf16 v[86:89], v[164:167], v[196:199], v[86:89]
	v_mfma_f32_16x16x32_bf16 v[86:89], v[168:171], v[200:203], v[86:89]
	v_mfma_f32_16x16x32_bf16 v[82:85], v[176:179], v[200:203], v[82:85]
	v_mfma_f32_16x16x32_bf16 v[82:85], v[172:175], v[196:199], v[82:85]
	v_mfma_f32_16x16x32_bf16 v[66:69], v[172:175], v[204:207], v[66:69]
	v_mfma_f32_16x16x32_bf16 v[66:69], v[176:179], v[208:211], v[66:69]
	s_setprio 2
	s_barrier
	v_mfma_f32_16x16x32_bf16 v[70:73], v[168:171], v[208:211], v[70:73]
	v_mfma_f32_16x16x32_bf16 v[70:73], v[164:167], v[204:207], v[70:73]
	s_setprio 0
	ds_read_b128 v[180:183], v145 offset:16384
	ds_read_b128 v[184:187], v145 offset:17408
	ds_read_b128 v[188:191], v145 offset:18432
	ds_read_b128 v[192:195], v145 offset:19456
	ds_read_b128 v[196:199], v145 offset:20480
	ds_read_b128 v[200:203], v145 offset:21504
	ds_read_b128 v[204:207], v145 offset:22528
	ds_read_b128 v[208:211], v145 offset:23552
	s_mov_b32 s78, m0
	s_mov_b32 m0, s35
	s_nop 0
	global_load_lds_dwordx4 v139, s[20:21]
	s_mov_b32 m0, s78
	s_nop 0
	s_mov_b32 s78, m0
	s_mov_b32 m0, s36
	s_nop 0
	global_load_lds_dwordx4 v141, s[20:21]
	s_mov_b32 m0, s78
	s_add_u32 s78, s20, 0x80000
	s_addc_u32 s79, s21, 0
	s_mov_b32 s80, m0
	s_mov_b32 m0, s37
	s_nop 0
	global_load_lds_dwordx4 v139, s[78:79]
	s_mov_b32 m0, s80
	s_nop 0
	s_mov_b32 s80, m0
	s_mov_b32 m0, s40
	s_nop 0
	global_load_lds_dwordx4 v141, s[78:79]
	s_mov_b32 m0, s80
	s_waitcnt vmcnt(4)
	s_waitcnt lgkmcnt(0)
	s_barrier
	s_setprio 1
	s_waitcnt lgkmcnt(7)
	v_mfma_f32_16x16x32_bf16 v[62:65], v[148:151], v[180:183], v[62:65]
	v_mfma_f32_16x16x32_bf16 v[62:65], v[152:155], v[184:187], v[62:65]
	s_waitcnt lgkmcnt(5)
	v_mfma_f32_16x16x32_bf16 v[58:61], v[160:163], v[184:187], v[58:61]
	v_mfma_f32_16x16x32_bf16 v[58:61], v[156:159], v[180:183], v[58:61]
	s_waitcnt lgkmcnt(3)
	v_mfma_f32_16x16x32_bf16 v[42:45], v[156:159], v[188:191], v[42:45]
	v_mfma_f32_16x16x32_bf16 v[42:45], v[160:163], v[192:195], v[42:45]
	s_waitcnt lgkmcnt(1)
	v_mfma_f32_16x16x32_bf16 v[46:49], v[152:155], v[192:195], v[46:49]
	v_mfma_f32_16x16x32_bf16 v[46:49], v[148:151], v[188:191], v[46:49]
	v_mfma_f32_16x16x32_bf16 v[30:33], v[148:151], v[196:199], v[30:33]
	v_mfma_f32_16x16x32_bf16 v[30:33], v[152:155], v[200:203], v[30:33]
	v_mfma_f32_16x16x32_bf16 v[26:29], v[160:163], v[200:203], v[26:29]
	v_mfma_f32_16x16x32_bf16 v[26:29], v[156:159], v[196:199], v[26:29]
	v_mfma_f32_16x16x32_bf16 v[10:13], v[156:159], v[204:207], v[10:13]
	v_mfma_f32_16x16x32_bf16 v[10:13], v[160:163], v[208:211], v[10:13]
	s_waitcnt lgkmcnt(0)
	v_mfma_f32_16x16x32_bf16 v[14:17], v[152:155], v[208:211], v[14:17]
	v_mfma_f32_16x16x32_bf16 v[14:17], v[148:151], v[204:207], v[14:17]
	s_setprio 0
	s_setprio 1
	v_mfma_f32_16x16x32_bf16 v[54:57], v[164:167], v[180:183], v[54:57]
	v_mfma_f32_16x16x32_bf16 v[54:57], v[168:171], v[184:187], v[54:57]
	v_mfma_f32_16x16x32_bf16 v[50:53], v[176:179], v[184:187], v[50:53]
	v_mfma_f32_16x16x32_bf16 v[50:53], v[172:175], v[180:183], v[50:53]
	v_mfma_f32_16x16x32_bf16 v[34:37], v[172:175], v[188:191], v[34:37]
	v_mfma_f32_16x16x32_bf16 v[34:37], v[176:179], v[192:195], v[34:37]
	v_mfma_f32_16x16x32_bf16 v[38:41], v[168:171], v[192:195], v[38:41]
	v_mfma_f32_16x16x32_bf16 v[38:41], v[164:167], v[188:191], v[38:41]
	v_mfma_f32_16x16x32_bf16 v[22:25], v[164:167], v[196:199], v[22:25]
	v_mfma_f32_16x16x32_bf16 v[22:25], v[168:171], v[200:203], v[22:25]
	v_mfma_f32_16x16x32_bf16 v[18:21], v[176:179], v[200:203], v[18:21]
	v_mfma_f32_16x16x32_bf16 v[18:21], v[172:175], v[196:199], v[18:21]
	v_mfma_f32_16x16x32_bf16 v[2:5], v[172:175], v[204:207], v[2:5]
	v_mfma_f32_16x16x32_bf16 v[2:5], v[176:179], v[208:211], v[2:5]
	s_setprio 2
	s_barrier
	v_mfma_f32_16x16x32_bf16 v[6:9], v[168:171], v[208:211], v[6:9]
	v_mfma_f32_16x16x32_bf16 v[6:9], v[164:167], v[204:207], v[6:9]
	s_setprio 0
	ds_read_b128 v[148:151], v146
	ds_read_b128 v[152:155], v146 offset:1024
	ds_read_b128 v[156:159], v146 offset:2048
	ds_read_b128 v[160:163], v146 offset:3072
	ds_read_b128 v[164:167], v147
	ds_read_b128 v[168:171], v147 offset:1024
	ds_read_b128 v[172:175], v147 offset:2048
	ds_read_b128 v[176:179], v147 offset:3072
	ds_read_b128 v[180:183], v145 offset:32768
	ds_read_b128 v[184:187], v145 offset:33792
	ds_read_b128 v[188:191], v145 offset:34816
	ds_read_b128 v[192:195], v145 offset:35840
	ds_read_b128 v[196:199], v145 offset:36864
	ds_read_b128 v[200:203], v145 offset:37888
	ds_read_b128 v[204:207], v145 offset:38912
	ds_read_b128 v[208:211], v145 offset:39936
	s_mov_b32 s78, m0
	s_mov_b32 m0, s31
	s_nop 0
	global_load_lds_dwordx4 v138, s[22:23]
	s_mov_b32 m0, s78
	s_nop 0
	s_mov_b32 s78, m0
	s_mov_b32 m0, s41
	s_nop 0
	global_load_lds_dwordx4 v140, s[22:23]
	s_mov_b32 m0, s78
	s_add_u32 s22, s22, 0x80000
	s_addc_u32 s23, s23, 0
	s_mov_b32 s78, m0
	s_mov_b32 m0, s42
	s_nop 0
	global_load_lds_dwordx4 v138, s[22:23]
	s_mov_b32 m0, s78
	s_nop 0
	s_mov_b32 s78, m0
	s_mov_b32 m0, s43
	s_nop 0
	global_load_lds_dwordx4 v140, s[22:23]
	s_mov_b32 m0, s78
	s_waitcnt vmcnt(8)
	s_waitcnt lgkmcnt(0)
	s_barrier
	s_setprio 1
	s_waitcnt lgkmcnt(7)
	v_mfma_f32_16x16x32_bf16 v[126:129], v[148:151], v[180:183], v[126:129]
	v_mfma_f32_16x16x32_bf16 v[126:129], v[152:155], v[184:187], v[126:129]
	s_waitcnt lgkmcnt(5)
	v_mfma_f32_16x16x32_bf16 v[122:125], v[160:163], v[184:187], v[122:125]
	v_mfma_f32_16x16x32_bf16 v[122:125], v[156:159], v[180:183], v[122:125]
	s_waitcnt lgkmcnt(3)
	v_mfma_f32_16x16x32_bf16 v[106:109], v[156:159], v[188:191], v[106:109]
	v_mfma_f32_16x16x32_bf16 v[106:109], v[160:163], v[192:195], v[106:109]
	s_waitcnt lgkmcnt(1)
	v_mfma_f32_16x16x32_bf16 v[110:113], v[152:155], v[192:195], v[110:113]
	v_mfma_f32_16x16x32_bf16 v[110:113], v[148:151], v[188:191], v[110:113]
	v_mfma_f32_16x16x32_bf16 v[94:97], v[148:151], v[196:199], v[94:97]
	v_mfma_f32_16x16x32_bf16 v[94:97], v[152:155], v[200:203], v[94:97]
	v_mfma_f32_16x16x32_bf16 v[90:93], v[160:163], v[200:203], v[90:93]
	v_mfma_f32_16x16x32_bf16 v[90:93], v[156:159], v[196:199], v[90:93]
	v_mfma_f32_16x16x32_bf16 v[74:77], v[156:159], v[204:207], v[74:77]
	v_mfma_f32_16x16x32_bf16 v[74:77], v[160:163], v[208:211], v[74:77]
	s_waitcnt lgkmcnt(0)
	v_mfma_f32_16x16x32_bf16 v[78:81], v[152:155], v[208:211], v[78:81]
	v_mfma_f32_16x16x32_bf16 v[78:81], v[148:151], v[204:207], v[78:81]
	s_setprio 0
	s_setprio 1
	v_mfma_f32_16x16x32_bf16 v[118:121], v[164:167], v[180:183], v[118:121]
	v_mfma_f32_16x16x32_bf16 v[118:121], v[168:171], v[184:187], v[118:121]
	v_mfma_f32_16x16x32_bf16 v[114:117], v[176:179], v[184:187], v[114:117]
	v_mfma_f32_16x16x32_bf16 v[114:117], v[172:175], v[180:183], v[114:117]
	v_mfma_f32_16x16x32_bf16 v[98:101], v[172:175], v[188:191], v[98:101]
	v_mfma_f32_16x16x32_bf16 v[98:101], v[176:179], v[192:195], v[98:101]
	v_mfma_f32_16x16x32_bf16 v[102:105], v[168:171], v[192:195], v[102:105]
	v_mfma_f32_16x16x32_bf16 v[102:105], v[164:167], v[188:191], v[102:105]
	v_mfma_f32_16x16x32_bf16 v[86:89], v[164:167], v[196:199], v[86:89]
	v_mfma_f32_16x16x32_bf16 v[86:89], v[168:171], v[200:203], v[86:89]
	v_mfma_f32_16x16x32_bf16 v[82:85], v[176:179], v[200:203], v[82:85]
	v_mfma_f32_16x16x32_bf16 v[82:85], v[172:175], v[196:199], v[82:85]
	v_mfma_f32_16x16x32_bf16 v[66:69], v[172:175], v[204:207], v[66:69]
	v_mfma_f32_16x16x32_bf16 v[66:69], v[176:179], v[208:211], v[66:69]
	s_setprio 2
	s_barrier
	v_mfma_f32_16x16x32_bf16 v[70:73], v[168:171], v[208:211], v[70:73]
	v_mfma_f32_16x16x32_bf16 v[70:73], v[164:167], v[204:207], v[70:73]
	s_setprio 0
	ds_read_b128 v[180:183], v145 offset:49152
	ds_read_b128 v[184:187], v145 offset:50176
	ds_read_b128 v[188:191], v145 offset:51200
	ds_read_b128 v[192:195], v145 offset:52224
	ds_read_b128 v[196:199], v145 offset:53248
	ds_read_b128 v[200:203], v145 offset:54272
	ds_read_b128 v[204:207], v145 offset:55296
	ds_read_b128 v[208:211], v145 offset:56320
	s_add_u32 s22, s20, 0x80
	s_addc_u32 s23, s21, 0
	s_mov_b32 s78, m0
	s_mov_b32 m0, s46
	s_nop 0
	global_load_lds_dwordx4 v139, s[22:23]
	s_mov_b32 m0, s78
	s_add_u32 s20, s20, 0x80080
	s_mov_b32 s78, m0
	s_mov_b32 m0, s47
	s_nop 0
	global_load_lds_dwordx4 v141, s[22:23]
	s_mov_b32 m0, s78
	s_addc_u32 s21, s21, 0
	s_mov_b32 s22, m0
	s_mov_b32 m0, s48
	s_nop 0
	global_load_lds_dwordx4 v139, s[20:21]
	s_mov_b32 m0, s22
	s_nop 0
	s_mov_b32 s22, m0
	s_mov_b32 m0, s49
	s_nop 0
	global_load_lds_dwordx4 v141, s[20:21]
	s_mov_b32 m0, s22
	s_waitcnt vmcnt(4)
	s_waitcnt lgkmcnt(0)
	s_barrier
	s_setprio 1
	s_waitcnt lgkmcnt(7)
	v_mfma_f32_16x16x32_bf16 v[62:65], v[148:151], v[180:183], v[62:65]
	v_mfma_f32_16x16x32_bf16 v[62:65], v[152:155], v[184:187], v[62:65]
	s_waitcnt lgkmcnt(5)
	v_mfma_f32_16x16x32_bf16 v[58:61], v[160:163], v[184:187], v[58:61]
	v_mfma_f32_16x16x32_bf16 v[58:61], v[156:159], v[180:183], v[58:61]
	s_waitcnt lgkmcnt(3)
	v_mfma_f32_16x16x32_bf16 v[42:45], v[156:159], v[188:191], v[42:45]
	v_mfma_f32_16x16x32_bf16 v[42:45], v[160:163], v[192:195], v[42:45]
	s_waitcnt lgkmcnt(1)
	v_mfma_f32_16x16x32_bf16 v[46:49], v[152:155], v[192:195], v[46:49]
	v_mfma_f32_16x16x32_bf16 v[46:49], v[148:151], v[188:191], v[46:49]
	v_mfma_f32_16x16x32_bf16 v[30:33], v[148:151], v[196:199], v[30:33]
	v_mfma_f32_16x16x32_bf16 v[30:33], v[152:155], v[200:203], v[30:33]
	v_mfma_f32_16x16x32_bf16 v[26:29], v[160:163], v[200:203], v[26:29]
	v_mfma_f32_16x16x32_bf16 v[26:29], v[156:159], v[196:199], v[26:29]
	v_mfma_f32_16x16x32_bf16 v[10:13], v[156:159], v[204:207], v[10:13]
	v_mfma_f32_16x16x32_bf16 v[10:13], v[160:163], v[208:211], v[10:13]
	s_waitcnt lgkmcnt(0)
	v_mfma_f32_16x16x32_bf16 v[14:17], v[152:155], v[208:211], v[14:17]
	v_mfma_f32_16x16x32_bf16 v[14:17], v[148:151], v[204:207], v[14:17]
	s_setprio 0
	s_setprio 1
	v_mfma_f32_16x16x32_bf16 v[54:57], v[164:167], v[180:183], v[54:57]
	v_mfma_f32_16x16x32_bf16 v[54:57], v[168:171], v[184:187], v[54:57]
	v_mfma_f32_16x16x32_bf16 v[50:53], v[176:179], v[184:187], v[50:53]
	v_mfma_f32_16x16x32_bf16 v[50:53], v[172:175], v[180:183], v[50:53]
	v_mfma_f32_16x16x32_bf16 v[34:37], v[172:175], v[188:191], v[34:37]
	v_mfma_f32_16x16x32_bf16 v[34:37], v[176:179], v[192:195], v[34:37]
	v_mfma_f32_16x16x32_bf16 v[38:41], v[168:171], v[192:195], v[38:41]
	v_mfma_f32_16x16x32_bf16 v[38:41], v[164:167], v[188:191], v[38:41]
	v_mfma_f32_16x16x32_bf16 v[22:25], v[164:167], v[196:199], v[22:25]
	v_mfma_f32_16x16x32_bf16 v[22:25], v[168:171], v[200:203], v[22:25]
	v_mfma_f32_16x16x32_bf16 v[18:21], v[176:179], v[200:203], v[18:21]
	v_mfma_f32_16x16x32_bf16 v[18:21], v[172:175], v[196:199], v[18:21]
	v_mfma_f32_16x16x32_bf16 v[2:5], v[172:175], v[204:207], v[2:5]
	v_mfma_f32_16x16x32_bf16 v[2:5], v[176:179], v[208:211], v[2:5]
	s_setprio 2
	s_barrier
	v_mfma_f32_16x16x32_bf16 v[6:9], v[168:171], v[208:211], v[6:9]
	v_mfma_f32_16x16x32_bf16 v[6:9], v[164:167], v[204:207], v[6:9]
	s_setprio 0
	s_add_i32 s77, s77, 2
	s_add_u32 s73, s73, 0x100
	s_addc_u32 s74, s74, 0
	s_add_u32 s18, s18, 0x100
	s_addc_u32 s19, s19, 0
	s_add_u32 s75, s75, 0x100
	s_addc_u32 s76, s76, 0
	s_cmp_gt_u32 s77, 29
	s_cbranch_scc0 .LBB0_1224
	s_and_b64 vcc, exec, s[6:7]
	s_cbranch_vccz .LBB0_1227
	s_barrier

.LBB0_1356:
	s_ashr_i32 s13, s12, 31
	s_lshl_b64 s[14:15], s[12:13], 15
	s_add_u32 s14, s28, s14
	s_addc_u32 s15, s29, s15
	s_and_b64 s[16:17], s[2:3], exec
	s_cselect_b32 s13, s15, s23
	s_cselect_b32 s67, s14, s22
	s_ashr_i32 s11, s10, 31
	s_lshl_b64 s[16:17], s[10:11], 15
	s_add_u32 s16, s30, s16
	s_addc_u32 s17, s31, s17
	s_and_b64 s[24:25], s[2:3], exec
	s_cselect_b32 s11, s17, s21
	s_cselect_b32 s73, s16, s20
	s_add_u32 s74, s20, 0x80000
	s_addc_u32 s75, s21, 0
	s_add_u32 s20, s22, 0x204000
	s_addc_u32 s21, s23, 0
	s_add_u32 s76, s22, 0x400000
	s_addc_u32 s77, s23, 0
	s_mov_b32 s78, -2
	s_waitcnt vmcnt(25)
	s_waitcnt vmcnt(24)
	s_waitcnt vmcnt(15)
	s_waitcnt vmcnt(14)
	s_waitcnt vmcnt(13)
	s_waitcnt vmcnt(12)
	s_waitcnt vmcnt(11)
	s_waitcnt vmcnt(10)
	s_waitcnt vmcnt(9)
	s_waitcnt vmcnt(8)
	s_waitcnt vmcnt(7)
	s_waitcnt vmcnt(6)
	s_waitcnt vmcnt(5)
	s_waitcnt vmcnt(4)
	s_waitcnt vmcnt(3)
	s_waitcnt vmcnt(2)
	s_waitcnt vmcnt(1)
	s_waitcnt vmcnt(0)
	ds_read_b128 v[130:133], v181
	ds_read_b128 v[134:137], v181 offset:1024
	ds_read_b128 v[138:141], v181 offset:2048
	ds_read_b128 v[142:145], v181 offset:3072
	ds_read_b128 v[150:153], v182
	ds_read_b128 v[154:157], v182 offset:1024
	ds_read_b128 v[158:161], v182 offset:2048
	ds_read_b128 v[162:165], v182 offset:3072
	s_cmpk_eq_i32 s78, 0x52
	s_cselect_b32 s23, s11, s75
	s_cselect_b32 s22, s73, s74
	s_cselect_b32 s25, s13, s77
	s_cselect_b32 s24, s67, s76
	ds_read_b128 v[166:169], v183
	ds_read_b128 v[170:173], v183 offset:1024
	ds_read_b128 v[186:189], v183 offset:2048
	ds_read_b128 v[190:193], v183 offset:3072
	ds_read_b128 v[194:197], v183 offset:4096
	ds_read_b128 v[198:201], v183 offset:5120
	ds_read_b128 v[202:205], v183 offset:6144
	ds_read_b128 v[206:209], v183 offset:7168
	s_add_u32 s80, s20, 0xffffc000
	s_addc_u32 s81, s21, -1
	s_mov_b32 s79, m0
	s_mov_b32 m0, s58
	s_nop 0
	global_load_lds_dwordx4 v1, s[80:81]
	s_mov_b32 m0, s79
	s_nop 0
	s_mov_b32 s79, m0
	s_mov_b32 m0, s64
	s_nop 0
	global_load_lds_dwordx4 v177, s[80:81]
	s_mov_b32 m0, s79
	s_nop 0
	s_mov_b32 s79, m0
	s_mov_b32 m0, s59
	s_nop 0
	global_load_lds_dwordx4 v1, s[20:21]
	s_mov_b32 m0, s79
	s_nop 0
	s_mov_b32 s79, m0
	s_mov_b32 m0, s65
	s_nop 0
	global_load_lds_dwordx4 v177, s[20:21]
	s_mov_b32 m0, s79
	s_waitcnt vmcnt(8)
	s_waitcnt lgkmcnt(0)
	s_barrier
	s_setprio 1
	s_waitcnt lgkmcnt(7)
	v_mfma_f32_16x16x32_bf16 v[126:129], v[130:133], v[166:169], 0
	v_mfma_f32_16x16x32_bf16 v[126:129], v[134:137], v[170:173], v[126:129]
	s_waitcnt lgkmcnt(5)
	v_mfma_f32_16x16x32_bf16 v[122:125], v[142:145], v[170:173], 0
	v_mfma_f32_16x16x32_bf16 v[122:125], v[138:141], v[166:169], v[122:125]
	s_waitcnt lgkmcnt(3)
	v_mfma_f32_16x16x32_bf16 v[110:113], v[138:141], v[186:189], 0
	v_mfma_f32_16x16x32_bf16 v[110:113], v[142:145], v[190:193], v[110:113]
	s_waitcnt lgkmcnt(1)
	v_mfma_f32_16x16x32_bf16 v[118:121], v[134:137], v[190:193], 0
	v_mfma_f32_16x16x32_bf16 v[118:121], v[130:133], v[186:189], v[118:121]
	v_mfma_f32_16x16x32_bf16 v[94:97], v[130:133], v[194:197], 0
	v_mfma_f32_16x16x32_bf16 v[94:97], v[134:137], v[198:201], v[94:97]
	v_mfma_f32_16x16x32_bf16 v[90:93], v[142:145], v[198:201], 0
	v_mfma_f32_16x16x32_bf16 v[90:93], v[138:141], v[194:197], v[90:93]
	v_mfma_f32_16x16x32_bf16 v[78:81], v[138:141], v[202:205], 0
	v_mfma_f32_16x16x32_bf16 v[78:81], v[142:145], v[206:209], v[78:81]
	s_waitcnt lgkmcnt(0)
	v_mfma_f32_16x16x32_bf16 v[86:89], v[134:137], v[206:209], 0
	v_mfma_f32_16x16x32_bf16 v[86:89], v[130:133], v[202:205], v[86:89]
	s_setprio 0
	s_setprio 1
	v_mfma_f32_16x16x32_bf16 v[114:117], v[150:153], v[166:169], 0
	v_mfma_f32_16x16x32_bf16 v[114:117], v[154:157], v[170:173], v[114:117]
	v_mfma_f32_16x16x32_bf16 v[106:109], v[162:165], v[170:173], 0
	v_mfma_f32_16x16x32_bf16 v[106:109], v[158:161], v[166:169], v[106:109]
	v_mfma_f32_16x16x32_bf16 v[98:101], v[158:161], v[186:189], 0
	v_mfma_f32_16x16x32_bf16 v[98:101], v[162:165], v[190:193], v[98:101]
	v_mfma_f32_16x16x32_bf16 v[102:105], v[154:157], v[190:193], 0
	v_mfma_f32_16x16x32_bf16 v[102:105], v[150:153], v[186:189], v[102:105]
	v_mfma_f32_16x16x32_bf16 v[82:85], v[150:153], v[194:197], 0
	v_mfma_f32_16x16x32_bf16 v[82:85], v[154:157], v[198:201], v[82:85]
	v_mfma_f32_16x16x32_bf16 v[74:77], v[162:165], v[198:201], 0
	v_mfma_f32_16x16x32_bf16 v[74:77], v[158:161], v[194:197], v[74:77]
	v_mfma_f32_16x16x32_bf16 v[66:69], v[158:161], v[202:205], 0
	v_mfma_f32_16x16x32_bf16 v[66:69], v[162:165], v[206:209], v[66:69]
	s_setprio 2
	s_barrier
	v_mfma_f32_16x16x32_bf16 v[70:73], v[154:157], v[206:209], 0
	v_mfma_f32_16x16x32_bf16 v[70:73], v[150:153], v[202:205], v[70:73]
	s_setprio 0
	ds_read_b128 v[166:169], v183 offset:16384
	ds_read_b128 v[170:173], v183 offset:17408
	ds_read_b128 v[186:189], v183 offset:18432
	ds_read_b128 v[190:193], v183 offset:19456
	ds_read_b128 v[194:197], v183 offset:20480
	ds_read_b128 v[198:201], v183 offset:21504
	ds_read_b128 v[202:205], v183 offset:22528
	ds_read_b128 v[206:209], v183 offset:23552
	s_mov_b32 s79, m0
	s_mov_b32 m0, s35
	s_nop 0
	global_load_lds_dwordx4 v176, s[22:23]
	s_mov_b32 m0, s79
	s_add_u32 s80, s22, 0x4000
	s_mov_b32 s79, m0
	s_mov_b32 m0, s36
	s_nop 0
	global_load_lds_dwordx4 v178, s[22:23]
	s_mov_b32 m0, s79
	s_addc_u32 s81, s23, 0
	s_mov_b32 s79, m0
	s_mov_b32 m0, s37
	s_nop 0
	global_load_lds_dwordx4 v176, s[80:81]
	s_mov_b32 m0, s79
	s_nop 0
	s_mov_b32 s79, m0
	s_mov_b32 m0, s40
	s_nop 0
	global_load_lds_dwordx4 v178, s[80:81]
	s_mov_b32 m0, s79
	s_waitcnt vmcnt(4)
	s_waitcnt lgkmcnt(0)
	s_barrier
	s_setprio 1
	s_waitcnt lgkmcnt(7)
	v_mfma_f32_16x16x32_bf16 v[62:65], v[130:133], v[166:169], 0
	v_mfma_f32_16x16x32_bf16 v[62:65], v[134:137], v[170:173], v[62:65]
	s_waitcnt lgkmcnt(5)
	v_mfma_f32_16x16x32_bf16 v[58:61], v[142:145], v[170:173], 0
	v_mfma_f32_16x16x32_bf16 v[58:61], v[138:141], v[166:169], v[58:61]
	s_waitcnt lgkmcnt(3)
	v_mfma_f32_16x16x32_bf16 v[42:45], v[138:141], v[186:189], 0
	v_mfma_f32_16x16x32_bf16 v[42:45], v[142:145], v[190:193], v[42:45]
	s_waitcnt lgkmcnt(1)
	v_mfma_f32_16x16x32_bf16 v[46:49], v[134:137], v[190:193], 0
	v_mfma_f32_16x16x32_bf16 v[46:49], v[130:133], v[186:189], v[46:49]
	v_mfma_f32_16x16x32_bf16 v[30:33], v[130:133], v[194:197], 0
	v_mfma_f32_16x16x32_bf16 v[30:33], v[134:137], v[198:201], v[30:33]
	v_mfma_f32_16x16x32_bf16 v[26:29], v[142:145], v[198:201], 0
	v_mfma_f32_16x16x32_bf16 v[26:29], v[138:141], v[194:197], v[26:29]
	v_mfma_f32_16x16x32_bf16 v[10:13], v[138:141], v[202:205], 0
	v_mfma_f32_16x16x32_bf16 v[10:13], v[142:145], v[206:209], v[10:13]
	s_waitcnt lgkmcnt(0)
	v_mfma_f32_16x16x32_bf16 v[14:17], v[134:137], v[206:209], 0
	v_mfma_f32_16x16x32_bf16 v[14:17], v[130:133], v[202:205], v[14:17]
	s_setprio 0
	s_setprio 1
	v_mfma_f32_16x16x32_bf16 v[54:57], v[150:153], v[166:169], 0
	v_mfma_f32_16x16x32_bf16 v[54:57], v[154:157], v[170:173], v[54:57]
	v_mfma_f32_16x16x32_bf16 v[50:53], v[162:165], v[170:173], 0
	v_mfma_f32_16x16x32_bf16 v[50:53], v[158:161], v[166:169], v[50:53]
	v_mfma_f32_16x16x32_bf16 v[34:37], v[158:161], v[186:189], 0
	v_mfma_f32_16x16x32_bf16 v[34:37], v[162:165], v[190:193], v[34:37]
	v_mfma_f32_16x16x32_bf16 v[38:41], v[154:157], v[190:193], 0
	v_mfma_f32_16x16x32_bf16 v[38:41], v[150:153], v[186:189], v[38:41]
	v_mfma_f32_16x16x32_bf16 v[22:25], v[150:153], v[194:197], 0
	v_mfma_f32_16x16x32_bf16 v[22:25], v[154:157], v[198:201], v[22:25]
	v_mfma_f32_16x16x32_bf16 v[18:21], v[162:165], v[198:201], 0
	v_mfma_f32_16x16x32_bf16 v[18:21], v[158:161], v[194:197], v[18:21]
	v_mfma_f32_16x16x32_bf16 v[2:5], v[158:161], v[202:205], 0
	v_mfma_f32_16x16x32_bf16 v[2:5], v[162:165], v[206:209], v[2:5]
	s_setprio 2
	s_barrier
	v_mfma_f32_16x16x32_bf16 v[6:9], v[154:157], v[206:209], 0
	v_mfma_f32_16x16x32_bf16 v[6:9], v[150:153], v[202:205], v[6:9]
	s_setprio 0
	ds_read_b128 v[130:133], v184
	ds_read_b128 v[134:137], v184 offset:1024
	ds_read_b128 v[138:141], v184 offset:2048
	ds_read_b128 v[142:145], v184 offset:3072
	ds_read_b128 v[150:153], v185
	ds_read_b128 v[154:157], v185 offset:1024
	ds_read_b128 v[158:161], v185 offset:2048
	ds_read_b128 v[162:165], v185 offset:3072
	ds_read_b128 v[166:169], v183 offset:32768
	ds_read_b128 v[170:173], v183 offset:33792
	ds_read_b128 v[186:189], v183 offset:34816
	ds_read_b128 v[190:193], v183 offset:35840
	ds_read_b128 v[194:197], v183 offset:36864
	ds_read_b128 v[198:201], v183 offset:37888
	ds_read_b128 v[202:205], v183 offset:38912
	ds_read_b128 v[206:209], v183 offset:39936
	s_mov_b32 s79, m0
	s_mov_b32 m0, s34
	s_nop 0
	global_load_lds_dwordx4 v1, s[24:25]
	s_mov_b32 m0, s79
	s_nop 0
	s_mov_b32 s79, m0
	s_mov_b32 m0, s41
	s_nop 0
	global_load_lds_dwordx4 v177, s[24:25]
	s_mov_b32 m0, s79
	s_add_u32 s24, s24, 0x4000
	s_addc_u32 s25, s25, 0
	s_mov_b32 s79, m0
	s_mov_b32 m0, s42
	s_nop 0
	global_load_lds_dwordx4 v1, s[24:25]
	s_mov_b32 m0, s79
	s_nop 0
	s_mov_b32 s79, m0
	s_mov_b32 m0, s43
	s_nop 0
	global_load_lds_dwordx4 v177, s[24:25]
	s_mov_b32 m0, s79
	s_waitcnt vmcnt(8)
	s_waitcnt lgkmcnt(0)
	s_barrier
	s_setprio 1
	s_waitcnt lgkmcnt(7)
	v_mfma_f32_16x16x32_bf16 v[126:129], v[130:133], v[166:169], v[126:129]
	v_mfma_f32_16x16x32_bf16 v[126:129], v[134:137], v[170:173], v[126:129]
	s_waitcnt lgkmcnt(5)
	v_mfma_f32_16x16x32_bf16 v[122:125], v[142:145], v[170:173], v[122:125]
	v_mfma_f32_16x16x32_bf16 v[122:125], v[138:141], v[166:169], v[122:125]
	s_waitcnt lgkmcnt(3)
	v_mfma_f32_16x16x32_bf16 v[110:113], v[138:141], v[186:189], v[110:113]
	v_mfma_f32_16x16x32_bf16 v[110:113], v[142:145], v[190:193], v[110:113]
	s_waitcnt lgkmcnt(1)
	v_mfma_f32_16x16x32_bf16 v[118:121], v[134:137], v[190:193], v[118:121]
	v_mfma_f32_16x16x32_bf16 v[118:121], v[130:133], v[186:189], v[118:121]
	v_mfma_f32_16x16x32_bf16 v[94:97], v[130:133], v[194:197], v[94:97]
	v_mfma_f32_16x16x32_bf16 v[94:97], v[134:137], v[198:201], v[94:97]
	v_mfma_f32_16x16x32_bf16 v[90:93], v[142:145], v[198:201], v[90:93]
	v_mfma_f32_16x16x32_bf16 v[90:93], v[138:141], v[194:197], v[90:93]
	v_mfma_f32_16x16x32_bf16 v[78:81], v[138:141], v[202:205], v[78:81]
	v_mfma_f32_16x16x32_bf16 v[78:81], v[142:145], v[206:209], v[78:81]
	s_waitcnt lgkmcnt(0)
	v_mfma_f32_16x16x32_bf16 v[86:89], v[134:137], v[206:209], v[86:89]
	v_mfma_f32_16x16x32_bf16 v[86:89], v[130:133], v[202:205], v[86:89]
	s_setprio 0
	s_setprio 1
	v_mfma_f32_16x16x32_bf16 v[114:117], v[150:153], v[166:169], v[114:117]
	v_mfma_f32_16x16x32_bf16 v[114:117], v[154:157], v[170:173], v[114:117]
	v_mfma_f32_16x16x32_bf16 v[106:109], v[162:165], v[170:173], v[106:109]
	v_mfma_f32_16x16x32_bf16 v[106:109], v[158:161], v[166:169], v[106:109]
	v_mfma_f32_16x16x32_bf16 v[98:101], v[158:161], v[186:189], v[98:101]
	v_mfma_f32_16x16x32_bf16 v[98:101], v[162:165], v[190:193], v[98:101]
	v_mfma_f32_16x16x32_bf16 v[102:105], v[154:157], v[190:193], v[102:105]
	v_mfma_f32_16x16x32_bf16 v[102:105], v[150:153], v[186:189], v[102:105]
	v_mfma_f32_16x16x32_bf16 v[82:85], v[150:153], v[194:197], v[82:85]
	v_mfma_f32_16x16x32_bf16 v[82:85], v[154:157], v[198:201], v[82:85]
	v_mfma_f32_16x16x32_bf16 v[74:77], v[162:165], v[198:201], v[74:77]
	v_mfma_f32_16x16x32_bf16 v[74:77], v[158:161], v[194:197], v[74:77]
	v_mfma_f32_16x16x32_bf16 v[66:69], v[158:161], v[202:205], v[66:69]
	v_mfma_f32_16x16x32_bf16 v[66:69], v[162:165], v[206:209], v[66:69]
	s_setprio 2
	s_barrier
	v_mfma_f32_16x16x32_bf16 v[70:73], v[154:157], v[206:209], v[70:73]
	v_mfma_f32_16x16x32_bf16 v[70:73], v[150:153], v[202:205], v[70:73]
	s_setprio 0
	ds_read_b128 v[166:169], v183 offset:49152
	ds_read_b128 v[170:173], v183 offset:50176
	ds_read_b128 v[186:189], v183 offset:51200
	ds_read_b128 v[190:193], v183 offset:52224
	ds_read_b128 v[194:197], v183 offset:53248
	ds_read_b128 v[198:201], v183 offset:54272
	ds_read_b128 v[202:205], v183 offset:55296
	ds_read_b128 v[206:209], v183 offset:56320
	s_add_u32 s24, s22, 0x40000
	s_addc_u32 s25, s23, 0
	s_mov_b32 s79, m0
	s_mov_b32 m0, s46
	s_nop 0
	global_load_lds_dwordx4 v176, s[24:25]
	s_mov_b32 m0, s79
	s_add_u32 s22, s22, 0x44000
	s_mov_b32 s79, m0
	s_mov_b32 m0, s47
	s_nop 0
	global_load_lds_dwordx4 v178, s[24:25]
	s_mov_b32 m0, s79
	s_addc_u32 s23, s23, 0
	s_mov_b32 s24, m0
	s_mov_b32 m0, s48
	s_nop 0
	global_load_lds_dwordx4 v176, s[22:23]
	s_mov_b32 m0, s24
	s_nop 0
	s_mov_b32 s24, m0
	s_mov_b32 m0, s49
	s_nop 0
	global_load_lds_dwordx4 v178, s[22:23]
	s_mov_b32 m0, s24
	s_waitcnt vmcnt(4)
	s_waitcnt lgkmcnt(0)
	s_barrier
	s_setprio 1
	s_waitcnt lgkmcnt(7)
	v_mfma_f32_16x16x32_bf16 v[62:65], v[130:133], v[166:169], v[62:65]
	v_mfma_f32_16x16x32_bf16 v[62:65], v[134:137], v[170:173], v[62:65]
	s_waitcnt lgkmcnt(5)
	v_mfma_f32_16x16x32_bf16 v[58:61], v[142:145], v[170:173], v[58:61]
	v_mfma_f32_16x16x32_bf16 v[58:61], v[138:141], v[166:169], v[58:61]
	s_waitcnt lgkmcnt(3)
	v_mfma_f32_16x16x32_bf16 v[42:45], v[138:141], v[186:189], v[42:45]
	v_mfma_f32_16x16x32_bf16 v[42:45], v[142:145], v[190:193], v[42:45]
	s_waitcnt lgkmcnt(1)
	v_mfma_f32_16x16x32_bf16 v[46:49], v[134:137], v[190:193], v[46:49]
	v_mfma_f32_16x16x32_bf16 v[46:49], v[130:133], v[186:189], v[46:49]
	v_mfma_f32_16x16x32_bf16 v[30:33], v[130:133], v[194:197], v[30:33]
	v_mfma_f32_16x16x32_bf16 v[30:33], v[134:137], v[198:201], v[30:33]
	v_mfma_f32_16x16x32_bf16 v[26:29], v[142:145], v[198:201], v[26:29]
	v_mfma_f32_16x16x32_bf16 v[26:29], v[138:141], v[194:197], v[26:29]
	v_mfma_f32_16x16x32_bf16 v[10:13], v[138:141], v[202:205], v[10:13]
	v_mfma_f32_16x16x32_bf16 v[10:13], v[142:145], v[206:209], v[10:13]
	s_waitcnt lgkmcnt(0)
	v_mfma_f32_16x16x32_bf16 v[14:17], v[134:137], v[206:209], v[14:17]
	v_mfma_f32_16x16x32_bf16 v[14:17], v[130:133], v[202:205], v[14:17]
	s_setprio 0
	s_setprio 1
	v_mfma_f32_16x16x32_bf16 v[54:57], v[150:153], v[166:169], v[54:57]
	v_mfma_f32_16x16x32_bf16 v[54:57], v[154:157], v[170:173], v[54:57]
	v_mfma_f32_16x16x32_bf16 v[50:53], v[162:165], v[170:173], v[50:53]
	v_mfma_f32_16x16x32_bf16 v[50:53], v[158:161], v[166:169], v[50:53]
	v_mfma_f32_16x16x32_bf16 v[34:37], v[158:161], v[186:189], v[34:37]
	v_mfma_f32_16x16x32_bf16 v[34:37], v[162:165], v[190:193], v[34:37]
	v_mfma_f32_16x16x32_bf16 v[38:41], v[154:157], v[190:193], v[38:41]
	v_mfma_f32_16x16x32_bf16 v[38:41], v[150:153], v[186:189], v[38:41]
	v_mfma_f32_16x16x32_bf16 v[22:25], v[150:153], v[194:197], v[22:25]
	v_mfma_f32_16x16x32_bf16 v[22:25], v[154:157], v[198:201], v[22:25]
	v_mfma_f32_16x16x32_bf16 v[18:21], v[162:165], v[198:201], v[18:21]
	v_mfma_f32_16x16x32_bf16 v[18:21], v[158:161], v[194:197], v[18:21]
	v_mfma_f32_16x16x32_bf16 v[2:5], v[158:161], v[202:205], v[2:5]
	v_mfma_f32_16x16x32_bf16 v[2:5], v[162:165], v[206:209], v[2:5]
	s_setprio 2
	s_barrier
	v_mfma_f32_16x16x32_bf16 v[6:9], v[154:157], v[206:209], v[6:9]
	v_mfma_f32_16x16x32_bf16 v[6:9], v[150:153], v[202:205], v[6:9]
	s_setprio 0
	s_add_i32 s78, s78, 2
	s_add_u32 s74, s74, 0x80000
	s_addc_u32 s75, s75, 0
	s_add_u32 s20, s20, 0x400000
	s_addc_u32 s21, s21, 0
	s_add_u32 s76, s76, 0x400000
	s_addc_u32 s77, s77, 0
	s_cmpk_gt_u32 s78, 0x53
	.p2align 6
.LBB0_1357:
	ds_read_b128 v[130:133], v181
	ds_read_b128 v[134:137], v181 offset:1024
	ds_read_b128 v[138:141], v181 offset:2048
	ds_read_b128 v[142:145], v181 offset:3072
	ds_read_b128 v[150:153], v182
	ds_read_b128 v[154:157], v182 offset:1024
	ds_read_b128 v[158:161], v182 offset:2048
	ds_read_b128 v[162:165], v182 offset:3072
	s_cmpk_eq_i32 s78, 0x52
	s_cselect_b32 s23, s11, s75
	s_cselect_b32 s22, s73, s74
	s_cselect_b32 s25, s13, s77
	s_cselect_b32 s24, s67, s76
	ds_read_b128 v[166:169], v183
	ds_read_b128 v[170:173], v183 offset:1024
	ds_read_b128 v[186:189], v183 offset:2048
	ds_read_b128 v[190:193], v183 offset:3072
	ds_read_b128 v[194:197], v183 offset:4096
	ds_read_b128 v[198:201], v183 offset:5120
	ds_read_b128 v[202:205], v183 offset:6144
	ds_read_b128 v[206:209], v183 offset:7168
	s_add_u32 s80, s20, 0xffffc000
	s_addc_u32 s81, s21, -1
	s_mov_b32 s79, m0
	s_mov_b32 m0, s58
	s_nop 0
	global_load_lds_dwordx4 v1, s[80:81]
	s_mov_b32 m0, s79
	s_nop 0
	s_mov_b32 s79, m0
	s_mov_b32 m0, s64
	s_nop 0
	global_load_lds_dwordx4 v177, s[80:81]
	s_mov_b32 m0, s79
	s_nop 0
	s_mov_b32 s79, m0
	s_mov_b32 m0, s59
	s_nop 0
	global_load_lds_dwordx4 v1, s[20:21]
	s_mov_b32 m0, s79
	s_nop 0
	s_mov_b32 s79, m0
	s_mov_b32 m0, s65
	s_nop 0
	global_load_lds_dwordx4 v177, s[20:21]
	s_mov_b32 m0, s79
	s_waitcnt vmcnt(8)
	s_waitcnt lgkmcnt(0)
	s_barrier
	s_setprio 1
	s_waitcnt lgkmcnt(7)
	v_mfma_f32_16x16x32_bf16 v[126:129], v[130:133], v[166:169], v[126:129]
	v_mfma_f32_16x16x32_bf16 v[126:129], v[134:137], v[170:173], v[126:129]
	s_waitcnt lgkmcnt(5)
	v_mfma_f32_16x16x32_bf16 v[122:125], v[142:145], v[170:173], v[122:125]
	v_mfma_f32_16x16x32_bf16 v[122:125], v[138:141], v[166:169], v[122:125]
	s_waitcnt lgkmcnt(3)
	v_mfma_f32_16x16x32_bf16 v[110:113], v[138:141], v[186:189], v[110:113]
	v_mfma_f32_16x16x32_bf16 v[110:113], v[142:145], v[190:193], v[110:113]
	s_waitcnt lgkmcnt(1)
	v_mfma_f32_16x16x32_bf16 v[118:121], v[134:137], v[190:193], v[118:121]
	v_mfma_f32_16x16x32_bf16 v[118:121], v[130:133], v[186:189], v[118:121]
	v_mfma_f32_16x16x32_bf16 v[94:97], v[130:133], v[194:197], v[94:97]
	v_mfma_f32_16x16x32_bf16 v[94:97], v[134:137], v[198:201], v[94:97]
	v_mfma_f32_16x16x32_bf16 v[90:93], v[142:145], v[198:201], v[90:93]
	v_mfma_f32_16x16x32_bf16 v[90:93], v[138:141], v[194:197], v[90:93]
	v_mfma_f32_16x16x32_bf16 v[78:81], v[138:141], v[202:205], v[78:81]
	v_mfma_f32_16x16x32_bf16 v[78:81], v[142:145], v[206:209], v[78:81]
	s_waitcnt lgkmcnt(0)
	v_mfma_f32_16x16x32_bf16 v[86:89], v[134:137], v[206:209], v[86:89]
	v_mfma_f32_16x16x32_bf16 v[86:89], v[130:133], v[202:205], v[86:89]
	s_setprio 0
	s_setprio 1
	v_mfma_f32_16x16x32_bf16 v[114:117], v[150:153], v[166:169], v[114:117]
	v_mfma_f32_16x16x32_bf16 v[114:117], v[154:157], v[170:173], v[114:117]
	v_mfma_f32_16x16x32_bf16 v[106:109], v[162:165], v[170:173], v[106:109]
	v_mfma_f32_16x16x32_bf16 v[106:109], v[158:161], v[166:169], v[106:109]
	v_mfma_f32_16x16x32_bf16 v[98:101], v[158:161], v[186:189], v[98:101]
	v_mfma_f32_16x16x32_bf16 v[98:101], v[162:165], v[190:193], v[98:101]
	v_mfma_f32_16x16x32_bf16 v[102:105], v[154:157], v[190:193], v[102:105]
	v_mfma_f32_16x16x32_bf16 v[102:105], v[150:153], v[186:189], v[102:105]
	v_mfma_f32_16x16x32_bf16 v[82:85], v[150:153], v[194:197], v[82:85]
	v_mfma_f32_16x16x32_bf16 v[82:85], v[154:157], v[198:201], v[82:85]
	v_mfma_f32_16x16x32_bf16 v[74:77], v[162:165], v[198:201], v[74:77]
	v_mfma_f32_16x16x32_bf16 v[74:77], v[158:161], v[194:197], v[74:77]
	v_mfma_f32_16x16x32_bf16 v[66:69], v[158:161], v[202:205], v[66:69]
	v_mfma_f32_16x16x32_bf16 v[66:69], v[162:165], v[206:209], v[66:69]
	s_setprio 2
	s_barrier
	v_mfma_f32_16x16x32_bf16 v[70:73], v[154:157], v[206:209], v[70:73]
	v_mfma_f32_16x16x32_bf16 v[70:73], v[150:153], v[202:205], v[70:73]
	s_setprio 0
	ds_read_b128 v[166:169], v183 offset:16384
	ds_read_b128 v[170:173], v183 offset:17408
	ds_read_b128 v[186:189], v183 offset:18432
	ds_read_b128 v[190:193], v183 offset:19456
	ds_read_b128 v[194:197], v183 offset:20480
	ds_read_b128 v[198:201], v183 offset:21504
	ds_read_b128 v[202:205], v183 offset:22528
	ds_read_b128 v[206:209], v183 offset:23552
	s_mov_b32 s79, m0
	s_mov_b32 m0, s35
	s_nop 0
	global_load_lds_dwordx4 v176, s[22:23]
	s_mov_b32 m0, s79
	s_add_u32 s80, s22, 0x4000
	s_mov_b32 s79, m0
	s_mov_b32 m0, s36
	s_nop 0
	global_load_lds_dwordx4 v178, s[22:23]
	s_mov_b32 m0, s79
	s_addc_u32 s81, s23, 0
	s_mov_b32 s79, m0
	s_mov_b32 m0, s37
	s_nop 0
	global_load_lds_dwordx4 v176, s[80:81]
	s_mov_b32 m0, s79
	s_nop 0
	s_mov_b32 s79, m0
	s_mov_b32 m0, s40
	s_nop 0
	global_load_lds_dwordx4 v178, s[80:81]
	s_mov_b32 m0, s79
	s_waitcnt vmcnt(4)
	s_waitcnt lgkmcnt(0)
	s_barrier
	s_setprio 1
	s_waitcnt lgkmcnt(7)
	v_mfma_f32_16x16x32_bf16 v[62:65], v[130:133], v[166:169], v[62:65]
	v_mfma_f32_16x16x32_bf16 v[62:65], v[134:137], v[170:173], v[62:65]
	s_waitcnt lgkmcnt(5)
	v_mfma_f32_16x16x32_bf16 v[58:61], v[142:145], v[170:173], v[58:61]
	v_mfma_f32_16x16x32_bf16 v[58:61], v[138:141], v[166:169], v[58:61]
	s_waitcnt lgkmcnt(3)
	v_mfma_f32_16x16x32_bf16 v[42:45], v[138:141], v[186:189], v[42:45]
	v_mfma_f32_16x16x32_bf16 v[42:45], v[142:145], v[190:193], v[42:45]
	s_waitcnt lgkmcnt(1)
	v_mfma_f32_16x16x32_bf16 v[46:49], v[134:137], v[190:193], v[46:49]
	v_mfma_f32_16x16x32_bf16 v[46:49], v[130:133], v[186:189], v[46:49]
	v_mfma_f32_16x16x32_bf16 v[30:33], v[130:133], v[194:197], v[30:33]
	v_mfma_f32_16x16x32_bf16 v[30:33], v[134:137], v[198:201], v[30:33]
	v_mfma_f32_16x16x32_bf16 v[26:29], v[142:145], v[198:201], v[26:29]
	v_mfma_f32_16x16x32_bf16 v[26:29], v[138:141], v[194:197], v[26:29]
	v_mfma_f32_16x16x32_bf16 v[10:13], v[138:141], v[202:205], v[10:13]
	v_mfma_f32_16x16x32_bf16 v[10:13], v[142:145], v[206:209], v[10:13]
	s_waitcnt lgkmcnt(0)
	v_mfma_f32_16x16x32_bf16 v[14:17], v[134:137], v[206:209], v[14:17]
	v_mfma_f32_16x16x32_bf16 v[14:17], v[130:133], v[202:205], v[14:17]
	s_setprio 0
	s_setprio 1
	v_mfma_f32_16x16x32_bf16 v[54:57], v[150:153], v[166:169], v[54:57]
	v_mfma_f32_16x16x32_bf16 v[54:57], v[154:157], v[170:173], v[54:57]
	v_mfma_f32_16x16x32_bf16 v[50:53], v[162:165], v[170:173], v[50:53]
	v_mfma_f32_16x16x32_bf16 v[50:53], v[158:161], v[166:169], v[50:53]
	v_mfma_f32_16x16x32_bf16 v[34:37], v[158:161], v[186:189], v[34:37]
	v_mfma_f32_16x16x32_bf16 v[34:37], v[162:165], v[190:193], v[34:37]
	v_mfma_f32_16x16x32_bf16 v[38:41], v[154:157], v[190:193], v[38:41]
	v_mfma_f32_16x16x32_bf16 v[38:41], v[150:153], v[186:189], v[38:41]
	v_mfma_f32_16x16x32_bf16 v[22:25], v[150:153], v[194:197], v[22:25]
	v_mfma_f32_16x16x32_bf16 v[22:25], v[154:157], v[198:201], v[22:25]
	v_mfma_f32_16x16x32_bf16 v[18:21], v[162:165], v[198:201], v[18:21]
	v_mfma_f32_16x16x32_bf16 v[18:21], v[158:161], v[194:197], v[18:21]
	v_mfma_f32_16x16x32_bf16 v[2:5], v[158:161], v[202:205], v[2:5]
	v_mfma_f32_16x16x32_bf16 v[2:5], v[162:165], v[206:209], v[2:5]
	s_setprio 2
	s_barrier
	v_mfma_f32_16x16x32_bf16 v[6:9], v[154:157], v[206:209], v[6:9]
	v_mfma_f32_16x16x32_bf16 v[6:9], v[150:153], v[202:205], v[6:9]
	s_setprio 0
	ds_read_b128 v[130:133], v184
	ds_read_b128 v[134:137], v184 offset:1024
	ds_read_b128 v[138:141], v184 offset:2048
	ds_read_b128 v[142:145], v184 offset:3072
	ds_read_b128 v[150:153], v185
	ds_read_b128 v[154:157], v185 offset:1024
	ds_read_b128 v[158:161], v185 offset:2048
	ds_read_b128 v[162:165], v185 offset:3072
	ds_read_b128 v[166:169], v183 offset:32768
	ds_read_b128 v[170:173], v183 offset:33792
	ds_read_b128 v[186:189], v183 offset:34816
	ds_read_b128 v[190:193], v183 offset:35840
	ds_read_b128 v[194:197], v183 offset:36864
	ds_read_b128 v[198:201], v183 offset:37888
	ds_read_b128 v[202:205], v183 offset:38912
	ds_read_b128 v[206:209], v183 offset:39936
	s_mov_b32 s79, m0
	s_mov_b32 m0, s34
	s_nop 0
	global_load_lds_dwordx4 v1, s[24:25]
	s_mov_b32 m0, s79
	s_nop 0
	s_mov_b32 s79, m0
	s_mov_b32 m0, s41
	s_nop 0
	global_load_lds_dwordx4 v177, s[24:25]
	s_mov_b32 m0, s79
	s_add_u32 s24, s24, 0x4000
	s_addc_u32 s25, s25, 0
	s_mov_b32 s79, m0
	s_mov_b32 m0, s42
	s_nop 0
	global_load_lds_dwordx4 v1, s[24:25]
	s_mov_b32 m0, s79
	s_nop 0
	s_mov_b32 s79, m0
	s_mov_b32 m0, s43
	s_nop 0
	global_load_lds_dwordx4 v177, s[24:25]
	s_mov_b32 m0, s79
	s_waitcnt vmcnt(8)
	s_waitcnt lgkmcnt(0)
	s_barrier
	s_setprio 1
	s_waitcnt lgkmcnt(7)
	v_mfma_f32_16x16x32_bf16 v[126:129], v[130:133], v[166:169], v[126:129]
	v_mfma_f32_16x16x32_bf16 v[126:129], v[134:137], v[170:173], v[126:129]
	s_waitcnt lgkmcnt(5)
	v_mfma_f32_16x16x32_bf16 v[122:125], v[142:145], v[170:173], v[122:125]
	v_mfma_f32_16x16x32_bf16 v[122:125], v[138:141], v[166:169], v[122:125]
	s_waitcnt lgkmcnt(3)
	v_mfma_f32_16x16x32_bf16 v[110:113], v[138:141], v[186:189], v[110:113]
	v_mfma_f32_16x16x32_bf16 v[110:113], v[142:145], v[190:193], v[110:113]
	s_waitcnt lgkmcnt(1)
	v_mfma_f32_16x16x32_bf16 v[118:121], v[134:137], v[190:193], v[118:121]
	v_mfma_f32_16x16x32_bf16 v[118:121], v[130:133], v[186:189], v[118:121]
	v_mfma_f32_16x16x32_bf16 v[94:97], v[130:133], v[194:197], v[94:97]
	v_mfma_f32_16x16x32_bf16 v[94:97], v[134:137], v[198:201], v[94:97]
	v_mfma_f32_16x16x32_bf16 v[90:93], v[142:145], v[198:201], v[90:93]
	v_mfma_f32_16x16x32_bf16 v[90:93], v[138:141], v[194:197], v[90:93]
	v_mfma_f32_16x16x32_bf16 v[78:81], v[138:141], v[202:205], v[78:81]
	v_mfma_f32_16x16x32_bf16 v[78:81], v[142:145], v[206:209], v[78:81]
	s_waitcnt lgkmcnt(0)
	v_mfma_f32_16x16x32_bf16 v[86:89], v[134:137], v[206:209], v[86:89]
	v_mfma_f32_16x16x32_bf16 v[86:89], v[130:133], v[202:205], v[86:89]
	s_setprio 0
	s_setprio 1
	v_mfma_f32_16x16x32_bf16 v[114:117], v[150:153], v[166:169], v[114:117]
	v_mfma_f32_16x16x32_bf16 v[114:117], v[154:157], v[170:173], v[114:117]
	v_mfma_f32_16x16x32_bf16 v[106:109], v[162:165], v[170:173], v[106:109]
	v_mfma_f32_16x16x32_bf16 v[106:109], v[158:161], v[166:169], v[106:109]
	v_mfma_f32_16x16x32_bf16 v[98:101], v[158:161], v[186:189], v[98:101]
	v_mfma_f32_16x16x32_bf16 v[98:101], v[162:165], v[190:193], v[98:101]
	v_mfma_f32_16x16x32_bf16 v[102:105], v[154:157], v[190:193], v[102:105]
	v_mfma_f32_16x16x32_bf16 v[102:105], v[150:153], v[186:189], v[102:105]
	v_mfma_f32_16x16x32_bf16 v[82:85], v[150:153], v[194:197], v[82:85]
	v_mfma_f32_16x16x32_bf16 v[82:85], v[154:157], v[198:201], v[82:85]
	v_mfma_f32_16x16x32_bf16 v[74:77], v[162:165], v[198:201], v[74:77]
	v_mfma_f32_16x16x32_bf16 v[74:77], v[158:161], v[194:197], v[74:77]
	v_mfma_f32_16x16x32_bf16 v[66:69], v[158:161], v[202:205], v[66:69]
	v_mfma_f32_16x16x32_bf16 v[66:69], v[162:165], v[206:209], v[66:69]
	s_setprio 2
	s_barrier
	v_mfma_f32_16x16x32_bf16 v[70:73], v[154:157], v[206:209], v[70:73]
	v_mfma_f32_16x16x32_bf16 v[70:73], v[150:153], v[202:205], v[70:73]
	s_setprio 0
	ds_read_b128 v[166:169], v183 offset:49152
	ds_read_b128 v[170:173], v183 offset:50176
	ds_read_b128 v[186:189], v183 offset:51200
	ds_read_b128 v[190:193], v183 offset:52224
	ds_read_b128 v[194:197], v183 offset:53248
	ds_read_b128 v[198:201], v183 offset:54272
	ds_read_b128 v[202:205], v183 offset:55296
	ds_read_b128 v[206:209], v183 offset:56320
	s_add_u32 s24, s22, 0x40000
	s_addc_u32 s25, s23, 0
	s_mov_b32 s79, m0
	s_mov_b32 m0, s46
	s_nop 0
	global_load_lds_dwordx4 v176, s[24:25]
	s_mov_b32 m0, s79
	s_add_u32 s22, s22, 0x44000
	s_mov_b32 s79, m0
	s_mov_b32 m0, s47
	s_nop 0
	global_load_lds_dwordx4 v178, s[24:25]
	s_mov_b32 m0, s79
	s_addc_u32 s23, s23, 0
	s_mov_b32 s24, m0
	s_mov_b32 m0, s48
	s_nop 0
	global_load_lds_dwordx4 v176, s[22:23]
	s_mov_b32 m0, s24
	s_nop 0
	s_mov_b32 s24, m0
	s_mov_b32 m0, s49
	s_nop 0
	global_load_lds_dwordx4 v178, s[22:23]
	s_mov_b32 m0, s24
	s_waitcnt vmcnt(4)
	s_waitcnt lgkmcnt(0)
	s_barrier
	s_setprio 1
	s_waitcnt lgkmcnt(7)
	v_mfma_f32_16x16x32_bf16 v[62:65], v[130:133], v[166:169], v[62:65]
	v_mfma_f32_16x16x32_bf16 v[62:65], v[134:137], v[170:173], v[62:65]
	s_waitcnt lgkmcnt(5)
	v_mfma_f32_16x16x32_bf16 v[58:61], v[142:145], v[170:173], v[58:61]
	v_mfma_f32_16x16x32_bf16 v[58:61], v[138:141], v[166:169], v[58:61]
	s_waitcnt lgkmcnt(3)
	v_mfma_f32_16x16x32_bf16 v[42:45], v[138:141], v[186:189], v[42:45]
	v_mfma_f32_16x16x32_bf16 v[42:45], v[142:145], v[190:193], v[42:45]
	s_waitcnt lgkmcnt(1)
	v_mfma_f32_16x16x32_bf16 v[46:49], v[134:137], v[190:193], v[46:49]
	v_mfma_f32_16x16x32_bf16 v[46:49], v[130:133], v[186:189], v[46:49]
	v_mfma_f32_16x16x32_bf16 v[30:33], v[130:133], v[194:197], v[30:33]
	v_mfma_f32_16x16x32_bf16 v[30:33], v[134:137], v[198:201], v[30:33]
	v_mfma_f32_16x16x32_bf16 v[26:29], v[142:145], v[198:201], v[26:29]
	v_mfma_f32_16x16x32_bf16 v[26:29], v[138:141], v[194:197], v[26:29]
	v_mfma_f32_16x16x32_bf16 v[10:13], v[138:141], v[202:205], v[10:13]
	v_mfma_f32_16x16x32_bf16 v[10:13], v[142:145], v[206:209], v[10:13]
	s_waitcnt lgkmcnt(0)
	v_mfma_f32_16x16x32_bf16 v[14:17], v[134:137], v[206:209], v[14:17]
	v_mfma_f32_16x16x32_bf16 v[14:17], v[130:133], v[202:205], v[14:17]
	s_setprio 0
	s_setprio 1
	v_mfma_f32_16x16x32_bf16 v[54:57], v[150:153], v[166:169], v[54:57]
	v_mfma_f32_16x16x32_bf16 v[54:57], v[154:157], v[170:173], v[54:57]
	v_mfma_f32_16x16x32_bf16 v[50:53], v[162:165], v[170:173], v[50:53]
	v_mfma_f32_16x16x32_bf16 v[50:53], v[158:161], v[166:169], v[50:53]
	v_mfma_f32_16x16x32_bf16 v[34:37], v[158:161], v[186:189], v[34:37]
	v_mfma_f32_16x16x32_bf16 v[34:37], v[162:165], v[190:193], v[34:37]
	v_mfma_f32_16x16x32_bf16 v[38:41], v[154:157], v[190:193], v[38:41]
	v_mfma_f32_16x16x32_bf16 v[38:41], v[150:153], v[186:189], v[38:41]
	v_mfma_f32_16x16x32_bf16 v[22:25], v[150:153], v[194:197], v[22:25]
	v_mfma_f32_16x16x32_bf16 v[22:25], v[154:157], v[198:201], v[22:25]
	v_mfma_f32_16x16x32_bf16 v[18:21], v[162:165], v[198:201], v[18:21]
	v_mfma_f32_16x16x32_bf16 v[18:21], v[158:161], v[194:197], v[18:21]
	v_mfma_f32_16x16x32_bf16 v[2:5], v[158:161], v[202:205], v[2:5]
	v_mfma_f32_16x16x32_bf16 v[2:5], v[162:165], v[206:209], v[2:5]
	s_setprio 2
	s_barrier
	v_mfma_f32_16x16x32_bf16 v[6:9], v[154:157], v[206:209], v[6:9]
	v_mfma_f32_16x16x32_bf16 v[6:9], v[150:153], v[202:205], v[6:9]
	s_setprio 0
	s_add_i32 s78, s78, 2
	s_add_u32 s74, s74, 0x80000
	s_addc_u32 s75, s75, 0
	s_add_u32 s20, s20, 0x400000
	s_addc_u32 s21, s21, 0
	s_add_u32 s76, s76, 0x400000
	s_addc_u32 s77, s77, 0
	s_cmpk_gt_u32 s78, 0x53
	s_cbranch_scc0 .LBB0_1357
	s_and_b64 vcc, exec, s[8:9]
	s_cbranch_vccz .LBB0_1360
	s_barrier

.LBB0_1784:
	s_ashr_i32 s11, s10, 31
	s_lshl_b64 s[12:13], s[10:11], 20
	s_add_u32 s12, s26, s12
	s_addc_u32 s13, s27, s13
	s_and_b64 s[14:15], s[2:3], exec
	s_cselect_b32 s11, s13, s21
	s_cselect_b32 s64, s12, s20
	s_ashr_i32 s9, s8, 31
	s_lshl_b64 s[14:15], s[8:9], 20
	s_add_u32 s14, s28, s14
	s_addc_u32 s15, s29, s15
	s_and_b64 s[22:23], s[2:3], exec
	s_cselect_b32 s9, s15, s19
	s_cselect_b32 s65, s14, s18
	s_add_u32 s66, s18, 0x100
	s_addc_u32 s67, s19, 0
	s_add_u32 s18, s20, 0x80080
	s_addc_u32 s19, s21, 0
	s_add_u32 s70, s20, 0x100
	s_addc_u32 s71, s21, 0
	s_mov_b32 s73, -2
	ds_read_b128 v[148:151], v143
	ds_read_b128 v[152:155], v143 offset:1024
	ds_read_b128 v[156:159], v143 offset:2048
	ds_read_b128 v[160:163], v143 offset:3072
	ds_read_b128 v[164:167], v144
	ds_read_b128 v[168:171], v144 offset:1024
	ds_read_b128 v[172:175], v144 offset:2048
	ds_read_b128 v[176:179], v144 offset:3072
	s_cmp_eq_u32 s73, 28
	s_cselect_b32 s21, s9, s67
	s_cselect_b32 s20, s65, s66
	s_cselect_b32 s23, s11, s71
	s_cselect_b32 s22, s64, s70
	ds_read_b128 v[180:183], v145
	ds_read_b128 v[184:187], v145 offset:1024
	ds_read_b128 v[188:191], v145 offset:2048
	ds_read_b128 v[192:195], v145 offset:3072
	ds_read_b128 v[196:199], v145 offset:4096
	ds_read_b128 v[200:203], v145 offset:5120
	ds_read_b128 v[204:207], v145 offset:6144
	ds_read_b128 v[208:211], v145 offset:7168
	s_add_u32 s74, s18, 0xfff80000
	s_addc_u32 s75, s19, -1
	s_mov_b32 s76, m0
	s_mov_b32 m0, s56
	s_nop 0
	global_load_lds_dwordx4 v138, s[74:75]
	s_mov_b32 m0, s76
	s_nop 0
	s_mov_b32 s76, m0
	s_mov_b32 m0, s59
	s_nop 0
	global_load_lds_dwordx4 v140, s[74:75]
	s_mov_b32 m0, s76
	s_mov_b32 s74, m0
	s_mov_b32 m0, s57
	s_nop 0
	global_load_lds_dwordx4 v138, s[18:19]
	s_mov_b32 m0, s74
	s_nop 0
	s_mov_b32 s74, m0
	s_mov_b32 m0, s62
	s_nop 0
	global_load_lds_dwordx4 v140, s[18:19]
	s_mov_b32 m0, s74
	s_waitcnt vmcnt(8)
	s_waitcnt lgkmcnt(0)
	s_barrier
	s_setprio 1
	s_waitcnt lgkmcnt(7)
	v_mfma_f32_16x16x32_bf16 v[126:129], v[148:151], v[180:183], 0
	v_mfma_f32_16x16x32_bf16 v[126:129], v[152:155], v[184:187], v[126:129]
	s_waitcnt lgkmcnt(5)
	v_mfma_f32_16x16x32_bf16 v[122:125], v[160:163], v[184:187], 0
	v_mfma_f32_16x16x32_bf16 v[122:125], v[156:159], v[180:183], v[122:125]
	s_waitcnt lgkmcnt(3)
	v_mfma_f32_16x16x32_bf16 v[106:109], v[156:159], v[188:191], 0
	v_mfma_f32_16x16x32_bf16 v[106:109], v[160:163], v[192:195], v[106:109]
	s_waitcnt lgkmcnt(1)
	v_mfma_f32_16x16x32_bf16 v[110:113], v[152:155], v[192:195], 0
	v_mfma_f32_16x16x32_bf16 v[110:113], v[148:151], v[188:191], v[110:113]
	v_mfma_f32_16x16x32_bf16 v[94:97], v[148:151], v[196:199], 0
	v_mfma_f32_16x16x32_bf16 v[94:97], v[152:155], v[200:203], v[94:97]
	v_mfma_f32_16x16x32_bf16 v[90:93], v[160:163], v[200:203], 0
	v_mfma_f32_16x16x32_bf16 v[90:93], v[156:159], v[196:199], v[90:93]
	v_mfma_f32_16x16x32_bf16 v[74:77], v[156:159], v[204:207], 0
	v_mfma_f32_16x16x32_bf16 v[74:77], v[160:163], v[208:211], v[74:77]
	s_waitcnt lgkmcnt(0)
	v_mfma_f32_16x16x32_bf16 v[78:81], v[152:155], v[208:211], 0
	v_mfma_f32_16x16x32_bf16 v[78:81], v[148:151], v[204:207], v[78:81]
	s_setprio 0
	s_setprio 1
	v_mfma_f32_16x16x32_bf16 v[118:121], v[164:167], v[180:183], 0
	v_mfma_f32_16x16x32_bf16 v[118:121], v[168:171], v[184:187], v[118:121]
	v_mfma_f32_16x16x32_bf16 v[114:117], v[176:179], v[184:187], 0
	v_mfma_f32_16x16x32_bf16 v[114:117], v[172:175], v[180:183], v[114:117]
	v_mfma_f32_16x16x32_bf16 v[98:101], v[172:175], v[188:191], 0
	v_mfma_f32_16x16x32_bf16 v[98:101], v[176:179], v[192:195], v[98:101]
	v_mfma_f32_16x16x32_bf16 v[102:105], v[168:171], v[192:195], 0
	v_mfma_f32_16x16x32_bf16 v[102:105], v[164:167], v[188:191], v[102:105]
	v_mfma_f32_16x16x32_bf16 v[86:89], v[164:167], v[196:199], 0
	v_mfma_f32_16x16x32_bf16 v[86:89], v[168:171], v[200:203], v[86:89]
	v_mfma_f32_16x16x32_bf16 v[82:85], v[176:179], v[200:203], 0
	v_mfma_f32_16x16x32_bf16 v[82:85], v[172:175], v[196:199], v[82:85]
	v_mfma_f32_16x16x32_bf16 v[66:69], v[172:175], v[204:207], 0
	v_mfma_f32_16x16x32_bf16 v[66:69], v[176:179], v[208:211], v[66:69]
	s_setprio 2
	s_barrier
	v_mfma_f32_16x16x32_bf16 v[70:73], v[168:171], v[208:211], 0
	v_mfma_f32_16x16x32_bf16 v[70:73], v[164:167], v[204:207], v[70:73]
	s_setprio 0
	ds_read_b128 v[180:183], v145 offset:16384
	ds_read_b128 v[184:187], v145 offset:17408
	ds_read_b128 v[188:191], v145 offset:18432
	ds_read_b128 v[192:195], v145 offset:19456
	ds_read_b128 v[196:199], v145 offset:20480
	ds_read_b128 v[200:203], v145 offset:21504
	ds_read_b128 v[204:207], v145 offset:22528
	ds_read_b128 v[208:211], v145 offset:23552
	s_mov_b32 s74, m0
	s_mov_b32 m0, s35
	s_nop 0
	global_load_lds_dwordx4 v139, s[20:21]
	s_mov_b32 m0, s74
	s_nop 0
	s_mov_b32 s74, m0
	s_mov_b32 m0, s36
	s_nop 0
	global_load_lds_dwordx4 v141, s[20:21]
	s_mov_b32 m0, s74
	s_add_u32 s74, s20, 0x80000
	s_addc_u32 s75, s21, 0
	s_mov_b32 s76, m0
	s_mov_b32 m0, s37
	s_nop 0
	global_load_lds_dwordx4 v139, s[74:75]
	s_mov_b32 m0, s76
	s_nop 0
	s_mov_b32 s76, m0
	s_mov_b32 m0, s40
	s_nop 0
	global_load_lds_dwordx4 v141, s[74:75]
	s_mov_b32 m0, s76
	s_waitcnt vmcnt(4)
	s_waitcnt lgkmcnt(0)
	s_barrier
	s_setprio 1
	s_waitcnt lgkmcnt(7)
	v_mfma_f32_16x16x32_bf16 v[62:65], v[148:151], v[180:183], 0
	v_mfma_f32_16x16x32_bf16 v[62:65], v[152:155], v[184:187], v[62:65]
	s_waitcnt lgkmcnt(5)
	v_mfma_f32_16x16x32_bf16 v[58:61], v[160:163], v[184:187], 0
	v_mfma_f32_16x16x32_bf16 v[58:61], v[156:159], v[180:183], v[58:61]
	s_waitcnt lgkmcnt(3)
	v_mfma_f32_16x16x32_bf16 v[42:45], v[156:159], v[188:191], 0
	v_mfma_f32_16x16x32_bf16 v[42:45], v[160:163], v[192:195], v[42:45]
	s_waitcnt lgkmcnt(1)
	v_mfma_f32_16x16x32_bf16 v[46:49], v[152:155], v[192:195], 0
	v_mfma_f32_16x16x32_bf16 v[46:49], v[148:151], v[188:191], v[46:49]
	v_mfma_f32_16x16x32_bf16 v[30:33], v[148:151], v[196:199], 0
	v_mfma_f32_16x16x32_bf16 v[30:33], v[152:155], v[200:203], v[30:33]
	v_mfma_f32_16x16x32_bf16 v[26:29], v[160:163], v[200:203], 0
	v_mfma_f32_16x16x32_bf16 v[26:29], v[156:159], v[196:199], v[26:29]
	v_mfma_f32_16x16x32_bf16 v[10:13], v[156:159], v[204:207], 0
	v_mfma_f32_16x16x32_bf16 v[10:13], v[160:163], v[208:211], v[10:13]
	s_waitcnt lgkmcnt(0)
	v_mfma_f32_16x16x32_bf16 v[14:17], v[152:155], v[208:211], 0
	v_mfma_f32_16x16x32_bf16 v[14:17], v[148:151], v[204:207], v[14:17]
	s_setprio 0
	s_setprio 1
	v_mfma_f32_16x16x32_bf16 v[54:57], v[164:167], v[180:183], 0
	v_mfma_f32_16x16x32_bf16 v[54:57], v[168:171], v[184:187], v[54:57]
	v_mfma_f32_16x16x32_bf16 v[50:53], v[176:179], v[184:187], 0
	v_mfma_f32_16x16x32_bf16 v[50:53], v[172:175], v[180:183], v[50:53]
	v_mfma_f32_16x16x32_bf16 v[34:37], v[172:175], v[188:191], 0
	v_mfma_f32_16x16x32_bf16 v[34:37], v[176:179], v[192:195], v[34:37]
	v_mfma_f32_16x16x32_bf16 v[38:41], v[168:171], v[192:195], 0
	v_mfma_f32_16x16x32_bf16 v[38:41], v[164:167], v[188:191], v[38:41]
	v_mfma_f32_16x16x32_bf16 v[22:25], v[164:167], v[196:199], 0
	v_mfma_f32_16x16x32_bf16 v[22:25], v[168:171], v[200:203], v[22:25]
	v_mfma_f32_16x16x32_bf16 v[18:21], v[176:179], v[200:203], 0
	v_mfma_f32_16x16x32_bf16 v[18:21], v[172:175], v[196:199], v[18:21]
	v_mfma_f32_16x16x32_bf16 v[2:5], v[172:175], v[204:207], 0
	v_mfma_f32_16x16x32_bf16 v[2:5], v[176:179], v[208:211], v[2:5]
	s_setprio 2
	s_barrier
	v_mfma_f32_16x16x32_bf16 v[6:9], v[168:171], v[208:211], 0
	v_mfma_f32_16x16x32_bf16 v[6:9], v[164:167], v[204:207], v[6:9]
	s_setprio 0
	ds_read_b128 v[148:151], v146
	ds_read_b128 v[152:155], v146 offset:1024
	ds_read_b128 v[156:159], v146 offset:2048
	ds_read_b128 v[160:163], v146 offset:3072
	ds_read_b128 v[164:167], v147
	ds_read_b128 v[168:171], v147 offset:1024
	ds_read_b128 v[172:175], v147 offset:2048
	ds_read_b128 v[176:179], v147 offset:3072
	ds_read_b128 v[180:183], v145 offset:32768
	ds_read_b128 v[184:187], v145 offset:33792
	ds_read_b128 v[188:191], v145 offset:34816
	ds_read_b128 v[192:195], v145 offset:35840
	ds_read_b128 v[196:199], v145 offset:36864
	ds_read_b128 v[200:203], v145 offset:37888
	ds_read_b128 v[204:207], v145 offset:38912
	ds_read_b128 v[208:211], v145 offset:39936
	s_mov_b32 s74, m0
	s_mov_b32 m0, s31
	s_nop 0
	global_load_lds_dwordx4 v138, s[22:23]
	s_mov_b32 m0, s74
	s_nop 0
	s_mov_b32 s74, m0
	s_mov_b32 m0, s41
	s_nop 0
	global_load_lds_dwordx4 v140, s[22:23]
	s_mov_b32 m0, s74
	s_add_u32 s22, s22, 0x80000
	s_addc_u32 s23, s23, 0
	s_mov_b32 s74, m0
	s_mov_b32 m0, s42
	s_nop 0
	global_load_lds_dwordx4 v138, s[22:23]
	s_mov_b32 m0, s74
	s_nop 0
	s_mov_b32 s74, m0
	s_mov_b32 m0, s43
	s_nop 0
	global_load_lds_dwordx4 v140, s[22:23]
	s_mov_b32 m0, s74
	s_waitcnt vmcnt(8)
	s_waitcnt lgkmcnt(0)
	s_barrier
	s_setprio 1
	s_waitcnt lgkmcnt(7)
	v_mfma_f32_16x16x32_bf16 v[126:129], v[148:151], v[180:183], v[126:129]
	v_mfma_f32_16x16x32_bf16 v[126:129], v[152:155], v[184:187], v[126:129]
	s_waitcnt lgkmcnt(5)
	v_mfma_f32_16x16x32_bf16 v[122:125], v[160:163], v[184:187], v[122:125]
	v_mfma_f32_16x16x32_bf16 v[122:125], v[156:159], v[180:183], v[122:125]
	s_waitcnt lgkmcnt(3)
	v_mfma_f32_16x16x32_bf16 v[106:109], v[156:159], v[188:191], v[106:109]
	v_mfma_f32_16x16x32_bf16 v[106:109], v[160:163], v[192:195], v[106:109]
	s_waitcnt lgkmcnt(1)
	v_mfma_f32_16x16x32_bf16 v[110:113], v[152:155], v[192:195], v[110:113]
	v_mfma_f32_16x16x32_bf16 v[110:113], v[148:151], v[188:191], v[110:113]
	v_mfma_f32_16x16x32_bf16 v[94:97], v[148:151], v[196:199], v[94:97]
	v_mfma_f32_16x16x32_bf16 v[94:97], v[152:155], v[200:203], v[94:97]
	v_mfma_f32_16x16x32_bf16 v[90:93], v[160:163], v[200:203], v[90:93]
	v_mfma_f32_16x16x32_bf16 v[90:93], v[156:159], v[196:199], v[90:93]
	v_mfma_f32_16x16x32_bf16 v[74:77], v[156:159], v[204:207], v[74:77]
	v_mfma_f32_16x16x32_bf16 v[74:77], v[160:163], v[208:211], v[74:77]
	s_waitcnt lgkmcnt(0)
	v_mfma_f32_16x16x32_bf16 v[78:81], v[152:155], v[208:211], v[78:81]
	v_mfma_f32_16x16x32_bf16 v[78:81], v[148:151], v[204:207], v[78:81]
	s_setprio 0
	s_setprio 1
	v_mfma_f32_16x16x32_bf16 v[118:121], v[164:167], v[180:183], v[118:121]
	v_mfma_f32_16x16x32_bf16 v[118:121], v[168:171], v[184:187], v[118:121]
	v_mfma_f32_16x16x32_bf16 v[114:117], v[176:179], v[184:187], v[114:117]
	v_mfma_f32_16x16x32_bf16 v[114:117], v[172:175], v[180:183], v[114:117]
	v_mfma_f32_16x16x32_bf16 v[98:101], v[172:175], v[188:191], v[98:101]
	v_mfma_f32_16x16x32_bf16 v[98:101], v[176:179], v[192:195], v[98:101]
	v_mfma_f32_16x16x32_bf16 v[102:105], v[168:171], v[192:195], v[102:105]
	v_mfma_f32_16x16x32_bf16 v[102:105], v[164:167], v[188:191], v[102:105]
	v_mfma_f32_16x16x32_bf16 v[86:89], v[164:167], v[196:199], v[86:89]
	v_mfma_f32_16x16x32_bf16 v[86:89], v[168:171], v[200:203], v[86:89]
	v_mfma_f32_16x16x32_bf16 v[82:85], v[176:179], v[200:203], v[82:85]
	v_mfma_f32_16x16x32_bf16 v[82:85], v[172:175], v[196:199], v[82:85]
	v_mfma_f32_16x16x32_bf16 v[66:69], v[172:175], v[204:207], v[66:69]
	v_mfma_f32_16x16x32_bf16 v[66:69], v[176:179], v[208:211], v[66:69]
	s_setprio 2
	s_barrier
	v_mfma_f32_16x16x32_bf16 v[70:73], v[168:171], v[208:211], v[70:73]
	v_mfma_f32_16x16x32_bf16 v[70:73], v[164:167], v[204:207], v[70:73]
	s_setprio 0
	ds_read_b128 v[180:183], v145 offset:49152
	ds_read_b128 v[184:187], v145 offset:50176
	ds_read_b128 v[188:191], v145 offset:51200
	ds_read_b128 v[192:195], v145 offset:52224
	ds_read_b128 v[196:199], v145 offset:53248
	ds_read_b128 v[200:203], v145 offset:54272
	ds_read_b128 v[204:207], v145 offset:55296
	ds_read_b128 v[208:211], v145 offset:56320
	s_add_u32 s22, s20, 0x80
	s_addc_u32 s23, s21, 0
	s_mov_b32 s74, m0
	s_mov_b32 m0, s46
	s_nop 0
	global_load_lds_dwordx4 v139, s[22:23]
	s_mov_b32 m0, s74
	s_add_u32 s20, s20, 0x80080
	s_mov_b32 s74, m0
	s_mov_b32 m0, s47
	s_nop 0
	global_load_lds_dwordx4 v141, s[22:23]
	s_mov_b32 m0, s74
	s_addc_u32 s21, s21, 0
	s_mov_b32 s22, m0
	s_mov_b32 m0, s48
	s_nop 0
	global_load_lds_dwordx4 v139, s[20:21]
	s_mov_b32 m0, s22
	s_nop 0
	s_mov_b32 s22, m0
	s_mov_b32 m0, s49
	s_nop 0
	global_load_lds_dwordx4 v141, s[20:21]
	s_mov_b32 m0, s22
	s_waitcnt vmcnt(4)
	s_waitcnt lgkmcnt(0)
	s_barrier
	s_setprio 1
	s_waitcnt lgkmcnt(7)
	v_mfma_f32_16x16x32_bf16 v[62:65], v[148:151], v[180:183], v[62:65]
	v_mfma_f32_16x16x32_bf16 v[62:65], v[152:155], v[184:187], v[62:65]
	s_waitcnt lgkmcnt(5)
	v_mfma_f32_16x16x32_bf16 v[58:61], v[160:163], v[184:187], v[58:61]
	v_mfma_f32_16x16x32_bf16 v[58:61], v[156:159], v[180:183], v[58:61]
	s_waitcnt lgkmcnt(3)
	v_mfma_f32_16x16x32_bf16 v[42:45], v[156:159], v[188:191], v[42:45]
	v_mfma_f32_16x16x32_bf16 v[42:45], v[160:163], v[192:195], v[42:45]
	s_waitcnt lgkmcnt(1)
	v_mfma_f32_16x16x32_bf16 v[46:49], v[152:155], v[192:195], v[46:49]
	v_mfma_f32_16x16x32_bf16 v[46:49], v[148:151], v[188:191], v[46:49]
	v_mfma_f32_16x16x32_bf16 v[30:33], v[148:151], v[196:199], v[30:33]
	v_mfma_f32_16x16x32_bf16 v[30:33], v[152:155], v[200:203], v[30:33]
	v_mfma_f32_16x16x32_bf16 v[26:29], v[160:163], v[200:203], v[26:29]
	v_mfma_f32_16x16x32_bf16 v[26:29], v[156:159], v[196:199], v[26:29]
	v_mfma_f32_16x16x32_bf16 v[10:13], v[156:159], v[204:207], v[10:13]
	v_mfma_f32_16x16x32_bf16 v[10:13], v[160:163], v[208:211], v[10:13]
	s_waitcnt lgkmcnt(0)
	v_mfma_f32_16x16x32_bf16 v[14:17], v[152:155], v[208:211], v[14:17]
	v_mfma_f32_16x16x32_bf16 v[14:17], v[148:151], v[204:207], v[14:17]
	s_setprio 0
	s_setprio 1
	v_mfma_f32_16x16x32_bf16 v[54:57], v[164:167], v[180:183], v[54:57]
	v_mfma_f32_16x16x32_bf16 v[54:57], v[168:171], v[184:187], v[54:57]
	v_mfma_f32_16x16x32_bf16 v[50:53], v[176:179], v[184:187], v[50:53]
	v_mfma_f32_16x16x32_bf16 v[50:53], v[172:175], v[180:183], v[50:53]
	v_mfma_f32_16x16x32_bf16 v[34:37], v[172:175], v[188:191], v[34:37]
	v_mfma_f32_16x16x32_bf16 v[34:37], v[176:179], v[192:195], v[34:37]
	v_mfma_f32_16x16x32_bf16 v[38:41], v[168:171], v[192:195], v[38:41]
	v_mfma_f32_16x16x32_bf16 v[38:41], v[164:167], v[188:191], v[38:41]
	v_mfma_f32_16x16x32_bf16 v[22:25], v[164:167], v[196:199], v[22:25]
	v_mfma_f32_16x16x32_bf16 v[22:25], v[168:171], v[200:203], v[22:25]
	v_mfma_f32_16x16x32_bf16 v[18:21], v[176:179], v[200:203], v[18:21]
	v_mfma_f32_16x16x32_bf16 v[18:21], v[172:175], v[196:199], v[18:21]
	v_mfma_f32_16x16x32_bf16 v[2:5], v[172:175], v[204:207], v[2:5]
	v_mfma_f32_16x16x32_bf16 v[2:5], v[176:179], v[208:211], v[2:5]
	s_setprio 2
	s_barrier
	v_mfma_f32_16x16x32_bf16 v[6:9], v[168:171], v[208:211], v[6:9]
	v_mfma_f32_16x16x32_bf16 v[6:9], v[164:167], v[204:207], v[6:9]
	s_setprio 0
	s_add_i32 s73, s73, 2
	s_add_u32 s66, s66, 0x100
	s_addc_u32 s67, s67, 0
	s_add_u32 s18, s18, 0x100
	s_addc_u32 s19, s19, 0
	s_add_u32 s70, s70, 0x100
	s_addc_u32 s71, s71, 0
	s_cmp_gt_u32 s73, 29
	.p2align 6
.LBB0_1785:
	ds_read_b128 v[148:151], v143
	ds_read_b128 v[152:155], v143 offset:1024
	ds_read_b128 v[156:159], v143 offset:2048
	ds_read_b128 v[160:163], v143 offset:3072
	ds_read_b128 v[164:167], v144
	ds_read_b128 v[168:171], v144 offset:1024
	ds_read_b128 v[172:175], v144 offset:2048
	ds_read_b128 v[176:179], v144 offset:3072
	s_cmp_eq_u32 s73, 28
	s_cselect_b32 s21, s9, s67
	s_cselect_b32 s20, s65, s66
	s_cselect_b32 s23, s11, s71
	s_cselect_b32 s22, s64, s70
	ds_read_b128 v[180:183], v145
	ds_read_b128 v[184:187], v145 offset:1024
	ds_read_b128 v[188:191], v145 offset:2048
	ds_read_b128 v[192:195], v145 offset:3072
	ds_read_b128 v[196:199], v145 offset:4096
	ds_read_b128 v[200:203], v145 offset:5120
	ds_read_b128 v[204:207], v145 offset:6144
	ds_read_b128 v[208:211], v145 offset:7168
	s_add_u32 s74, s18, 0xfff80000
	s_addc_u32 s75, s19, -1
	s_mov_b32 s76, m0
	s_mov_b32 m0, s56
	s_nop 0
	global_load_lds_dwordx4 v138, s[74:75]
	s_mov_b32 m0, s76
	s_nop 0
	s_mov_b32 s76, m0
	s_mov_b32 m0, s59
	s_nop 0
	global_load_lds_dwordx4 v140, s[74:75]
	s_mov_b32 m0, s76
	s_mov_b32 s74, m0
	s_mov_b32 m0, s57
	s_nop 0
	global_load_lds_dwordx4 v138, s[18:19]
	s_mov_b32 m0, s74
	s_nop 0
	s_mov_b32 s74, m0
	s_mov_b32 m0, s62
	s_nop 0
	global_load_lds_dwordx4 v140, s[18:19]
	s_mov_b32 m0, s74
	s_waitcnt vmcnt(8)
	s_waitcnt lgkmcnt(0)
	s_barrier
	s_setprio 1
	s_waitcnt lgkmcnt(7)
	v_mfma_f32_16x16x32_bf16 v[126:129], v[148:151], v[180:183], v[126:129]
	v_mfma_f32_16x16x32_bf16 v[126:129], v[152:155], v[184:187], v[126:129]
	s_waitcnt lgkmcnt(5)
	v_mfma_f32_16x16x32_bf16 v[122:125], v[160:163], v[184:187], v[122:125]
	v_mfma_f32_16x16x32_bf16 v[122:125], v[156:159], v[180:183], v[122:125]
	s_waitcnt lgkmcnt(3)
	v_mfma_f32_16x16x32_bf16 v[106:109], v[156:159], v[188:191], v[106:109]
	v_mfma_f32_16x16x32_bf16 v[106:109], v[160:163], v[192:195], v[106:109]
	s_waitcnt lgkmcnt(1)
	v_mfma_f32_16x16x32_bf16 v[110:113], v[152:155], v[192:195], v[110:113]
	v_mfma_f32_16x16x32_bf16 v[110:113], v[148:151], v[188:191], v[110:113]
	v_mfma_f32_16x16x32_bf16 v[94:97], v[148:151], v[196:199], v[94:97]
	v_mfma_f32_16x16x32_bf16 v[94:97], v[152:155], v[200:203], v[94:97]
	v_mfma_f32_16x16x32_bf16 v[90:93], v[160:163], v[200:203], v[90:93]
	v_mfma_f32_16x16x32_bf16 v[90:93], v[156:159], v[196:199], v[90:93]
	v_mfma_f32_16x16x32_bf16 v[74:77], v[156:159], v[204:207], v[74:77]
	v_mfma_f32_16x16x32_bf16 v[74:77], v[160:163], v[208:211], v[74:77]
	s_waitcnt lgkmcnt(0)
	v_mfma_f32_16x16x32_bf16 v[78:81], v[152:155], v[208:211], v[78:81]
	v_mfma_f32_16x16x32_bf16 v[78:81], v[148:151], v[204:207], v[78:81]
	s_setprio 0
	s_setprio 1
	v_mfma_f32_16x16x32_bf16 v[118:121], v[164:167], v[180:183], v[118:121]
	v_mfma_f32_16x16x32_bf16 v[118:121], v[168:171], v[184:187], v[118:121]
	v_mfma_f32_16x16x32_bf16 v[114:117], v[176:179], v[184:187], v[114:117]
	v_mfma_f32_16x16x32_bf16 v[114:117], v[172:175], v[180:183], v[114:117]
	v_mfma_f32_16x16x32_bf16 v[98:101], v[172:175], v[188:191], v[98:101]
	v_mfma_f32_16x16x32_bf16 v[98:101], v[176:179], v[192:195], v[98:101]
	v_mfma_f32_16x16x32_bf16 v[102:105], v[168:171], v[192:195], v[102:105]
	v_mfma_f32_16x16x32_bf16 v[102:105], v[164:167], v[188:191], v[102:105]
	v_mfma_f32_16x16x32_bf16 v[86:89], v[164:167], v[196:199], v[86:89]
	v_mfma_f32_16x16x32_bf16 v[86:89], v[168:171], v[200:203], v[86:89]
	v_mfma_f32_16x16x32_bf16 v[82:85], v[176:179], v[200:203], v[82:85]
	v_mfma_f32_16x16x32_bf16 v[82:85], v[172:175], v[196:199], v[82:85]
	v_mfma_f32_16x16x32_bf16 v[66:69], v[172:175], v[204:207], v[66:69]
	v_mfma_f32_16x16x32_bf16 v[66:69], v[176:179], v[208:211], v[66:69]
	s_setprio 2
	s_barrier
	v_mfma_f32_16x16x32_bf16 v[70:73], v[168:171], v[208:211], v[70:73]
	v_mfma_f32_16x16x32_bf16 v[70:73], v[164:167], v[204:207], v[70:73]
	s_setprio 0
	ds_read_b128 v[180:183], v145 offset:16384
	ds_read_b128 v[184:187], v145 offset:17408
	ds_read_b128 v[188:191], v145 offset:18432
	ds_read_b128 v[192:195], v145 offset:19456
	ds_read_b128 v[196:199], v145 offset:20480
	ds_read_b128 v[200:203], v145 offset:21504
	ds_read_b128 v[204:207], v145 offset:22528
	ds_read_b128 v[208:211], v145 offset:23552
	s_mov_b32 s74, m0
	s_mov_b32 m0, s35
	s_nop 0
	global_load_lds_dwordx4 v139, s[20:21]
	s_mov_b32 m0, s74
	s_nop 0
	s_mov_b32 s74, m0
	s_mov_b32 m0, s36
	s_nop 0
	global_load_lds_dwordx4 v141, s[20:21]
	s_mov_b32 m0, s74
	s_add_u32 s74, s20, 0x80000
	s_addc_u32 s75, s21, 0
	s_mov_b32 s76, m0
	s_mov_b32 m0, s37
	s_nop 0
	global_load_lds_dwordx4 v139, s[74:75]
	s_mov_b32 m0, s76
	s_nop 0
	s_mov_b32 s76, m0
	s_mov_b32 m0, s40
	s_nop 0
	global_load_lds_dwordx4 v141, s[74:75]
	s_mov_b32 m0, s76
	s_waitcnt vmcnt(4)
	s_waitcnt lgkmcnt(0)
	s_barrier
	s_setprio 1
	s_waitcnt lgkmcnt(7)
	v_mfma_f32_16x16x32_bf16 v[62:65], v[148:151], v[180:183], v[62:65]
	v_mfma_f32_16x16x32_bf16 v[62:65], v[152:155], v[184:187], v[62:65]
	s_waitcnt lgkmcnt(5)
	v_mfma_f32_16x16x32_bf16 v[58:61], v[160:163], v[184:187], v[58:61]
	v_mfma_f32_16x16x32_bf16 v[58:61], v[156:159], v[180:183], v[58:61]
	s_waitcnt lgkmcnt(3)
	v_mfma_f32_16x16x32_bf16 v[42:45], v[156:159], v[188:191], v[42:45]
	v_mfma_f32_16x16x32_bf16 v[42:45], v[160:163], v[192:195], v[42:45]
	s_waitcnt lgkmcnt(1)
	v_mfma_f32_16x16x32_bf16 v[46:49], v[152:155], v[192:195], v[46:49]
	v_mfma_f32_16x16x32_bf16 v[46:49], v[148:151], v[188:191], v[46:49]
	v_mfma_f32_16x16x32_bf16 v[30:33], v[148:151], v[196:199], v[30:33]
	v_mfma_f32_16x16x32_bf16 v[30:33], v[152:155], v[200:203], v[30:33]
	v_mfma_f32_16x16x32_bf16 v[26:29], v[160:163], v[200:203], v[26:29]
	v_mfma_f32_16x16x32_bf16 v[26:29], v[156:159], v[196:199], v[26:29]
	v_mfma_f32_16x16x32_bf16 v[10:13], v[156:159], v[204:207], v[10:13]
	v_mfma_f32_16x16x32_bf16 v[10:13], v[160:163], v[208:211], v[10:13]
	s_waitcnt lgkmcnt(0)
	v_mfma_f32_16x16x32_bf16 v[14:17], v[152:155], v[208:211], v[14:17]
	v_mfma_f32_16x16x32_bf16 v[14:17], v[148:151], v[204:207], v[14:17]
	s_setprio 0
	s_setprio 1
	v_mfma_f32_16x16x32_bf16 v[54:57], v[164:167], v[180:183], v[54:57]
	v_mfma_f32_16x16x32_bf16 v[54:57], v[168:171], v[184:187], v[54:57]
	v_mfma_f32_16x16x32_bf16 v[50:53], v[176:179], v[184:187], v[50:53]
	v_mfma_f32_16x16x32_bf16 v[50:53], v[172:175], v[180:183], v[50:53]
	v_mfma_f32_16x16x32_bf16 v[34:37], v[172:175], v[188:191], v[34:37]
	v_mfma_f32_16x16x32_bf16 v[34:37], v[176:179], v[192:195], v[34:37]
	v_mfma_f32_16x16x32_bf16 v[38:41], v[168:171], v[192:195], v[38:41]
	v_mfma_f32_16x16x32_bf16 v[38:41], v[164:167], v[188:191], v[38:41]
	v_mfma_f32_16x16x32_bf16 v[22:25], v[164:167], v[196:199], v[22:25]
	v_mfma_f32_16x16x32_bf16 v[22:25], v[168:171], v[200:203], v[22:25]
	v_mfma_f32_16x16x32_bf16 v[18:21], v[176:179], v[200:203], v[18:21]
	v_mfma_f32_16x16x32_bf16 v[18:21], v[172:175], v[196:199], v[18:21]
	v_mfma_f32_16x16x32_bf16 v[2:5], v[172:175], v[204:207], v[2:5]
	v_mfma_f32_16x16x32_bf16 v[2:5], v[176:179], v[208:211], v[2:5]
	s_setprio 2
	s_barrier
	v_mfma_f32_16x16x32_bf16 v[6:9], v[168:171], v[208:211], v[6:9]
	v_mfma_f32_16x16x32_bf16 v[6:9], v[164:167], v[204:207], v[6:9]
	s_setprio 0
	ds_read_b128 v[148:151], v146
	ds_read_b128 v[152:155], v146 offset:1024
	ds_read_b128 v[156:159], v146 offset:2048
	ds_read_b128 v[160:163], v146 offset:3072
	ds_read_b128 v[164:167], v147
	ds_read_b128 v[168:171], v147 offset:1024
	ds_read_b128 v[172:175], v147 offset:2048
	ds_read_b128 v[176:179], v147 offset:3072
	ds_read_b128 v[180:183], v145 offset:32768
	ds_read_b128 v[184:187], v145 offset:33792
	ds_read_b128 v[188:191], v145 offset:34816
	ds_read_b128 v[192:195], v145 offset:35840
	ds_read_b128 v[196:199], v145 offset:36864
	ds_read_b128 v[200:203], v145 offset:37888
	ds_read_b128 v[204:207], v145 offset:38912
	ds_read_b128 v[208:211], v145 offset:39936
	s_mov_b32 s74, m0
	s_mov_b32 m0, s31
	s_nop 0
	global_load_lds_dwordx4 v138, s[22:23]
	s_mov_b32 m0, s74
	s_nop 0
	s_mov_b32 s74, m0
	s_mov_b32 m0, s41
	s_nop 0
	global_load_lds_dwordx4 v140, s[22:23]
	s_mov_b32 m0, s74
	s_add_u32 s22, s22, 0x80000
	s_addc_u32 s23, s23, 0
	s_mov_b32 s74, m0
	s_mov_b32 m0, s42
	s_nop 0
	global_load_lds_dwordx4 v138, s[22:23]
	s_mov_b32 m0, s74
	s_nop 0
	s_mov_b32 s74, m0
	s_mov_b32 m0, s43
	s_nop 0
	global_load_lds_dwordx4 v140, s[22:23]
	s_mov_b32 m0, s74
	s_waitcnt vmcnt(8)
	s_waitcnt lgkmcnt(0)
	s_barrier
	s_setprio 1
	s_waitcnt lgkmcnt(7)
	v_mfma_f32_16x16x32_bf16 v[126:129], v[148:151], v[180:183], v[126:129]
	v_mfma_f32_16x16x32_bf16 v[126:129], v[152:155], v[184:187], v[126:129]
	s_waitcnt lgkmcnt(5)
	v_mfma_f32_16x16x32_bf16 v[122:125], v[160:163], v[184:187], v[122:125]
	v_mfma_f32_16x16x32_bf16 v[122:125], v[156:159], v[180:183], v[122:125]
	s_waitcnt lgkmcnt(3)
	v_mfma_f32_16x16x32_bf16 v[106:109], v[156:159], v[188:191], v[106:109]
	v_mfma_f32_16x16x32_bf16 v[106:109], v[160:163], v[192:195], v[106:109]
	s_waitcnt lgkmcnt(1)
	v_mfma_f32_16x16x32_bf16 v[110:113], v[152:155], v[192:195], v[110:113]
	v_mfma_f32_16x16x32_bf16 v[110:113], v[148:151], v[188:191], v[110:113]
	v_mfma_f32_16x16x32_bf16 v[94:97], v[148:151], v[196:199], v[94:97]
	v_mfma_f32_16x16x32_bf16 v[94:97], v[152:155], v[200:203], v[94:97]
	v_mfma_f32_16x16x32_bf16 v[90:93], v[160:163], v[200:203], v[90:93]
	v_mfma_f32_16x16x32_bf16 v[90:93], v[156:159], v[196:199], v[90:93]
	v_mfma_f32_16x16x32_bf16 v[74:77], v[156:159], v[204:207], v[74:77]
	v_mfma_f32_16x16x32_bf16 v[74:77], v[160:163], v[208:211], v[74:77]
	s_waitcnt lgkmcnt(0)
	v_mfma_f32_16x16x32_bf16 v[78:81], v[152:155], v[208:211], v[78:81]
	v_mfma_f32_16x16x32_bf16 v[78:81], v[148:151], v[204:207], v[78:81]
	s_setprio 0
	s_setprio 1
	v_mfma_f32_16x16x32_bf16 v[118:121], v[164:167], v[180:183], v[118:121]
	v_mfma_f32_16x16x32_bf16 v[118:121], v[168:171], v[184:187], v[118:121]
	v_mfma_f32_16x16x32_bf16 v[114:117], v[176:179], v[184:187], v[114:117]
	v_mfma_f32_16x16x32_bf16 v[114:117], v[172:175], v[180:183], v[114:117]
	v_mfma_f32_16x16x32_bf16 v[98:101], v[172:175], v[188:191], v[98:101]
	v_mfma_f32_16x16x32_bf16 v[98:101], v[176:179], v[192:195], v[98:101]
	v_mfma_f32_16x16x32_bf16 v[102:105], v[168:171], v[192:195], v[102:105]
	v_mfma_f32_16x16x32_bf16 v[102:105], v[164:167], v[188:191], v[102:105]
	v_mfma_f32_16x16x32_bf16 v[86:89], v[164:167], v[196:199], v[86:89]
	v_mfma_f32_16x16x32_bf16 v[86:89], v[168:171], v[200:203], v[86:89]
	v_mfma_f32_16x16x32_bf16 v[82:85], v[176:179], v[200:203], v[82:85]
	v_mfma_f32_16x16x32_bf16 v[82:85], v[172:175], v[196:199], v[82:85]
	v_mfma_f32_16x16x32_bf16 v[66:69], v[172:175], v[204:207], v[66:69]
	v_mfma_f32_16x16x32_bf16 v[66:69], v[176:179], v[208:211], v[66:69]
	s_setprio 2
	s_barrier
	v_mfma_f32_16x16x32_bf16 v[70:73], v[168:171], v[208:211], v[70:73]
	v_mfma_f32_16x16x32_bf16 v[70:73], v[164:167], v[204:207], v[70:73]
	s_setprio 0
	ds_read_b128 v[180:183], v145 offset:49152
	ds_read_b128 v[184:187], v145 offset:50176
	ds_read_b128 v[188:191], v145 offset:51200
	ds_read_b128 v[192:195], v145 offset:52224
	ds_read_b128 v[196:199], v145 offset:53248
	ds_read_b128 v[200:203], v145 offset:54272
	ds_read_b128 v[204:207], v145 offset:55296
	ds_read_b128 v[208:211], v145 offset:56320
	s_add_u32 s22, s20, 0x80
	s_addc_u32 s23, s21, 0
	s_mov_b32 s74, m0
	s_mov_b32 m0, s46
	s_nop 0
	global_load_lds_dwordx4 v139, s[22:23]
	s_mov_b32 m0, s74
	s_add_u32 s20, s20, 0x80080
	s_mov_b32 s74, m0
	s_mov_b32 m0, s47
	s_nop 0
	global_load_lds_dwordx4 v141, s[22:23]
	s_mov_b32 m0, s74
	s_addc_u32 s21, s21, 0
	s_mov_b32 s22, m0
	s_mov_b32 m0, s48
	s_nop 0
	global_load_lds_dwordx4 v139, s[20:21]
	s_mov_b32 m0, s22
	s_nop 0
	s_mov_b32 s22, m0
	s_mov_b32 m0, s49
	s_nop 0
	global_load_lds_dwordx4 v141, s[20:21]
	s_mov_b32 m0, s22
	s_waitcnt vmcnt(4)
	s_waitcnt lgkmcnt(0)
	s_barrier
	s_setprio 1
	s_waitcnt lgkmcnt(7)
	v_mfma_f32_16x16x32_bf16 v[62:65], v[148:151], v[180:183], v[62:65]
	v_mfma_f32_16x16x32_bf16 v[62:65], v[152:155], v[184:187], v[62:65]
	s_waitcnt lgkmcnt(5)
	v_mfma_f32_16x16x32_bf16 v[58:61], v[160:163], v[184:187], v[58:61]
	v_mfma_f32_16x16x32_bf16 v[58:61], v[156:159], v[180:183], v[58:61]
	s_waitcnt lgkmcnt(3)
	v_mfma_f32_16x16x32_bf16 v[42:45], v[156:159], v[188:191], v[42:45]
	v_mfma_f32_16x16x32_bf16 v[42:45], v[160:163], v[192:195], v[42:45]
	s_waitcnt lgkmcnt(1)
	v_mfma_f32_16x16x32_bf16 v[46:49], v[152:155], v[192:195], v[46:49]
	v_mfma_f32_16x16x32_bf16 v[46:49], v[148:151], v[188:191], v[46:49]
	v_mfma_f32_16x16x32_bf16 v[30:33], v[148:151], v[196:199], v[30:33]
	v_mfma_f32_16x16x32_bf16 v[30:33], v[152:155], v[200:203], v[30:33]
	v_mfma_f32_16x16x32_bf16 v[26:29], v[160:163], v[200:203], v[26:29]
	v_mfma_f32_16x16x32_bf16 v[26:29], v[156:159], v[196:199], v[26:29]
	v_mfma_f32_16x16x32_bf16 v[10:13], v[156:159], v[204:207], v[10:13]
	v_mfma_f32_16x16x32_bf16 v[10:13], v[160:163], v[208:211], v[10:13]
	s_waitcnt lgkmcnt(0)
	v_mfma_f32_16x16x32_bf16 v[14:17], v[152:155], v[208:211], v[14:17]
	v_mfma_f32_16x16x32_bf16 v[14:17], v[148:151], v[204:207], v[14:17]
	s_setprio 0
	s_setprio 1
	v_mfma_f32_16x16x32_bf16 v[54:57], v[164:167], v[180:183], v[54:57]
	v_mfma_f32_16x16x32_bf16 v[54:57], v[168:171], v[184:187], v[54:57]
	v_mfma_f32_16x16x32_bf16 v[50:53], v[176:179], v[184:187], v[50:53]
	v_mfma_f32_16x16x32_bf16 v[50:53], v[172:175], v[180:183], v[50:53]
	v_mfma_f32_16x16x32_bf16 v[34:37], v[172:175], v[188:191], v[34:37]
	v_mfma_f32_16x16x32_bf16 v[34:37], v[176:179], v[192:195], v[34:37]
	v_mfma_f32_16x16x32_bf16 v[38:41], v[168:171], v[192:195], v[38:41]
	v_mfma_f32_16x16x32_bf16 v[38:41], v[164:167], v[188:191], v[38:41]
	v_mfma_f32_16x16x32_bf16 v[22:25], v[164:167], v[196:199], v[22:25]
	v_mfma_f32_16x16x32_bf16 v[22:25], v[168:171], v[200:203], v[22:25]
	v_mfma_f32_16x16x32_bf16 v[18:21], v[176:179], v[200:203], v[18:21]
	v_mfma_f32_16x16x32_bf16 v[18:21], v[172:175], v[196:199], v[18:21]
	v_mfma_f32_16x16x32_bf16 v[2:5], v[172:175], v[204:207], v[2:5]
	v_mfma_f32_16x16x32_bf16 v[2:5], v[176:179], v[208:211], v[2:5]
	s_setprio 2
	s_barrier
	v_mfma_f32_16x16x32_bf16 v[6:9], v[168:171], v[208:211], v[6:9]
	v_mfma_f32_16x16x32_bf16 v[6:9], v[164:167], v[204:207], v[6:9]
	s_setprio 0
	s_add_i32 s73, s73, 2
	s_add_u32 s66, s66, 0x100
	s_addc_u32 s67, s67, 0
	s_add_u32 s18, s18, 0x100
	s_addc_u32 s19, s19, 0
	s_add_u32 s70, s70, 0x100
	s_addc_u32 s71, s71, 0
	s_cmp_gt_u32 s73, 29
	s_cbranch_scc0 .LBB0_1785
	s_and_b64 vcc, exec, s[6:7]
	s_cbranch_vccz .LBB0_1788
	s_barrier

.LBB0_1951:
	s_ashr_i32 s13, s12, 31
	s_lshl_b64 s[14:15], s[12:13], 15
	s_add_u32 s14, s28, s14
	s_addc_u32 s15, s29, s15
	s_and_b64 s[16:17], s[2:3], exec
	s_cselect_b32 s13, s15, s23
	s_cselect_b32 s65, s14, s22
	s_ashr_i32 s11, s10, 31
	s_lshl_b64 s[16:17], s[10:11], 15
	s_add_u32 s16, s30, s16
	s_addc_u32 s17, s31, s17
	s_and_b64 s[24:25], s[2:3], exec
	s_cselect_b32 s11, s17, s21
	s_cselect_b32 s66, s16, s20
	s_add_u32 s67, s20, 0x80000
	s_addc_u32 s70, s21, 0
	s_add_u32 s20, s22, 0x204000
	s_addc_u32 s21, s23, 0
	s_add_u32 s71, s22, 0x400000
	s_addc_u32 s73, s23, 0
	s_mov_b32 s74, -2
	s_waitcnt vmcnt(25)
	s_waitcnt vmcnt(24)
	s_waitcnt vmcnt(4)
	s_waitcnt vmcnt(2)
	s_waitcnt vmcnt(1)
	s_waitcnt vmcnt(0)
	ds_read_b128 v[130:133], v181
	ds_read_b128 v[134:137], v181 offset:1024
	ds_read_b128 v[138:141], v181 offset:2048
	ds_read_b128 v[142:145], v181 offset:3072
	ds_read_b128 v[150:153], v182
	ds_read_b128 v[154:157], v182 offset:1024
	ds_read_b128 v[158:161], v182 offset:2048
	ds_read_b128 v[162:165], v182 offset:3072
	s_cmpk_eq_i32 s74, 0x52
	s_cselect_b32 s23, s11, s70
	s_cselect_b32 s22, s66, s67
	s_cselect_b32 s25, s13, s73
	s_cselect_b32 s24, s65, s71
	ds_read_b128 v[166:169], v183
	ds_read_b128 v[170:173], v183 offset:1024
	ds_read_b128 v[186:189], v183 offset:2048
	ds_read_b128 v[190:193], v183 offset:3072
	ds_read_b128 v[194:197], v183 offset:4096
	ds_read_b128 v[198:201], v183 offset:5120
	ds_read_b128 v[202:205], v183 offset:6144
	ds_read_b128 v[206:209], v183 offset:7168
	s_add_u32 s76, s20, 0xffffc000
	s_addc_u32 s77, s21, -1
	s_mov_b32 s75, m0
	s_mov_b32 m0, s58
	s_nop 0
	global_load_lds_dwordx4 v1, s[76:77]
	s_mov_b32 m0, s75
	s_nop 0
	s_mov_b32 s75, m0
	s_mov_b32 m0, s62
	s_nop 0
	global_load_lds_dwordx4 v177, s[76:77]
	s_mov_b32 m0, s75
	s_nop 0
	s_mov_b32 s75, m0
	s_mov_b32 m0, s59
	s_nop 0
	global_load_lds_dwordx4 v1, s[20:21]
	s_mov_b32 m0, s75
	s_nop 0
	s_mov_b32 s75, m0
	s_mov_b32 m0, s63
	s_nop 0
	global_load_lds_dwordx4 v177, s[20:21]
	s_mov_b32 m0, s75
	s_waitcnt vmcnt(8)
	s_waitcnt lgkmcnt(0)
	s_barrier
	s_setprio 1
	s_waitcnt lgkmcnt(7)
	v_mfma_f32_16x16x32_bf16 v[126:129], v[130:133], v[166:169], 0
	v_mfma_f32_16x16x32_bf16 v[126:129], v[134:137], v[170:173], v[126:129]
	s_waitcnt lgkmcnt(5)
	v_mfma_f32_16x16x32_bf16 v[122:125], v[142:145], v[170:173], 0
	v_mfma_f32_16x16x32_bf16 v[122:125], v[138:141], v[166:169], v[122:125]
	s_waitcnt lgkmcnt(3)
	v_mfma_f32_16x16x32_bf16 v[110:113], v[138:141], v[186:189], 0
	v_mfma_f32_16x16x32_bf16 v[110:113], v[142:145], v[190:193], v[110:113]
	s_waitcnt lgkmcnt(1)
	v_mfma_f32_16x16x32_bf16 v[118:121], v[134:137], v[190:193], 0
	v_mfma_f32_16x16x32_bf16 v[118:121], v[130:133], v[186:189], v[118:121]
	v_mfma_f32_16x16x32_bf16 v[94:97], v[130:133], v[194:197], 0
	v_mfma_f32_16x16x32_bf16 v[94:97], v[134:137], v[198:201], v[94:97]
	v_mfma_f32_16x16x32_bf16 v[90:93], v[142:145], v[198:201], 0
	v_mfma_f32_16x16x32_bf16 v[90:93], v[138:141], v[194:197], v[90:93]
	v_mfma_f32_16x16x32_bf16 v[78:81], v[138:141], v[202:205], 0
	v_mfma_f32_16x16x32_bf16 v[78:81], v[142:145], v[206:209], v[78:81]
	s_waitcnt lgkmcnt(0)
	v_mfma_f32_16x16x32_bf16 v[86:89], v[134:137], v[206:209], 0
	v_mfma_f32_16x16x32_bf16 v[86:89], v[130:133], v[202:205], v[86:89]
	s_setprio 0
	s_setprio 1
	v_mfma_f32_16x16x32_bf16 v[114:117], v[150:153], v[166:169], 0
	v_mfma_f32_16x16x32_bf16 v[114:117], v[154:157], v[170:173], v[114:117]
	v_mfma_f32_16x16x32_bf16 v[106:109], v[162:165], v[170:173], 0
	v_mfma_f32_16x16x32_bf16 v[106:109], v[158:161], v[166:169], v[106:109]
	v_mfma_f32_16x16x32_bf16 v[98:101], v[158:161], v[186:189], 0
	v_mfma_f32_16x16x32_bf16 v[98:101], v[162:165], v[190:193], v[98:101]
	v_mfma_f32_16x16x32_bf16 v[102:105], v[154:157], v[190:193], 0
	v_mfma_f32_16x16x32_bf16 v[102:105], v[150:153], v[186:189], v[102:105]
	v_mfma_f32_16x16x32_bf16 v[82:85], v[150:153], v[194:197], 0
	v_mfma_f32_16x16x32_bf16 v[82:85], v[154:157], v[198:201], v[82:85]
	v_mfma_f32_16x16x32_bf16 v[74:77], v[162:165], v[198:201], 0
	v_mfma_f32_16x16x32_bf16 v[74:77], v[158:161], v[194:197], v[74:77]
	v_mfma_f32_16x16x32_bf16 v[66:69], v[158:161], v[202:205], 0
	v_mfma_f32_16x16x32_bf16 v[66:69], v[162:165], v[206:209], v[66:69]
	s_setprio 2
	s_barrier
	v_mfma_f32_16x16x32_bf16 v[70:73], v[154:157], v[206:209], 0
	v_mfma_f32_16x16x32_bf16 v[70:73], v[150:153], v[202:205], v[70:73]
	s_setprio 0
	ds_read_b128 v[166:169], v183 offset:16384
	ds_read_b128 v[170:173], v183 offset:17408
	ds_read_b128 v[186:189], v183 offset:18432
	ds_read_b128 v[190:193], v183 offset:19456
	ds_read_b128 v[194:197], v183 offset:20480
	ds_read_b128 v[198:201], v183 offset:21504
	ds_read_b128 v[202:205], v183 offset:22528
	ds_read_b128 v[206:209], v183 offset:23552
	s_mov_b32 s75, m0
	s_mov_b32 m0, s35
	s_nop 0
	global_load_lds_dwordx4 v176, s[22:23]
	s_mov_b32 m0, s75
	s_add_u32 s76, s22, 0x4000
	s_mov_b32 s75, m0
	s_mov_b32 m0, s36
	s_nop 0
	global_load_lds_dwordx4 v178, s[22:23]
	s_mov_b32 m0, s75
	s_addc_u32 s77, s23, 0
	s_mov_b32 s75, m0
	s_mov_b32 m0, s37
	s_nop 0
	global_load_lds_dwordx4 v176, s[76:77]
	s_mov_b32 m0, s75
	s_nop 0
	s_mov_b32 s75, m0
	s_mov_b32 m0, s40
	s_nop 0
	global_load_lds_dwordx4 v178, s[76:77]
	s_mov_b32 m0, s75
	s_waitcnt vmcnt(4)
	s_waitcnt lgkmcnt(0)
	s_barrier
	s_setprio 1
	s_waitcnt lgkmcnt(7)
	v_mfma_f32_16x16x32_bf16 v[62:65], v[130:133], v[166:169], 0
	v_mfma_f32_16x16x32_bf16 v[62:65], v[134:137], v[170:173], v[62:65]
	s_waitcnt lgkmcnt(5)
	v_mfma_f32_16x16x32_bf16 v[58:61], v[142:145], v[170:173], 0
	v_mfma_f32_16x16x32_bf16 v[58:61], v[138:141], v[166:169], v[58:61]
	s_waitcnt lgkmcnt(3)
	v_mfma_f32_16x16x32_bf16 v[42:45], v[138:141], v[186:189], 0
	v_mfma_f32_16x16x32_bf16 v[42:45], v[142:145], v[190:193], v[42:45]
	s_waitcnt lgkmcnt(1)
	v_mfma_f32_16x16x32_bf16 v[46:49], v[134:137], v[190:193], 0
	v_mfma_f32_16x16x32_bf16 v[46:49], v[130:133], v[186:189], v[46:49]
	v_mfma_f32_16x16x32_bf16 v[30:33], v[130:133], v[194:197], 0
	v_mfma_f32_16x16x32_bf16 v[30:33], v[134:137], v[198:201], v[30:33]
	v_mfma_f32_16x16x32_bf16 v[26:29], v[142:145], v[198:201], 0
	v_mfma_f32_16x16x32_bf16 v[26:29], v[138:141], v[194:197], v[26:29]
	v_mfma_f32_16x16x32_bf16 v[10:13], v[138:141], v[202:205], 0
	v_mfma_f32_16x16x32_bf16 v[10:13], v[142:145], v[206:209], v[10:13]
	s_waitcnt lgkmcnt(0)
	v_mfma_f32_16x16x32_bf16 v[14:17], v[134:137], v[206:209], 0
	v_mfma_f32_16x16x32_bf16 v[14:17], v[130:133], v[202:205], v[14:17]
	s_setprio 0
	s_setprio 1
	v_mfma_f32_16x16x32_bf16 v[54:57], v[150:153], v[166:169], 0
	v_mfma_f32_16x16x32_bf16 v[54:57], v[154:157], v[170:173], v[54:57]
	v_mfma_f32_16x16x32_bf16 v[50:53], v[162:165], v[170:173], 0
	v_mfma_f32_16x16x32_bf16 v[50:53], v[158:161], v[166:169], v[50:53]
	v_mfma_f32_16x16x32_bf16 v[34:37], v[158:161], v[186:189], 0
	v_mfma_f32_16x16x32_bf16 v[34:37], v[162:165], v[190:193], v[34:37]
	v_mfma_f32_16x16x32_bf16 v[38:41], v[154:157], v[190:193], 0
	v_mfma_f32_16x16x32_bf16 v[38:41], v[150:153], v[186:189], v[38:41]
	v_mfma_f32_16x16x32_bf16 v[22:25], v[150:153], v[194:197], 0
	v_mfma_f32_16x16x32_bf16 v[22:25], v[154:157], v[198:201], v[22:25]
	v_mfma_f32_16x16x32_bf16 v[18:21], v[162:165], v[198:201], 0
	v_mfma_f32_16x16x32_bf16 v[18:21], v[158:161], v[194:197], v[18:21]
	v_mfma_f32_16x16x32_bf16 v[2:5], v[158:161], v[202:205], 0
	v_mfma_f32_16x16x32_bf16 v[2:5], v[162:165], v[206:209], v[2:5]
	s_setprio 2
	s_barrier
	v_mfma_f32_16x16x32_bf16 v[6:9], v[154:157], v[206:209], 0
	v_mfma_f32_16x16x32_bf16 v[6:9], v[150:153], v[202:205], v[6:9]
	s_setprio 0
	ds_read_b128 v[130:133], v184
	ds_read_b128 v[134:137], v184 offset:1024
	ds_read_b128 v[138:141], v184 offset:2048
	ds_read_b128 v[142:145], v184 offset:3072
	ds_read_b128 v[150:153], v185
	ds_read_b128 v[154:157], v185 offset:1024
	ds_read_b128 v[158:161], v185 offset:2048
	ds_read_b128 v[162:165], v185 offset:3072
	ds_read_b128 v[166:169], v183 offset:32768
	ds_read_b128 v[170:173], v183 offset:33792
	ds_read_b128 v[186:189], v183 offset:34816
	ds_read_b128 v[190:193], v183 offset:35840
	ds_read_b128 v[194:197], v183 offset:36864
	ds_read_b128 v[198:201], v183 offset:37888
	ds_read_b128 v[202:205], v183 offset:38912
	ds_read_b128 v[206:209], v183 offset:39936
	s_mov_b32 s75, m0
	s_mov_b32 m0, s34
	s_nop 0
	global_load_lds_dwordx4 v1, s[24:25]
	s_mov_b32 m0, s75
	s_nop 0
	s_mov_b32 s75, m0
	s_mov_b32 m0, s41
	s_nop 0
	global_load_lds_dwordx4 v177, s[24:25]
	s_mov_b32 m0, s75
	s_add_u32 s24, s24, 0x4000
	s_addc_u32 s25, s25, 0
	s_mov_b32 s75, m0
	s_mov_b32 m0, s42
	s_nop 0
	global_load_lds_dwordx4 v1, s[24:25]
	s_mov_b32 m0, s75
	s_nop 0
	s_mov_b32 s75, m0
	s_mov_b32 m0, s43
	s_nop 0
	global_load_lds_dwordx4 v177, s[24:25]
	s_mov_b32 m0, s75
	s_waitcnt vmcnt(8)
	s_waitcnt lgkmcnt(0)
	s_barrier
	s_setprio 1
	s_waitcnt lgkmcnt(7)
	v_mfma_f32_16x16x32_bf16 v[126:129], v[130:133], v[166:169], v[126:129]
	v_mfma_f32_16x16x32_bf16 v[126:129], v[134:137], v[170:173], v[126:129]
	s_waitcnt lgkmcnt(5)
	v_mfma_f32_16x16x32_bf16 v[122:125], v[142:145], v[170:173], v[122:125]
	v_mfma_f32_16x16x32_bf16 v[122:125], v[138:141], v[166:169], v[122:125]
	s_waitcnt lgkmcnt(3)
	v_mfma_f32_16x16x32_bf16 v[110:113], v[138:141], v[186:189], v[110:113]
	v_mfma_f32_16x16x32_bf16 v[110:113], v[142:145], v[190:193], v[110:113]
	s_waitcnt lgkmcnt(1)
	v_mfma_f32_16x16x32_bf16 v[118:121], v[134:137], v[190:193], v[118:121]
	v_mfma_f32_16x16x32_bf16 v[118:121], v[130:133], v[186:189], v[118:121]
	v_mfma_f32_16x16x32_bf16 v[94:97], v[130:133], v[194:197], v[94:97]
	v_mfma_f32_16x16x32_bf16 v[94:97], v[134:137], v[198:201], v[94:97]
	v_mfma_f32_16x16x32_bf16 v[90:93], v[142:145], v[198:201], v[90:93]
	v_mfma_f32_16x16x32_bf16 v[90:93], v[138:141], v[194:197], v[90:93]
	v_mfma_f32_16x16x32_bf16 v[78:81], v[138:141], v[202:205], v[78:81]
	v_mfma_f32_16x16x32_bf16 v[78:81], v[142:145], v[206:209], v[78:81]
	s_waitcnt lgkmcnt(0)
	v_mfma_f32_16x16x32_bf16 v[86:89], v[134:137], v[206:209], v[86:89]
	v_mfma_f32_16x16x32_bf16 v[86:89], v[130:133], v[202:205], v[86:89]
	s_setprio 0
	s_setprio 1
	v_mfma_f32_16x16x32_bf16 v[114:117], v[150:153], v[166:169], v[114:117]
	v_mfma_f32_16x16x32_bf16 v[114:117], v[154:157], v[170:173], v[114:117]
	v_mfma_f32_16x16x32_bf16 v[106:109], v[162:165], v[170:173], v[106:109]
	v_mfma_f32_16x16x32_bf16 v[106:109], v[158:161], v[166:169], v[106:109]
	v_mfma_f32_16x16x32_bf16 v[98:101], v[158:161], v[186:189], v[98:101]
	v_mfma_f32_16x16x32_bf16 v[98:101], v[162:165], v[190:193], v[98:101]
	v_mfma_f32_16x16x32_bf16 v[102:105], v[154:157], v[190:193], v[102:105]
	v_mfma_f32_16x16x32_bf16 v[102:105], v[150:153], v[186:189], v[102:105]
	v_mfma_f32_16x16x32_bf16 v[82:85], v[150:153], v[194:197], v[82:85]
	v_mfma_f32_16x16x32_bf16 v[82:85], v[154:157], v[198:201], v[82:85]
	v_mfma_f32_16x16x32_bf16 v[74:77], v[162:165], v[198:201], v[74:77]
	v_mfma_f32_16x16x32_bf16 v[74:77], v[158:161], v[194:197], v[74:77]
	v_mfma_f32_16x16x32_bf16 v[66:69], v[158:161], v[202:205], v[66:69]
	v_mfma_f32_16x16x32_bf16 v[66:69], v[162:165], v[206:209], v[66:69]
	s_setprio 2
	s_barrier
	v_mfma_f32_16x16x32_bf16 v[70:73], v[154:157], v[206:209], v[70:73]
	v_mfma_f32_16x16x32_bf16 v[70:73], v[150:153], v[202:205], v[70:73]
	s_setprio 0
	ds_read_b128 v[166:169], v183 offset:49152
	ds_read_b128 v[170:173], v183 offset:50176
	ds_read_b128 v[186:189], v183 offset:51200
	ds_read_b128 v[190:193], v183 offset:52224
	ds_read_b128 v[194:197], v183 offset:53248
	ds_read_b128 v[198:201], v183 offset:54272
	ds_read_b128 v[202:205], v183 offset:55296
	ds_read_b128 v[206:209], v183 offset:56320
	s_add_u32 s24, s22, 0x40000
	s_addc_u32 s25, s23, 0
	s_mov_b32 s75, m0
	s_mov_b32 m0, s46
	s_nop 0
	global_load_lds_dwordx4 v176, s[24:25]
	s_mov_b32 m0, s75
	s_add_u32 s22, s22, 0x44000
	s_mov_b32 s75, m0
	s_mov_b32 m0, s47
	s_nop 0
	global_load_lds_dwordx4 v178, s[24:25]
	s_mov_b32 m0, s75
	s_addc_u32 s23, s23, 0
	s_mov_b32 s24, m0
	s_mov_b32 m0, s48
	s_nop 0
	global_load_lds_dwordx4 v176, s[22:23]
	s_mov_b32 m0, s24
	s_nop 0
	s_mov_b32 s24, m0
	s_mov_b32 m0, s49
	s_nop 0
	global_load_lds_dwordx4 v178, s[22:23]
	s_mov_b32 m0, s24
	s_waitcnt vmcnt(4)
	s_waitcnt lgkmcnt(0)
	s_barrier
	s_setprio 1
	s_waitcnt lgkmcnt(7)
	v_mfma_f32_16x16x32_bf16 v[62:65], v[130:133], v[166:169], v[62:65]
	v_mfma_f32_16x16x32_bf16 v[62:65], v[134:137], v[170:173], v[62:65]
	s_waitcnt lgkmcnt(5)
	v_mfma_f32_16x16x32_bf16 v[58:61], v[142:145], v[170:173], v[58:61]
	v_mfma_f32_16x16x32_bf16 v[58:61], v[138:141], v[166:169], v[58:61]
	s_waitcnt lgkmcnt(3)
	v_mfma_f32_16x16x32_bf16 v[42:45], v[138:141], v[186:189], v[42:45]
	v_mfma_f32_16x16x32_bf16 v[42:45], v[142:145], v[190:193], v[42:45]
	s_waitcnt lgkmcnt(1)
	v_mfma_f32_16x16x32_bf16 v[46:49], v[134:137], v[190:193], v[46:49]
	v_mfma_f32_16x16x32_bf16 v[46:49], v[130:133], v[186:189], v[46:49]
	v_mfma_f32_16x16x32_bf16 v[30:33], v[130:133], v[194:197], v[30:33]
	v_mfma_f32_16x16x32_bf16 v[30:33], v[134:137], v[198:201], v[30:33]
	v_mfma_f32_16x16x32_bf16 v[26:29], v[142:145], v[198:201], v[26:29]
	v_mfma_f32_16x16x32_bf16 v[26:29], v[138:141], v[194:197], v[26:29]
	v_mfma_f32_16x16x32_bf16 v[10:13], v[138:141], v[202:205], v[10:13]
	v_mfma_f32_16x16x32_bf16 v[10:13], v[142:145], v[206:209], v[10:13]
	s_waitcnt lgkmcnt(0)
	v_mfma_f32_16x16x32_bf16 v[14:17], v[134:137], v[206:209], v[14:17]
	v_mfma_f32_16x16x32_bf16 v[14:17], v[130:133], v[202:205], v[14:17]
	s_setprio 0
	s_setprio 1
	v_mfma_f32_16x16x32_bf16 v[54:57], v[150:153], v[166:169], v[54:57]
	v_mfma_f32_16x16x32_bf16 v[54:57], v[154:157], v[170:173], v[54:57]
	v_mfma_f32_16x16x32_bf16 v[50:53], v[162:165], v[170:173], v[50:53]
	v_mfma_f32_16x16x32_bf16 v[50:53], v[158:161], v[166:169], v[50:53]
	v_mfma_f32_16x16x32_bf16 v[34:37], v[158:161], v[186:189], v[34:37]
	v_mfma_f32_16x16x32_bf16 v[34:37], v[162:165], v[190:193], v[34:37]
	v_mfma_f32_16x16x32_bf16 v[38:41], v[154:157], v[190:193], v[38:41]
	v_mfma_f32_16x16x32_bf16 v[38:41], v[150:153], v[186:189], v[38:41]
	v_mfma_f32_16x16x32_bf16 v[22:25], v[150:153], v[194:197], v[22:25]
	v_mfma_f32_16x16x32_bf16 v[22:25], v[154:157], v[198:201], v[22:25]
	v_mfma_f32_16x16x32_bf16 v[18:21], v[162:165], v[198:201], v[18:21]
	v_mfma_f32_16x16x32_bf16 v[18:21], v[158:161], v[194:197], v[18:21]
	v_mfma_f32_16x16x32_bf16 v[2:5], v[158:161], v[202:205], v[2:5]
	v_mfma_f32_16x16x32_bf16 v[2:5], v[162:165], v[206:209], v[2:5]
	s_setprio 2
	s_barrier
	v_mfma_f32_16x16x32_bf16 v[6:9], v[154:157], v[206:209], v[6:9]
	v_mfma_f32_16x16x32_bf16 v[6:9], v[150:153], v[202:205], v[6:9]
	s_setprio 0
	s_add_i32 s74, s74, 2
	s_add_u32 s67, s67, 0x80000
	s_addc_u32 s70, s70, 0
	s_add_u32 s20, s20, 0x400000
	s_addc_u32 s21, s21, 0
	s_add_u32 s71, s71, 0x400000
	s_addc_u32 s73, s73, 0
	s_cmpk_gt_u32 s74, 0x53
	.p2align 6
.LBB0_1952:
	ds_read_b128 v[130:133], v181
	ds_read_b128 v[134:137], v181 offset:1024
	ds_read_b128 v[138:141], v181 offset:2048
	ds_read_b128 v[142:145], v181 offset:3072
	ds_read_b128 v[150:153], v182
	ds_read_b128 v[154:157], v182 offset:1024
	ds_read_b128 v[158:161], v182 offset:2048
	ds_read_b128 v[162:165], v182 offset:3072
	s_cmpk_eq_i32 s74, 0x52
	s_cselect_b32 s23, s11, s70
	s_cselect_b32 s22, s66, s67
	s_cselect_b32 s25, s13, s73
	s_cselect_b32 s24, s65, s71
	ds_read_b128 v[166:169], v183
	ds_read_b128 v[170:173], v183 offset:1024
	ds_read_b128 v[186:189], v183 offset:2048
	ds_read_b128 v[190:193], v183 offset:3072
	ds_read_b128 v[194:197], v183 offset:4096
	ds_read_b128 v[198:201], v183 offset:5120
	ds_read_b128 v[202:205], v183 offset:6144
	ds_read_b128 v[206:209], v183 offset:7168
	s_add_u32 s76, s20, 0xffffc000
	s_addc_u32 s77, s21, -1
	s_mov_b32 s75, m0
	s_mov_b32 m0, s58
	s_nop 0
	global_load_lds_dwordx4 v1, s[76:77]
	s_mov_b32 m0, s75
	s_nop 0
	s_mov_b32 s75, m0
	s_mov_b32 m0, s62
	s_nop 0
	global_load_lds_dwordx4 v177, s[76:77]
	s_mov_b32 m0, s75
	s_nop 0
	s_mov_b32 s75, m0
	s_mov_b32 m0, s59
	s_nop 0
	global_load_lds_dwordx4 v1, s[20:21]
	s_mov_b32 m0, s75
	s_nop 0
	s_mov_b32 s75, m0
	s_mov_b32 m0, s63
	s_nop 0
	global_load_lds_dwordx4 v177, s[20:21]
	s_mov_b32 m0, s75
	s_waitcnt vmcnt(8)
	s_waitcnt lgkmcnt(0)
	s_barrier
	s_setprio 1
	s_waitcnt lgkmcnt(7)
	v_mfma_f32_16x16x32_bf16 v[126:129], v[130:133], v[166:169], v[126:129]
	v_mfma_f32_16x16x32_bf16 v[126:129], v[134:137], v[170:173], v[126:129]
	s_waitcnt lgkmcnt(5)
	v_mfma_f32_16x16x32_bf16 v[122:125], v[142:145], v[170:173], v[122:125]
	v_mfma_f32_16x16x32_bf16 v[122:125], v[138:141], v[166:169], v[122:125]
	s_waitcnt lgkmcnt(3)
	v_mfma_f32_16x16x32_bf16 v[110:113], v[138:141], v[186:189], v[110:113]
	v_mfma_f32_16x16x32_bf16 v[110:113], v[142:145], v[190:193], v[110:113]
	s_waitcnt lgkmcnt(1)
	v_mfma_f32_16x16x32_bf16 v[118:121], v[134:137], v[190:193], v[118:121]
	v_mfma_f32_16x16x32_bf16 v[118:121], v[130:133], v[186:189], v[118:121]
	v_mfma_f32_16x16x32_bf16 v[94:97], v[130:133], v[194:197], v[94:97]
	v_mfma_f32_16x16x32_bf16 v[94:97], v[134:137], v[198:201], v[94:97]
	v_mfma_f32_16x16x32_bf16 v[90:93], v[142:145], v[198:201], v[90:93]
	v_mfma_f32_16x16x32_bf16 v[90:93], v[138:141], v[194:197], v[90:93]
	v_mfma_f32_16x16x32_bf16 v[78:81], v[138:141], v[202:205], v[78:81]
	v_mfma_f32_16x16x32_bf16 v[78:81], v[142:145], v[206:209], v[78:81]
	s_waitcnt lgkmcnt(0)
	v_mfma_f32_16x16x32_bf16 v[86:89], v[134:137], v[206:209], v[86:89]
	v_mfma_f32_16x16x32_bf16 v[86:89], v[130:133], v[202:205], v[86:89]
	s_setprio 0
	s_setprio 1
	v_mfma_f32_16x16x32_bf16 v[114:117], v[150:153], v[166:169], v[114:117]
	v_mfma_f32_16x16x32_bf16 v[114:117], v[154:157], v[170:173], v[114:117]
	v_mfma_f32_16x16x32_bf16 v[106:109], v[162:165], v[170:173], v[106:109]
	v_mfma_f32_16x16x32_bf16 v[106:109], v[158:161], v[166:169], v[106:109]
	v_mfma_f32_16x16x32_bf16 v[98:101], v[158:161], v[186:189], v[98:101]
	v_mfma_f32_16x16x32_bf16 v[98:101], v[162:165], v[190:193], v[98:101]
	v_mfma_f32_16x16x32_bf16 v[102:105], v[154:157], v[190:193], v[102:105]
	v_mfma_f32_16x16x32_bf16 v[102:105], v[150:153], v[186:189], v[102:105]
	v_mfma_f32_16x16x32_bf16 v[82:85], v[150:153], v[194:197], v[82:85]
	v_mfma_f32_16x16x32_bf16 v[82:85], v[154:157], v[198:201], v[82:85]
	v_mfma_f32_16x16x32_bf16 v[74:77], v[162:165], v[198:201], v[74:77]
	v_mfma_f32_16x16x32_bf16 v[74:77], v[158:161], v[194:197], v[74:77]
	v_mfma_f32_16x16x32_bf16 v[66:69], v[158:161], v[202:205], v[66:69]
	v_mfma_f32_16x16x32_bf16 v[66:69], v[162:165], v[206:209], v[66:69]
	s_setprio 2
	s_barrier
	v_mfma_f32_16x16x32_bf16 v[70:73], v[154:157], v[206:209], v[70:73]
	v_mfma_f32_16x16x32_bf16 v[70:73], v[150:153], v[202:205], v[70:73]
	s_setprio 0
	ds_read_b128 v[166:169], v183 offset:16384
	ds_read_b128 v[170:173], v183 offset:17408
	ds_read_b128 v[186:189], v183 offset:18432
	ds_read_b128 v[190:193], v183 offset:19456
	ds_read_b128 v[194:197], v183 offset:20480
	ds_read_b128 v[198:201], v183 offset:21504
	ds_read_b128 v[202:205], v183 offset:22528
	ds_read_b128 v[206:209], v183 offset:23552
	s_mov_b32 s75, m0
	s_mov_b32 m0, s35
	s_nop 0
	global_load_lds_dwordx4 v176, s[22:23]
	s_mov_b32 m0, s75
	s_add_u32 s76, s22, 0x4000
	s_mov_b32 s75, m0
	s_mov_b32 m0, s36
	s_nop 0
	global_load_lds_dwordx4 v178, s[22:23]
	s_mov_b32 m0, s75
	s_addc_u32 s77, s23, 0
	s_mov_b32 s75, m0
	s_mov_b32 m0, s37
	s_nop 0
	global_load_lds_dwordx4 v176, s[76:77]
	s_mov_b32 m0, s75
	s_nop 0
	s_mov_b32 s75, m0
	s_mov_b32 m0, s40
	s_nop 0
	global_load_lds_dwordx4 v178, s[76:77]
	s_mov_b32 m0, s75
	s_waitcnt vmcnt(4)
	s_waitcnt lgkmcnt(0)
	s_barrier
	s_setprio 1
	s_waitcnt lgkmcnt(7)
	v_mfma_f32_16x16x32_bf16 v[62:65], v[130:133], v[166:169], v[62:65]
	v_mfma_f32_16x16x32_bf16 v[62:65], v[134:137], v[170:173], v[62:65]
	s_waitcnt lgkmcnt(5)
	v_mfma_f32_16x16x32_bf16 v[58:61], v[142:145], v[170:173], v[58:61]
	v_mfma_f32_16x16x32_bf16 v[58:61], v[138:141], v[166:169], v[58:61]
	s_waitcnt lgkmcnt(3)
	v_mfma_f32_16x16x32_bf16 v[42:45], v[138:141], v[186:189], v[42:45]
	v_mfma_f32_16x16x32_bf16 v[42:45], v[142:145], v[190:193], v[42:45]
	s_waitcnt lgkmcnt(1)
	v_mfma_f32_16x16x32_bf16 v[46:49], v[134:137], v[190:193], v[46:49]
	v_mfma_f32_16x16x32_bf16 v[46:49], v[130:133], v[186:189], v[46:49]
	v_mfma_f32_16x16x32_bf16 v[30:33], v[130:133], v[194:197], v[30:33]
	v_mfma_f32_16x16x32_bf16 v[30:33], v[134:137], v[198:201], v[30:33]
	v_mfma_f32_16x16x32_bf16 v[26:29], v[142:145], v[198:201], v[26:29]
	v_mfma_f32_16x16x32_bf16 v[26:29], v[138:141], v[194:197], v[26:29]
	v_mfma_f32_16x16x32_bf16 v[10:13], v[138:141], v[202:205], v[10:13]
	v_mfma_f32_16x16x32_bf16 v[10:13], v[142:145], v[206:209], v[10:13]
	s_waitcnt lgkmcnt(0)
	v_mfma_f32_16x16x32_bf16 v[14:17], v[134:137], v[206:209], v[14:17]
	v_mfma_f32_16x16x32_bf16 v[14:17], v[130:133], v[202:205], v[14:17]
	s_setprio 0
	s_setprio 1
	v_mfma_f32_16x16x32_bf16 v[54:57], v[150:153], v[166:169], v[54:57]
	v_mfma_f32_16x16x32_bf16 v[54:57], v[154:157], v[170:173], v[54:57]
	v_mfma_f32_16x16x32_bf16 v[50:53], v[162:165], v[170:173], v[50:53]
	v_mfma_f32_16x16x32_bf16 v[50:53], v[158:161], v[166:169], v[50:53]
	v_mfma_f32_16x16x32_bf16 v[34:37], v[158:161], v[186:189], v[34:37]
	v_mfma_f32_16x16x32_bf16 v[34:37], v[162:165], v[190:193], v[34:37]
	v_mfma_f32_16x16x32_bf16 v[38:41], v[154:157], v[190:193], v[38:41]
	v_mfma_f32_16x16x32_bf16 v[38:41], v[150:153], v[186:189], v[38:41]
	v_mfma_f32_16x16x32_bf16 v[22:25], v[150:153], v[194:197], v[22:25]
	v_mfma_f32_16x16x32_bf16 v[22:25], v[154:157], v[198:201], v[22:25]
	v_mfma_f32_16x16x32_bf16 v[18:21], v[162:165], v[198:201], v[18:21]
	v_mfma_f32_16x16x32_bf16 v[18:21], v[158:161], v[194:197], v[18:21]
	v_mfma_f32_16x16x32_bf16 v[2:5], v[158:161], v[202:205], v[2:5]
	v_mfma_f32_16x16x32_bf16 v[2:5], v[162:165], v[206:209], v[2:5]
	s_setprio 2
	s_barrier
	v_mfma_f32_16x16x32_bf16 v[6:9], v[154:157], v[206:209], v[6:9]
	v_mfma_f32_16x16x32_bf16 v[6:9], v[150:153], v[202:205], v[6:9]
	s_setprio 0
	ds_read_b128 v[130:133], v184
	ds_read_b128 v[134:137], v184 offset:1024
	ds_read_b128 v[138:141], v184 offset:2048
	ds_read_b128 v[142:145], v184 offset:3072
	ds_read_b128 v[150:153], v185
	ds_read_b128 v[154:157], v185 offset:1024
	ds_read_b128 v[158:161], v185 offset:2048
	ds_read_b128 v[162:165], v185 offset:3072
	ds_read_b128 v[166:169], v183 offset:32768
	ds_read_b128 v[170:173], v183 offset:33792
	ds_read_b128 v[186:189], v183 offset:34816
	ds_read_b128 v[190:193], v183 offset:35840
	ds_read_b128 v[194:197], v183 offset:36864
	ds_read_b128 v[198:201], v183 offset:37888
	ds_read_b128 v[202:205], v183 offset:38912
	ds_read_b128 v[206:209], v183 offset:39936
	s_mov_b32 s75, m0
	s_mov_b32 m0, s34
	s_nop 0
	global_load_lds_dwordx4 v1, s[24:25]
	s_mov_b32 m0, s75
	s_nop 0
	s_mov_b32 s75, m0
	s_mov_b32 m0, s41
	s_nop 0
	global_load_lds_dwordx4 v177, s[24:25]
	s_mov_b32 m0, s75
	s_add_u32 s24, s24, 0x4000
	s_addc_u32 s25, s25, 0
	s_mov_b32 s75, m0
	s_mov_b32 m0, s42
	s_nop 0
	global_load_lds_dwordx4 v1, s[24:25]
	s_mov_b32 m0, s75
	s_nop 0
	s_mov_b32 s75, m0
	s_mov_b32 m0, s43
	s_nop 0
	global_load_lds_dwordx4 v177, s[24:25]
	s_mov_b32 m0, s75
	s_waitcnt vmcnt(8)
	s_waitcnt lgkmcnt(0)
	s_barrier
	s_setprio 1
	s_waitcnt lgkmcnt(7)
	v_mfma_f32_16x16x32_bf16 v[126:129], v[130:133], v[166:169], v[126:129]
	v_mfma_f32_16x16x32_bf16 v[126:129], v[134:137], v[170:173], v[126:129]
	s_waitcnt lgkmcnt(5)
	v_mfma_f32_16x16x32_bf16 v[122:125], v[142:145], v[170:173], v[122:125]
	v_mfma_f32_16x16x32_bf16 v[122:125], v[138:141], v[166:169], v[122:125]
	s_waitcnt lgkmcnt(3)
	v_mfma_f32_16x16x32_bf16 v[110:113], v[138:141], v[186:189], v[110:113]
	v_mfma_f32_16x16x32_bf16 v[110:113], v[142:145], v[190:193], v[110:113]
	s_waitcnt lgkmcnt(1)
	v_mfma_f32_16x16x32_bf16 v[118:121], v[134:137], v[190:193], v[118:121]
	v_mfma_f32_16x16x32_bf16 v[118:121], v[130:133], v[186:189], v[118:121]
	v_mfma_f32_16x16x32_bf16 v[94:97], v[130:133], v[194:197], v[94:97]
	v_mfma_f32_16x16x32_bf16 v[94:97], v[134:137], v[198:201], v[94:97]
	v_mfma_f32_16x16x32_bf16 v[90:93], v[142:145], v[198:201], v[90:93]
	v_mfma_f32_16x16x32_bf16 v[90:93], v[138:141], v[194:197], v[90:93]
	v_mfma_f32_16x16x32_bf16 v[78:81], v[138:141], v[202:205], v[78:81]
	v_mfma_f32_16x16x32_bf16 v[78:81], v[142:145], v[206:209], v[78:81]
	s_waitcnt lgkmcnt(0)
	v_mfma_f32_16x16x32_bf16 v[86:89], v[134:137], v[206:209], v[86:89]
	v_mfma_f32_16x16x32_bf16 v[86:89], v[130:133], v[202:205], v[86:89]
	s_setprio 0
	s_setprio 1
	v_mfma_f32_16x16x32_bf16 v[114:117], v[150:153], v[166:169], v[114:117]
	v_mfma_f32_16x16x32_bf16 v[114:117], v[154:157], v[170:173], v[114:117]
	v_mfma_f32_16x16x32_bf16 v[106:109], v[162:165], v[170:173], v[106:109]
	v_mfma_f32_16x16x32_bf16 v[106:109], v[158:161], v[166:169], v[106:109]
	v_mfma_f32_16x16x32_bf16 v[98:101], v[158:161], v[186:189], v[98:101]
	v_mfma_f32_16x16x32_bf16 v[98:101], v[162:165], v[190:193], v[98:101]
	v_mfma_f32_16x16x32_bf16 v[102:105], v[154:157], v[190:193], v[102:105]
	v_mfma_f32_16x16x32_bf16 v[102:105], v[150:153], v[186:189], v[102:105]
	v_mfma_f32_16x16x32_bf16 v[82:85], v[150:153], v[194:197], v[82:85]
	v_mfma_f32_16x16x32_bf16 v[82:85], v[154:157], v[198:201], v[82:85]
	v_mfma_f32_16x16x32_bf16 v[74:77], v[162:165], v[198:201], v[74:77]
	v_mfma_f32_16x16x32_bf16 v[74:77], v[158:161], v[194:197], v[74:77]
	v_mfma_f32_16x16x32_bf16 v[66:69], v[158:161], v[202:205], v[66:69]
	v_mfma_f32_16x16x32_bf16 v[66:69], v[162:165], v[206:209], v[66:69]
	s_setprio 2
	s_barrier
	v_mfma_f32_16x16x32_bf16 v[70:73], v[154:157], v[206:209], v[70:73]
	v_mfma_f32_16x16x32_bf16 v[70:73], v[150:153], v[202:205], v[70:73]
	s_setprio 0
	ds_read_b128 v[166:169], v183 offset:49152
	ds_read_b128 v[170:173], v183 offset:50176
	ds_read_b128 v[186:189], v183 offset:51200
	ds_read_b128 v[190:193], v183 offset:52224
	ds_read_b128 v[194:197], v183 offset:53248
	ds_read_b128 v[198:201], v183 offset:54272
	ds_read_b128 v[202:205], v183 offset:55296
	ds_read_b128 v[206:209], v183 offset:56320
	s_add_u32 s24, s22, 0x40000
	s_addc_u32 s25, s23, 0
	s_mov_b32 s75, m0
	s_mov_b32 m0, s46
	s_nop 0
	global_load_lds_dwordx4 v176, s[24:25]
	s_mov_b32 m0, s75
	s_add_u32 s22, s22, 0x44000
	s_mov_b32 s75, m0
	s_mov_b32 m0, s47
	s_nop 0
	global_load_lds_dwordx4 v178, s[24:25]
	s_mov_b32 m0, s75
	s_addc_u32 s23, s23, 0
	s_mov_b32 s24, m0
	s_mov_b32 m0, s48
	s_nop 0
	global_load_lds_dwordx4 v176, s[22:23]
	s_mov_b32 m0, s24
	s_nop 0
	s_mov_b32 s24, m0
	s_mov_b32 m0, s49
	s_nop 0
	global_load_lds_dwordx4 v178, s[22:23]
	s_mov_b32 m0, s24
	s_waitcnt vmcnt(4)
	s_waitcnt lgkmcnt(0)
	s_barrier
	s_setprio 1
	s_waitcnt lgkmcnt(7)
	v_mfma_f32_16x16x32_bf16 v[62:65], v[130:133], v[166:169], v[62:65]
	v_mfma_f32_16x16x32_bf16 v[62:65], v[134:137], v[170:173], v[62:65]
	s_waitcnt lgkmcnt(5)
	v_mfma_f32_16x16x32_bf16 v[58:61], v[142:145], v[170:173], v[58:61]
	v_mfma_f32_16x16x32_bf16 v[58:61], v[138:141], v[166:169], v[58:61]
	s_waitcnt lgkmcnt(3)
	v_mfma_f32_16x16x32_bf16 v[42:45], v[138:141], v[186:189], v[42:45]
	v_mfma_f32_16x16x32_bf16 v[42:45], v[142:145], v[190:193], v[42:45]
	s_waitcnt lgkmcnt(1)
	v_mfma_f32_16x16x32_bf16 v[46:49], v[134:137], v[190:193], v[46:49]
	v_mfma_f32_16x16x32_bf16 v[46:49], v[130:133], v[186:189], v[46:49]
	v_mfma_f32_16x16x32_bf16 v[30:33], v[130:133], v[194:197], v[30:33]
	v_mfma_f32_16x16x32_bf16 v[30:33], v[134:137], v[198:201], v[30:33]
	v_mfma_f32_16x16x32_bf16 v[26:29], v[142:145], v[198:201], v[26:29]
	v_mfma_f32_16x16x32_bf16 v[26:29], v[138:141], v[194:197], v[26:29]
	v_mfma_f32_16x16x32_bf16 v[10:13], v[138:141], v[202:205], v[10:13]
	v_mfma_f32_16x16x32_bf16 v[10:13], v[142:145], v[206:209], v[10:13]
	s_waitcnt lgkmcnt(0)
	v_mfma_f32_16x16x32_bf16 v[14:17], v[134:137], v[206:209], v[14:17]
	v_mfma_f32_16x16x32_bf16 v[14:17], v[130:133], v[202:205], v[14:17]
	s_setprio 0
	s_setprio 1
	v_mfma_f32_16x16x32_bf16 v[54:57], v[150:153], v[166:169], v[54:57]
	v_mfma_f32_16x16x32_bf16 v[54:57], v[154:157], v[170:173], v[54:57]
	v_mfma_f32_16x16x32_bf16 v[50:53], v[162:165], v[170:173], v[50:53]
	v_mfma_f32_16x16x32_bf16 v[50:53], v[158:161], v[166:169], v[50:53]
	v_mfma_f32_16x16x32_bf16 v[34:37], v[158:161], v[186:189], v[34:37]
	v_mfma_f32_16x16x32_bf16 v[34:37], v[162:165], v[190:193], v[34:37]
	v_mfma_f32_16x16x32_bf16 v[38:41], v[154:157], v[190:193], v[38:41]
	v_mfma_f32_16x16x32_bf16 v[38:41], v[150:153], v[186:189], v[38:41]
	v_mfma_f32_16x16x32_bf16 v[22:25], v[150:153], v[194:197], v[22:25]
	v_mfma_f32_16x16x32_bf16 v[22:25], v[154:157], v[198:201], v[22:25]
	v_mfma_f32_16x16x32_bf16 v[18:21], v[162:165], v[198:201], v[18:21]
	v_mfma_f32_16x16x32_bf16 v[18:21], v[158:161], v[194:197], v[18:21]
	v_mfma_f32_16x16x32_bf16 v[2:5], v[158:161], v[202:205], v[2:5]
	v_mfma_f32_16x16x32_bf16 v[2:5], v[162:165], v[206:209], v[2:5]
	s_setprio 2
	s_barrier
	v_mfma_f32_16x16x32_bf16 v[6:9], v[154:157], v[206:209], v[6:9]
	v_mfma_f32_16x16x32_bf16 v[6:9], v[150:153], v[202:205], v[6:9]
	s_setprio 0
	s_add_i32 s74, s74, 2
	s_add_u32 s67, s67, 0x80000
	s_addc_u32 s70, s70, 0
	s_add_u32 s20, s20, 0x400000
	s_addc_u32 s21, s21, 0
	s_add_u32 s71, s71, 0x400000
	s_addc_u32 s73, s73, 0
	s_cmpk_gt_u32 s74, 0x53
	s_cbranch_scc0 .LBB0_1952
	s_and_b64 vcc, exec, s[8:9]
	s_cbranch_vccz .LBB0_1955
	s_barrier

.LBB0_2409:
	s_ashr_i32 s17, s16, 31
	s_lshl_b64 s[18:19], s[16:17], 20
	s_add_u32 s18, s33, s18
	s_addc_u32 s19, s34, s19
	s_and_b64 s[20:21], s[2:3], exec
	s_cselect_b32 s17, s19, s27
	s_cselect_b32 s71, s18, s26
	s_ashr_i32 s15, s14, 31
	s_lshl_b64 s[20:21], s[14:15], 20
	s_add_u32 s20, s35, s20
	s_addc_u32 s21, s36, s21
	s_and_b64 s[28:29], s[2:3], exec
	s_cselect_b32 s15, s21, s25
	s_cselect_b32 s73, s20, s24
	s_add_u32 s74, s24, 0x100
	s_addc_u32 s75, s25, 0
	s_add_u32 s24, s26, 0x80080
	s_addc_u32 s25, s27, 0
	s_add_u32 s76, s26, 0x100
	s_addc_u32 s77, s27, 0
	s_mov_b32 s78, -2
	s_waitcnt vmcnt(25)
	s_waitcnt vmcnt(24)
	s_waitcnt vmcnt(4)
	s_waitcnt vmcnt(2)
	s_waitcnt vmcnt(1)
	s_waitcnt vmcnt(0)
	ds_read_b128 v[130:133], v181
	ds_read_b128 v[134:137], v181 offset:1024
	ds_read_b128 v[138:141], v181 offset:2048
	ds_read_b128 v[142:145], v181 offset:3072
	ds_read_b128 v[146:149], v182
	ds_read_b128 v[150:153], v182 offset:1024
	ds_read_b128 v[154:157], v182 offset:2048
	ds_read_b128 v[158:161], v182 offset:3072
	s_cmp_eq_u32 s78, 28
	s_cselect_b32 s27, s15, s75
	s_cselect_b32 s26, s73, s74
	s_cselect_b32 s29, s17, s77
	s_cselect_b32 s28, s71, s76
	ds_read_b128 v[166:169], v183
	ds_read_b128 v[170:173], v183 offset:1024
	ds_read_b128 v[186:189], v183 offset:2048
	ds_read_b128 v[190:193], v183 offset:3072
	ds_read_b128 v[194:197], v183 offset:4096
	ds_read_b128 v[198:201], v183 offset:5120
	ds_read_b128 v[202:205], v183 offset:6144
	ds_read_b128 v[206:209], v183 offset:7168
	s_add_u32 s80, s24, 0xfff80000
	s_addc_u32 s81, s25, -1
	s_mov_b32 s79, m0
	s_mov_b32 m0, s64
	s_nop 0
	global_load_lds_dwordx4 v1, s[80:81]
	s_mov_b32 m0, s79
	s_nop 0
	s_mov_b32 s79, m0
	s_mov_b32 m0, s66
	s_nop 0
	global_load_lds_dwordx4 v177, s[80:81]
	s_mov_b32 m0, s79
	s_nop 0
	s_mov_b32 s79, m0
	s_mov_b32 m0, s65
	s_nop 0
	global_load_lds_dwordx4 v1, s[24:25]
	s_mov_b32 m0, s79
	s_nop 0
	s_mov_b32 s79, m0
	s_mov_b32 m0, s67
	s_nop 0
	global_load_lds_dwordx4 v177, s[24:25]
	s_mov_b32 m0, s79
	s_waitcnt vmcnt(8)
	s_waitcnt lgkmcnt(0)
	s_barrier
	s_setprio 1
	s_waitcnt lgkmcnt(7)
	v_mfma_f32_16x16x32_bf16 v[126:129], v[130:133], v[166:169], 0
	v_mfma_f32_16x16x32_bf16 v[126:129], v[134:137], v[170:173], v[126:129]
	s_waitcnt lgkmcnt(5)
	v_mfma_f32_16x16x32_bf16 v[122:125], v[142:145], v[170:173], 0
	v_mfma_f32_16x16x32_bf16 v[122:125], v[138:141], v[166:169], v[122:125]
	s_waitcnt lgkmcnt(3)
	v_mfma_f32_16x16x32_bf16 v[114:117], v[138:141], v[186:189], 0
	v_mfma_f32_16x16x32_bf16 v[114:117], v[142:145], v[190:193], v[114:117]
	s_waitcnt lgkmcnt(1)
	v_mfma_f32_16x16x32_bf16 v[118:121], v[134:137], v[190:193], 0
	v_mfma_f32_16x16x32_bf16 v[118:121], v[130:133], v[186:189], v[118:121]
	v_mfma_f32_16x16x32_bf16 v[94:97], v[130:133], v[194:197], 0
	v_mfma_f32_16x16x32_bf16 v[94:97], v[134:137], v[198:201], v[94:97]
	v_mfma_f32_16x16x32_bf16 v[90:93], v[142:145], v[198:201], 0
	v_mfma_f32_16x16x32_bf16 v[90:93], v[138:141], v[194:197], v[90:93]
	v_mfma_f32_16x16x32_bf16 v[78:81], v[138:141], v[202:205], 0
	v_mfma_f32_16x16x32_bf16 v[78:81], v[142:145], v[206:209], v[78:81]
	s_waitcnt lgkmcnt(0)
	v_mfma_f32_16x16x32_bf16 v[86:89], v[134:137], v[206:209], 0
	v_mfma_f32_16x16x32_bf16 v[86:89], v[130:133], v[202:205], v[86:89]
	s_setprio 0
	s_setprio 1
	v_mfma_f32_16x16x32_bf16 v[110:113], v[146:149], v[166:169], 0
	v_mfma_f32_16x16x32_bf16 v[110:113], v[150:153], v[170:173], v[110:113]
	v_mfma_f32_16x16x32_bf16 v[106:109], v[158:161], v[170:173], 0
	v_mfma_f32_16x16x32_bf16 v[106:109], v[154:157], v[166:169], v[106:109]
	v_mfma_f32_16x16x32_bf16 v[98:101], v[154:157], v[186:189], 0
	v_mfma_f32_16x16x32_bf16 v[98:101], v[158:161], v[190:193], v[98:101]
	v_mfma_f32_16x16x32_bf16 v[102:105], v[150:153], v[190:193], 0
	v_mfma_f32_16x16x32_bf16 v[102:105], v[146:149], v[186:189], v[102:105]
	v_mfma_f32_16x16x32_bf16 v[82:85], v[146:149], v[194:197], 0
	v_mfma_f32_16x16x32_bf16 v[82:85], v[150:153], v[198:201], v[82:85]
	v_mfma_f32_16x16x32_bf16 v[74:77], v[158:161], v[198:201], 0
	v_mfma_f32_16x16x32_bf16 v[74:77], v[154:157], v[194:197], v[74:77]
	v_mfma_f32_16x16x32_bf16 v[66:69], v[154:157], v[202:205], 0
	v_mfma_f32_16x16x32_bf16 v[66:69], v[158:161], v[206:209], v[66:69]
	s_setprio 2
	s_barrier
	v_mfma_f32_16x16x32_bf16 v[70:73], v[150:153], v[206:209], 0
	v_mfma_f32_16x16x32_bf16 v[70:73], v[146:149], v[202:205], v[70:73]
	s_setprio 0
	ds_read_b128 v[166:169], v183 offset:16384
	ds_read_b128 v[170:173], v183 offset:17408
	ds_read_b128 v[186:189], v183 offset:18432
	ds_read_b128 v[190:193], v183 offset:19456
	ds_read_b128 v[194:197], v183 offset:20480
	ds_read_b128 v[198:201], v183 offset:21504
	ds_read_b128 v[202:205], v183 offset:22528
	ds_read_b128 v[206:209], v183 offset:23552
	s_mov_b32 s79, m0
	s_mov_b32 m0, s41
	s_nop 0
	global_load_lds_dwordx4 v176, s[26:27]
	s_mov_b32 m0, s79
	s_add_u32 s80, s26, 0x80000
	s_mov_b32 s79, m0
	s_mov_b32 m0, s42
	s_nop 0
	global_load_lds_dwordx4 v178, s[26:27]
	s_mov_b32 m0, s79
	s_addc_u32 s81, s27, 0
	s_mov_b32 s79, m0
	s_mov_b32 m0, s43
	s_nop 0
	global_load_lds_dwordx4 v176, s[80:81]
	s_mov_b32 m0, s79
	s_nop 0
	s_mov_b32 s79, m0
	s_mov_b32 m0, s46
	s_nop 0
	global_load_lds_dwordx4 v178, s[80:81]
	s_mov_b32 m0, s79
	s_waitcnt vmcnt(4)
	s_waitcnt lgkmcnt(0)
	s_barrier
	s_setprio 1
	s_waitcnt lgkmcnt(7)
	v_mfma_f32_16x16x32_bf16 v[62:65], v[130:133], v[166:169], 0
	v_mfma_f32_16x16x32_bf16 v[62:65], v[134:137], v[170:173], v[62:65]
	s_waitcnt lgkmcnt(5)
	v_mfma_f32_16x16x32_bf16 v[58:61], v[142:145], v[170:173], 0
	v_mfma_f32_16x16x32_bf16 v[58:61], v[138:141], v[166:169], v[58:61]
	s_waitcnt lgkmcnt(3)
	v_mfma_f32_16x16x32_bf16 v[42:45], v[138:141], v[186:189], 0
	v_mfma_f32_16x16x32_bf16 v[42:45], v[142:145], v[190:193], v[42:45]
	s_waitcnt lgkmcnt(1)
	v_mfma_f32_16x16x32_bf16 v[46:49], v[134:137], v[190:193], 0
	v_mfma_f32_16x16x32_bf16 v[46:49], v[130:133], v[186:189], v[46:49]
	v_mfma_f32_16x16x32_bf16 v[30:33], v[130:133], v[194:197], 0
	v_mfma_f32_16x16x32_bf16 v[30:33], v[134:137], v[198:201], v[30:33]
	v_mfma_f32_16x16x32_bf16 v[26:29], v[142:145], v[198:201], 0
	v_mfma_f32_16x16x32_bf16 v[26:29], v[138:141], v[194:197], v[26:29]
	v_mfma_f32_16x16x32_bf16 v[10:13], v[138:141], v[202:205], 0
	v_mfma_f32_16x16x32_bf16 v[10:13], v[142:145], v[206:209], v[10:13]
	s_waitcnt lgkmcnt(0)
	v_mfma_f32_16x16x32_bf16 v[14:17], v[134:137], v[206:209], 0
	v_mfma_f32_16x16x32_bf16 v[14:17], v[130:133], v[202:205], v[14:17]
	s_setprio 0
	s_setprio 1
	v_mfma_f32_16x16x32_bf16 v[54:57], v[146:149], v[166:169], 0
	v_mfma_f32_16x16x32_bf16 v[54:57], v[150:153], v[170:173], v[54:57]
	v_mfma_f32_16x16x32_bf16 v[50:53], v[158:161], v[170:173], 0
	v_mfma_f32_16x16x32_bf16 v[50:53], v[154:157], v[166:169], v[50:53]
	v_mfma_f32_16x16x32_bf16 v[34:37], v[154:157], v[186:189], 0
	v_mfma_f32_16x16x32_bf16 v[34:37], v[158:161], v[190:193], v[34:37]
	v_mfma_f32_16x16x32_bf16 v[38:41], v[150:153], v[190:193], 0
	v_mfma_f32_16x16x32_bf16 v[38:41], v[146:149], v[186:189], v[38:41]
	v_mfma_f32_16x16x32_bf16 v[22:25], v[146:149], v[194:197], 0
	v_mfma_f32_16x16x32_bf16 v[22:25], v[150:153], v[198:201], v[22:25]
	v_mfma_f32_16x16x32_bf16 v[18:21], v[158:161], v[198:201], 0
	v_mfma_f32_16x16x32_bf16 v[18:21], v[154:157], v[194:197], v[18:21]
	v_mfma_f32_16x16x32_bf16 v[2:5], v[154:157], v[202:205], 0
	v_mfma_f32_16x16x32_bf16 v[2:5], v[158:161], v[206:209], v[2:5]
	s_setprio 2
	s_barrier
	v_mfma_f32_16x16x32_bf16 v[6:9], v[150:153], v[206:209], 0
	v_mfma_f32_16x16x32_bf16 v[6:9], v[146:149], v[202:205], v[6:9]
	s_setprio 0
	ds_read_b128 v[130:133], v184
	ds_read_b128 v[134:137], v184 offset:1024
	ds_read_b128 v[138:141], v184 offset:2048
	ds_read_b128 v[142:145], v184 offset:3072
	ds_read_b128 v[146:149], v185
	ds_read_b128 v[150:153], v185 offset:1024
	ds_read_b128 v[154:157], v185 offset:2048
	ds_read_b128 v[158:161], v185 offset:3072
	ds_read_b128 v[166:169], v183 offset:32768
	ds_read_b128 v[170:173], v183 offset:33792
	ds_read_b128 v[186:189], v183 offset:34816
	ds_read_b128 v[190:193], v183 offset:35840
	ds_read_b128 v[194:197], v183 offset:36864
	ds_read_b128 v[198:201], v183 offset:37888
	ds_read_b128 v[202:205], v183 offset:38912
	ds_read_b128 v[206:209], v183 offset:39936
	s_mov_b32 s79, m0
	s_mov_b32 m0, s40
	s_nop 0
	global_load_lds_dwordx4 v1, s[28:29]
	s_mov_b32 m0, s79
	s_nop 0
	s_mov_b32 s79, m0
	s_mov_b32 m0, s47
	s_nop 0
	global_load_lds_dwordx4 v177, s[28:29]
	s_mov_b32 m0, s79
	s_add_u32 s28, s28, 0x80000
	s_addc_u32 s29, s29, 0
	s_mov_b32 s79, m0
	s_mov_b32 m0, s48
	s_nop 0
	global_load_lds_dwordx4 v1, s[28:29]
	s_mov_b32 m0, s79
	s_nop 0
	s_mov_b32 s79, m0
	s_mov_b32 m0, s49
	s_nop 0
	global_load_lds_dwordx4 v177, s[28:29]
	s_mov_b32 m0, s79
	s_waitcnt vmcnt(8)
	s_waitcnt lgkmcnt(0)
	s_barrier
	s_setprio 1
	s_waitcnt lgkmcnt(7)
	v_mfma_f32_16x16x32_bf16 v[126:129], v[130:133], v[166:169], v[126:129]
	v_mfma_f32_16x16x32_bf16 v[126:129], v[134:137], v[170:173], v[126:129]
	s_waitcnt lgkmcnt(5)
	v_mfma_f32_16x16x32_bf16 v[122:125], v[142:145], v[170:173], v[122:125]
	v_mfma_f32_16x16x32_bf16 v[122:125], v[138:141], v[166:169], v[122:125]
	s_waitcnt lgkmcnt(3)
	v_mfma_f32_16x16x32_bf16 v[114:117], v[138:141], v[186:189], v[114:117]
	v_mfma_f32_16x16x32_bf16 v[114:117], v[142:145], v[190:193], v[114:117]
	s_waitcnt lgkmcnt(1)
	v_mfma_f32_16x16x32_bf16 v[118:121], v[134:137], v[190:193], v[118:121]
	v_mfma_f32_16x16x32_bf16 v[118:121], v[130:133], v[186:189], v[118:121]
	v_mfma_f32_16x16x32_bf16 v[94:97], v[130:133], v[194:197], v[94:97]
	v_mfma_f32_16x16x32_bf16 v[94:97], v[134:137], v[198:201], v[94:97]
	v_mfma_f32_16x16x32_bf16 v[90:93], v[142:145], v[198:201], v[90:93]
	v_mfma_f32_16x16x32_bf16 v[90:93], v[138:141], v[194:197], v[90:93]
	v_mfma_f32_16x16x32_bf16 v[78:81], v[138:141], v[202:205], v[78:81]
	v_mfma_f32_16x16x32_bf16 v[78:81], v[142:145], v[206:209], v[78:81]
	s_waitcnt lgkmcnt(0)
	v_mfma_f32_16x16x32_bf16 v[86:89], v[134:137], v[206:209], v[86:89]
	v_mfma_f32_16x16x32_bf16 v[86:89], v[130:133], v[202:205], v[86:89]
	s_setprio 0
	s_setprio 1
	v_mfma_f32_16x16x32_bf16 v[110:113], v[146:149], v[166:169], v[110:113]
	v_mfma_f32_16x16x32_bf16 v[110:113], v[150:153], v[170:173], v[110:113]
	v_mfma_f32_16x16x32_bf16 v[106:109], v[158:161], v[170:173], v[106:109]
	v_mfma_f32_16x16x32_bf16 v[106:109], v[154:157], v[166:169], v[106:109]
	v_mfma_f32_16x16x32_bf16 v[98:101], v[154:157], v[186:189], v[98:101]
	v_mfma_f32_16x16x32_bf16 v[98:101], v[158:161], v[190:193], v[98:101]
	v_mfma_f32_16x16x32_bf16 v[102:105], v[150:153], v[190:193], v[102:105]
	v_mfma_f32_16x16x32_bf16 v[102:105], v[146:149], v[186:189], v[102:105]
	v_mfma_f32_16x16x32_bf16 v[82:85], v[146:149], v[194:197], v[82:85]
	v_mfma_f32_16x16x32_bf16 v[82:85], v[150:153], v[198:201], v[82:85]
	v_mfma_f32_16x16x32_bf16 v[74:77], v[158:161], v[198:201], v[74:77]
	v_mfma_f32_16x16x32_bf16 v[74:77], v[154:157], v[194:197], v[74:77]
	v_mfma_f32_16x16x32_bf16 v[66:69], v[154:157], v[202:205], v[66:69]
	v_mfma_f32_16x16x32_bf16 v[66:69], v[158:161], v[206:209], v[66:69]
	s_setprio 2
	s_barrier
	v_mfma_f32_16x16x32_bf16 v[70:73], v[150:153], v[206:209], v[70:73]
	v_mfma_f32_16x16x32_bf16 v[70:73], v[146:149], v[202:205], v[70:73]
	s_setprio 0
	ds_read_b128 v[166:169], v183 offset:49152
	ds_read_b128 v[170:173], v183 offset:50176
	ds_read_b128 v[186:189], v183 offset:51200
	ds_read_b128 v[190:193], v183 offset:52224
	ds_read_b128 v[194:197], v183 offset:53248
	ds_read_b128 v[198:201], v183 offset:54272
	ds_read_b128 v[202:205], v183 offset:55296
	ds_read_b128 v[206:209], v183 offset:56320
	s_add_u32 s28, s26, 0x80
	s_addc_u32 s29, s27, 0
	s_mov_b32 s79, m0
	s_mov_b32 m0, s56
	s_nop 0
	global_load_lds_dwordx4 v176, s[28:29]
	s_mov_b32 m0, s79
	s_add_u32 s26, s26, 0x80080
	s_mov_b32 s79, m0
	s_mov_b32 m0, s57
	s_nop 0
	global_load_lds_dwordx4 v178, s[28:29]
	s_mov_b32 m0, s79
	s_addc_u32 s27, s27, 0
	s_mov_b32 s28, m0
	s_mov_b32 m0, s58
	s_nop 0
	global_load_lds_dwordx4 v176, s[26:27]
	s_mov_b32 m0, s28
	s_nop 0
	s_mov_b32 s28, m0
	s_mov_b32 m0, s59
	s_nop 0
	global_load_lds_dwordx4 v178, s[26:27]
	s_mov_b32 m0, s28
	s_waitcnt vmcnt(4)
	s_waitcnt lgkmcnt(0)
	s_barrier
	s_setprio 1
	s_waitcnt lgkmcnt(7)
	v_mfma_f32_16x16x32_bf16 v[62:65], v[130:133], v[166:169], v[62:65]
	v_mfma_f32_16x16x32_bf16 v[62:65], v[134:137], v[170:173], v[62:65]
	s_waitcnt lgkmcnt(5)
	v_mfma_f32_16x16x32_bf16 v[58:61], v[142:145], v[170:173], v[58:61]
	v_mfma_f32_16x16x32_bf16 v[58:61], v[138:141], v[166:169], v[58:61]
	s_waitcnt lgkmcnt(3)
	v_mfma_f32_16x16x32_bf16 v[42:45], v[138:141], v[186:189], v[42:45]
	v_mfma_f32_16x16x32_bf16 v[42:45], v[142:145], v[190:193], v[42:45]
	s_waitcnt lgkmcnt(1)
	v_mfma_f32_16x16x32_bf16 v[46:49], v[134:137], v[190:193], v[46:49]
	v_mfma_f32_16x16x32_bf16 v[46:49], v[130:133], v[186:189], v[46:49]
	v_mfma_f32_16x16x32_bf16 v[30:33], v[130:133], v[194:197], v[30:33]
	v_mfma_f32_16x16x32_bf16 v[30:33], v[134:137], v[198:201], v[30:33]
	v_mfma_f32_16x16x32_bf16 v[26:29], v[142:145], v[198:201], v[26:29]
	v_mfma_f32_16x16x32_bf16 v[26:29], v[138:141], v[194:197], v[26:29]
	v_mfma_f32_16x16x32_bf16 v[10:13], v[138:141], v[202:205], v[10:13]
	v_mfma_f32_16x16x32_bf16 v[10:13], v[142:145], v[206:209], v[10:13]
	s_waitcnt lgkmcnt(0)
	v_mfma_f32_16x16x32_bf16 v[14:17], v[134:137], v[206:209], v[14:17]
	v_mfma_f32_16x16x32_bf16 v[14:17], v[130:133], v[202:205], v[14:17]
	s_setprio 0
	s_setprio 1
	v_mfma_f32_16x16x32_bf16 v[54:57], v[146:149], v[166:169], v[54:57]
	v_mfma_f32_16x16x32_bf16 v[54:57], v[150:153], v[170:173], v[54:57]
	v_mfma_f32_16x16x32_bf16 v[50:53], v[158:161], v[170:173], v[50:53]
	v_mfma_f32_16x16x32_bf16 v[50:53], v[154:157], v[166:169], v[50:53]
	v_mfma_f32_16x16x32_bf16 v[34:37], v[154:157], v[186:189], v[34:37]
	v_mfma_f32_16x16x32_bf16 v[34:37], v[158:161], v[190:193], v[34:37]
	v_mfma_f32_16x16x32_bf16 v[38:41], v[150:153], v[190:193], v[38:41]
	v_mfma_f32_16x16x32_bf16 v[38:41], v[146:149], v[186:189], v[38:41]
	v_mfma_f32_16x16x32_bf16 v[22:25], v[146:149], v[194:197], v[22:25]
	v_mfma_f32_16x16x32_bf16 v[22:25], v[150:153], v[198:201], v[22:25]
	v_mfma_f32_16x16x32_bf16 v[18:21], v[158:161], v[198:201], v[18:21]
	v_mfma_f32_16x16x32_bf16 v[18:21], v[154:157], v[194:197], v[18:21]
	v_mfma_f32_16x16x32_bf16 v[2:5], v[154:157], v[202:205], v[2:5]
	v_mfma_f32_16x16x32_bf16 v[2:5], v[158:161], v[206:209], v[2:5]
	s_setprio 2
	s_barrier
	v_mfma_f32_16x16x32_bf16 v[6:9], v[150:153], v[206:209], v[6:9]
	v_mfma_f32_16x16x32_bf16 v[6:9], v[146:149], v[202:205], v[6:9]
	s_setprio 0
	s_add_i32 s78, s78, 2
	s_add_u32 s74, s74, 0x100
	s_addc_u32 s75, s75, 0
	s_add_u32 s24, s24, 0x100
	s_addc_u32 s25, s25, 0
	s_add_u32 s76, s76, 0x100
	s_addc_u32 s77, s77, 0
	s_cmp_gt_u32 s78, 29
	.p2align 6
.LBB0_2410:
	ds_read_b128 v[130:133], v181
	ds_read_b128 v[134:137], v181 offset:1024
	ds_read_b128 v[138:141], v181 offset:2048
	ds_read_b128 v[142:145], v181 offset:3072
	ds_read_b128 v[146:149], v182
	ds_read_b128 v[150:153], v182 offset:1024
	ds_read_b128 v[154:157], v182 offset:2048
	ds_read_b128 v[158:161], v182 offset:3072
	s_cmp_eq_u32 s78, 28
	s_cselect_b32 s27, s15, s75
	s_cselect_b32 s26, s73, s74
	s_cselect_b32 s29, s17, s77
	s_cselect_b32 s28, s71, s76
	ds_read_b128 v[166:169], v183
	ds_read_b128 v[170:173], v183 offset:1024
	ds_read_b128 v[186:189], v183 offset:2048
	ds_read_b128 v[190:193], v183 offset:3072
	ds_read_b128 v[194:197], v183 offset:4096
	ds_read_b128 v[198:201], v183 offset:5120
	ds_read_b128 v[202:205], v183 offset:6144
	ds_read_b128 v[206:209], v183 offset:7168
	s_add_u32 s80, s24, 0xfff80000
	s_addc_u32 s81, s25, -1
	s_mov_b32 s79, m0
	s_mov_b32 m0, s64
	s_nop 0
	global_load_lds_dwordx4 v1, s[80:81]
	s_mov_b32 m0, s79
	s_nop 0
	s_mov_b32 s79, m0
	s_mov_b32 m0, s66
	s_nop 0
	global_load_lds_dwordx4 v177, s[80:81]
	s_mov_b32 m0, s79
	s_nop 0
	s_mov_b32 s79, m0
	s_mov_b32 m0, s65
	s_nop 0
	global_load_lds_dwordx4 v1, s[24:25]
	s_mov_b32 m0, s79
	s_nop 0
	s_mov_b32 s79, m0
	s_mov_b32 m0, s67
	s_nop 0
	global_load_lds_dwordx4 v177, s[24:25]
	s_mov_b32 m0, s79
	s_waitcnt vmcnt(8)
	s_waitcnt lgkmcnt(0)
	s_barrier
	s_setprio 1
	s_waitcnt lgkmcnt(7)
	v_mfma_f32_16x16x32_bf16 v[126:129], v[130:133], v[166:169], v[126:129]
	v_mfma_f32_16x16x32_bf16 v[126:129], v[134:137], v[170:173], v[126:129]
	s_waitcnt lgkmcnt(5)
	v_mfma_f32_16x16x32_bf16 v[122:125], v[142:145], v[170:173], v[122:125]
	v_mfma_f32_16x16x32_bf16 v[122:125], v[138:141], v[166:169], v[122:125]
	s_waitcnt lgkmcnt(3)
	v_mfma_f32_16x16x32_bf16 v[114:117], v[138:141], v[186:189], v[114:117]
	v_mfma_f32_16x16x32_bf16 v[114:117], v[142:145], v[190:193], v[114:117]
	s_waitcnt lgkmcnt(1)
	v_mfma_f32_16x16x32_bf16 v[118:121], v[134:137], v[190:193], v[118:121]
	v_mfma_f32_16x16x32_bf16 v[118:121], v[130:133], v[186:189], v[118:121]
	v_mfma_f32_16x16x32_bf16 v[94:97], v[130:133], v[194:197], v[94:97]
	v_mfma_f32_16x16x32_bf16 v[94:97], v[134:137], v[198:201], v[94:97]
	v_mfma_f32_16x16x32_bf16 v[90:93], v[142:145], v[198:201], v[90:93]
	v_mfma_f32_16x16x32_bf16 v[90:93], v[138:141], v[194:197], v[90:93]
	v_mfma_f32_16x16x32_bf16 v[78:81], v[138:141], v[202:205], v[78:81]
	v_mfma_f32_16x16x32_bf16 v[78:81], v[142:145], v[206:209], v[78:81]
	s_waitcnt lgkmcnt(0)
	v_mfma_f32_16x16x32_bf16 v[86:89], v[134:137], v[206:209], v[86:89]
	v_mfma_f32_16x16x32_bf16 v[86:89], v[130:133], v[202:205], v[86:89]
	s_setprio 0
	s_setprio 1
	v_mfma_f32_16x16x32_bf16 v[110:113], v[146:149], v[166:169], v[110:113]
	v_mfma_f32_16x16x32_bf16 v[110:113], v[150:153], v[170:173], v[110:113]
	v_mfma_f32_16x16x32_bf16 v[106:109], v[158:161], v[170:173], v[106:109]
	v_mfma_f32_16x16x32_bf16 v[106:109], v[154:157], v[166:169], v[106:109]
	v_mfma_f32_16x16x32_bf16 v[98:101], v[154:157], v[186:189], v[98:101]
	v_mfma_f32_16x16x32_bf16 v[98:101], v[158:161], v[190:193], v[98:101]
	v_mfma_f32_16x16x32_bf16 v[102:105], v[150:153], v[190:193], v[102:105]
	v_mfma_f32_16x16x32_bf16 v[102:105], v[146:149], v[186:189], v[102:105]
	v_mfma_f32_16x16x32_bf16 v[82:85], v[146:149], v[194:197], v[82:85]
	v_mfma_f32_16x16x32_bf16 v[82:85], v[150:153], v[198:201], v[82:85]
	v_mfma_f32_16x16x32_bf16 v[74:77], v[158:161], v[198:201], v[74:77]
	v_mfma_f32_16x16x32_bf16 v[74:77], v[154:157], v[194:197], v[74:77]
	v_mfma_f32_16x16x32_bf16 v[66:69], v[154:157], v[202:205], v[66:69]
	v_mfma_f32_16x16x32_bf16 v[66:69], v[158:161], v[206:209], v[66:69]
	s_setprio 2
	s_barrier
	v_mfma_f32_16x16x32_bf16 v[70:73], v[150:153], v[206:209], v[70:73]
	v_mfma_f32_16x16x32_bf16 v[70:73], v[146:149], v[202:205], v[70:73]
	s_setprio 0
	ds_read_b128 v[166:169], v183 offset:16384
	ds_read_b128 v[170:173], v183 offset:17408
	ds_read_b128 v[186:189], v183 offset:18432
	ds_read_b128 v[190:193], v183 offset:19456
	ds_read_b128 v[194:197], v183 offset:20480
	ds_read_b128 v[198:201], v183 offset:21504
	ds_read_b128 v[202:205], v183 offset:22528
	ds_read_b128 v[206:209], v183 offset:23552
	s_mov_b32 s79, m0
	s_mov_b32 m0, s41
	s_nop 0
	global_load_lds_dwordx4 v176, s[26:27]
	s_mov_b32 m0, s79
	s_add_u32 s80, s26, 0x80000
	s_mov_b32 s79, m0
	s_mov_b32 m0, s42
	s_nop 0
	global_load_lds_dwordx4 v178, s[26:27]
	s_mov_b32 m0, s79
	s_addc_u32 s81, s27, 0
	s_mov_b32 s79, m0
	s_mov_b32 m0, s43
	s_nop 0
	global_load_lds_dwordx4 v176, s[80:81]
	s_mov_b32 m0, s79
	s_nop 0
	s_mov_b32 s79, m0
	s_mov_b32 m0, s46
	s_nop 0
	global_load_lds_dwordx4 v178, s[80:81]
	s_mov_b32 m0, s79
	s_waitcnt vmcnt(4)
	s_waitcnt lgkmcnt(0)
	s_barrier
	s_setprio 1
	s_waitcnt lgkmcnt(7)
	v_mfma_f32_16x16x32_bf16 v[62:65], v[130:133], v[166:169], v[62:65]
	v_mfma_f32_16x16x32_bf16 v[62:65], v[134:137], v[170:173], v[62:65]
	s_waitcnt lgkmcnt(5)
	v_mfma_f32_16x16x32_bf16 v[58:61], v[142:145], v[170:173], v[58:61]
	v_mfma_f32_16x16x32_bf16 v[58:61], v[138:141], v[166:169], v[58:61]
	s_waitcnt lgkmcnt(3)
	v_mfma_f32_16x16x32_bf16 v[42:45], v[138:141], v[186:189], v[42:45]
	v_mfma_f32_16x16x32_bf16 v[42:45], v[142:145], v[190:193], v[42:45]
	s_waitcnt lgkmcnt(1)
	v_mfma_f32_16x16x32_bf16 v[46:49], v[134:137], v[190:193], v[46:49]
	v_mfma_f32_16x16x32_bf16 v[46:49], v[130:133], v[186:189], v[46:49]
	v_mfma_f32_16x16x32_bf16 v[30:33], v[130:133], v[194:197], v[30:33]
	v_mfma_f32_16x16x32_bf16 v[30:33], v[134:137], v[198:201], v[30:33]
	v_mfma_f32_16x16x32_bf16 v[26:29], v[142:145], v[198:201], v[26:29]
	v_mfma_f32_16x16x32_bf16 v[26:29], v[138:141], v[194:197], v[26:29]
	v_mfma_f32_16x16x32_bf16 v[10:13], v[138:141], v[202:205], v[10:13]
	v_mfma_f32_16x16x32_bf16 v[10:13], v[142:145], v[206:209], v[10:13]
	s_waitcnt lgkmcnt(0)
	v_mfma_f32_16x16x32_bf16 v[14:17], v[134:137], v[206:209], v[14:17]
	v_mfma_f32_16x16x32_bf16 v[14:17], v[130:133], v[202:205], v[14:17]
	s_setprio 0
	s_setprio 1
	v_mfma_f32_16x16x32_bf16 v[54:57], v[146:149], v[166:169], v[54:57]
	v_mfma_f32_16x16x32_bf16 v[54:57], v[150:153], v[170:173], v[54:57]
	v_mfma_f32_16x16x32_bf16 v[50:53], v[158:161], v[170:173], v[50:53]
	v_mfma_f32_16x16x32_bf16 v[50:53], v[154:157], v[166:169], v[50:53]
	v_mfma_f32_16x16x32_bf16 v[34:37], v[154:157], v[186:189], v[34:37]
	v_mfma_f32_16x16x32_bf16 v[34:37], v[158:161], v[190:193], v[34:37]
	v_mfma_f32_16x16x32_bf16 v[38:41], v[150:153], v[190:193], v[38:41]
	v_mfma_f32_16x16x32_bf16 v[38:41], v[146:149], v[186:189], v[38:41]
	v_mfma_f32_16x16x32_bf16 v[22:25], v[146:149], v[194:197], v[22:25]
	v_mfma_f32_16x16x32_bf16 v[22:25], v[150:153], v[198:201], v[22:25]
	v_mfma_f32_16x16x32_bf16 v[18:21], v[158:161], v[198:201], v[18:21]
	v_mfma_f32_16x16x32_bf16 v[18:21], v[154:157], v[194:197], v[18:21]
	v_mfma_f32_16x16x32_bf16 v[2:5], v[154:157], v[202:205], v[2:5]
	v_mfma_f32_16x16x32_bf16 v[2:5], v[158:161], v[206:209], v[2:5]
	s_setprio 2
	s_barrier
	v_mfma_f32_16x16x32_bf16 v[6:9], v[150:153], v[206:209], v[6:9]
	v_mfma_f32_16x16x32_bf16 v[6:9], v[146:149], v[202:205], v[6:9]
	s_setprio 0
	ds_read_b128 v[130:133], v184
	ds_read_b128 v[134:137], v184 offset:1024
	ds_read_b128 v[138:141], v184 offset:2048
	ds_read_b128 v[142:145], v184 offset:3072
	ds_read_b128 v[146:149], v185
	ds_read_b128 v[150:153], v185 offset:1024
	ds_read_b128 v[154:157], v185 offset:2048
	ds_read_b128 v[158:161], v185 offset:3072
	ds_read_b128 v[166:169], v183 offset:32768
	ds_read_b128 v[170:173], v183 offset:33792
	ds_read_b128 v[186:189], v183 offset:34816
	ds_read_b128 v[190:193], v183 offset:35840
	ds_read_b128 v[194:197], v183 offset:36864
	ds_read_b128 v[198:201], v183 offset:37888
	ds_read_b128 v[202:205], v183 offset:38912
	ds_read_b128 v[206:209], v183 offset:39936
	s_mov_b32 s79, m0
	s_mov_b32 m0, s40
	s_nop 0
	global_load_lds_dwordx4 v1, s[28:29]
	s_mov_b32 m0, s79
	s_nop 0
	s_mov_b32 s79, m0
	s_mov_b32 m0, s47
	s_nop 0
	global_load_lds_dwordx4 v177, s[28:29]
	s_mov_b32 m0, s79
	s_add_u32 s28, s28, 0x80000
	s_addc_u32 s29, s29, 0
	s_mov_b32 s79, m0
	s_mov_b32 m0, s48
	s_nop 0
	global_load_lds_dwordx4 v1, s[28:29]
	s_mov_b32 m0, s79
	s_nop 0
	s_mov_b32 s79, m0
	s_mov_b32 m0, s49
	s_nop 0
	global_load_lds_dwordx4 v177, s[28:29]
	s_mov_b32 m0, s79
	s_waitcnt vmcnt(8)
	s_waitcnt lgkmcnt(0)
	s_barrier
	s_setprio 1
	s_waitcnt lgkmcnt(7)
	v_mfma_f32_16x16x32_bf16 v[126:129], v[130:133], v[166:169], v[126:129]
	v_mfma_f32_16x16x32_bf16 v[126:129], v[134:137], v[170:173], v[126:129]
	s_waitcnt lgkmcnt(5)
	v_mfma_f32_16x16x32_bf16 v[122:125], v[142:145], v[170:173], v[122:125]
	v_mfma_f32_16x16x32_bf16 v[122:125], v[138:141], v[166:169], v[122:125]
	s_waitcnt lgkmcnt(3)
	v_mfma_f32_16x16x32_bf16 v[114:117], v[138:141], v[186:189], v[114:117]
	v_mfma_f32_16x16x32_bf16 v[114:117], v[142:145], v[190:193], v[114:117]
	s_waitcnt lgkmcnt(1)
	v_mfma_f32_16x16x32_bf16 v[118:121], v[134:137], v[190:193], v[118:121]
	v_mfma_f32_16x16x32_bf16 v[118:121], v[130:133], v[186:189], v[118:121]
	v_mfma_f32_16x16x32_bf16 v[94:97], v[130:133], v[194:197], v[94:97]
	v_mfma_f32_16x16x32_bf16 v[94:97], v[134:137], v[198:201], v[94:97]
	v_mfma_f32_16x16x32_bf16 v[90:93], v[142:145], v[198:201], v[90:93]
	v_mfma_f32_16x16x32_bf16 v[90:93], v[138:141], v[194:197], v[90:93]
	v_mfma_f32_16x16x32_bf16 v[78:81], v[138:141], v[202:205], v[78:81]
	v_mfma_f32_16x16x32_bf16 v[78:81], v[142:145], v[206:209], v[78:81]
	s_waitcnt lgkmcnt(0)
	v_mfma_f32_16x16x32_bf16 v[86:89], v[134:137], v[206:209], v[86:89]
	v_mfma_f32_16x16x32_bf16 v[86:89], v[130:133], v[202:205], v[86:89]
	s_setprio 0
	s_setprio 1
	v_mfma_f32_16x16x32_bf16 v[110:113], v[146:149], v[166:169], v[110:113]
	v_mfma_f32_16x16x32_bf16 v[110:113], v[150:153], v[170:173], v[110:113]
	v_mfma_f32_16x16x32_bf16 v[106:109], v[158:161], v[170:173], v[106:109]
	v_mfma_f32_16x16x32_bf16 v[106:109], v[154:157], v[166:169], v[106:109]
	v_mfma_f32_16x16x32_bf16 v[98:101], v[154:157], v[186:189], v[98:101]
	v_mfma_f32_16x16x32_bf16 v[98:101], v[158:161], v[190:193], v[98:101]
	v_mfma_f32_16x16x32_bf16 v[102:105], v[150:153], v[190:193], v[102:105]
	v_mfma_f32_16x16x32_bf16 v[102:105], v[146:149], v[186:189], v[102:105]
	v_mfma_f32_16x16x32_bf16 v[82:85], v[146:149], v[194:197], v[82:85]
	v_mfma_f32_16x16x32_bf16 v[82:85], v[150:153], v[198:201], v[82:85]
	v_mfma_f32_16x16x32_bf16 v[74:77], v[158:161], v[198:201], v[74:77]
	v_mfma_f32_16x16x32_bf16 v[74:77], v[154:157], v[194:197], v[74:77]
	v_mfma_f32_16x16x32_bf16 v[66:69], v[154:157], v[202:205], v[66:69]
	v_mfma_f32_16x16x32_bf16 v[66:69], v[158:161], v[206:209], v[66:69]
	s_setprio 2
	s_barrier
	v_mfma_f32_16x16x32_bf16 v[70:73], v[150:153], v[206:209], v[70:73]
	v_mfma_f32_16x16x32_bf16 v[70:73], v[146:149], v[202:205], v[70:73]
	s_setprio 0
	ds_read_b128 v[166:169], v183 offset:49152
	ds_read_b128 v[170:173], v183 offset:50176
	ds_read_b128 v[186:189], v183 offset:51200
	ds_read_b128 v[190:193], v183 offset:52224
	ds_read_b128 v[194:197], v183 offset:53248
	ds_read_b128 v[198:201], v183 offset:54272
	ds_read_b128 v[202:205], v183 offset:55296
	ds_read_b128 v[206:209], v183 offset:56320
	s_add_u32 s28, s26, 0x80
	s_addc_u32 s29, s27, 0
	s_mov_b32 s79, m0
	s_mov_b32 m0, s56
	s_nop 0
	global_load_lds_dwordx4 v176, s[28:29]
	s_mov_b32 m0, s79
	s_add_u32 s26, s26, 0x80080
	s_mov_b32 s79, m0
	s_mov_b32 m0, s57
	s_nop 0
	global_load_lds_dwordx4 v178, s[28:29]
	s_mov_b32 m0, s79
	s_addc_u32 s27, s27, 0
	s_mov_b32 s28, m0
	s_mov_b32 m0, s58
	s_nop 0
	global_load_lds_dwordx4 v176, s[26:27]
	s_mov_b32 m0, s28
	s_nop 0
	s_mov_b32 s28, m0
	s_mov_b32 m0, s59
	s_nop 0
	global_load_lds_dwordx4 v178, s[26:27]
	s_mov_b32 m0, s28
	s_waitcnt vmcnt(4)
	s_waitcnt lgkmcnt(0)
	s_barrier
	s_setprio 1
	s_waitcnt lgkmcnt(7)
	v_mfma_f32_16x16x32_bf16 v[62:65], v[130:133], v[166:169], v[62:65]
	v_mfma_f32_16x16x32_bf16 v[62:65], v[134:137], v[170:173], v[62:65]
	s_waitcnt lgkmcnt(5)
	v_mfma_f32_16x16x32_bf16 v[58:61], v[142:145], v[170:173], v[58:61]
	v_mfma_f32_16x16x32_bf16 v[58:61], v[138:141], v[166:169], v[58:61]
	s_waitcnt lgkmcnt(3)
	v_mfma_f32_16x16x32_bf16 v[42:45], v[138:141], v[186:189], v[42:45]
	v_mfma_f32_16x16x32_bf16 v[42:45], v[142:145], v[190:193], v[42:45]
	s_waitcnt lgkmcnt(1)
	v_mfma_f32_16x16x32_bf16 v[46:49], v[134:137], v[190:193], v[46:49]
	v_mfma_f32_16x16x32_bf16 v[46:49], v[130:133], v[186:189], v[46:49]
	v_mfma_f32_16x16x32_bf16 v[30:33], v[130:133], v[194:197], v[30:33]
	v_mfma_f32_16x16x32_bf16 v[30:33], v[134:137], v[198:201], v[30:33]
	v_mfma_f32_16x16x32_bf16 v[26:29], v[142:145], v[198:201], v[26:29]
	v_mfma_f32_16x16x32_bf16 v[26:29], v[138:141], v[194:197], v[26:29]
	v_mfma_f32_16x16x32_bf16 v[10:13], v[138:141], v[202:205], v[10:13]
	v_mfma_f32_16x16x32_bf16 v[10:13], v[142:145], v[206:209], v[10:13]
	s_waitcnt lgkmcnt(0)
	v_mfma_f32_16x16x32_bf16 v[14:17], v[134:137], v[206:209], v[14:17]
	v_mfma_f32_16x16x32_bf16 v[14:17], v[130:133], v[202:205], v[14:17]
	s_setprio 0
	s_setprio 1
	v_mfma_f32_16x16x32_bf16 v[54:57], v[146:149], v[166:169], v[54:57]
	v_mfma_f32_16x16x32_bf16 v[54:57], v[150:153], v[170:173], v[54:57]
	v_mfma_f32_16x16x32_bf16 v[50:53], v[158:161], v[170:173], v[50:53]
	v_mfma_f32_16x16x32_bf16 v[50:53], v[154:157], v[166:169], v[50:53]
	v_mfma_f32_16x16x32_bf16 v[34:37], v[154:157], v[186:189], v[34:37]
	v_mfma_f32_16x16x32_bf16 v[34:37], v[158:161], v[190:193], v[34:37]
	v_mfma_f32_16x16x32_bf16 v[38:41], v[150:153], v[190:193], v[38:41]
	v_mfma_f32_16x16x32_bf16 v[38:41], v[146:149], v[186:189], v[38:41]
	v_mfma_f32_16x16x32_bf16 v[22:25], v[146:149], v[194:197], v[22:25]
	v_mfma_f32_16x16x32_bf16 v[22:25], v[150:153], v[198:201], v[22:25]
	v_mfma_f32_16x16x32_bf16 v[18:21], v[158:161], v[198:201], v[18:21]
	v_mfma_f32_16x16x32_bf16 v[18:21], v[154:157], v[194:197], v[18:21]
	v_mfma_f32_16x16x32_bf16 v[2:5], v[154:157], v[202:205], v[2:5]
	v_mfma_f32_16x16x32_bf16 v[2:5], v[158:161], v[206:209], v[2:5]
	s_setprio 2
	s_barrier
	v_mfma_f32_16x16x32_bf16 v[6:9], v[150:153], v[206:209], v[6:9]
	v_mfma_f32_16x16x32_bf16 v[6:9], v[146:149], v[202:205], v[6:9]
	s_setprio 0
	s_add_i32 s78, s78, 2
	s_add_u32 s74, s74, 0x100
	s_addc_u32 s75, s75, 0
	s_add_u32 s24, s24, 0x100
	s_addc_u32 s25, s25, 0
	s_add_u32 s76, s76, 0x100
	s_addc_u32 s77, s77, 0
	s_cmp_gt_u32 s78, 29
	s_cbranch_scc0 .LBB0_2410
	s_and_b64 vcc, exec, s[8:9]
	s_cbranch_vccz .LBB0_2413
	s_barrier

.LBB0_2593:
	s_ashr_i32 s11, s10, 31
	s_lshl_b64 s[12:13], s[10:11], 20
	s_add_u32 s12, s26, s12
	s_addc_u32 s13, s27, s13
	s_and_b64 s[14:15], s[2:3], exec
	s_cselect_b32 s11, s13, s21
	s_cselect_b32 s62, s12, s20
	s_ashr_i32 s9, s8, 31
	s_lshl_b64 s[14:15], s[8:9], 20
	s_add_u32 s14, s28, s14
	s_addc_u32 s15, s29, s15
	s_and_b64 s[22:23], s[2:3], exec
	s_cselect_b32 s9, s15, s19
	s_cselect_b32 s63, s14, s18
	s_add_u32 s64, s18, 0x100
	s_addc_u32 s65, s19, 0
	s_add_u32 s18, s20, 0x80080
	s_addc_u32 s19, s21, 0
	s_add_u32 s66, s20, 0x100
	s_addc_u32 s67, s21, 0
	s_mov_b32 s70, -2
	ds_read_b128 v[148:151], v143
	ds_read_b128 v[152:155], v143 offset:1024
	ds_read_b128 v[156:159], v143 offset:2048
	ds_read_b128 v[160:163], v143 offset:3072
	ds_read_b128 v[164:167], v144
	ds_read_b128 v[168:171], v144 offset:1024
	ds_read_b128 v[172:175], v144 offset:2048
	ds_read_b128 v[176:179], v144 offset:3072
	s_cmp_eq_u32 s70, 28
	s_cselect_b32 s21, s9, s65
	s_cselect_b32 s20, s63, s64
	s_cselect_b32 s23, s11, s67
	s_cselect_b32 s22, s62, s66
	ds_read_b128 v[180:183], v145
	ds_read_b128 v[184:187], v145 offset:1024
	ds_read_b128 v[188:191], v145 offset:2048
	ds_read_b128 v[192:195], v145 offset:3072
	ds_read_b128 v[196:199], v145 offset:4096
	ds_read_b128 v[200:203], v145 offset:5120
	ds_read_b128 v[204:207], v145 offset:6144
	ds_read_b128 v[208:211], v145 offset:7168
	s_add_u32 s74, s18, 0xfff80000
	s_addc_u32 s75, s19, -1
	s_mov_b32 s71, m0
	s_mov_b32 m0, s48
	s_nop 0
	global_load_lds_dwordx4 v138, s[74:75]
	s_mov_b32 m0, s71
	s_nop 0
	s_mov_b32 s71, m0
	s_mov_b32 m0, s57
	s_nop 0
	global_load_lds_dwordx4 v140, s[74:75]
	s_mov_b32 m0, s71
	s_nop 0
	s_mov_b32 s71, m0
	s_mov_b32 m0, s49
	s_nop 0
	global_load_lds_dwordx4 v138, s[18:19]
	s_mov_b32 m0, s71
	s_nop 0
	s_mov_b32 s71, m0
	s_mov_b32 m0, s58
	s_nop 0
	global_load_lds_dwordx4 v140, s[18:19]
	s_mov_b32 m0, s71
	s_waitcnt vmcnt(8)
	s_waitcnt lgkmcnt(0)
	s_barrier
	s_setprio 1
	s_waitcnt lgkmcnt(7)
	v_mfma_f32_16x16x32_bf16 v[126:129], v[148:151], v[180:183], 0
	v_mfma_f32_16x16x32_bf16 v[126:129], v[152:155], v[184:187], v[126:129]
	s_waitcnt lgkmcnt(5)
	v_mfma_f32_16x16x32_bf16 v[122:125], v[160:163], v[184:187], 0
	v_mfma_f32_16x16x32_bf16 v[122:125], v[156:159], v[180:183], v[122:125]
	s_waitcnt lgkmcnt(3)
	v_mfma_f32_16x16x32_bf16 v[106:109], v[156:159], v[188:191], 0
	v_mfma_f32_16x16x32_bf16 v[106:109], v[160:163], v[192:195], v[106:109]
	s_waitcnt lgkmcnt(1)
	v_mfma_f32_16x16x32_bf16 v[110:113], v[152:155], v[192:195], 0
	v_mfma_f32_16x16x32_bf16 v[110:113], v[148:151], v[188:191], v[110:113]
	v_mfma_f32_16x16x32_bf16 v[94:97], v[148:151], v[196:199], 0
	v_mfma_f32_16x16x32_bf16 v[94:97], v[152:155], v[200:203], v[94:97]
	v_mfma_f32_16x16x32_bf16 v[90:93], v[160:163], v[200:203], 0
	v_mfma_f32_16x16x32_bf16 v[90:93], v[156:159], v[196:199], v[90:93]
	v_mfma_f32_16x16x32_bf16 v[74:77], v[156:159], v[204:207], 0
	v_mfma_f32_16x16x32_bf16 v[74:77], v[160:163], v[208:211], v[74:77]
	s_waitcnt lgkmcnt(0)
	v_mfma_f32_16x16x32_bf16 v[78:81], v[152:155], v[208:211], 0
	v_mfma_f32_16x16x32_bf16 v[78:81], v[148:151], v[204:207], v[78:81]
	s_setprio 0
	s_setprio 1
	v_mfma_f32_16x16x32_bf16 v[118:121], v[164:167], v[180:183], 0
	v_mfma_f32_16x16x32_bf16 v[118:121], v[168:171], v[184:187], v[118:121]
	v_mfma_f32_16x16x32_bf16 v[114:117], v[176:179], v[184:187], 0
	v_mfma_f32_16x16x32_bf16 v[114:117], v[172:175], v[180:183], v[114:117]
	v_mfma_f32_16x16x32_bf16 v[98:101], v[172:175], v[188:191], 0
	v_mfma_f32_16x16x32_bf16 v[98:101], v[176:179], v[192:195], v[98:101]
	v_mfma_f32_16x16x32_bf16 v[102:105], v[168:171], v[192:195], 0
	v_mfma_f32_16x16x32_bf16 v[102:105], v[164:167], v[188:191], v[102:105]
	v_mfma_f32_16x16x32_bf16 v[86:89], v[164:167], v[196:199], 0
	v_mfma_f32_16x16x32_bf16 v[86:89], v[168:171], v[200:203], v[86:89]
	v_mfma_f32_16x16x32_bf16 v[82:85], v[176:179], v[200:203], 0
	v_mfma_f32_16x16x32_bf16 v[82:85], v[172:175], v[196:199], v[82:85]
	v_mfma_f32_16x16x32_bf16 v[66:69], v[172:175], v[204:207], 0
	v_mfma_f32_16x16x32_bf16 v[66:69], v[176:179], v[208:211], v[66:69]
	s_setprio 2
	s_barrier
	v_mfma_f32_16x16x32_bf16 v[70:73], v[168:171], v[208:211], 0
	v_mfma_f32_16x16x32_bf16 v[70:73], v[164:167], v[204:207], v[70:73]
	s_setprio 0
	ds_read_b128 v[180:183], v145 offset:16384
	ds_read_b128 v[184:187], v145 offset:17408
	ds_read_b128 v[188:191], v145 offset:18432
	ds_read_b128 v[192:195], v145 offset:19456
	ds_read_b128 v[196:199], v145 offset:20480
	ds_read_b128 v[200:203], v145 offset:21504
	ds_read_b128 v[204:207], v145 offset:22528
	ds_read_b128 v[208:211], v145 offset:23552
	s_mov_b32 s71, m0
	s_mov_b32 m0, s35
	s_nop 0
	global_load_lds_dwordx4 v139, s[20:21]
	s_mov_b32 m0, s71
	s_add_u32 s74, s20, 0x80000
	s_mov_b32 s71, m0
	s_mov_b32 m0, s36
	s_nop 0
	global_load_lds_dwordx4 v141, s[20:21]
	s_mov_b32 m0, s71
	s_addc_u32 s75, s21, 0
	s_mov_b32 s71, m0
	s_mov_b32 m0, s37
	s_nop 0
	global_load_lds_dwordx4 v139, s[74:75]
	s_mov_b32 m0, s71
	s_nop 0
	s_mov_b32 s71, m0
	s_mov_b32 m0, s40
	s_nop 0
	global_load_lds_dwordx4 v141, s[74:75]
	s_mov_b32 m0, s71
	s_waitcnt vmcnt(4)
	s_waitcnt lgkmcnt(0)
	s_barrier
	s_setprio 1
	s_waitcnt lgkmcnt(7)
	v_mfma_f32_16x16x32_bf16 v[62:65], v[148:151], v[180:183], 0
	v_mfma_f32_16x16x32_bf16 v[62:65], v[152:155], v[184:187], v[62:65]
	s_waitcnt lgkmcnt(5)
	v_mfma_f32_16x16x32_bf16 v[58:61], v[160:163], v[184:187], 0
	v_mfma_f32_16x16x32_bf16 v[58:61], v[156:159], v[180:183], v[58:61]
	s_waitcnt lgkmcnt(3)
	v_mfma_f32_16x16x32_bf16 v[42:45], v[156:159], v[188:191], 0
	v_mfma_f32_16x16x32_bf16 v[42:45], v[160:163], v[192:195], v[42:45]
	s_waitcnt lgkmcnt(1)
	v_mfma_f32_16x16x32_bf16 v[46:49], v[152:155], v[192:195], 0
	v_mfma_f32_16x16x32_bf16 v[46:49], v[148:151], v[188:191], v[46:49]
	v_mfma_f32_16x16x32_bf16 v[30:33], v[148:151], v[196:199], 0
	v_mfma_f32_16x16x32_bf16 v[30:33], v[152:155], v[200:203], v[30:33]
	v_mfma_f32_16x16x32_bf16 v[26:29], v[160:163], v[200:203], 0
	v_mfma_f32_16x16x32_bf16 v[26:29], v[156:159], v[196:199], v[26:29]
	v_mfma_f32_16x16x32_bf16 v[10:13], v[156:159], v[204:207], 0
	v_mfma_f32_16x16x32_bf16 v[10:13], v[160:163], v[208:211], v[10:13]
	s_waitcnt lgkmcnt(0)
	v_mfma_f32_16x16x32_bf16 v[14:17], v[152:155], v[208:211], 0
	v_mfma_f32_16x16x32_bf16 v[14:17], v[148:151], v[204:207], v[14:17]
	s_setprio 0
	s_setprio 1
	v_mfma_f32_16x16x32_bf16 v[54:57], v[164:167], v[180:183], 0
	v_mfma_f32_16x16x32_bf16 v[54:57], v[168:171], v[184:187], v[54:57]
	v_mfma_f32_16x16x32_bf16 v[50:53], v[176:179], v[184:187], 0
	v_mfma_f32_16x16x32_bf16 v[50:53], v[172:175], v[180:183], v[50:53]
	v_mfma_f32_16x16x32_bf16 v[34:37], v[172:175], v[188:191], 0
	v_mfma_f32_16x16x32_bf16 v[34:37], v[176:179], v[192:195], v[34:37]
	v_mfma_f32_16x16x32_bf16 v[38:41], v[168:171], v[192:195], 0
	v_mfma_f32_16x16x32_bf16 v[38:41], v[164:167], v[188:191], v[38:41]
	v_mfma_f32_16x16x32_bf16 v[22:25], v[164:167], v[196:199], 0
	v_mfma_f32_16x16x32_bf16 v[22:25], v[168:171], v[200:203], v[22:25]
	v_mfma_f32_16x16x32_bf16 v[18:21], v[176:179], v[200:203], 0
	v_mfma_f32_16x16x32_bf16 v[18:21], v[172:175], v[196:199], v[18:21]
	v_mfma_f32_16x16x32_bf16 v[2:5], v[172:175], v[204:207], 0
	v_mfma_f32_16x16x32_bf16 v[2:5], v[176:179], v[208:211], v[2:5]
	s_setprio 2
	s_barrier
	v_mfma_f32_16x16x32_bf16 v[6:9], v[168:171], v[208:211], 0
	v_mfma_f32_16x16x32_bf16 v[6:9], v[164:167], v[204:207], v[6:9]
	s_setprio 0
	ds_read_b128 v[148:151], v146
	ds_read_b128 v[152:155], v146 offset:1024
	ds_read_b128 v[156:159], v146 offset:2048
	ds_read_b128 v[160:163], v146 offset:3072
	ds_read_b128 v[164:167], v147
	ds_read_b128 v[168:171], v147 offset:1024
	ds_read_b128 v[172:175], v147 offset:2048
	ds_read_b128 v[176:179], v147 offset:3072
	ds_read_b128 v[180:183], v145 offset:32768
	ds_read_b128 v[184:187], v145 offset:33792
	ds_read_b128 v[188:191], v145 offset:34816
	ds_read_b128 v[192:195], v145 offset:35840
	ds_read_b128 v[196:199], v145 offset:36864
	ds_read_b128 v[200:203], v145 offset:37888
	ds_read_b128 v[204:207], v145 offset:38912
	ds_read_b128 v[208:211], v145 offset:39936
	s_mov_b32 s71, m0
	s_mov_b32 m0, s31
	s_nop 0
	global_load_lds_dwordx4 v138, s[22:23]
	s_mov_b32 m0, s71
	s_nop 0
	s_mov_b32 s71, m0
	s_mov_b32 m0, s41
	s_nop 0
	global_load_lds_dwordx4 v140, s[22:23]
	s_mov_b32 m0, s71
	s_add_u32 s22, s22, 0x80000
	s_addc_u32 s23, s23, 0
	s_mov_b32 s71, m0
	s_mov_b32 m0, s42
	s_nop 0
	global_load_lds_dwordx4 v138, s[22:23]
	s_mov_b32 m0, s71
	s_nop 0
	s_mov_b32 s71, m0
	s_mov_b32 m0, s43
	s_nop 0
	global_load_lds_dwordx4 v140, s[22:23]
	s_mov_b32 m0, s71
	s_waitcnt vmcnt(8)
	s_waitcnt lgkmcnt(0)
	s_barrier
	s_setprio 1
	s_waitcnt lgkmcnt(7)
	v_mfma_f32_16x16x32_bf16 v[126:129], v[148:151], v[180:183], v[126:129]
	v_mfma_f32_16x16x32_bf16 v[126:129], v[152:155], v[184:187], v[126:129]
	s_waitcnt lgkmcnt(5)
	v_mfma_f32_16x16x32_bf16 v[122:125], v[160:163], v[184:187], v[122:125]
	v_mfma_f32_16x16x32_bf16 v[122:125], v[156:159], v[180:183], v[122:125]
	s_waitcnt lgkmcnt(3)
	v_mfma_f32_16x16x32_bf16 v[106:109], v[156:159], v[188:191], v[106:109]
	v_mfma_f32_16x16x32_bf16 v[106:109], v[160:163], v[192:195], v[106:109]
	s_waitcnt lgkmcnt(1)
	v_mfma_f32_16x16x32_bf16 v[110:113], v[152:155], v[192:195], v[110:113]
	v_mfma_f32_16x16x32_bf16 v[110:113], v[148:151], v[188:191], v[110:113]
	v_mfma_f32_16x16x32_bf16 v[94:97], v[148:151], v[196:199], v[94:97]
	v_mfma_f32_16x16x32_bf16 v[94:97], v[152:155], v[200:203], v[94:97]
	v_mfma_f32_16x16x32_bf16 v[90:93], v[160:163], v[200:203], v[90:93]
	v_mfma_f32_16x16x32_bf16 v[90:93], v[156:159], v[196:199], v[90:93]
	v_mfma_f32_16x16x32_bf16 v[74:77], v[156:159], v[204:207], v[74:77]
	v_mfma_f32_16x16x32_bf16 v[74:77], v[160:163], v[208:211], v[74:77]
	s_waitcnt lgkmcnt(0)
	v_mfma_f32_16x16x32_bf16 v[78:81], v[152:155], v[208:211], v[78:81]
	v_mfma_f32_16x16x32_bf16 v[78:81], v[148:151], v[204:207], v[78:81]
	s_setprio 0
	s_setprio 1
	v_mfma_f32_16x16x32_bf16 v[118:121], v[164:167], v[180:183], v[118:121]
	v_mfma_f32_16x16x32_bf16 v[118:121], v[168:171], v[184:187], v[118:121]
	v_mfma_f32_16x16x32_bf16 v[114:117], v[176:179], v[184:187], v[114:117]
	v_mfma_f32_16x16x32_bf16 v[114:117], v[172:175], v[180:183], v[114:117]
	v_mfma_f32_16x16x32_bf16 v[98:101], v[172:175], v[188:191], v[98:101]
	v_mfma_f32_16x16x32_bf16 v[98:101], v[176:179], v[192:195], v[98:101]
	v_mfma_f32_16x16x32_bf16 v[102:105], v[168:171], v[192:195], v[102:105]
	v_mfma_f32_16x16x32_bf16 v[102:105], v[164:167], v[188:191], v[102:105]
	v_mfma_f32_16x16x32_bf16 v[86:89], v[164:167], v[196:199], v[86:89]
	v_mfma_f32_16x16x32_bf16 v[86:89], v[168:171], v[200:203], v[86:89]
	v_mfma_f32_16x16x32_bf16 v[82:85], v[176:179], v[200:203], v[82:85]
	v_mfma_f32_16x16x32_bf16 v[82:85], v[172:175], v[196:199], v[82:85]
	v_mfma_f32_16x16x32_bf16 v[66:69], v[172:175], v[204:207], v[66:69]
	v_mfma_f32_16x16x32_bf16 v[66:69], v[176:179], v[208:211], v[66:69]
	s_setprio 2
	s_barrier
	v_mfma_f32_16x16x32_bf16 v[70:73], v[168:171], v[208:211], v[70:73]
	v_mfma_f32_16x16x32_bf16 v[70:73], v[164:167], v[204:207], v[70:73]
	s_setprio 0
	ds_read_b128 v[180:183], v145 offset:49152
	ds_read_b128 v[184:187], v145 offset:50176
	ds_read_b128 v[188:191], v145 offset:51200
	ds_read_b128 v[192:195], v145 offset:52224
	ds_read_b128 v[196:199], v145 offset:53248
	ds_read_b128 v[200:203], v145 offset:54272
	ds_read_b128 v[204:207], v145 offset:55296
	ds_read_b128 v[208:211], v145 offset:56320
	s_add_u32 s22, s20, 0x80
	s_addc_u32 s23, s21, 0
	s_mov_b32 s71, m0
	s_mov_b32 m0, s44
	s_nop 0
	global_load_lds_dwordx4 v139, s[22:23]
	s_mov_b32 m0, s71
	s_add_u32 s20, s20, 0x80080
	s_mov_b32 s71, m0
	s_mov_b32 m0, s45
	s_nop 0
	global_load_lds_dwordx4 v141, s[22:23]
	s_mov_b32 m0, s71
	s_addc_u32 s21, s21, 0
	s_mov_b32 s22, m0
	s_mov_b32 m0, s46
	s_nop 0
	global_load_lds_dwordx4 v139, s[20:21]
	s_mov_b32 m0, s22
	s_nop 0
	s_mov_b32 s22, m0
	s_mov_b32 m0, s47
	s_nop 0
	global_load_lds_dwordx4 v141, s[20:21]
	s_mov_b32 m0, s22
	s_waitcnt vmcnt(4)
	s_waitcnt lgkmcnt(0)
	s_barrier
	s_setprio 1
	s_waitcnt lgkmcnt(7)
	v_mfma_f32_16x16x32_bf16 v[62:65], v[148:151], v[180:183], v[62:65]
	v_mfma_f32_16x16x32_bf16 v[62:65], v[152:155], v[184:187], v[62:65]
	s_waitcnt lgkmcnt(5)
	v_mfma_f32_16x16x32_bf16 v[58:61], v[160:163], v[184:187], v[58:61]
	v_mfma_f32_16x16x32_bf16 v[58:61], v[156:159], v[180:183], v[58:61]
	s_waitcnt lgkmcnt(3)
	v_mfma_f32_16x16x32_bf16 v[42:45], v[156:159], v[188:191], v[42:45]
	v_mfma_f32_16x16x32_bf16 v[42:45], v[160:163], v[192:195], v[42:45]
	s_waitcnt lgkmcnt(1)
	v_mfma_f32_16x16x32_bf16 v[46:49], v[152:155], v[192:195], v[46:49]
	v_mfma_f32_16x16x32_bf16 v[46:49], v[148:151], v[188:191], v[46:49]
	v_mfma_f32_16x16x32_bf16 v[30:33], v[148:151], v[196:199], v[30:33]
	v_mfma_f32_16x16x32_bf16 v[30:33], v[152:155], v[200:203], v[30:33]
	v_mfma_f32_16x16x32_bf16 v[26:29], v[160:163], v[200:203], v[26:29]
	v_mfma_f32_16x16x32_bf16 v[26:29], v[156:159], v[196:199], v[26:29]
	v_mfma_f32_16x16x32_bf16 v[10:13], v[156:159], v[204:207], v[10:13]
	v_mfma_f32_16x16x32_bf16 v[10:13], v[160:163], v[208:211], v[10:13]
	s_waitcnt lgkmcnt(0)
	v_mfma_f32_16x16x32_bf16 v[14:17], v[152:155], v[208:211], v[14:17]
	v_mfma_f32_16x16x32_bf16 v[14:17], v[148:151], v[204:207], v[14:17]
	s_setprio 0
	s_setprio 1
	v_mfma_f32_16x16x32_bf16 v[54:57], v[164:167], v[180:183], v[54:57]
	v_mfma_f32_16x16x32_bf16 v[54:57], v[168:171], v[184:187], v[54:57]
	v_mfma_f32_16x16x32_bf16 v[50:53], v[176:179], v[184:187], v[50:53]
	v_mfma_f32_16x16x32_bf16 v[50:53], v[172:175], v[180:183], v[50:53]
	v_mfma_f32_16x16x32_bf16 v[34:37], v[172:175], v[188:191], v[34:37]
	v_mfma_f32_16x16x32_bf16 v[34:37], v[176:179], v[192:195], v[34:37]
	v_mfma_f32_16x16x32_bf16 v[38:41], v[168:171], v[192:195], v[38:41]
	v_mfma_f32_16x16x32_bf16 v[38:41], v[164:167], v[188:191], v[38:41]
	v_mfma_f32_16x16x32_bf16 v[22:25], v[164:167], v[196:199], v[22:25]
	v_mfma_f32_16x16x32_bf16 v[22:25], v[168:171], v[200:203], v[22:25]
	v_mfma_f32_16x16x32_bf16 v[18:21], v[176:179], v[200:203], v[18:21]
	v_mfma_f32_16x16x32_bf16 v[18:21], v[172:175], v[196:199], v[18:21]
	v_mfma_f32_16x16x32_bf16 v[2:5], v[172:175], v[204:207], v[2:5]
	v_mfma_f32_16x16x32_bf16 v[2:5], v[176:179], v[208:211], v[2:5]
	s_setprio 2
	s_barrier
	v_mfma_f32_16x16x32_bf16 v[6:9], v[168:171], v[208:211], v[6:9]
	v_mfma_f32_16x16x32_bf16 v[6:9], v[164:167], v[204:207], v[6:9]
	s_setprio 0
	s_add_i32 s70, s70, 2
	s_add_u32 s64, s64, 0x100
	s_addc_u32 s65, s65, 0
	s_add_u32 s18, s18, 0x100
	s_addc_u32 s19, s19, 0
	s_add_u32 s66, s66, 0x100
	s_addc_u32 s67, s67, 0
	s_cmp_gt_u32 s70, 29
	.p2align 6
.LBB0_2594:
	ds_read_b128 v[148:151], v143
	ds_read_b128 v[152:155], v143 offset:1024
	ds_read_b128 v[156:159], v143 offset:2048
	ds_read_b128 v[160:163], v143 offset:3072
	ds_read_b128 v[164:167], v144
	ds_read_b128 v[168:171], v144 offset:1024
	ds_read_b128 v[172:175], v144 offset:2048
	ds_read_b128 v[176:179], v144 offset:3072
	s_cmp_eq_u32 s70, 28
	s_cselect_b32 s21, s9, s65
	s_cselect_b32 s20, s63, s64
	s_cselect_b32 s23, s11, s67
	s_cselect_b32 s22, s62, s66
	ds_read_b128 v[180:183], v145
	ds_read_b128 v[184:187], v145 offset:1024
	ds_read_b128 v[188:191], v145 offset:2048
	ds_read_b128 v[192:195], v145 offset:3072
	ds_read_b128 v[196:199], v145 offset:4096
	ds_read_b128 v[200:203], v145 offset:5120
	ds_read_b128 v[204:207], v145 offset:6144
	ds_read_b128 v[208:211], v145 offset:7168
	s_add_u32 s74, s18, 0xfff80000
	s_addc_u32 s75, s19, -1
	s_mov_b32 s71, m0
	s_mov_b32 m0, s48
	s_nop 0
	global_load_lds_dwordx4 v138, s[74:75]
	s_mov_b32 m0, s71
	s_nop 0
	s_mov_b32 s71, m0
	s_mov_b32 m0, s57
	s_nop 0
	global_load_lds_dwordx4 v140, s[74:75]
	s_mov_b32 m0, s71
	s_nop 0
	s_mov_b32 s71, m0
	s_mov_b32 m0, s49
	s_nop 0
	global_load_lds_dwordx4 v138, s[18:19]
	s_mov_b32 m0, s71
	s_nop 0
	s_mov_b32 s71, m0
	s_mov_b32 m0, s58
	s_nop 0
	global_load_lds_dwordx4 v140, s[18:19]
	s_mov_b32 m0, s71
	s_waitcnt vmcnt(8)
	s_waitcnt lgkmcnt(0)
	s_barrier
	s_setprio 1
	s_waitcnt lgkmcnt(7)
	v_mfma_f32_16x16x32_bf16 v[126:129], v[148:151], v[180:183], v[126:129]
	v_mfma_f32_16x16x32_bf16 v[126:129], v[152:155], v[184:187], v[126:129]
	s_waitcnt lgkmcnt(5)
	v_mfma_f32_16x16x32_bf16 v[122:125], v[160:163], v[184:187], v[122:125]
	v_mfma_f32_16x16x32_bf16 v[122:125], v[156:159], v[180:183], v[122:125]
	s_waitcnt lgkmcnt(3)
	v_mfma_f32_16x16x32_bf16 v[106:109], v[156:159], v[188:191], v[106:109]
	v_mfma_f32_16x16x32_bf16 v[106:109], v[160:163], v[192:195], v[106:109]
	s_waitcnt lgkmcnt(1)
	v_mfma_f32_16x16x32_bf16 v[110:113], v[152:155], v[192:195], v[110:113]
	v_mfma_f32_16x16x32_bf16 v[110:113], v[148:151], v[188:191], v[110:113]
	v_mfma_f32_16x16x32_bf16 v[94:97], v[148:151], v[196:199], v[94:97]
	v_mfma_f32_16x16x32_bf16 v[94:97], v[152:155], v[200:203], v[94:97]
	v_mfma_f32_16x16x32_bf16 v[90:93], v[160:163], v[200:203], v[90:93]
	v_mfma_f32_16x16x32_bf16 v[90:93], v[156:159], v[196:199], v[90:93]
	v_mfma_f32_16x16x32_bf16 v[74:77], v[156:159], v[204:207], v[74:77]
	v_mfma_f32_16x16x32_bf16 v[74:77], v[160:163], v[208:211], v[74:77]
	s_waitcnt lgkmcnt(0)
	v_mfma_f32_16x16x32_bf16 v[78:81], v[152:155], v[208:211], v[78:81]
	v_mfma_f32_16x16x32_bf16 v[78:81], v[148:151], v[204:207], v[78:81]
	s_setprio 0
	s_setprio 1
	v_mfma_f32_16x16x32_bf16 v[118:121], v[164:167], v[180:183], v[118:121]
	v_mfma_f32_16x16x32_bf16 v[118:121], v[168:171], v[184:187], v[118:121]
	v_mfma_f32_16x16x32_bf16 v[114:117], v[176:179], v[184:187], v[114:117]
	v_mfma_f32_16x16x32_bf16 v[114:117], v[172:175], v[180:183], v[114:117]
	v_mfma_f32_16x16x32_bf16 v[98:101], v[172:175], v[188:191], v[98:101]
	v_mfma_f32_16x16x32_bf16 v[98:101], v[176:179], v[192:195], v[98:101]
	v_mfma_f32_16x16x32_bf16 v[102:105], v[168:171], v[192:195], v[102:105]
	v_mfma_f32_16x16x32_bf16 v[102:105], v[164:167], v[188:191], v[102:105]
	v_mfma_f32_16x16x32_bf16 v[86:89], v[164:167], v[196:199], v[86:89]
	v_mfma_f32_16x16x32_bf16 v[86:89], v[168:171], v[200:203], v[86:89]
	v_mfma_f32_16x16x32_bf16 v[82:85], v[176:179], v[200:203], v[82:85]
	v_mfma_f32_16x16x32_bf16 v[82:85], v[172:175], v[196:199], v[82:85]
	v_mfma_f32_16x16x32_bf16 v[66:69], v[172:175], v[204:207], v[66:69]
	v_mfma_f32_16x16x32_bf16 v[66:69], v[176:179], v[208:211], v[66:69]
	s_setprio 2
	s_barrier
	v_mfma_f32_16x16x32_bf16 v[70:73], v[168:171], v[208:211], v[70:73]
	v_mfma_f32_16x16x32_bf16 v[70:73], v[164:167], v[204:207], v[70:73]
	s_setprio 0
	ds_read_b128 v[180:183], v145 offset:16384
	ds_read_b128 v[184:187], v145 offset:17408
	ds_read_b128 v[188:191], v145 offset:18432
	ds_read_b128 v[192:195], v145 offset:19456
	ds_read_b128 v[196:199], v145 offset:20480
	ds_read_b128 v[200:203], v145 offset:21504
	ds_read_b128 v[204:207], v145 offset:22528
	ds_read_b128 v[208:211], v145 offset:23552
	s_mov_b32 s71, m0
	s_mov_b32 m0, s35
	s_nop 0
	global_load_lds_dwordx4 v139, s[20:21]
	s_mov_b32 m0, s71
	s_add_u32 s74, s20, 0x80000
	s_mov_b32 s71, m0
	s_mov_b32 m0, s36
	s_nop 0
	global_load_lds_dwordx4 v141, s[20:21]
	s_mov_b32 m0, s71
	s_addc_u32 s75, s21, 0
	s_mov_b32 s71, m0
	s_mov_b32 m0, s37
	s_nop 0
	global_load_lds_dwordx4 v139, s[74:75]
	s_mov_b32 m0, s71
	s_nop 0
	s_mov_b32 s71, m0
	s_mov_b32 m0, s40
	s_nop 0
	global_load_lds_dwordx4 v141, s[74:75]
	s_mov_b32 m0, s71
	s_waitcnt vmcnt(4)
	s_waitcnt lgkmcnt(0)
	s_barrier
	s_setprio 1
	s_waitcnt lgkmcnt(7)
	v_mfma_f32_16x16x32_bf16 v[62:65], v[148:151], v[180:183], v[62:65]
	v_mfma_f32_16x16x32_bf16 v[62:65], v[152:155], v[184:187], v[62:65]
	s_waitcnt lgkmcnt(5)
	v_mfma_f32_16x16x32_bf16 v[58:61], v[160:163], v[184:187], v[58:61]
	v_mfma_f32_16x16x32_bf16 v[58:61], v[156:159], v[180:183], v[58:61]
	s_waitcnt lgkmcnt(3)
	v_mfma_f32_16x16x32_bf16 v[42:45], v[156:159], v[188:191], v[42:45]
	v_mfma_f32_16x16x32_bf16 v[42:45], v[160:163], v[192:195], v[42:45]
	s_waitcnt lgkmcnt(1)
	v_mfma_f32_16x16x32_bf16 v[46:49], v[152:155], v[192:195], v[46:49]
	v_mfma_f32_16x16x32_bf16 v[46:49], v[148:151], v[188:191], v[46:49]
	v_mfma_f32_16x16x32_bf16 v[30:33], v[148:151], v[196:199], v[30:33]
	v_mfma_f32_16x16x32_bf16 v[30:33], v[152:155], v[200:203], v[30:33]
	v_mfma_f32_16x16x32_bf16 v[26:29], v[160:163], v[200:203], v[26:29]
	v_mfma_f32_16x16x32_bf16 v[26:29], v[156:159], v[196:199], v[26:29]
	v_mfma_f32_16x16x32_bf16 v[10:13], v[156:159], v[204:207], v[10:13]
	v_mfma_f32_16x16x32_bf16 v[10:13], v[160:163], v[208:211], v[10:13]
	s_waitcnt lgkmcnt(0)
	v_mfma_f32_16x16x32_bf16 v[14:17], v[152:155], v[208:211], v[14:17]
	v_mfma_f32_16x16x32_bf16 v[14:17], v[148:151], v[204:207], v[14:17]
	s_setprio 0
	s_setprio 1
	v_mfma_f32_16x16x32_bf16 v[54:57], v[164:167], v[180:183], v[54:57]
	v_mfma_f32_16x16x32_bf16 v[54:57], v[168:171], v[184:187], v[54:57]
	v_mfma_f32_16x16x32_bf16 v[50:53], v[176:179], v[184:187], v[50:53]
	v_mfma_f32_16x16x32_bf16 v[50:53], v[172:175], v[180:183], v[50:53]
	v_mfma_f32_16x16x32_bf16 v[34:37], v[172:175], v[188:191], v[34:37]
	v_mfma_f32_16x16x32_bf16 v[34:37], v[176:179], v[192:195], v[34:37]
	v_mfma_f32_16x16x32_bf16 v[38:41], v[168:171], v[192:195], v[38:41]
	v_mfma_f32_16x16x32_bf16 v[38:41], v[164:167], v[188:191], v[38:41]
	v_mfma_f32_16x16x32_bf16 v[22:25], v[164:167], v[196:199], v[22:25]
	v_mfma_f32_16x16x32_bf16 v[22:25], v[168:171], v[200:203], v[22:25]
	v_mfma_f32_16x16x32_bf16 v[18:21], v[176:179], v[200:203], v[18:21]
	v_mfma_f32_16x16x32_bf16 v[18:21], v[172:175], v[196:199], v[18:21]
	v_mfma_f32_16x16x32_bf16 v[2:5], v[172:175], v[204:207], v[2:5]
	v_mfma_f32_16x16x32_bf16 v[2:5], v[176:179], v[208:211], v[2:5]
	s_setprio 2
	s_barrier
	v_mfma_f32_16x16x32_bf16 v[6:9], v[168:171], v[208:211], v[6:9]
	v_mfma_f32_16x16x32_bf16 v[6:9], v[164:167], v[204:207], v[6:9]
	s_setprio 0
	ds_read_b128 v[148:151], v146
	ds_read_b128 v[152:155], v146 offset:1024
	ds_read_b128 v[156:159], v146 offset:2048
	ds_read_b128 v[160:163], v146 offset:3072
	ds_read_b128 v[164:167], v147
	ds_read_b128 v[168:171], v147 offset:1024
	ds_read_b128 v[172:175], v147 offset:2048
	ds_read_b128 v[176:179], v147 offset:3072
	ds_read_b128 v[180:183], v145 offset:32768
	ds_read_b128 v[184:187], v145 offset:33792
	ds_read_b128 v[188:191], v145 offset:34816
	ds_read_b128 v[192:195], v145 offset:35840
	ds_read_b128 v[196:199], v145 offset:36864
	ds_read_b128 v[200:203], v145 offset:37888
	ds_read_b128 v[204:207], v145 offset:38912
	ds_read_b128 v[208:211], v145 offset:39936
	s_mov_b32 s71, m0
	s_mov_b32 m0, s31
	s_nop 0
	global_load_lds_dwordx4 v138, s[22:23]
	s_mov_b32 m0, s71
	s_nop 0
	s_mov_b32 s71, m0
	s_mov_b32 m0, s41
	s_nop 0
	global_load_lds_dwordx4 v140, s[22:23]
	s_mov_b32 m0, s71
	s_add_u32 s22, s22, 0x80000
	s_addc_u32 s23, s23, 0
	s_mov_b32 s71, m0
	s_mov_b32 m0, s42
	s_nop 0
	global_load_lds_dwordx4 v138, s[22:23]
	s_mov_b32 m0, s71
	s_nop 0
	s_mov_b32 s71, m0
	s_mov_b32 m0, s43
	s_nop 0
	global_load_lds_dwordx4 v140, s[22:23]
	s_mov_b32 m0, s71
	s_waitcnt vmcnt(8)
	s_waitcnt lgkmcnt(0)
	s_barrier
	s_setprio 1
	s_waitcnt lgkmcnt(7)
	v_mfma_f32_16x16x32_bf16 v[126:129], v[148:151], v[180:183], v[126:129]
	v_mfma_f32_16x16x32_bf16 v[126:129], v[152:155], v[184:187], v[126:129]
	s_waitcnt lgkmcnt(5)
	v_mfma_f32_16x16x32_bf16 v[122:125], v[160:163], v[184:187], v[122:125]
	v_mfma_f32_16x16x32_bf16 v[122:125], v[156:159], v[180:183], v[122:125]
	s_waitcnt lgkmcnt(3)
	v_mfma_f32_16x16x32_bf16 v[106:109], v[156:159], v[188:191], v[106:109]
	v_mfma_f32_16x16x32_bf16 v[106:109], v[160:163], v[192:195], v[106:109]
	s_waitcnt lgkmcnt(1)
	v_mfma_f32_16x16x32_bf16 v[110:113], v[152:155], v[192:195], v[110:113]
	v_mfma_f32_16x16x32_bf16 v[110:113], v[148:151], v[188:191], v[110:113]
	v_mfma_f32_16x16x32_bf16 v[94:97], v[148:151], v[196:199], v[94:97]
	v_mfma_f32_16x16x32_bf16 v[94:97], v[152:155], v[200:203], v[94:97]
	v_mfma_f32_16x16x32_bf16 v[90:93], v[160:163], v[200:203], v[90:93]
	v_mfma_f32_16x16x32_bf16 v[90:93], v[156:159], v[196:199], v[90:93]
	v_mfma_f32_16x16x32_bf16 v[74:77], v[156:159], v[204:207], v[74:77]
	v_mfma_f32_16x16x32_bf16 v[74:77], v[160:163], v[208:211], v[74:77]
	s_waitcnt lgkmcnt(0)
	v_mfma_f32_16x16x32_bf16 v[78:81], v[152:155], v[208:211], v[78:81]
	v_mfma_f32_16x16x32_bf16 v[78:81], v[148:151], v[204:207], v[78:81]
	s_setprio 0
	s_setprio 1
	v_mfma_f32_16x16x32_bf16 v[118:121], v[164:167], v[180:183], v[118:121]
	v_mfma_f32_16x16x32_bf16 v[118:121], v[168:171], v[184:187], v[118:121]
	v_mfma_f32_16x16x32_bf16 v[114:117], v[176:179], v[184:187], v[114:117]
	v_mfma_f32_16x16x32_bf16 v[114:117], v[172:175], v[180:183], v[114:117]
	v_mfma_f32_16x16x32_bf16 v[98:101], v[172:175], v[188:191], v[98:101]
	v_mfma_f32_16x16x32_bf16 v[98:101], v[176:179], v[192:195], v[98:101]
	v_mfma_f32_16x16x32_bf16 v[102:105], v[168:171], v[192:195], v[102:105]
	v_mfma_f32_16x16x32_bf16 v[102:105], v[164:167], v[188:191], v[102:105]
	v_mfma_f32_16x16x32_bf16 v[86:89], v[164:167], v[196:199], v[86:89]
	v_mfma_f32_16x16x32_bf16 v[86:89], v[168:171], v[200:203], v[86:89]
	v_mfma_f32_16x16x32_bf16 v[82:85], v[176:179], v[200:203], v[82:85]
	v_mfma_f32_16x16x32_bf16 v[82:85], v[172:175], v[196:199], v[82:85]
	v_mfma_f32_16x16x32_bf16 v[66:69], v[172:175], v[204:207], v[66:69]
	v_mfma_f32_16x16x32_bf16 v[66:69], v[176:179], v[208:211], v[66:69]
	s_setprio 2
	s_barrier
	v_mfma_f32_16x16x32_bf16 v[70:73], v[168:171], v[208:211], v[70:73]
	v_mfma_f32_16x16x32_bf16 v[70:73], v[164:167], v[204:207], v[70:73]
	s_setprio 0
	ds_read_b128 v[180:183], v145 offset:49152
	ds_read_b128 v[184:187], v145 offset:50176
	ds_read_b128 v[188:191], v145 offset:51200
	ds_read_b128 v[192:195], v145 offset:52224
	ds_read_b128 v[196:199], v145 offset:53248
	ds_read_b128 v[200:203], v145 offset:54272
	ds_read_b128 v[204:207], v145 offset:55296
	ds_read_b128 v[208:211], v145 offset:56320
	s_add_u32 s22, s20, 0x80
	s_addc_u32 s23, s21, 0
	s_mov_b32 s71, m0
	s_mov_b32 m0, s44
	s_nop 0
	global_load_lds_dwordx4 v139, s[22:23]
	s_mov_b32 m0, s71
	s_add_u32 s20, s20, 0x80080
	s_mov_b32 s71, m0
	s_mov_b32 m0, s45
	s_nop 0
	global_load_lds_dwordx4 v141, s[22:23]
	s_mov_b32 m0, s71
	s_addc_u32 s21, s21, 0
	s_mov_b32 s22, m0
	s_mov_b32 m0, s46
	s_nop 0
	global_load_lds_dwordx4 v139, s[20:21]
	s_mov_b32 m0, s22
	s_nop 0
	s_mov_b32 s22, m0
	s_mov_b32 m0, s47
	s_nop 0
	global_load_lds_dwordx4 v141, s[20:21]
	s_mov_b32 m0, s22
	s_waitcnt vmcnt(4)
	s_waitcnt lgkmcnt(0)
	s_barrier
	s_setprio 1
	s_waitcnt lgkmcnt(7)
	v_mfma_f32_16x16x32_bf16 v[62:65], v[148:151], v[180:183], v[62:65]
	v_mfma_f32_16x16x32_bf16 v[62:65], v[152:155], v[184:187], v[62:65]
	s_waitcnt lgkmcnt(5)
	v_mfma_f32_16x16x32_bf16 v[58:61], v[160:163], v[184:187], v[58:61]
	v_mfma_f32_16x16x32_bf16 v[58:61], v[156:159], v[180:183], v[58:61]
	s_waitcnt lgkmcnt(3)
	v_mfma_f32_16x16x32_bf16 v[42:45], v[156:159], v[188:191], v[42:45]
	v_mfma_f32_16x16x32_bf16 v[42:45], v[160:163], v[192:195], v[42:45]
	s_waitcnt lgkmcnt(1)
	v_mfma_f32_16x16x32_bf16 v[46:49], v[152:155], v[192:195], v[46:49]
	v_mfma_f32_16x16x32_bf16 v[46:49], v[148:151], v[188:191], v[46:49]
	v_mfma_f32_16x16x32_bf16 v[30:33], v[148:151], v[196:199], v[30:33]
	v_mfma_f32_16x16x32_bf16 v[30:33], v[152:155], v[200:203], v[30:33]
	v_mfma_f32_16x16x32_bf16 v[26:29], v[160:163], v[200:203], v[26:29]
	v_mfma_f32_16x16x32_bf16 v[26:29], v[156:159], v[196:199], v[26:29]
	v_mfma_f32_16x16x32_bf16 v[10:13], v[156:159], v[204:207], v[10:13]
	v_mfma_f32_16x16x32_bf16 v[10:13], v[160:163], v[208:211], v[10:13]
	s_waitcnt lgkmcnt(0)
	v_mfma_f32_16x16x32_bf16 v[14:17], v[152:155], v[208:211], v[14:17]
	v_mfma_f32_16x16x32_bf16 v[14:17], v[148:151], v[204:207], v[14:17]
	s_setprio 0
	s_setprio 1
	v_mfma_f32_16x16x32_bf16 v[54:57], v[164:167], v[180:183], v[54:57]
	v_mfma_f32_16x16x32_bf16 v[54:57], v[168:171], v[184:187], v[54:57]
	v_mfma_f32_16x16x32_bf16 v[50:53], v[176:179], v[184:187], v[50:53]
	v_mfma_f32_16x16x32_bf16 v[50:53], v[172:175], v[180:183], v[50:53]
	v_mfma_f32_16x16x32_bf16 v[34:37], v[172:175], v[188:191], v[34:37]
	v_mfma_f32_16x16x32_bf16 v[34:37], v[176:179], v[192:195], v[34:37]
	v_mfma_f32_16x16x32_bf16 v[38:41], v[168:171], v[192:195], v[38:41]
	v_mfma_f32_16x16x32_bf16 v[38:41], v[164:167], v[188:191], v[38:41]
	v_mfma_f32_16x16x32_bf16 v[22:25], v[164:167], v[196:199], v[22:25]
	v_mfma_f32_16x16x32_bf16 v[22:25], v[168:171], v[200:203], v[22:25]
	v_mfma_f32_16x16x32_bf16 v[18:21], v[176:179], v[200:203], v[18:21]
	v_mfma_f32_16x16x32_bf16 v[18:21], v[172:175], v[196:199], v[18:21]
	v_mfma_f32_16x16x32_bf16 v[2:5], v[172:175], v[204:207], v[2:5]
	v_mfma_f32_16x16x32_bf16 v[2:5], v[176:179], v[208:211], v[2:5]
	s_setprio 2
	s_barrier
	v_mfma_f32_16x16x32_bf16 v[6:9], v[168:171], v[208:211], v[6:9]
	v_mfma_f32_16x16x32_bf16 v[6:9], v[164:167], v[204:207], v[6:9]
	s_setprio 0
	s_add_i32 s70, s70, 2
	s_add_u32 s64, s64, 0x100
	s_addc_u32 s65, s65, 0
	s_add_u32 s18, s18, 0x100
	s_addc_u32 s19, s19, 0
	s_add_u32 s66, s66, 0x100
	s_addc_u32 s67, s67, 0
	s_cmp_gt_u32 s70, 29
	s_cbranch_scc0 .LBB0_2594
	s_and_b64 vcc, exec, s[6:7]
	s_cbranch_vccz .LBB0_2597
	s_barrier

.LBB0_2791:
	s_ashr_i32 s21, s20, 31
	s_lshl_b64 s[22:23], s[20:21], 15
	s_add_u32 s22, s37, s22
	s_addc_u32 s23, s40, s23
	s_and_b64 s[24:25], s[2:3], exec
	s_cselect_b32 s21, s23, s31
	s_cselect_b32 s63, s22, s30
	s_ashr_i32 s19, s18, 31
	s_lshl_b64 s[24:25], s[18:19], 15
	s_add_u32 s24, s41, s24
	s_addc_u32 s25, s42, s25
	s_and_b64 s[34:35], s[2:3], exec
	s_cselect_b32 s19, s25, s29
	s_cselect_b32 s64, s24, s28
	s_add_u32 s65, s28, 0x80000
	s_addc_u32 s66, s29, 0
	s_add_u32 s28, s30, 0x204000
	s_addc_u32 s29, s31, 0
	s_add_u32 s67, s30, 0x400000
	s_addc_u32 s68, s31, 0
	s_mov_b32 s69, -2
	s_waitcnt vmcnt(25)
	s_waitcnt vmcnt(24)
	s_waitcnt vmcnt(4)
	s_waitcnt vmcnt(2)
	s_waitcnt vmcnt(1)
	s_waitcnt vmcnt(0)
	ds_read_b128 v[130:133], v181
	ds_read_b128 v[134:137], v181 offset:1024
	ds_read_b128 v[138:141], v181 offset:2048
	ds_read_b128 v[142:145], v181 offset:3072
	ds_read_b128 v[150:153], v182
	ds_read_b128 v[154:157], v182 offset:1024
	ds_read_b128 v[158:161], v182 offset:2048
	ds_read_b128 v[162:165], v182 offset:3072
	s_cmpk_eq_i32 s69, 0x52
	s_cselect_b32 s31, s19, s66
	s_cselect_b32 s30, s64, s65
	s_cselect_b32 s35, s21, s68
	s_cselect_b32 s34, s63, s67
	ds_read_b128 v[166:169], v183
	ds_read_b128 v[170:173], v183 offset:1024
	ds_read_b128 v[186:189], v183 offset:2048
	ds_read_b128 v[190:193], v183 offset:3072
	ds_read_b128 v[194:197], v183 offset:4096
	ds_read_b128 v[198:201], v183 offset:5120
	ds_read_b128 v[202:205], v183 offset:6144
	ds_read_b128 v[206:209], v183 offset:7168
	s_add_u32 s70, s28, 0xffffc000
	s_addc_u32 s71, s29, -1
	s_mov_b32 s73, m0
	s_mov_b32 m0, s57
	s_nop 0
	global_load_lds_dwordx4 v1, s[70:71]
	s_mov_b32 m0, s73
	s_nop 0
	s_mov_b32 s73, m0
	s_mov_b32 m0, s59
	s_nop 0
	global_load_lds_dwordx4 v177, s[70:71]
	s_mov_b32 m0, s73
	s_mov_b32 s70, m0
	s_mov_b32 m0, s58
	s_nop 0
	global_load_lds_dwordx4 v1, s[28:29]
	s_mov_b32 m0, s70
	s_nop 0
	s_mov_b32 s70, m0
	s_mov_b32 m0, s60
	s_nop 0
	global_load_lds_dwordx4 v177, s[28:29]
	s_mov_b32 m0, s70
	s_waitcnt vmcnt(8)
	s_waitcnt lgkmcnt(0)
	s_barrier
	s_setprio 1
	s_waitcnt lgkmcnt(7)
	v_mfma_f32_16x16x32_bf16 v[126:129], v[130:133], v[166:169], 0
	v_mfma_f32_16x16x32_bf16 v[126:129], v[134:137], v[170:173], v[126:129]
	s_waitcnt lgkmcnt(5)
	v_mfma_f32_16x16x32_bf16 v[122:125], v[142:145], v[170:173], 0
	v_mfma_f32_16x16x32_bf16 v[122:125], v[138:141], v[166:169], v[122:125]
	s_waitcnt lgkmcnt(3)
	v_mfma_f32_16x16x32_bf16 v[110:113], v[138:141], v[186:189], 0
	v_mfma_f32_16x16x32_bf16 v[110:113], v[142:145], v[190:193], v[110:113]
	s_waitcnt lgkmcnt(1)
	v_mfma_f32_16x16x32_bf16 v[118:121], v[134:137], v[190:193], 0
	v_mfma_f32_16x16x32_bf16 v[118:121], v[130:133], v[186:189], v[118:121]
	v_mfma_f32_16x16x32_bf16 v[94:97], v[130:133], v[194:197], 0
	v_mfma_f32_16x16x32_bf16 v[94:97], v[134:137], v[198:201], v[94:97]
	v_mfma_f32_16x16x32_bf16 v[90:93], v[142:145], v[198:201], 0
	v_mfma_f32_16x16x32_bf16 v[90:93], v[138:141], v[194:197], v[90:93]
	v_mfma_f32_16x16x32_bf16 v[78:81], v[138:141], v[202:205], 0
	v_mfma_f32_16x16x32_bf16 v[78:81], v[142:145], v[206:209], v[78:81]
	s_waitcnt lgkmcnt(0)
	v_mfma_f32_16x16x32_bf16 v[86:89], v[134:137], v[206:209], 0
	v_mfma_f32_16x16x32_bf16 v[86:89], v[130:133], v[202:205], v[86:89]
	s_setprio 0
	s_setprio 1
	v_mfma_f32_16x16x32_bf16 v[114:117], v[150:153], v[166:169], 0
	v_mfma_f32_16x16x32_bf16 v[114:117], v[154:157], v[170:173], v[114:117]
	v_mfma_f32_16x16x32_bf16 v[106:109], v[162:165], v[170:173], 0
	v_mfma_f32_16x16x32_bf16 v[106:109], v[158:161], v[166:169], v[106:109]
	v_mfma_f32_16x16x32_bf16 v[98:101], v[158:161], v[186:189], 0
	v_mfma_f32_16x16x32_bf16 v[98:101], v[162:165], v[190:193], v[98:101]
	v_mfma_f32_16x16x32_bf16 v[102:105], v[154:157], v[190:193], 0
	v_mfma_f32_16x16x32_bf16 v[102:105], v[150:153], v[186:189], v[102:105]
	v_mfma_f32_16x16x32_bf16 v[82:85], v[150:153], v[194:197], 0
	v_mfma_f32_16x16x32_bf16 v[82:85], v[154:157], v[198:201], v[82:85]
	v_mfma_f32_16x16x32_bf16 v[74:77], v[162:165], v[198:201], 0
	v_mfma_f32_16x16x32_bf16 v[74:77], v[158:161], v[194:197], v[74:77]
	v_mfma_f32_16x16x32_bf16 v[66:69], v[158:161], v[202:205], 0
	v_mfma_f32_16x16x32_bf16 v[66:69], v[162:165], v[206:209], v[66:69]
	s_setprio 2
	s_barrier
	v_mfma_f32_16x16x32_bf16 v[70:73], v[154:157], v[206:209], 0
	v_mfma_f32_16x16x32_bf16 v[70:73], v[150:153], v[202:205], v[70:73]
	s_setprio 0
	ds_read_b128 v[166:169], v183 offset:16384
	ds_read_b128 v[170:173], v183 offset:17408
	ds_read_b128 v[186:189], v183 offset:18432
	ds_read_b128 v[190:193], v183 offset:19456
	ds_read_b128 v[194:197], v183 offset:20480
	ds_read_b128 v[198:201], v183 offset:21504
	ds_read_b128 v[202:205], v183 offset:22528
	ds_read_b128 v[206:209], v183 offset:23552
	s_mov_b32 s70, m0
	s_mov_b32 m0, s27
	s_nop 0
	global_load_lds_dwordx4 v176, s[30:31]
	s_mov_b32 m0, s70
	s_nop 0
	s_mov_b32 s70, m0
	s_mov_b32 m0, s45
	s_nop 0
	global_load_lds_dwordx4 v178, s[30:31]
	s_mov_b32 m0, s70
	s_add_u32 s70, s30, 0x4000
	s_addc_u32 s71, s31, 0
	s_mov_b32 s73, m0
	s_mov_b32 m0, s46
	s_nop 0
	global_load_lds_dwordx4 v176, s[70:71]
	s_mov_b32 m0, s73
	s_nop 0
	s_mov_b32 s73, m0
	s_mov_b32 m0, s47
	s_nop 0
	global_load_lds_dwordx4 v178, s[70:71]
	s_mov_b32 m0, s73
	s_waitcnt vmcnt(4)
	s_waitcnt lgkmcnt(0)
	s_barrier
	s_setprio 1
	s_waitcnt lgkmcnt(7)
	v_mfma_f32_16x16x32_bf16 v[62:65], v[130:133], v[166:169], 0
	v_mfma_f32_16x16x32_bf16 v[62:65], v[134:137], v[170:173], v[62:65]
	s_waitcnt lgkmcnt(5)
	v_mfma_f32_16x16x32_bf16 v[58:61], v[142:145], v[170:173], 0
	v_mfma_f32_16x16x32_bf16 v[58:61], v[138:141], v[166:169], v[58:61]
	s_waitcnt lgkmcnt(3)
	v_mfma_f32_16x16x32_bf16 v[42:45], v[138:141], v[186:189], 0
	v_mfma_f32_16x16x32_bf16 v[42:45], v[142:145], v[190:193], v[42:45]
	s_waitcnt lgkmcnt(1)
	v_mfma_f32_16x16x32_bf16 v[46:49], v[134:137], v[190:193], 0
	v_mfma_f32_16x16x32_bf16 v[46:49], v[130:133], v[186:189], v[46:49]
	v_mfma_f32_16x16x32_bf16 v[30:33], v[130:133], v[194:197], 0
	v_mfma_f32_16x16x32_bf16 v[30:33], v[134:137], v[198:201], v[30:33]
	v_mfma_f32_16x16x32_bf16 v[26:29], v[142:145], v[198:201], 0
	v_mfma_f32_16x16x32_bf16 v[26:29], v[138:141], v[194:197], v[26:29]
	v_mfma_f32_16x16x32_bf16 v[10:13], v[138:141], v[202:205], 0
	v_mfma_f32_16x16x32_bf16 v[10:13], v[142:145], v[206:209], v[10:13]
	s_waitcnt lgkmcnt(0)
	v_mfma_f32_16x16x32_bf16 v[14:17], v[134:137], v[206:209], 0
	v_mfma_f32_16x16x32_bf16 v[14:17], v[130:133], v[202:205], v[14:17]
	s_setprio 0
	s_setprio 1
	v_mfma_f32_16x16x32_bf16 v[54:57], v[150:153], v[166:169], 0
	v_mfma_f32_16x16x32_bf16 v[54:57], v[154:157], v[170:173], v[54:57]
	v_mfma_f32_16x16x32_bf16 v[50:53], v[162:165], v[170:173], 0
	v_mfma_f32_16x16x32_bf16 v[50:53], v[158:161], v[166:169], v[50:53]
	v_mfma_f32_16x16x32_bf16 v[34:37], v[158:161], v[186:189], 0
	v_mfma_f32_16x16x32_bf16 v[34:37], v[162:165], v[190:193], v[34:37]
	v_mfma_f32_16x16x32_bf16 v[38:41], v[154:157], v[190:193], 0
	v_mfma_f32_16x16x32_bf16 v[38:41], v[150:153], v[186:189], v[38:41]
	v_mfma_f32_16x16x32_bf16 v[22:25], v[150:153], v[194:197], 0
	v_mfma_f32_16x16x32_bf16 v[22:25], v[154:157], v[198:201], v[22:25]
	v_mfma_f32_16x16x32_bf16 v[18:21], v[162:165], v[198:201], 0
	v_mfma_f32_16x16x32_bf16 v[18:21], v[158:161], v[194:197], v[18:21]
	v_mfma_f32_16x16x32_bf16 v[2:5], v[158:161], v[202:205], 0
	v_mfma_f32_16x16x32_bf16 v[2:5], v[162:165], v[206:209], v[2:5]
	s_setprio 2
	s_barrier
	v_mfma_f32_16x16x32_bf16 v[6:9], v[154:157], v[206:209], 0
	v_mfma_f32_16x16x32_bf16 v[6:9], v[150:153], v[202:205], v[6:9]
	s_setprio 0
	ds_read_b128 v[130:133], v184
	ds_read_b128 v[134:137], v184 offset:1024
	ds_read_b128 v[138:141], v184 offset:2048
	ds_read_b128 v[142:145], v184 offset:3072
	ds_read_b128 v[150:153], v185
	ds_read_b128 v[154:157], v185 offset:1024
	ds_read_b128 v[158:161], v185 offset:2048
	ds_read_b128 v[162:165], v185 offset:3072
	ds_read_b128 v[166:169], v183 offset:32768
	ds_read_b128 v[170:173], v183 offset:33792
	ds_read_b128 v[186:189], v183 offset:34816
	ds_read_b128 v[190:193], v183 offset:35840
	ds_read_b128 v[194:197], v183 offset:36864
	ds_read_b128 v[198:201], v183 offset:37888
	ds_read_b128 v[202:205], v183 offset:38912
	ds_read_b128 v[206:209], v183 offset:39936
	s_mov_b32 s70, m0
	s_mov_b32 m0, s44
	s_nop 0
	global_load_lds_dwordx4 v1, s[34:35]
	s_mov_b32 m0, s70
	s_nop 0
	s_mov_b32 s70, m0
	s_mov_b32 m0, s48
	s_nop 0
	global_load_lds_dwordx4 v177, s[34:35]
	s_mov_b32 m0, s70
	s_add_u32 s34, s34, 0x4000
	s_addc_u32 s35, s35, 0
	s_mov_b32 s70, m0
	s_mov_b32 m0, s49
	s_nop 0
	global_load_lds_dwordx4 v1, s[34:35]
	s_mov_b32 m0, s70
	s_nop 0
	s_mov_b32 s70, m0
	s_mov_b32 m0, s50
	s_nop 0
	global_load_lds_dwordx4 v177, s[34:35]
	s_mov_b32 m0, s70
	s_waitcnt vmcnt(8)
	s_waitcnt lgkmcnt(0)
	s_barrier
	s_setprio 1
	s_waitcnt lgkmcnt(7)
	v_mfma_f32_16x16x32_bf16 v[126:129], v[130:133], v[166:169], v[126:129]
	v_mfma_f32_16x16x32_bf16 v[126:129], v[134:137], v[170:173], v[126:129]
	s_waitcnt lgkmcnt(5)
	v_mfma_f32_16x16x32_bf16 v[122:125], v[142:145], v[170:173], v[122:125]
	v_mfma_f32_16x16x32_bf16 v[122:125], v[138:141], v[166:169], v[122:125]
	s_waitcnt lgkmcnt(3)
	v_mfma_f32_16x16x32_bf16 v[110:113], v[138:141], v[186:189], v[110:113]
	v_mfma_f32_16x16x32_bf16 v[110:113], v[142:145], v[190:193], v[110:113]
	s_waitcnt lgkmcnt(1)
	v_mfma_f32_16x16x32_bf16 v[118:121], v[134:137], v[190:193], v[118:121]
	v_mfma_f32_16x16x32_bf16 v[118:121], v[130:133], v[186:189], v[118:121]
	v_mfma_f32_16x16x32_bf16 v[94:97], v[130:133], v[194:197], v[94:97]
	v_mfma_f32_16x16x32_bf16 v[94:97], v[134:137], v[198:201], v[94:97]
	v_mfma_f32_16x16x32_bf16 v[90:93], v[142:145], v[198:201], v[90:93]
	v_mfma_f32_16x16x32_bf16 v[90:93], v[138:141], v[194:197], v[90:93]
	v_mfma_f32_16x16x32_bf16 v[78:81], v[138:141], v[202:205], v[78:81]
	v_mfma_f32_16x16x32_bf16 v[78:81], v[142:145], v[206:209], v[78:81]
	s_waitcnt lgkmcnt(0)
	v_mfma_f32_16x16x32_bf16 v[86:89], v[134:137], v[206:209], v[86:89]
	v_mfma_f32_16x16x32_bf16 v[86:89], v[130:133], v[202:205], v[86:89]
	s_setprio 0
	s_setprio 1
	v_mfma_f32_16x16x32_bf16 v[114:117], v[150:153], v[166:169], v[114:117]
	v_mfma_f32_16x16x32_bf16 v[114:117], v[154:157], v[170:173], v[114:117]
	v_mfma_f32_16x16x32_bf16 v[106:109], v[162:165], v[170:173], v[106:109]
	v_mfma_f32_16x16x32_bf16 v[106:109], v[158:161], v[166:169], v[106:109]
	v_mfma_f32_16x16x32_bf16 v[98:101], v[158:161], v[186:189], v[98:101]
	v_mfma_f32_16x16x32_bf16 v[98:101], v[162:165], v[190:193], v[98:101]
	v_mfma_f32_16x16x32_bf16 v[102:105], v[154:157], v[190:193], v[102:105]
	v_mfma_f32_16x16x32_bf16 v[102:105], v[150:153], v[186:189], v[102:105]
	v_mfma_f32_16x16x32_bf16 v[82:85], v[150:153], v[194:197], v[82:85]
	v_mfma_f32_16x16x32_bf16 v[82:85], v[154:157], v[198:201], v[82:85]
	v_mfma_f32_16x16x32_bf16 v[74:77], v[162:165], v[198:201], v[74:77]
	v_mfma_f32_16x16x32_bf16 v[74:77], v[158:161], v[194:197], v[74:77]
	v_mfma_f32_16x16x32_bf16 v[66:69], v[158:161], v[202:205], v[66:69]
	v_mfma_f32_16x16x32_bf16 v[66:69], v[162:165], v[206:209], v[66:69]
	s_setprio 2
	s_barrier
	v_mfma_f32_16x16x32_bf16 v[70:73], v[154:157], v[206:209], v[70:73]
	v_mfma_f32_16x16x32_bf16 v[70:73], v[150:153], v[202:205], v[70:73]
	s_setprio 0
	ds_read_b128 v[166:169], v183 offset:49152
	ds_read_b128 v[170:173], v183 offset:50176
	ds_read_b128 v[186:189], v183 offset:51200
	ds_read_b128 v[190:193], v183 offset:52224
	ds_read_b128 v[194:197], v183 offset:53248
	ds_read_b128 v[198:201], v183 offset:54272
	ds_read_b128 v[202:205], v183 offset:55296
	ds_read_b128 v[206:209], v183 offset:56320
	s_add_u32 s34, s30, 0x40000
	s_addc_u32 s35, s31, 0
	s_mov_b32 s70, m0
	s_mov_b32 m0, s51
	s_nop 0
	global_load_lds_dwordx4 v176, s[34:35]
	s_mov_b32 m0, s70
	s_add_u32 s30, s30, 0x44000
	s_mov_b32 s70, m0
	s_mov_b32 m0, s52
	s_nop 0
	global_load_lds_dwordx4 v178, s[34:35]
	s_mov_b32 m0, s70
	s_addc_u32 s31, s31, 0
	s_mov_b32 s34, m0
	s_mov_b32 m0, s53
	s_nop 0
	global_load_lds_dwordx4 v176, s[30:31]
	s_mov_b32 m0, s34
	s_nop 0
	s_mov_b32 s34, m0
	s_mov_b32 m0, s54
	s_nop 0
	global_load_lds_dwordx4 v178, s[30:31]
	s_mov_b32 m0, s34
	s_waitcnt vmcnt(4)
	s_waitcnt lgkmcnt(0)
	s_barrier
	s_setprio 1
	s_waitcnt lgkmcnt(7)
	v_mfma_f32_16x16x32_bf16 v[62:65], v[130:133], v[166:169], v[62:65]
	v_mfma_f32_16x16x32_bf16 v[62:65], v[134:137], v[170:173], v[62:65]
	s_waitcnt lgkmcnt(5)
	v_mfma_f32_16x16x32_bf16 v[58:61], v[142:145], v[170:173], v[58:61]
	v_mfma_f32_16x16x32_bf16 v[58:61], v[138:141], v[166:169], v[58:61]
	s_waitcnt lgkmcnt(3)
	v_mfma_f32_16x16x32_bf16 v[42:45], v[138:141], v[186:189], v[42:45]
	v_mfma_f32_16x16x32_bf16 v[42:45], v[142:145], v[190:193], v[42:45]
	s_waitcnt lgkmcnt(1)
	v_mfma_f32_16x16x32_bf16 v[46:49], v[134:137], v[190:193], v[46:49]
	v_mfma_f32_16x16x32_bf16 v[46:49], v[130:133], v[186:189], v[46:49]
	v_mfma_f32_16x16x32_bf16 v[30:33], v[130:133], v[194:197], v[30:33]
	v_mfma_f32_16x16x32_bf16 v[30:33], v[134:137], v[198:201], v[30:33]
	v_mfma_f32_16x16x32_bf16 v[26:29], v[142:145], v[198:201], v[26:29]
	v_mfma_f32_16x16x32_bf16 v[26:29], v[138:141], v[194:197], v[26:29]
	v_mfma_f32_16x16x32_bf16 v[10:13], v[138:141], v[202:205], v[10:13]
	v_mfma_f32_16x16x32_bf16 v[10:13], v[142:145], v[206:209], v[10:13]
	s_waitcnt lgkmcnt(0)
	v_mfma_f32_16x16x32_bf16 v[14:17], v[134:137], v[206:209], v[14:17]
	v_mfma_f32_16x16x32_bf16 v[14:17], v[130:133], v[202:205], v[14:17]
	s_setprio 0
	s_setprio 1
	v_mfma_f32_16x16x32_bf16 v[54:57], v[150:153], v[166:169], v[54:57]
	v_mfma_f32_16x16x32_bf16 v[54:57], v[154:157], v[170:173], v[54:57]
	v_mfma_f32_16x16x32_bf16 v[50:53], v[162:165], v[170:173], v[50:53]
	v_mfma_f32_16x16x32_bf16 v[50:53], v[158:161], v[166:169], v[50:53]
	v_mfma_f32_16x16x32_bf16 v[34:37], v[158:161], v[186:189], v[34:37]
	v_mfma_f32_16x16x32_bf16 v[34:37], v[162:165], v[190:193], v[34:37]
	v_mfma_f32_16x16x32_bf16 v[38:41], v[154:157], v[190:193], v[38:41]
	v_mfma_f32_16x16x32_bf16 v[38:41], v[150:153], v[186:189], v[38:41]
	v_mfma_f32_16x16x32_bf16 v[22:25], v[150:153], v[194:197], v[22:25]
	v_mfma_f32_16x16x32_bf16 v[22:25], v[154:157], v[198:201], v[22:25]
	v_mfma_f32_16x16x32_bf16 v[18:21], v[162:165], v[198:201], v[18:21]
	v_mfma_f32_16x16x32_bf16 v[18:21], v[158:161], v[194:197], v[18:21]
	v_mfma_f32_16x16x32_bf16 v[2:5], v[158:161], v[202:205], v[2:5]
	v_mfma_f32_16x16x32_bf16 v[2:5], v[162:165], v[206:209], v[2:5]
	s_setprio 2
	s_barrier
	v_mfma_f32_16x16x32_bf16 v[6:9], v[154:157], v[206:209], v[6:9]
	v_mfma_f32_16x16x32_bf16 v[6:9], v[150:153], v[202:205], v[6:9]
	s_setprio 0
	s_add_i32 s69, s69, 2
	s_add_u32 s65, s65, 0x80000
	s_addc_u32 s66, s66, 0
	s_add_u32 s28, s28, 0x400000
	s_addc_u32 s29, s29, 0
	s_add_u32 s67, s67, 0x400000
	s_addc_u32 s68, s68, 0
	s_cmpk_gt_u32 s69, 0x53
	.p2align 6
.LBB0_2792:
	ds_read_b128 v[130:133], v181
	ds_read_b128 v[134:137], v181 offset:1024
	ds_read_b128 v[138:141], v181 offset:2048
	ds_read_b128 v[142:145], v181 offset:3072
	ds_read_b128 v[150:153], v182
	ds_read_b128 v[154:157], v182 offset:1024
	ds_read_b128 v[158:161], v182 offset:2048
	ds_read_b128 v[162:165], v182 offset:3072
	s_cmpk_eq_i32 s69, 0x52
	s_cselect_b32 s31, s19, s66
	s_cselect_b32 s30, s64, s65
	s_cselect_b32 s35, s21, s68
	s_cselect_b32 s34, s63, s67
	ds_read_b128 v[166:169], v183
	ds_read_b128 v[170:173], v183 offset:1024
	ds_read_b128 v[186:189], v183 offset:2048
	ds_read_b128 v[190:193], v183 offset:3072
	ds_read_b128 v[194:197], v183 offset:4096
	ds_read_b128 v[198:201], v183 offset:5120
	ds_read_b128 v[202:205], v183 offset:6144
	ds_read_b128 v[206:209], v183 offset:7168
	s_add_u32 s70, s28, 0xffffc000
	s_addc_u32 s71, s29, -1
	s_mov_b32 s73, m0
	s_mov_b32 m0, s57
	s_nop 0
	global_load_lds_dwordx4 v1, s[70:71]
	s_mov_b32 m0, s73
	s_nop 0
	s_mov_b32 s73, m0
	s_mov_b32 m0, s59
	s_nop 0
	global_load_lds_dwordx4 v177, s[70:71]
	s_mov_b32 m0, s73
	s_mov_b32 s70, m0
	s_mov_b32 m0, s58
	s_nop 0
	global_load_lds_dwordx4 v1, s[28:29]
	s_mov_b32 m0, s70
	s_nop 0
	s_mov_b32 s70, m0
	s_mov_b32 m0, s60
	s_nop 0
	global_load_lds_dwordx4 v177, s[28:29]
	s_mov_b32 m0, s70
	s_waitcnt vmcnt(8)
	s_waitcnt lgkmcnt(0)
	s_barrier
	s_setprio 1
	s_waitcnt lgkmcnt(7)
	v_mfma_f32_16x16x32_bf16 v[126:129], v[130:133], v[166:169], v[126:129]
	v_mfma_f32_16x16x32_bf16 v[126:129], v[134:137], v[170:173], v[126:129]
	s_waitcnt lgkmcnt(5)
	v_mfma_f32_16x16x32_bf16 v[122:125], v[142:145], v[170:173], v[122:125]
	v_mfma_f32_16x16x32_bf16 v[122:125], v[138:141], v[166:169], v[122:125]
	s_waitcnt lgkmcnt(3)
	v_mfma_f32_16x16x32_bf16 v[110:113], v[138:141], v[186:189], v[110:113]
	v_mfma_f32_16x16x32_bf16 v[110:113], v[142:145], v[190:193], v[110:113]
	s_waitcnt lgkmcnt(1)
	v_mfma_f32_16x16x32_bf16 v[118:121], v[134:137], v[190:193], v[118:121]
	v_mfma_f32_16x16x32_bf16 v[118:121], v[130:133], v[186:189], v[118:121]
	v_mfma_f32_16x16x32_bf16 v[94:97], v[130:133], v[194:197], v[94:97]
	v_mfma_f32_16x16x32_bf16 v[94:97], v[134:137], v[198:201], v[94:97]
	v_mfma_f32_16x16x32_bf16 v[90:93], v[142:145], v[198:201], v[90:93]
	v_mfma_f32_16x16x32_bf16 v[90:93], v[138:141], v[194:197], v[90:93]
	v_mfma_f32_16x16x32_bf16 v[78:81], v[138:141], v[202:205], v[78:81]
	v_mfma_f32_16x16x32_bf16 v[78:81], v[142:145], v[206:209], v[78:81]
	s_waitcnt lgkmcnt(0)
	v_mfma_f32_16x16x32_bf16 v[86:89], v[134:137], v[206:209], v[86:89]
	v_mfma_f32_16x16x32_bf16 v[86:89], v[130:133], v[202:205], v[86:89]
	s_setprio 0
	s_setprio 1
	v_mfma_f32_16x16x32_bf16 v[114:117], v[150:153], v[166:169], v[114:117]
	v_mfma_f32_16x16x32_bf16 v[114:117], v[154:157], v[170:173], v[114:117]
	v_mfma_f32_16x16x32_bf16 v[106:109], v[162:165], v[170:173], v[106:109]
	v_mfma_f32_16x16x32_bf16 v[106:109], v[158:161], v[166:169], v[106:109]
	v_mfma_f32_16x16x32_bf16 v[98:101], v[158:161], v[186:189], v[98:101]
	v_mfma_f32_16x16x32_bf16 v[98:101], v[162:165], v[190:193], v[98:101]
	v_mfma_f32_16x16x32_bf16 v[102:105], v[154:157], v[190:193], v[102:105]
	v_mfma_f32_16x16x32_bf16 v[102:105], v[150:153], v[186:189], v[102:105]
	v_mfma_f32_16x16x32_bf16 v[82:85], v[150:153], v[194:197], v[82:85]
	v_mfma_f32_16x16x32_bf16 v[82:85], v[154:157], v[198:201], v[82:85]
	v_mfma_f32_16x16x32_bf16 v[74:77], v[162:165], v[198:201], v[74:77]
	v_mfma_f32_16x16x32_bf16 v[74:77], v[158:161], v[194:197], v[74:77]
	v_mfma_f32_16x16x32_bf16 v[66:69], v[158:161], v[202:205], v[66:69]
	v_mfma_f32_16x16x32_bf16 v[66:69], v[162:165], v[206:209], v[66:69]
	s_setprio 2
	s_barrier
	v_mfma_f32_16x16x32_bf16 v[70:73], v[154:157], v[206:209], v[70:73]
	v_mfma_f32_16x16x32_bf16 v[70:73], v[150:153], v[202:205], v[70:73]
	s_setprio 0
	ds_read_b128 v[166:169], v183 offset:16384
	ds_read_b128 v[170:173], v183 offset:17408
	ds_read_b128 v[186:189], v183 offset:18432
	ds_read_b128 v[190:193], v183 offset:19456
	ds_read_b128 v[194:197], v183 offset:20480
	ds_read_b128 v[198:201], v183 offset:21504
	ds_read_b128 v[202:205], v183 offset:22528
	ds_read_b128 v[206:209], v183 offset:23552
	s_mov_b32 s70, m0
	s_mov_b32 m0, s27
	s_nop 0
	global_load_lds_dwordx4 v176, s[30:31]
	s_mov_b32 m0, s70
	s_nop 0
	s_mov_b32 s70, m0
	s_mov_b32 m0, s45
	s_nop 0
	global_load_lds_dwordx4 v178, s[30:31]
	s_mov_b32 m0, s70
	s_add_u32 s70, s30, 0x4000
	s_addc_u32 s71, s31, 0
	s_mov_b32 s73, m0
	s_mov_b32 m0, s46
	s_nop 0
	global_load_lds_dwordx4 v176, s[70:71]
	s_mov_b32 m0, s73
	s_nop 0
	s_mov_b32 s73, m0
	s_mov_b32 m0, s47
	s_nop 0
	global_load_lds_dwordx4 v178, s[70:71]
	s_mov_b32 m0, s73
	s_waitcnt vmcnt(4)
	s_waitcnt lgkmcnt(0)
	s_barrier
	s_setprio 1
	s_waitcnt lgkmcnt(7)
	v_mfma_f32_16x16x32_bf16 v[62:65], v[130:133], v[166:169], v[62:65]
	v_mfma_f32_16x16x32_bf16 v[62:65], v[134:137], v[170:173], v[62:65]
	s_waitcnt lgkmcnt(5)
	v_mfma_f32_16x16x32_bf16 v[58:61], v[142:145], v[170:173], v[58:61]
	v_mfma_f32_16x16x32_bf16 v[58:61], v[138:141], v[166:169], v[58:61]
	s_waitcnt lgkmcnt(3)
	v_mfma_f32_16x16x32_bf16 v[42:45], v[138:141], v[186:189], v[42:45]
	v_mfma_f32_16x16x32_bf16 v[42:45], v[142:145], v[190:193], v[42:45]
	s_waitcnt lgkmcnt(1)
	v_mfma_f32_16x16x32_bf16 v[46:49], v[134:137], v[190:193], v[46:49]
	v_mfma_f32_16x16x32_bf16 v[46:49], v[130:133], v[186:189], v[46:49]
	v_mfma_f32_16x16x32_bf16 v[30:33], v[130:133], v[194:197], v[30:33]
	v_mfma_f32_16x16x32_bf16 v[30:33], v[134:137], v[198:201], v[30:33]
	v_mfma_f32_16x16x32_bf16 v[26:29], v[142:145], v[198:201], v[26:29]
	v_mfma_f32_16x16x32_bf16 v[26:29], v[138:141], v[194:197], v[26:29]
	v_mfma_f32_16x16x32_bf16 v[10:13], v[138:141], v[202:205], v[10:13]
	v_mfma_f32_16x16x32_bf16 v[10:13], v[142:145], v[206:209], v[10:13]
	s_waitcnt lgkmcnt(0)
	v_mfma_f32_16x16x32_bf16 v[14:17], v[134:137], v[206:209], v[14:17]
	v_mfma_f32_16x16x32_bf16 v[14:17], v[130:133], v[202:205], v[14:17]
	s_setprio 0
	s_setprio 1
	v_mfma_f32_16x16x32_bf16 v[54:57], v[150:153], v[166:169], v[54:57]
	v_mfma_f32_16x16x32_bf16 v[54:57], v[154:157], v[170:173], v[54:57]
	v_mfma_f32_16x16x32_bf16 v[50:53], v[162:165], v[170:173], v[50:53]
	v_mfma_f32_16x16x32_bf16 v[50:53], v[158:161], v[166:169], v[50:53]
	v_mfma_f32_16x16x32_bf16 v[34:37], v[158:161], v[186:189], v[34:37]
	v_mfma_f32_16x16x32_bf16 v[34:37], v[162:165], v[190:193], v[34:37]
	v_mfma_f32_16x16x32_bf16 v[38:41], v[154:157], v[190:193], v[38:41]
	v_mfma_f32_16x16x32_bf16 v[38:41], v[150:153], v[186:189], v[38:41]
	v_mfma_f32_16x16x32_bf16 v[22:25], v[150:153], v[194:197], v[22:25]
	v_mfma_f32_16x16x32_bf16 v[22:25], v[154:157], v[198:201], v[22:25]
	v_mfma_f32_16x16x32_bf16 v[18:21], v[162:165], v[198:201], v[18:21]
	v_mfma_f32_16x16x32_bf16 v[18:21], v[158:161], v[194:197], v[18:21]
	v_mfma_f32_16x16x32_bf16 v[2:5], v[158:161], v[202:205], v[2:5]
	v_mfma_f32_16x16x32_bf16 v[2:5], v[162:165], v[206:209], v[2:5]
	s_setprio 2
	s_barrier
	v_mfma_f32_16x16x32_bf16 v[6:9], v[154:157], v[206:209], v[6:9]
	v_mfma_f32_16x16x32_bf16 v[6:9], v[150:153], v[202:205], v[6:9]
	s_setprio 0
	ds_read_b128 v[130:133], v184
	ds_read_b128 v[134:137], v184 offset:1024
	ds_read_b128 v[138:141], v184 offset:2048
	ds_read_b128 v[142:145], v184 offset:3072
	ds_read_b128 v[150:153], v185
	ds_read_b128 v[154:157], v185 offset:1024
	ds_read_b128 v[158:161], v185 offset:2048
	ds_read_b128 v[162:165], v185 offset:3072
	ds_read_b128 v[166:169], v183 offset:32768
	ds_read_b128 v[170:173], v183 offset:33792
	ds_read_b128 v[186:189], v183 offset:34816
	ds_read_b128 v[190:193], v183 offset:35840
	ds_read_b128 v[194:197], v183 offset:36864
	ds_read_b128 v[198:201], v183 offset:37888
	ds_read_b128 v[202:205], v183 offset:38912
	ds_read_b128 v[206:209], v183 offset:39936
	s_mov_b32 s70, m0
	s_mov_b32 m0, s44
	s_nop 0
	global_load_lds_dwordx4 v1, s[34:35]
	s_mov_b32 m0, s70
	s_nop 0
	s_mov_b32 s70, m0
	s_mov_b32 m0, s48
	s_nop 0
	global_load_lds_dwordx4 v177, s[34:35]
	s_mov_b32 m0, s70
	s_add_u32 s34, s34, 0x4000
	s_addc_u32 s35, s35, 0
	s_mov_b32 s70, m0
	s_mov_b32 m0, s49
	s_nop 0
	global_load_lds_dwordx4 v1, s[34:35]
	s_mov_b32 m0, s70
	s_nop 0
	s_mov_b32 s70, m0
	s_mov_b32 m0, s50
	s_nop 0
	global_load_lds_dwordx4 v177, s[34:35]
	s_mov_b32 m0, s70
	s_waitcnt vmcnt(8)
	s_waitcnt lgkmcnt(0)
	s_barrier
	s_setprio 1
	s_waitcnt lgkmcnt(7)
	v_mfma_f32_16x16x32_bf16 v[126:129], v[130:133], v[166:169], v[126:129]
	v_mfma_f32_16x16x32_bf16 v[126:129], v[134:137], v[170:173], v[126:129]
	s_waitcnt lgkmcnt(5)
	v_mfma_f32_16x16x32_bf16 v[122:125], v[142:145], v[170:173], v[122:125]
	v_mfma_f32_16x16x32_bf16 v[122:125], v[138:141], v[166:169], v[122:125]
	s_waitcnt lgkmcnt(3)
	v_mfma_f32_16x16x32_bf16 v[110:113], v[138:141], v[186:189], v[110:113]
	v_mfma_f32_16x16x32_bf16 v[110:113], v[142:145], v[190:193], v[110:113]
	s_waitcnt lgkmcnt(1)
	v_mfma_f32_16x16x32_bf16 v[118:121], v[134:137], v[190:193], v[118:121]
	v_mfma_f32_16x16x32_bf16 v[118:121], v[130:133], v[186:189], v[118:121]
	v_mfma_f32_16x16x32_bf16 v[94:97], v[130:133], v[194:197], v[94:97]
	v_mfma_f32_16x16x32_bf16 v[94:97], v[134:137], v[198:201], v[94:97]
	v_mfma_f32_16x16x32_bf16 v[90:93], v[142:145], v[198:201], v[90:93]
	v_mfma_f32_16x16x32_bf16 v[90:93], v[138:141], v[194:197], v[90:93]
	v_mfma_f32_16x16x32_bf16 v[78:81], v[138:141], v[202:205], v[78:81]
	v_mfma_f32_16x16x32_bf16 v[78:81], v[142:145], v[206:209], v[78:81]
	s_waitcnt lgkmcnt(0)
	v_mfma_f32_16x16x32_bf16 v[86:89], v[134:137], v[206:209], v[86:89]
	v_mfma_f32_16x16x32_bf16 v[86:89], v[130:133], v[202:205], v[86:89]
	s_setprio 0
	s_setprio 1
	v_mfma_f32_16x16x32_bf16 v[114:117], v[150:153], v[166:169], v[114:117]
	v_mfma_f32_16x16x32_bf16 v[114:117], v[154:157], v[170:173], v[114:117]
	v_mfma_f32_16x16x32_bf16 v[106:109], v[162:165], v[170:173], v[106:109]
	v_mfma_f32_16x16x32_bf16 v[106:109], v[158:161], v[166:169], v[106:109]
	v_mfma_f32_16x16x32_bf16 v[98:101], v[158:161], v[186:189], v[98:101]
	v_mfma_f32_16x16x32_bf16 v[98:101], v[162:165], v[190:193], v[98:101]
	v_mfma_f32_16x16x32_bf16 v[102:105], v[154:157], v[190:193], v[102:105]
	v_mfma_f32_16x16x32_bf16 v[102:105], v[150:153], v[186:189], v[102:105]
	v_mfma_f32_16x16x32_bf16 v[82:85], v[150:153], v[194:197], v[82:85]
	v_mfma_f32_16x16x32_bf16 v[82:85], v[154:157], v[198:201], v[82:85]
	v_mfma_f32_16x16x32_bf16 v[74:77], v[162:165], v[198:201], v[74:77]
	v_mfma_f32_16x16x32_bf16 v[74:77], v[158:161], v[194:197], v[74:77]
	v_mfma_f32_16x16x32_bf16 v[66:69], v[158:161], v[202:205], v[66:69]
	v_mfma_f32_16x16x32_bf16 v[66:69], v[162:165], v[206:209], v[66:69]
	s_setprio 2
	s_barrier
	v_mfma_f32_16x16x32_bf16 v[70:73], v[154:157], v[206:209], v[70:73]
	v_mfma_f32_16x16x32_bf16 v[70:73], v[150:153], v[202:205], v[70:73]
	s_setprio 0
	ds_read_b128 v[166:169], v183 offset:49152
	ds_read_b128 v[170:173], v183 offset:50176
	ds_read_b128 v[186:189], v183 offset:51200
	ds_read_b128 v[190:193], v183 offset:52224
	ds_read_b128 v[194:197], v183 offset:53248
	ds_read_b128 v[198:201], v183 offset:54272
	ds_read_b128 v[202:205], v183 offset:55296
	ds_read_b128 v[206:209], v183 offset:56320
	s_add_u32 s34, s30, 0x40000
	s_addc_u32 s35, s31, 0
	s_mov_b32 s70, m0
	s_mov_b32 m0, s51
	s_nop 0
	global_load_lds_dwordx4 v176, s[34:35]
	s_mov_b32 m0, s70
	s_add_u32 s30, s30, 0x44000
	s_mov_b32 s70, m0
	s_mov_b32 m0, s52
	s_nop 0
	global_load_lds_dwordx4 v178, s[34:35]
	s_mov_b32 m0, s70
	s_addc_u32 s31, s31, 0
	s_mov_b32 s34, m0
	s_mov_b32 m0, s53
	s_nop 0
	global_load_lds_dwordx4 v176, s[30:31]
	s_mov_b32 m0, s34
	s_nop 0
	s_mov_b32 s34, m0
	s_mov_b32 m0, s54
	s_nop 0
	global_load_lds_dwordx4 v178, s[30:31]
	s_mov_b32 m0, s34
	s_waitcnt vmcnt(4)
	s_waitcnt lgkmcnt(0)
	s_barrier
	s_setprio 1
	s_waitcnt lgkmcnt(7)
	v_mfma_f32_16x16x32_bf16 v[62:65], v[130:133], v[166:169], v[62:65]
	v_mfma_f32_16x16x32_bf16 v[62:65], v[134:137], v[170:173], v[62:65]
	s_waitcnt lgkmcnt(5)
	v_mfma_f32_16x16x32_bf16 v[58:61], v[142:145], v[170:173], v[58:61]
	v_mfma_f32_16x16x32_bf16 v[58:61], v[138:141], v[166:169], v[58:61]
	s_waitcnt lgkmcnt(3)
	v_mfma_f32_16x16x32_bf16 v[42:45], v[138:141], v[186:189], v[42:45]
	v_mfma_f32_16x16x32_bf16 v[42:45], v[142:145], v[190:193], v[42:45]
	s_waitcnt lgkmcnt(1)
	v_mfma_f32_16x16x32_bf16 v[46:49], v[134:137], v[190:193], v[46:49]
	v_mfma_f32_16x16x32_bf16 v[46:49], v[130:133], v[186:189], v[46:49]
	v_mfma_f32_16x16x32_bf16 v[30:33], v[130:133], v[194:197], v[30:33]
	v_mfma_f32_16x16x32_bf16 v[30:33], v[134:137], v[198:201], v[30:33]
	v_mfma_f32_16x16x32_bf16 v[26:29], v[142:145], v[198:201], v[26:29]
	v_mfma_f32_16x16x32_bf16 v[26:29], v[138:141], v[194:197], v[26:29]
	v_mfma_f32_16x16x32_bf16 v[10:13], v[138:141], v[202:205], v[10:13]
	v_mfma_f32_16x16x32_bf16 v[10:13], v[142:145], v[206:209], v[10:13]
	s_waitcnt lgkmcnt(0)
	v_mfma_f32_16x16x32_bf16 v[14:17], v[134:137], v[206:209], v[14:17]
	v_mfma_f32_16x16x32_bf16 v[14:17], v[130:133], v[202:205], v[14:17]
	s_setprio 0
	s_setprio 1
	v_mfma_f32_16x16x32_bf16 v[54:57], v[150:153], v[166:169], v[54:57]
	v_mfma_f32_16x16x32_bf16 v[54:57], v[154:157], v[170:173], v[54:57]
	v_mfma_f32_16x16x32_bf16 v[50:53], v[162:165], v[170:173], v[50:53]
	v_mfma_f32_16x16x32_bf16 v[50:53], v[158:161], v[166:169], v[50:53]
	v_mfma_f32_16x16x32_bf16 v[34:37], v[158:161], v[186:189], v[34:37]
	v_mfma_f32_16x16x32_bf16 v[34:37], v[162:165], v[190:193], v[34:37]
	v_mfma_f32_16x16x32_bf16 v[38:41], v[154:157], v[190:193], v[38:41]
	v_mfma_f32_16x16x32_bf16 v[38:41], v[150:153], v[186:189], v[38:41]
	v_mfma_f32_16x16x32_bf16 v[22:25], v[150:153], v[194:197], v[22:25]
	v_mfma_f32_16x16x32_bf16 v[22:25], v[154:157], v[198:201], v[22:25]
	v_mfma_f32_16x16x32_bf16 v[18:21], v[162:165], v[198:201], v[18:21]
	v_mfma_f32_16x16x32_bf16 v[18:21], v[158:161], v[194:197], v[18:21]
	v_mfma_f32_16x16x32_bf16 v[2:5], v[158:161], v[202:205], v[2:5]
	v_mfma_f32_16x16x32_bf16 v[2:5], v[162:165], v[206:209], v[2:5]
	s_setprio 2
	s_barrier
	v_mfma_f32_16x16x32_bf16 v[6:9], v[154:157], v[206:209], v[6:9]
	v_mfma_f32_16x16x32_bf16 v[6:9], v[150:153], v[202:205], v[6:9]
	s_setprio 0
	s_add_i32 s69, s69, 2
	s_add_u32 s65, s65, 0x80000
	s_addc_u32 s66, s66, 0
	s_add_u32 s28, s28, 0x400000
	s_addc_u32 s29, s29, 0
	s_add_u32 s67, s67, 0x400000
	s_addc_u32 s68, s68, 0
	s_cmpk_gt_u32 s69, 0x53
	s_cbranch_scc0 .LBB0_2792
	s_and_b64 vcc, exec, s[8:9]
	s_cbranch_vccz .LBB0_2795
	s_barrier
